# hand-specialised Hyena fft8192: per-pass constant strides, immediate LDS offsets, pk f32 butterflies (same f32 algorithm); plus LRU scan chunking and P6 ctx-half LDS read hoist
# speedup vs baseline: 1.0752x; 1.0578x over previous
;     ...
;     if (tid < 64) {
;       const int c = tid;
;       float h = 0.f, A = 1.f;
;       if (pass == 3) { const f32x2 c0 = ((const f32x2*)carry)[(0 * 2 + dir) * 64 + c], c1 = ((const f32x2*)carry)[(1 * 2 + dir) * 64 + c]; h = c1.x * c0.y + c1.y; }
;       if (dir == 0) {
; #pragma unroll 8
;         for (int t = 0; t < 64; ++t) { float a = sa[c * 65 + t]; h = a * h + sb[c * 65 + t]; A *= a; sb[c * 65 + t] = h; }
;       } else {
; #pragma unroll 8
;         for (int t = 63; t >= 0; --t) { float a = sa[c * 65 + t]; h = a * h + sb[c * 65 + t]; A *= a; sb[c * 65 + t] = h; }
;       }
;       if (pass == 1) agg[((size_t)(b * 68 + j) * 2 + dir) * 512 + g * 64 + c] = mkf2(A, h);
;     }
.LBB0_631:
	v_mov_b32_e32 v44, v39
	v_add_u32_e32 v45, 0x4100, v44
	ds_read2_b32 v[132:133], v44 offset0:0 offset1:1
	ds_read2_b32 v[134:135], v44 offset0:2 offset1:3
	ds_read2_b32 v[136:137], v44 offset0:4 offset1:5
	ds_read2_b32 v[138:139], v44 offset0:6 offset1:7
	ds_read2_b32 v[140:141], v45 offset0:0 offset1:1
	ds_read2_b32 v[142:143], v45 offset0:2 offset1:3
	ds_read2_b32 v[144:145], v45 offset0:4 offset1:5
	ds_read2_b32 v[146:147], v45 offset0:6 offset1:7
	ds_read2_b32 v[148:149], v44 offset0:8 offset1:9
	ds_read2_b32 v[150:151], v44 offset0:10 offset1:11
	ds_read2_b32 v[152:153], v44 offset0:12 offset1:13
	ds_read2_b32 v[154:155], v44 offset0:14 offset1:15
	ds_read2_b32 v[156:157], v45 offset0:8 offset1:9
	ds_read2_b32 v[158:159], v45 offset0:10 offset1:11
	ds_read2_b32 v[160:161], v45 offset0:12 offset1:13
	ds_read2_b32 v[162:163], v45 offset0:14 offset1:15
	s_waitcnt lgkmcnt(8)
	v_mul_f32_e32 v36, v36, v132
	v_fma_f32 v140, v37, v132, v140
	v_mul_f32_e32 v36, v36, v133
	v_fma_f32 v141, v140, v133, v141
	v_mul_f32_e32 v36, v36, v134
	v_fma_f32 v142, v141, v134, v142
	v_mul_f32_e32 v36, v36, v135
	v_fma_f32 v143, v142, v135, v143
	v_mul_f32_e32 v36, v36, v136
	v_fma_f32 v144, v143, v136, v144
	v_mul_f32_e32 v36, v36, v137
	v_fma_f32 v145, v144, v137, v145
	v_mul_f32_e32 v36, v36, v138
	v_fma_f32 v146, v145, v138, v146
	v_mul_f32_e32 v36, v36, v139
	v_fma_f32 v147, v146, v139, v147
	v_mov_b32_e32 v37, v147
	ds_write2_b32 v45, v140, v141 offset0:0 offset1:1
	ds_write2_b32 v45, v142, v143 offset0:2 offset1:3
	ds_write2_b32 v45, v144, v145 offset0:4 offset1:5
	ds_write2_b32 v45, v146, v147 offset0:6 offset1:7
	ds_read2_b32 v[132:133], v44 offset0:16 offset1:17
	ds_read2_b32 v[134:135], v44 offset0:18 offset1:19
	ds_read2_b32 v[136:137], v44 offset0:20 offset1:21
	ds_read2_b32 v[138:139], v44 offset0:22 offset1:23
	ds_read2_b32 v[140:141], v45 offset0:16 offset1:17
	ds_read2_b32 v[142:143], v45 offset0:18 offset1:19
	ds_read2_b32 v[144:145], v45 offset0:20 offset1:21
	ds_read2_b32 v[146:147], v45 offset0:22 offset1:23
	s_waitcnt lgkmcnt(12)
	v_mul_f32_e32 v36, v36, v148
	v_fma_f32 v156, v37, v148, v156
	v_mul_f32_e32 v36, v36, v149
	v_fma_f32 v157, v156, v149, v157
	v_mul_f32_e32 v36, v36, v150
	v_fma_f32 v158, v157, v150, v158
	v_mul_f32_e32 v36, v36, v151
	v_fma_f32 v159, v158, v151, v159
	v_mul_f32_e32 v36, v36, v152
	v_fma_f32 v160, v159, v152, v160
	v_mul_f32_e32 v36, v36, v153
	v_fma_f32 v161, v160, v153, v161
	v_mul_f32_e32 v36, v36, v154
	v_fma_f32 v162, v161, v154, v162
	v_mul_f32_e32 v36, v36, v155
	v_fma_f32 v163, v162, v155, v163
	v_mov_b32_e32 v37, v163
	ds_write2_b32 v45, v156, v157 offset0:8 offset1:9
	ds_write2_b32 v45, v158, v159 offset0:10 offset1:11
	ds_write2_b32 v45, v160, v161 offset0:12 offset1:13
	ds_write2_b32 v45, v162, v163 offset0:14 offset1:15
	ds_read2_b32 v[148:149], v44 offset0:24 offset1:25
	ds_read2_b32 v[150:151], v44 offset0:26 offset1:27
	ds_read2_b32 v[152:153], v44 offset0:28 offset1:29
	ds_read2_b32 v[154:155], v44 offset0:30 offset1:31
	ds_read2_b32 v[156:157], v45 offset0:24 offset1:25
	ds_read2_b32 v[158:159], v45 offset0:26 offset1:27
	ds_read2_b32 v[160:161], v45 offset0:28 offset1:29
	ds_read2_b32 v[162:163], v45 offset0:30 offset1:31
	s_waitcnt lgkmcnt(12)
	v_mul_f32_e32 v36, v36, v132
	v_fma_f32 v140, v37, v132, v140
	v_mul_f32_e32 v36, v36, v133
	v_fma_f32 v141, v140, v133, v141
	v_mul_f32_e32 v36, v36, v134
	v_fma_f32 v142, v141, v134, v142
	v_mul_f32_e32 v36, v36, v135
	v_fma_f32 v143, v142, v135, v143
	v_mul_f32_e32 v36, v36, v136
	v_fma_f32 v144, v143, v136, v144
	v_mul_f32_e32 v36, v36, v137
	v_fma_f32 v145, v144, v137, v145
	v_mul_f32_e32 v36, v36, v138
	v_fma_f32 v146, v145, v138, v146
	v_mul_f32_e32 v36, v36, v139
	v_fma_f32 v147, v146, v139, v147
	v_mov_b32_e32 v37, v147
	ds_write2_b32 v45, v140, v141 offset0:16 offset1:17
	ds_write2_b32 v45, v142, v143 offset0:18 offset1:19
	ds_write2_b32 v45, v144, v145 offset0:20 offset1:21
	ds_write2_b32 v45, v146, v147 offset0:22 offset1:23
	ds_read2_b32 v[132:133], v44 offset0:32 offset1:33
	ds_read2_b32 v[134:135], v44 offset0:34 offset1:35
	ds_read2_b32 v[136:137], v44 offset0:36 offset1:37
	ds_read2_b32 v[138:139], v44 offset0:38 offset1:39
	ds_read2_b32 v[140:141], v45 offset0:32 offset1:33
	ds_read2_b32 v[142:143], v45 offset0:34 offset1:35
	ds_read2_b32 v[144:145], v45 offset0:36 offset1:37
	ds_read2_b32 v[146:147], v45 offset0:38 offset1:39
	s_waitcnt lgkmcnt(12)
;     ...
;     if (tid < 64) {
;       const int c = tid;
;       float h = 0.f, A = 1.f;
;       if (pass == 3) { const f32x2 c0 = ((const f32x2*)carry)[(0 * 2 + dir) * 64 + c], c1 = ((const f32x2*)carry)[(1 * 2 + dir) * 64 + c]; h = c1.x * c0.y + c1.y; }
;       if (dir == 0) {
; #pragma unroll 8
;         for (int t = 0; t < 64; ++t) { float a = sa[c * 65 + t]; h = a * h + sb[c * 65 + t]; A *= a; sb[c * 65 + t] = h; }
;       } else {
; #pragma unroll 8
;         for (int t = 63; t >= 0; --t) { float a = sa[c * 65 + t]; h = a * h + sb[c * 65 + t]; A *= a; sb[c * 65 + t] = h; }
;       }
;       if (pass == 1) agg[((size_t)(b * 68 + j) * 2 + dir) * 512 + g * 64 + c] = mkf2(A, h);
;     }
	v_mul_f32_e32 v36, v36, v148
	v_fma_f32 v156, v37, v148, v156
	v_mul_f32_e32 v36, v36, v149
	v_fma_f32 v157, v156, v149, v157
	v_mul_f32_e32 v36, v36, v150
	v_fma_f32 v158, v157, v150, v158
	v_mul_f32_e32 v36, v36, v151
	v_fma_f32 v159, v158, v151, v159
	v_mul_f32_e32 v36, v36, v152
	v_fma_f32 v160, v159, v152, v160
	v_mul_f32_e32 v36, v36, v153
	v_fma_f32 v161, v160, v153, v161
	v_mul_f32_e32 v36, v36, v154
	v_fma_f32 v162, v161, v154, v162
	v_mul_f32_e32 v36, v36, v155
	v_fma_f32 v163, v162, v155, v163
	v_mov_b32_e32 v37, v163
	ds_write2_b32 v45, v156, v157 offset0:24 offset1:25
	ds_write2_b32 v45, v158, v159 offset0:26 offset1:27
	ds_write2_b32 v45, v160, v161 offset0:28 offset1:29
	ds_write2_b32 v45, v162, v163 offset0:30 offset1:31
	ds_read2_b32 v[148:149], v44 offset0:40 offset1:41
	ds_read2_b32 v[150:151], v44 offset0:42 offset1:43
	ds_read2_b32 v[152:153], v44 offset0:44 offset1:45
	ds_read2_b32 v[154:155], v44 offset0:46 offset1:47
	ds_read2_b32 v[156:157], v45 offset0:40 offset1:41
	ds_read2_b32 v[158:159], v45 offset0:42 offset1:43
	ds_read2_b32 v[160:161], v45 offset0:44 offset1:45
	ds_read2_b32 v[162:163], v45 offset0:46 offset1:47
	s_waitcnt lgkmcnt(12)
	v_mul_f32_e32 v36, v36, v132
	v_fma_f32 v140, v37, v132, v140
	v_mul_f32_e32 v36, v36, v133
	v_fma_f32 v141, v140, v133, v141
	v_mul_f32_e32 v36, v36, v134
	v_fma_f32 v142, v141, v134, v142
	v_mul_f32_e32 v36, v36, v135
	v_fma_f32 v143, v142, v135, v143
	v_mul_f32_e32 v36, v36, v136
	v_fma_f32 v144, v143, v136, v144
	v_mul_f32_e32 v36, v36, v137
	v_fma_f32 v145, v144, v137, v145
	v_mul_f32_e32 v36, v36, v138
	v_fma_f32 v146, v145, v138, v146
	v_mul_f32_e32 v36, v36, v139
	v_fma_f32 v147, v146, v139, v147
	v_mov_b32_e32 v37, v147
	ds_write2_b32 v45, v140, v141 offset0:32 offset1:33
	ds_write2_b32 v45, v142, v143 offset0:34 offset1:35
	ds_write2_b32 v45, v144, v145 offset0:36 offset1:37
	ds_write2_b32 v45, v146, v147 offset0:38 offset1:39
	ds_read2_b32 v[132:133], v44 offset0:48 offset1:49
	ds_read2_b32 v[134:135], v44 offset0:50 offset1:51
	ds_read2_b32 v[136:137], v44 offset0:52 offset1:53
	ds_read2_b32 v[138:139], v44 offset0:54 offset1:55
	ds_read2_b32 v[140:141], v45 offset0:48 offset1:49
	ds_read2_b32 v[142:143], v45 offset0:50 offset1:51
	ds_read2_b32 v[144:145], v45 offset0:52 offset1:53
	ds_read2_b32 v[146:147], v45 offset0:54 offset1:55
	s_waitcnt lgkmcnt(12)
	v_mul_f32_e32 v36, v36, v148
	v_fma_f32 v156, v37, v148, v156
	v_mul_f32_e32 v36, v36, v149
	v_fma_f32 v157, v156, v149, v157
	v_mul_f32_e32 v36, v36, v150
	v_fma_f32 v158, v157, v150, v158
	v_mul_f32_e32 v36, v36, v151
	v_fma_f32 v159, v158, v151, v159
	v_mul_f32_e32 v36, v36, v152
	v_fma_f32 v160, v159, v152, v160
	v_mul_f32_e32 v36, v36, v153
	v_fma_f32 v161, v160, v153, v161
	v_mul_f32_e32 v36, v36, v154
	v_fma_f32 v162, v161, v154, v162
	v_mul_f32_e32 v36, v36, v155
	v_fma_f32 v163, v162, v155, v163
	v_mov_b32_e32 v37, v163
	ds_write2_b32 v45, v156, v157 offset0:40 offset1:41
	ds_write2_b32 v45, v158, v159 offset0:42 offset1:43
	ds_write2_b32 v45, v160, v161 offset0:44 offset1:45
	ds_write2_b32 v45, v162, v163 offset0:46 offset1:47
	ds_read2_b32 v[148:149], v44 offset0:56 offset1:57
	ds_read2_b32 v[150:151], v44 offset0:58 offset1:59
	ds_read2_b32 v[152:153], v44 offset0:60 offset1:61
	ds_read2_b32 v[154:155], v44 offset0:62 offset1:63
	ds_read2_b32 v[156:157], v45 offset0:56 offset1:57
	ds_read2_b32 v[158:159], v45 offset0:58 offset1:59
	ds_read2_b32 v[160:161], v45 offset0:60 offset1:61
	ds_read2_b32 v[162:163], v45 offset0:62 offset1:63
	s_waitcnt lgkmcnt(12)
	v_mul_f32_e32 v36, v36, v132
	v_fma_f32 v140, v37, v132, v140
	v_mul_f32_e32 v36, v36, v133
	v_fma_f32 v141, v140, v133, v141
	v_mul_f32_e32 v36, v36, v134
	v_fma_f32 v142, v141, v134, v142
	v_mul_f32_e32 v36, v36, v135
	v_fma_f32 v143, v142, v135, v143
	v_mul_f32_e32 v36, v36, v136
	v_fma_f32 v144, v143, v136, v144
	v_mul_f32_e32 v36, v36, v137
	v_fma_f32 v145, v144, v137, v145
	v_mul_f32_e32 v36, v36, v138
	v_fma_f32 v146, v145, v138, v146
	v_mul_f32_e32 v36, v36, v139
	v_fma_f32 v147, v146, v139, v147
	v_mov_b32_e32 v37, v147
	ds_write2_b32 v45, v140, v141 offset0:48 offset1:49
	ds_write2_b32 v45, v142, v143 offset0:50 offset1:51
	ds_write2_b32 v45, v144, v145 offset0:52 offset1:53
	ds_write2_b32 v45, v146, v147 offset0:54 offset1:55
	s_waitcnt lgkmcnt(4)
	v_mul_f32_e32 v36, v36, v148
	v_fma_f32 v156, v37, v148, v156
	v_mul_f32_e32 v36, v36, v149
	v_fma_f32 v157, v156, v149, v157
	v_mul_f32_e32 v36, v36, v150
	v_fma_f32 v158, v157, v150, v158
	v_mul_f32_e32 v36, v36, v151
	v_fma_f32 v159, v158, v151, v159
	v_mul_f32_e32 v36, v36, v152
	v_fma_f32 v160, v159, v152, v160
	v_mul_f32_e32 v36, v36, v153
	v_fma_f32 v161, v160, v153, v161
	v_mul_f32_e32 v36, v36, v154
	v_fma_f32 v162, v161, v154, v162
	v_mul_f32_e32 v36, v36, v155
	v_fma_f32 v163, v162, v155, v163
	v_mov_b32_e32 v37, v163
	ds_write2_b32 v45, v156, v157 offset0:56 offset1:57
	ds_write2_b32 v45, v158, v159 offset0:58 offset1:59
	ds_write2_b32 v45, v160, v161 offset0:60 offset1:61
	ds_write2_b32 v45, v162, v163 offset0:62 offset1:63
	global_store_dwordx2 v[34:35], v[36:37], off

;     ...
;     if (tid < 64) {
;       const int c = tid;
;       float h = 0.f, A = 1.f;
;       if (pass == 3) { const f32x2 c0 = ((const f32x2*)carry)[(0 * 2 + dir) * 64 + c], c1 = ((const f32x2*)carry)[(1 * 2 + dir) * 64 + c]; h = c1.x * c0.y + c1.y; }
;       if (dir == 0) {
; #pragma unroll 8
;         for (int t = 0; t < 64; ++t) { float a = sa[c * 65 + t]; h = a * h + sb[c * 65 + t]; A *= a; sb[c * 65 + t] = h; }
;       } else {
; #pragma unroll 8
;         for (int t = 63; t >= 0; --t) { float a = sa[c * 65 + t]; h = a * h + sb[c * 65 + t]; A *= a; sb[c * 65 + t] = h; }
;       }
;       if (pass == 1) agg[((size_t)(b * 68 + j) * 2 + dir) * 512 + g * 64 + c] = mkf2(A, h);
;     }
.LBB0_703:
	v_add_u32_e32 v10, 0xffffff20, v5
	v_add_u32_e32 v3, 0x4100, v10
	ds_read2_b32 v[132:133], v10 offset0:56 offset1:57
	ds_read2_b32 v[134:135], v10 offset0:58 offset1:59
	ds_read2_b32 v[136:137], v10 offset0:60 offset1:61
	ds_read2_b32 v[138:139], v10 offset0:62 offset1:63
	ds_read2_b32 v[140:141], v3 offset0:56 offset1:57
	ds_read2_b32 v[142:143], v3 offset0:58 offset1:59
	ds_read2_b32 v[144:145], v3 offset0:60 offset1:61
	ds_read2_b32 v[146:147], v3 offset0:62 offset1:63
	ds_read2_b32 v[148:149], v10 offset0:48 offset1:49
	ds_read2_b32 v[150:151], v10 offset0:50 offset1:51
	ds_read2_b32 v[152:153], v10 offset0:52 offset1:53
	ds_read2_b32 v[154:155], v10 offset0:54 offset1:55
	ds_read2_b32 v[156:157], v3 offset0:48 offset1:49
	ds_read2_b32 v[158:159], v3 offset0:50 offset1:51
	ds_read2_b32 v[160:161], v3 offset0:52 offset1:53
	ds_read2_b32 v[162:163], v3 offset0:54 offset1:55
	s_waitcnt lgkmcnt(8)
	v_mul_f32_e32 v4, v4, v139
	v_fma_f32 v147, v2, v139, v147
	v_mul_f32_e32 v4, v4, v138
	v_fma_f32 v146, v147, v138, v146
	v_mul_f32_e32 v4, v4, v137
	v_fma_f32 v145, v146, v137, v145
	v_mul_f32_e32 v4, v4, v136
	v_fma_f32 v144, v145, v136, v144
	v_mul_f32_e32 v4, v4, v135
	v_fma_f32 v143, v144, v135, v143
	v_mul_f32_e32 v4, v4, v134
	v_fma_f32 v142, v143, v134, v142
	v_mul_f32_e32 v4, v4, v133
	v_fma_f32 v141, v142, v133, v141
	v_mul_f32_e32 v4, v4, v132
	v_fma_f32 v140, v141, v132, v140
	v_mov_b32_e32 v2, v140
	ds_write2_b32 v3, v140, v141 offset0:56 offset1:57
	ds_write2_b32 v3, v142, v143 offset0:58 offset1:59
	ds_write2_b32 v3, v144, v145 offset0:60 offset1:61
	ds_write2_b32 v3, v146, v147 offset0:62 offset1:63
	ds_read2_b32 v[132:133], v10 offset0:40 offset1:41
	ds_read2_b32 v[134:135], v10 offset0:42 offset1:43
	ds_read2_b32 v[136:137], v10 offset0:44 offset1:45
	ds_read2_b32 v[138:139], v10 offset0:46 offset1:47
	ds_read2_b32 v[140:141], v3 offset0:40 offset1:41
	ds_read2_b32 v[142:143], v3 offset0:42 offset1:43
	ds_read2_b32 v[144:145], v3 offset0:44 offset1:45
	ds_read2_b32 v[146:147], v3 offset0:46 offset1:47
	s_waitcnt lgkmcnt(12)
	v_mul_f32_e32 v4, v4, v155
	v_fma_f32 v163, v2, v155, v163
	v_mul_f32_e32 v4, v4, v154
	v_fma_f32 v162, v163, v154, v162
	v_mul_f32_e32 v4, v4, v153
	v_fma_f32 v161, v162, v153, v161
	v_mul_f32_e32 v4, v4, v152
	v_fma_f32 v160, v161, v152, v160
	v_mul_f32_e32 v4, v4, v151
	v_fma_f32 v159, v160, v151, v159
	v_mul_f32_e32 v4, v4, v150
	v_fma_f32 v158, v159, v150, v158
	v_mul_f32_e32 v4, v4, v149
	v_fma_f32 v157, v158, v149, v157
	v_mul_f32_e32 v4, v4, v148
	v_fma_f32 v156, v157, v148, v156
	v_mov_b32_e32 v2, v156
	ds_write2_b32 v3, v156, v157 offset0:48 offset1:49
	ds_write2_b32 v3, v158, v159 offset0:50 offset1:51
	ds_write2_b32 v3, v160, v161 offset0:52 offset1:53
	ds_write2_b32 v3, v162, v163 offset0:54 offset1:55
	ds_read2_b32 v[148:149], v10 offset0:32 offset1:33
	ds_read2_b32 v[150:151], v10 offset0:34 offset1:35
	ds_read2_b32 v[152:153], v10 offset0:36 offset1:37
	ds_read2_b32 v[154:155], v10 offset0:38 offset1:39
	ds_read2_b32 v[156:157], v3 offset0:32 offset1:33
	ds_read2_b32 v[158:159], v3 offset0:34 offset1:35
	ds_read2_b32 v[160:161], v3 offset0:36 offset1:37
	ds_read2_b32 v[162:163], v3 offset0:38 offset1:39
	s_waitcnt lgkmcnt(12)
	v_mul_f32_e32 v4, v4, v139
	v_fma_f32 v147, v2, v139, v147
	v_mul_f32_e32 v4, v4, v138
	v_fma_f32 v146, v147, v138, v146
	v_mul_f32_e32 v4, v4, v137
	v_fma_f32 v145, v146, v137, v145
	v_mul_f32_e32 v4, v4, v136
	v_fma_f32 v144, v145, v136, v144
	v_mul_f32_e32 v4, v4, v135
	v_fma_f32 v143, v144, v135, v143
	v_mul_f32_e32 v4, v4, v134
	v_fma_f32 v142, v143, v134, v142
	v_mul_f32_e32 v4, v4, v133
	v_fma_f32 v141, v142, v133, v141
	v_mul_f32_e32 v4, v4, v132
	v_fma_f32 v140, v141, v132, v140
	v_mov_b32_e32 v2, v140
	ds_write2_b32 v3, v140, v141 offset0:40 offset1:41
	ds_write2_b32 v3, v142, v143 offset0:42 offset1:43
	ds_write2_b32 v3, v144, v145 offset0:44 offset1:45
	ds_write2_b32 v3, v146, v147 offset0:46 offset1:47
	ds_read2_b32 v[132:133], v10 offset0:24 offset1:25
	ds_read2_b32 v[134:135], v10 offset0:26 offset1:27
	ds_read2_b32 v[136:137], v10 offset0:28 offset1:29
	ds_read2_b32 v[138:139], v10 offset0:30 offset1:31
	ds_read2_b32 v[140:141], v3 offset0:24 offset1:25
	ds_read2_b32 v[142:143], v3 offset0:26 offset1:27
	ds_read2_b32 v[144:145], v3 offset0:28 offset1:29
	ds_read2_b32 v[146:147], v3 offset0:30 offset1:31
	s_waitcnt lgkmcnt(12)
;     ...
;     if (tid < 64) {
;       const int c = tid;
;       float h = 0.f, A = 1.f;
;       if (pass == 3) { const f32x2 c0 = ((const f32x2*)carry)[(0 * 2 + dir) * 64 + c], c1 = ((const f32x2*)carry)[(1 * 2 + dir) * 64 + c]; h = c1.x * c0.y + c1.y; }
;       if (dir == 0) {
; #pragma unroll 8
;         for (int t = 0; t < 64; ++t) { float a = sa[c * 65 + t]; h = a * h + sb[c * 65 + t]; A *= a; sb[c * 65 + t] = h; }
;       } else {
; #pragma unroll 8
;         for (int t = 63; t >= 0; --t) { float a = sa[c * 65 + t]; h = a * h + sb[c * 65 + t]; A *= a; sb[c * 65 + t] = h; }
;       }
;       if (pass == 1) agg[((size_t)(b * 68 + j) * 2 + dir) * 512 + g * 64 + c] = mkf2(A, h);
;     }
	v_mul_f32_e32 v4, v4, v155
	v_fma_f32 v163, v2, v155, v163
	v_mul_f32_e32 v4, v4, v154
	v_fma_f32 v162, v163, v154, v162
	v_mul_f32_e32 v4, v4, v153
	v_fma_f32 v161, v162, v153, v161
	v_mul_f32_e32 v4, v4, v152
	v_fma_f32 v160, v161, v152, v160
	v_mul_f32_e32 v4, v4, v151
	v_fma_f32 v159, v160, v151, v159
	v_mul_f32_e32 v4, v4, v150
	v_fma_f32 v158, v159, v150, v158
	v_mul_f32_e32 v4, v4, v149
	v_fma_f32 v157, v158, v149, v157
	v_mul_f32_e32 v4, v4, v148
	v_fma_f32 v156, v157, v148, v156
	v_mov_b32_e32 v2, v156
	ds_write2_b32 v3, v156, v157 offset0:32 offset1:33
	ds_write2_b32 v3, v158, v159 offset0:34 offset1:35
	ds_write2_b32 v3, v160, v161 offset0:36 offset1:37
	ds_write2_b32 v3, v162, v163 offset0:38 offset1:39
	ds_read2_b32 v[148:149], v10 offset0:16 offset1:17
	ds_read2_b32 v[150:151], v10 offset0:18 offset1:19
	ds_read2_b32 v[152:153], v10 offset0:20 offset1:21
	ds_read2_b32 v[154:155], v10 offset0:22 offset1:23
	ds_read2_b32 v[156:157], v3 offset0:16 offset1:17
	ds_read2_b32 v[158:159], v3 offset0:18 offset1:19
	ds_read2_b32 v[160:161], v3 offset0:20 offset1:21
	ds_read2_b32 v[162:163], v3 offset0:22 offset1:23
	s_waitcnt lgkmcnt(12)
	v_mul_f32_e32 v4, v4, v139
	v_fma_f32 v147, v2, v139, v147
	v_mul_f32_e32 v4, v4, v138
	v_fma_f32 v146, v147, v138, v146
	v_mul_f32_e32 v4, v4, v137
	v_fma_f32 v145, v146, v137, v145
	v_mul_f32_e32 v4, v4, v136
	v_fma_f32 v144, v145, v136, v144
	v_mul_f32_e32 v4, v4, v135
	v_fma_f32 v143, v144, v135, v143
	v_mul_f32_e32 v4, v4, v134
	v_fma_f32 v142, v143, v134, v142
	v_mul_f32_e32 v4, v4, v133
	v_fma_f32 v141, v142, v133, v141
	v_mul_f32_e32 v4, v4, v132
	v_fma_f32 v140, v141, v132, v140
	v_mov_b32_e32 v2, v140
	ds_write2_b32 v3, v140, v141 offset0:24 offset1:25
	ds_write2_b32 v3, v142, v143 offset0:26 offset1:27
	ds_write2_b32 v3, v144, v145 offset0:28 offset1:29
	ds_write2_b32 v3, v146, v147 offset0:30 offset1:31
	ds_read2_b32 v[132:133], v10 offset0:8 offset1:9
	ds_read2_b32 v[134:135], v10 offset0:10 offset1:11
	ds_read2_b32 v[136:137], v10 offset0:12 offset1:13
	ds_read2_b32 v[138:139], v10 offset0:14 offset1:15
	ds_read2_b32 v[140:141], v3 offset0:8 offset1:9
	ds_read2_b32 v[142:143], v3 offset0:10 offset1:11
	ds_read2_b32 v[144:145], v3 offset0:12 offset1:13
	ds_read2_b32 v[146:147], v3 offset0:14 offset1:15
	s_waitcnt lgkmcnt(12)
	v_mul_f32_e32 v4, v4, v155
	v_fma_f32 v163, v2, v155, v163
	v_mul_f32_e32 v4, v4, v154
	v_fma_f32 v162, v163, v154, v162
	v_mul_f32_e32 v4, v4, v153
	v_fma_f32 v161, v162, v153, v161
	v_mul_f32_e32 v4, v4, v152
	v_fma_f32 v160, v161, v152, v160
	v_mul_f32_e32 v4, v4, v151
	v_fma_f32 v159, v160, v151, v159
	v_mul_f32_e32 v4, v4, v150
	v_fma_f32 v158, v159, v150, v158
	v_mul_f32_e32 v4, v4, v149
	v_fma_f32 v157, v158, v149, v157
	v_mul_f32_e32 v4, v4, v148
	v_fma_f32 v156, v157, v148, v156
	v_mov_b32_e32 v2, v156
	ds_write2_b32 v3, v156, v157 offset0:16 offset1:17
	ds_write2_b32 v3, v158, v159 offset0:18 offset1:19
	ds_write2_b32 v3, v160, v161 offset0:20 offset1:21
	ds_write2_b32 v3, v162, v163 offset0:22 offset1:23
	ds_read2_b32 v[148:149], v10 offset0:0 offset1:1
	ds_read2_b32 v[150:151], v10 offset0:2 offset1:3
	ds_read2_b32 v[152:153], v10 offset0:4 offset1:5
	ds_read2_b32 v[154:155], v10 offset0:6 offset1:7
	ds_read2_b32 v[156:157], v3 offset0:0 offset1:1
	ds_read2_b32 v[158:159], v3 offset0:2 offset1:3
	ds_read2_b32 v[160:161], v3 offset0:4 offset1:5
	ds_read2_b32 v[162:163], v3 offset0:6 offset1:7
	s_waitcnt lgkmcnt(12)
	v_mul_f32_e32 v4, v4, v139
	v_fma_f32 v147, v2, v139, v147
	v_mul_f32_e32 v4, v4, v138
	v_fma_f32 v146, v147, v138, v146
	v_mul_f32_e32 v4, v4, v137
	v_fma_f32 v145, v146, v137, v145
	v_mul_f32_e32 v4, v4, v136
	v_fma_f32 v144, v145, v136, v144
	v_mul_f32_e32 v4, v4, v135
	v_fma_f32 v143, v144, v135, v143
	v_mul_f32_e32 v4, v4, v134
	v_fma_f32 v142, v143, v134, v142
	v_mul_f32_e32 v4, v4, v133
	v_fma_f32 v141, v142, v133, v141
	v_mul_f32_e32 v4, v4, v132
	v_fma_f32 v140, v141, v132, v140
	v_mov_b32_e32 v2, v140
	ds_write2_b32 v3, v140, v141 offset0:8 offset1:9
	ds_write2_b32 v3, v142, v143 offset0:10 offset1:11
	ds_write2_b32 v3, v144, v145 offset0:12 offset1:13
	ds_write2_b32 v3, v146, v147 offset0:14 offset1:15
	s_waitcnt lgkmcnt(4)
	v_mul_f32_e32 v4, v4, v155
	v_fma_f32 v163, v2, v155, v163
	v_mul_f32_e32 v4, v4, v154
	v_fma_f32 v162, v163, v154, v162
	v_mul_f32_e32 v4, v4, v153
	v_fma_f32 v161, v162, v153, v161
	v_mul_f32_e32 v4, v4, v152
	v_fma_f32 v160, v161, v152, v160
	v_mul_f32_e32 v4, v4, v151
	v_fma_f32 v159, v160, v151, v159
	v_mul_f32_e32 v4, v4, v150
	v_fma_f32 v158, v159, v150, v158
	v_mul_f32_e32 v4, v4, v149
	v_fma_f32 v157, v158, v149, v157
	v_mul_f32_e32 v4, v4, v148
	v_fma_f32 v156, v157, v148, v156
	v_mov_b32_e32 v2, v156
	ds_write2_b32 v3, v156, v157 offset0:0 offset1:1
	ds_write2_b32 v3, v158, v159 offset0:2 offset1:3
	ds_write2_b32 v3, v160, v161 offset0:4 offset1:5
	ds_write2_b32 v3, v162, v163 offset0:6 offset1:7
	v_add_co_u32_e32 v6, vcc, 0x1000, v34
	v_mov_b32_e32 v5, v2
	s_nop 0
	v_addc_co_u32_e32 v7, vcc, 0, v35, vcc
	global_store_dwordx2 v[6:7], v[4:5], off

; DI f32x2 cmul(f32x2 a, f32x2 b) { return mkf2(a.x * b.x - a.y * b.y, a.x * b.y + a.y * b.x); }
; DI void fft8192(f32x2* buf, const f32x2* __restrict__ tw) {
;     ...
;   for (int ls = 0; ls < 12; ls += 2) {
;     const int s = 1 << ls;
;     f32x2 a[8], b[8], c[8], d[8];
;     __syncthreads();
; #pragma unroll
;     for (int e = 0; e < 8; ++e) {
;       const int i = tid + 256 * e;
;       const int pi = SW(i);
;       a[e] = buf[pi]; b[e] = buf[pi + 2048]; c[e] = buf[pi + 4096]; d[e] = buf[pi + 6144];
;     }
;     __syncthreads();
; #pragma unroll
;     for (int e = 0; e < 8; ++e) {
;       const int i = tid + 256 * e;
;       const int q = i & (s - 1);
;       const int ps = i - q;
;       const float rev = (float)ps * (1.f / 8192.f);
;       const f32x2 w1 = mkf2(__builtin_amdgcn_cosf(rev), -__builtin_amdgcn_sinf(rev));
;       const f32x2 w2 = cmul(w1, w1), w3 = cmul(w1, w2);
;       const f32x2 apc = mkf2(a[e].x + c[e].x, a[e].y + c[e].y), amc = mkf2(a[e].x - c[e].x, a[e].y - c[e].y);
;       const f32x2 bpd = mkf2(b[e].x + d[e].x, b[e].y + d[e].y), bmd = mkf2(b[e].x - d[e].x, b[e].y - d[e].y);
;       const int o = 4 * i - 3 * q;
;       buf[SW(o)] = mkf2(apc.x + bpd.x, apc.y + bpd.y);
;       buf[SW(o + s)] = cmul(w1, mkf2(amc.x + bmd.y, amc.y - bmd.x));
;       buf[SW(o + 2 * s)] = cmul(w2, mkf2(apc.x - bpd.x, apc.y - bpd.y));
;       buf[SW(o + 3 * s)] = cmul(w3, mkf2(amc.x - bmd.y, amc.y + bmd.x));
;     }
.LBB0_933:
	v_bfe_i32 v166, v0, 5, 1
	v_bfe_i32 v168, v0, 6, 1
	v_and_b32_e32 v166, 5, v166
	v_and_b32_e32 v168, 26, v168
	v_xor_b32_e32 v166, v166, v168
	v_xor_b32_e32 v166, v166, v0
	v_lshlrev_b32_e32 v154, 3, v166
	s_waitcnt lgkmcnt(0)
	s_barrier
	ds_read2st64_b64 v[2:5], v154 offset0:0 offset1:32
	ds_read2st64_b64 v[6:9], v154 offset0:64 offset1:96
	ds_read2st64_b64 v[10:13], v154 offset0:4 offset1:36
	ds_read2st64_b64 v[14:17], v154 offset0:68 offset1:100
	ds_read2st64_b64 v[18:21], v154 offset0:8 offset1:40
	ds_read2st64_b64 v[22:25], v154 offset0:72 offset1:104
	ds_read2st64_b64 v[26:29], v154 offset0:12 offset1:44
	ds_read2st64_b64 v[30:33], v154 offset0:76 offset1:108
	ds_read2st64_b64 v[34:37], v154 offset0:16 offset1:48
	ds_read2st64_b64 v[38:41], v154 offset0:80 offset1:112
	ds_read2st64_b64 v[42:45], v154 offset0:20 offset1:52
	ds_read2st64_b64 v[46:49], v154 offset0:84 offset1:116
	ds_read2st64_b64 v[50:53], v154 offset0:24 offset1:56
	ds_read2st64_b64 v[54:57], v154 offset0:88 offset1:120
	ds_read2st64_b64 v[58:61], v154 offset0:28 offset1:60
	ds_read2st64_b64 v[62:65], v154 offset0:92 offset1:124
	v_lshlrev_b32_e32 v164, 2, v0
	v_cvt_f32_u32_e32 v201, v0
	v_mul_f32_e32 v201, 0x39000000, v201
	v_bfe_i32 v166, v164, 5, 1
	v_bfe_i32 v168, v164, 6, 1
	v_and_b32_e32 v166, 5, v166
	v_and_b32_e32 v168, 26, v168
	v_xor_b32_e32 v166, v166, v168
	v_xor_b32_e32 v166, v166, v164
	v_lshlrev_b32_e32 v156, 3, v166
	v_xor_b32_e32 v158, 8, v156
	v_xor_b32_e32 v160, 16, v156
	v_xor_b32_e32 v162, 24, v156
	v_cos_f32_e32 v210, v201
	v_sin_f32_e64 v211, -v201
	s_waitcnt lgkmcnt(14)
	v_pk_add_f32 v[202:203], v[2:3], v[6:7]
	v_pk_add_f32 v[2:3], v[2:3], v[6:7] neg_lo:[0,1] neg_hi:[0,1]
	v_pk_add_f32 v[204:205], v[4:5], v[8:9]
	v_pk_add_f32 v[4:5], v[4:5], v[8:9] neg_lo:[0,1] neg_hi:[0,1]
	v_pk_add_f32 v[6:7], v[202:203], v[204:205]
	v_pk_add_f32 v[8:9], v[202:203], v[204:205] neg_lo:[0,1] neg_hi:[0,1]
	v_pk_add_f32 v[202:203], v[2:3], v[4:5] op_sel:[0,1] op_sel_hi:[1,0] neg_hi:[0,1]
	v_pk_add_f32 v[204:205], v[2:3], v[4:5] op_sel:[0,1] op_sel_hi:[1,0] neg_lo:[0,1]
	v_pk_mul_f32 v[206:207], v[210:211], v[210:211] op_sel:[1,1] op_sel_hi:[1,0]
	v_pk_fma_f32 v[212:213], v[210:211], v[210:211], v[206:207] op_sel_hi:[0,1,1] neg_lo:[0,0,1]
	v_pk_mul_f32 v[206:207], v[210:211], v[212:213] op_sel:[1,1] op_sel_hi:[1,0]
	v_pk_fma_f32 v[220:221], v[210:211], v[212:213], v[206:207] op_sel_hi:[0,1,1] neg_lo:[0,0,1]
	v_pk_mul_f32 v[2:3], v[210:211], v[202:203] op_sel:[1,1] op_sel_hi:[1,0]
	v_pk_fma_f32 v[2:3], v[210:211], v[202:203], v[2:3] op_sel_hi:[0,1,1] neg_lo:[0,0,1]
	v_pk_mul_f32 v[4:5], v[212:213], v[8:9] op_sel:[1,1] op_sel_hi:[1,0]
	v_pk_fma_f32 v[4:5], v[212:213], v[8:9], v[4:5] op_sel_hi:[0,1,1] neg_lo:[0,0,1]
	v_pk_mul_f32 v[8:9], v[220:221], v[204:205] op_sel:[1,1] op_sel_hi:[1,0]
	v_pk_fma_f32 v[8:9], v[220:221], v[204:205], v[8:9] op_sel_hi:[0,1,1] neg_lo:[0,0,1]
	v_add_f32_e32 v214, 0x3d000000, v201
	v_cos_f32_e32 v210, v214
	v_sin_f32_e64 v211, -v214
	s_waitcnt lgkmcnt(12)
	v_pk_add_f32 v[202:203], v[10:11], v[14:15]
	v_pk_add_f32 v[10:11], v[10:11], v[14:15] neg_lo:[0,1] neg_hi:[0,1]
	v_pk_add_f32 v[204:205], v[12:13], v[16:17]
	v_pk_add_f32 v[12:13], v[12:13], v[16:17] neg_lo:[0,1] neg_hi:[0,1]
	v_pk_add_f32 v[14:15], v[202:203], v[204:205]
	v_pk_add_f32 v[16:17], v[202:203], v[204:205] neg_lo:[0,1] neg_hi:[0,1]
	v_pk_add_f32 v[202:203], v[10:11], v[12:13] op_sel:[0,1] op_sel_hi:[1,0] neg_hi:[0,1]
	v_pk_add_f32 v[204:205], v[10:11], v[12:13] op_sel:[0,1] op_sel_hi:[1,0] neg_lo:[0,1]
	v_pk_mul_f32 v[206:207], v[210:211], v[210:211] op_sel:[1,1] op_sel_hi:[1,0]
	v_pk_fma_f32 v[212:213], v[210:211], v[210:211], v[206:207] op_sel_hi:[0,1,1] neg_lo:[0,0,1]
	v_pk_mul_f32 v[206:207], v[210:211], v[212:213] op_sel:[1,1] op_sel_hi:[1,0]
	v_pk_fma_f32 v[220:221], v[210:211], v[212:213], v[206:207] op_sel_hi:[0,1,1] neg_lo:[0,0,1]
	v_pk_mul_f32 v[10:11], v[210:211], v[202:203] op_sel:[1,1] op_sel_hi:[1,0]
	v_pk_fma_f32 v[10:11], v[210:211], v[202:203], v[10:11] op_sel_hi:[0,1,1] neg_lo:[0,0,1]
	v_pk_mul_f32 v[12:13], v[212:213], v[16:17] op_sel:[1,1] op_sel_hi:[1,0]
	v_pk_fma_f32 v[12:13], v[212:213], v[16:17], v[12:13] op_sel_hi:[0,1,1] neg_lo:[0,0,1]
	v_pk_mul_f32 v[16:17], v[220:221], v[204:205] op_sel:[1,1] op_sel_hi:[1,0]
	v_pk_fma_f32 v[16:17], v[220:221], v[204:205], v[16:17] op_sel_hi:[0,1,1] neg_lo:[0,0,1]
	v_add_f32_e32 v214, 0x3d800000, v201
	v_cos_f32_e32 v210, v214
	v_sin_f32_e64 v211, -v214
	s_waitcnt lgkmcnt(10)
	v_pk_add_f32 v[202:203], v[18:19], v[22:23]
	v_pk_add_f32 v[18:19], v[18:19], v[22:23] neg_lo:[0,1] neg_hi:[0,1]
	v_pk_add_f32 v[204:205], v[20:21], v[24:25]
	v_pk_add_f32 v[20:21], v[20:21], v[24:25] neg_lo:[0,1] neg_hi:[0,1]
	v_pk_add_f32 v[22:23], v[202:203], v[204:205]
	v_pk_add_f32 v[24:25], v[202:203], v[204:205] neg_lo:[0,1] neg_hi:[0,1]
	v_pk_add_f32 v[202:203], v[18:19], v[20:21] op_sel:[0,1] op_sel_hi:[1,0] neg_hi:[0,1]
	v_pk_add_f32 v[204:205], v[18:19], v[20:21] op_sel:[0,1] op_sel_hi:[1,0] neg_lo:[0,1]
	v_pk_mul_f32 v[206:207], v[210:211], v[210:211] op_sel:[1,1] op_sel_hi:[1,0]
	v_pk_fma_f32 v[212:213], v[210:211], v[210:211], v[206:207] op_sel_hi:[0,1,1] neg_lo:[0,0,1]
	v_pk_mul_f32 v[206:207], v[210:211], v[212:213] op_sel:[1,1] op_sel_hi:[1,0]
	v_pk_fma_f32 v[220:221], v[210:211], v[212:213], v[206:207] op_sel_hi:[0,1,1] neg_lo:[0,0,1]
	v_pk_mul_f32 v[18:19], v[210:211], v[202:203] op_sel:[1,1] op_sel_hi:[1,0]
	v_pk_fma_f32 v[18:19], v[210:211], v[202:203], v[18:19] op_sel_hi:[0,1,1] neg_lo:[0,0,1]
	v_pk_mul_f32 v[20:21], v[212:213], v[24:25] op_sel:[1,1] op_sel_hi:[1,0]
	v_pk_fma_f32 v[20:21], v[212:213], v[24:25], v[20:21] op_sel_hi:[0,1,1] neg_lo:[0,0,1]
	v_pk_mul_f32 v[24:25], v[220:221], v[204:205] op_sel:[1,1] op_sel_hi:[1,0]
	v_pk_fma_f32 v[24:25], v[220:221], v[204:205], v[24:25] op_sel_hi:[0,1,1] neg_lo:[0,0,1]
	v_add_f32_e32 v214, 0x3dc00000, v201
	v_cos_f32_e32 v210, v214
	v_sin_f32_e64 v211, -v214
	s_waitcnt lgkmcnt(8)
; DI f32x2 cmul(f32x2 a, f32x2 b) { return mkf2(a.x * b.x - a.y * b.y, a.x * b.y + a.y * b.x); }
; DI void fft8192(f32x2* buf, const f32x2* __restrict__ tw) {
;     ...
;   for (int ls = 0; ls < 12; ls += 2) {
;     const int s = 1 << ls;
;     f32x2 a[8], b[8], c[8], d[8];
;     __syncthreads();
; #pragma unroll
;     for (int e = 0; e < 8; ++e) {
;       const int i = tid + 256 * e;
;       const int pi = SW(i);
;       a[e] = buf[pi]; b[e] = buf[pi + 2048]; c[e] = buf[pi + 4096]; d[e] = buf[pi + 6144];
;     }
;     __syncthreads();
; #pragma unroll
;     for (int e = 0; e < 8; ++e) {
;       const int i = tid + 256 * e;
;       const int q = i & (s - 1);
;       const int ps = i - q;
;       const float rev = (float)ps * (1.f / 8192.f);
;       const f32x2 w1 = mkf2(__builtin_amdgcn_cosf(rev), -__builtin_amdgcn_sinf(rev));
;       const f32x2 w2 = cmul(w1, w1), w3 = cmul(w1, w2);
;       const f32x2 apc = mkf2(a[e].x + c[e].x, a[e].y + c[e].y), amc = mkf2(a[e].x - c[e].x, a[e].y - c[e].y);
;       const f32x2 bpd = mkf2(b[e].x + d[e].x, b[e].y + d[e].y), bmd = mkf2(b[e].x - d[e].x, b[e].y - d[e].y);
;       const int o = 4 * i - 3 * q;
;       buf[SW(o)] = mkf2(apc.x + bpd.x, apc.y + bpd.y);
;       buf[SW(o + s)] = cmul(w1, mkf2(amc.x + bmd.y, amc.y - bmd.x));
;       buf[SW(o + 2 * s)] = cmul(w2, mkf2(apc.x - bpd.x, apc.y - bpd.y));
;       buf[SW(o + 3 * s)] = cmul(w3, mkf2(amc.x - bmd.y, amc.y + bmd.x));
;     }
	v_pk_add_f32 v[202:203], v[26:27], v[30:31]
	v_pk_add_f32 v[26:27], v[26:27], v[30:31] neg_lo:[0,1] neg_hi:[0,1]
	v_pk_add_f32 v[204:205], v[28:29], v[32:33]
	v_pk_add_f32 v[28:29], v[28:29], v[32:33] neg_lo:[0,1] neg_hi:[0,1]
	v_pk_add_f32 v[30:31], v[202:203], v[204:205]
	v_pk_add_f32 v[32:33], v[202:203], v[204:205] neg_lo:[0,1] neg_hi:[0,1]
	v_pk_add_f32 v[202:203], v[26:27], v[28:29] op_sel:[0,1] op_sel_hi:[1,0] neg_hi:[0,1]
	v_pk_add_f32 v[204:205], v[26:27], v[28:29] op_sel:[0,1] op_sel_hi:[1,0] neg_lo:[0,1]
	v_pk_mul_f32 v[206:207], v[210:211], v[210:211] op_sel:[1,1] op_sel_hi:[1,0]
	v_pk_fma_f32 v[212:213], v[210:211], v[210:211], v[206:207] op_sel_hi:[0,1,1] neg_lo:[0,0,1]
	v_pk_mul_f32 v[206:207], v[210:211], v[212:213] op_sel:[1,1] op_sel_hi:[1,0]
	v_pk_fma_f32 v[220:221], v[210:211], v[212:213], v[206:207] op_sel_hi:[0,1,1] neg_lo:[0,0,1]
	v_pk_mul_f32 v[26:27], v[210:211], v[202:203] op_sel:[1,1] op_sel_hi:[1,0]
	v_pk_fma_f32 v[26:27], v[210:211], v[202:203], v[26:27] op_sel_hi:[0,1,1] neg_lo:[0,0,1]
	v_pk_mul_f32 v[28:29], v[212:213], v[32:33] op_sel:[1,1] op_sel_hi:[1,0]
	v_pk_fma_f32 v[28:29], v[212:213], v[32:33], v[28:29] op_sel_hi:[0,1,1] neg_lo:[0,0,1]
	v_pk_mul_f32 v[32:33], v[220:221], v[204:205] op_sel:[1,1] op_sel_hi:[1,0]
	v_pk_fma_f32 v[32:33], v[220:221], v[204:205], v[32:33] op_sel_hi:[0,1,1] neg_lo:[0,0,1]
	v_add_f32_e32 v214, 0x3e000000, v201
	v_cos_f32_e32 v210, v214
	v_sin_f32_e64 v211, -v214
	s_waitcnt lgkmcnt(6)
	v_pk_add_f32 v[202:203], v[34:35], v[38:39]
	v_pk_add_f32 v[34:35], v[34:35], v[38:39] neg_lo:[0,1] neg_hi:[0,1]
	v_pk_add_f32 v[204:205], v[36:37], v[40:41]
	v_pk_add_f32 v[36:37], v[36:37], v[40:41] neg_lo:[0,1] neg_hi:[0,1]
	v_pk_add_f32 v[38:39], v[202:203], v[204:205]
	v_pk_add_f32 v[40:41], v[202:203], v[204:205] neg_lo:[0,1] neg_hi:[0,1]
	v_pk_add_f32 v[202:203], v[34:35], v[36:37] op_sel:[0,1] op_sel_hi:[1,0] neg_hi:[0,1]
	v_pk_add_f32 v[204:205], v[34:35], v[36:37] op_sel:[0,1] op_sel_hi:[1,0] neg_lo:[0,1]
	v_pk_mul_f32 v[206:207], v[210:211], v[210:211] op_sel:[1,1] op_sel_hi:[1,0]
	v_pk_fma_f32 v[212:213], v[210:211], v[210:211], v[206:207] op_sel_hi:[0,1,1] neg_lo:[0,0,1]
	v_pk_mul_f32 v[206:207], v[210:211], v[212:213] op_sel:[1,1] op_sel_hi:[1,0]
	v_pk_fma_f32 v[220:221], v[210:211], v[212:213], v[206:207] op_sel_hi:[0,1,1] neg_lo:[0,0,1]
	v_pk_mul_f32 v[34:35], v[210:211], v[202:203] op_sel:[1,1] op_sel_hi:[1,0]
	v_pk_fma_f32 v[34:35], v[210:211], v[202:203], v[34:35] op_sel_hi:[0,1,1] neg_lo:[0,0,1]
	v_pk_mul_f32 v[36:37], v[212:213], v[40:41] op_sel:[1,1] op_sel_hi:[1,0]
	v_pk_fma_f32 v[36:37], v[212:213], v[40:41], v[36:37] op_sel_hi:[0,1,1] neg_lo:[0,0,1]
	v_pk_mul_f32 v[40:41], v[220:221], v[204:205] op_sel:[1,1] op_sel_hi:[1,0]
	v_pk_fma_f32 v[40:41], v[220:221], v[204:205], v[40:41] op_sel_hi:[0,1,1] neg_lo:[0,0,1]
	v_add_f32_e32 v214, 0x3e200000, v201
	v_cos_f32_e32 v210, v214
	v_sin_f32_e64 v211, -v214
	s_waitcnt lgkmcnt(4)
	v_pk_add_f32 v[202:203], v[42:43], v[46:47]
	v_pk_add_f32 v[42:43], v[42:43], v[46:47] neg_lo:[0,1] neg_hi:[0,1]
	v_pk_add_f32 v[204:205], v[44:45], v[48:49]
	v_pk_add_f32 v[44:45], v[44:45], v[48:49] neg_lo:[0,1] neg_hi:[0,1]
	v_pk_add_f32 v[46:47], v[202:203], v[204:205]
	v_pk_add_f32 v[48:49], v[202:203], v[204:205] neg_lo:[0,1] neg_hi:[0,1]
	v_pk_add_f32 v[202:203], v[42:43], v[44:45] op_sel:[0,1] op_sel_hi:[1,0] neg_hi:[0,1]
	v_pk_add_f32 v[204:205], v[42:43], v[44:45] op_sel:[0,1] op_sel_hi:[1,0] neg_lo:[0,1]
	v_pk_mul_f32 v[206:207], v[210:211], v[210:211] op_sel:[1,1] op_sel_hi:[1,0]
	v_pk_fma_f32 v[212:213], v[210:211], v[210:211], v[206:207] op_sel_hi:[0,1,1] neg_lo:[0,0,1]
	v_pk_mul_f32 v[206:207], v[210:211], v[212:213] op_sel:[1,1] op_sel_hi:[1,0]
	v_pk_fma_f32 v[220:221], v[210:211], v[212:213], v[206:207] op_sel_hi:[0,1,1] neg_lo:[0,0,1]
	v_pk_mul_f32 v[42:43], v[210:211], v[202:203] op_sel:[1,1] op_sel_hi:[1,0]
	v_pk_fma_f32 v[42:43], v[210:211], v[202:203], v[42:43] op_sel_hi:[0,1,1] neg_lo:[0,0,1]
	v_pk_mul_f32 v[44:45], v[212:213], v[48:49] op_sel:[1,1] op_sel_hi:[1,0]
	v_pk_fma_f32 v[44:45], v[212:213], v[48:49], v[44:45] op_sel_hi:[0,1,1] neg_lo:[0,0,1]
	v_pk_mul_f32 v[48:49], v[220:221], v[204:205] op_sel:[1,1] op_sel_hi:[1,0]
	v_pk_fma_f32 v[48:49], v[220:221], v[204:205], v[48:49] op_sel_hi:[0,1,1] neg_lo:[0,0,1]
	v_add_f32_e32 v214, 0x3e400000, v201
	v_cos_f32_e32 v210, v214
	v_sin_f32_e64 v211, -v214
	s_waitcnt lgkmcnt(2)
	v_pk_add_f32 v[202:203], v[50:51], v[54:55]
	v_pk_add_f32 v[50:51], v[50:51], v[54:55] neg_lo:[0,1] neg_hi:[0,1]
	v_pk_add_f32 v[204:205], v[52:53], v[56:57]
	v_pk_add_f32 v[52:53], v[52:53], v[56:57] neg_lo:[0,1] neg_hi:[0,1]
	v_pk_add_f32 v[54:55], v[202:203], v[204:205]
	v_pk_add_f32 v[56:57], v[202:203], v[204:205] neg_lo:[0,1] neg_hi:[0,1]
	v_pk_add_f32 v[202:203], v[50:51], v[52:53] op_sel:[0,1] op_sel_hi:[1,0] neg_hi:[0,1]
	v_pk_add_f32 v[204:205], v[50:51], v[52:53] op_sel:[0,1] op_sel_hi:[1,0] neg_lo:[0,1]
	v_pk_mul_f32 v[206:207], v[210:211], v[210:211] op_sel:[1,1] op_sel_hi:[1,0]
	v_pk_fma_f32 v[212:213], v[210:211], v[210:211], v[206:207] op_sel_hi:[0,1,1] neg_lo:[0,0,1]
	v_pk_mul_f32 v[206:207], v[210:211], v[212:213] op_sel:[1,1] op_sel_hi:[1,0]
	v_pk_fma_f32 v[220:221], v[210:211], v[212:213], v[206:207] op_sel_hi:[0,1,1] neg_lo:[0,0,1]
	v_pk_mul_f32 v[50:51], v[210:211], v[202:203] op_sel:[1,1] op_sel_hi:[1,0]
	v_pk_fma_f32 v[50:51], v[210:211], v[202:203], v[50:51] op_sel_hi:[0,1,1] neg_lo:[0,0,1]
	v_pk_mul_f32 v[52:53], v[212:213], v[56:57] op_sel:[1,1] op_sel_hi:[1,0]
	v_pk_fma_f32 v[52:53], v[212:213], v[56:57], v[52:53] op_sel_hi:[0,1,1] neg_lo:[0,0,1]
	v_pk_mul_f32 v[56:57], v[220:221], v[204:205] op_sel:[1,1] op_sel_hi:[1,0]
	v_pk_fma_f32 v[56:57], v[220:221], v[204:205], v[56:57] op_sel_hi:[0,1,1] neg_lo:[0,0,1]
	v_add_f32_e32 v214, 0x3e600000, v201
	v_cos_f32_e32 v210, v214
	v_sin_f32_e64 v211, -v214
	s_waitcnt lgkmcnt(0)
; DI f32x2 cmul(f32x2 a, f32x2 b) { return mkf2(a.x * b.x - a.y * b.y, a.x * b.y + a.y * b.x); }
; DI void fft8192(f32x2* buf, const f32x2* __restrict__ tw) {
;     ...
;   for (int ls = 0; ls < 12; ls += 2) {
;     const int s = 1 << ls;
;     f32x2 a[8], b[8], c[8], d[8];
;     __syncthreads();
; #pragma unroll
;     for (int e = 0; e < 8; ++e) {
;       const int i = tid + 256 * e;
;       const int pi = SW(i);
;       a[e] = buf[pi]; b[e] = buf[pi + 2048]; c[e] = buf[pi + 4096]; d[e] = buf[pi + 6144];
;     }
;     __syncthreads();
; #pragma unroll
;     for (int e = 0; e < 8; ++e) {
;       const int i = tid + 256 * e;
;       const int q = i & (s - 1);
;       const int ps = i - q;
;       const float rev = (float)ps * (1.f / 8192.f);
;       const f32x2 w1 = mkf2(__builtin_amdgcn_cosf(rev), -__builtin_amdgcn_sinf(rev));
;       const f32x2 w2 = cmul(w1, w1), w3 = cmul(w1, w2);
;       const f32x2 apc = mkf2(a[e].x + c[e].x, a[e].y + c[e].y), amc = mkf2(a[e].x - c[e].x, a[e].y - c[e].y);
;       const f32x2 bpd = mkf2(b[e].x + d[e].x, b[e].y + d[e].y), bmd = mkf2(b[e].x - d[e].x, b[e].y - d[e].y);
;       const int o = 4 * i - 3 * q;
;       buf[SW(o)] = mkf2(apc.x + bpd.x, apc.y + bpd.y);
;       buf[SW(o + s)] = cmul(w1, mkf2(amc.x + bmd.y, amc.y - bmd.x));
;       buf[SW(o + 2 * s)] = cmul(w2, mkf2(apc.x - bpd.x, apc.y - bpd.y));
;       buf[SW(o + 3 * s)] = cmul(w3, mkf2(amc.x - bmd.y, amc.y + bmd.x));
;     }
	v_pk_add_f32 v[202:203], v[58:59], v[62:63]
	v_pk_add_f32 v[58:59], v[58:59], v[62:63] neg_lo:[0,1] neg_hi:[0,1]
	v_pk_add_f32 v[204:205], v[60:61], v[64:65]
	v_pk_add_f32 v[60:61], v[60:61], v[64:65] neg_lo:[0,1] neg_hi:[0,1]
	v_pk_add_f32 v[62:63], v[202:203], v[204:205]
	v_pk_add_f32 v[64:65], v[202:203], v[204:205] neg_lo:[0,1] neg_hi:[0,1]
	v_pk_add_f32 v[202:203], v[58:59], v[60:61] op_sel:[0,1] op_sel_hi:[1,0] neg_hi:[0,1]
	v_pk_add_f32 v[204:205], v[58:59], v[60:61] op_sel:[0,1] op_sel_hi:[1,0] neg_lo:[0,1]
	v_pk_mul_f32 v[206:207], v[210:211], v[210:211] op_sel:[1,1] op_sel_hi:[1,0]
	v_pk_fma_f32 v[212:213], v[210:211], v[210:211], v[206:207] op_sel_hi:[0,1,1] neg_lo:[0,0,1]
	v_pk_mul_f32 v[206:207], v[210:211], v[212:213] op_sel:[1,1] op_sel_hi:[1,0]
	v_pk_fma_f32 v[220:221], v[210:211], v[212:213], v[206:207] op_sel_hi:[0,1,1] neg_lo:[0,0,1]
	v_pk_mul_f32 v[58:59], v[210:211], v[202:203] op_sel:[1,1] op_sel_hi:[1,0]
	v_pk_fma_f32 v[58:59], v[210:211], v[202:203], v[58:59] op_sel_hi:[0,1,1] neg_lo:[0,0,1]
	v_pk_mul_f32 v[60:61], v[212:213], v[64:65] op_sel:[1,1] op_sel_hi:[1,0]
	v_pk_fma_f32 v[60:61], v[212:213], v[64:65], v[60:61] op_sel_hi:[0,1,1] neg_lo:[0,0,1]
	v_pk_mul_f32 v[64:65], v[220:221], v[204:205] op_sel:[1,1] op_sel_hi:[1,0]
	v_pk_fma_f32 v[64:65], v[220:221], v[204:205], v[64:65] op_sel_hi:[0,1,1] neg_lo:[0,0,1]
	s_barrier
	ds_write_b64 v156, v[6:7] offset:0
	ds_write_b64 v158, v[2:3] offset:0
	ds_write_b64 v160, v[4:5] offset:0
	ds_write_b64 v162, v[8:9] offset:0
	ds_write_b64 v156, v[14:15] offset:8192
	ds_write_b64 v158, v[10:11] offset:8192
	ds_write_b64 v160, v[12:13] offset:8192
	ds_write_b64 v162, v[16:17] offset:8192
	ds_write_b64 v156, v[22:23] offset:16384
	ds_write_b64 v158, v[18:19] offset:16384
	ds_write_b64 v160, v[20:21] offset:16384
	ds_write_b64 v162, v[24:25] offset:16384
	ds_write_b64 v156, v[30:31] offset:24576
	ds_write_b64 v158, v[26:27] offset:24576
	ds_write_b64 v160, v[28:29] offset:24576
	ds_write_b64 v162, v[32:33] offset:24576
	ds_write_b64 v156, v[38:39] offset:32768
	ds_write_b64 v158, v[34:35] offset:32768
	ds_write_b64 v160, v[36:37] offset:32768
	ds_write_b64 v162, v[40:41] offset:32768
	ds_write_b64 v156, v[46:47] offset:40960
	ds_write_b64 v158, v[42:43] offset:40960
	ds_write_b64 v160, v[44:45] offset:40960
	ds_write_b64 v162, v[48:49] offset:40960
	ds_write_b64 v156, v[54:55] offset:49152
	ds_write_b64 v158, v[50:51] offset:49152
	ds_write_b64 v160, v[52:53] offset:49152
	ds_write_b64 v162, v[56:57] offset:49152
	ds_write_b64 v156, v[62:63] offset:57344
	ds_write_b64 v158, v[58:59] offset:57344
	ds_write_b64 v160, v[60:61] offset:57344
	ds_write_b64 v162, v[64:65] offset:57344
	s_waitcnt lgkmcnt(0)
	s_barrier
	ds_read2st64_b64 v[2:5], v154 offset0:0 offset1:32
	ds_read2st64_b64 v[6:9], v154 offset0:64 offset1:96
	ds_read2st64_b64 v[10:13], v154 offset0:4 offset1:36
	ds_read2st64_b64 v[14:17], v154 offset0:68 offset1:100
	ds_read2st64_b64 v[18:21], v154 offset0:8 offset1:40
	ds_read2st64_b64 v[22:25], v154 offset0:72 offset1:104
	ds_read2st64_b64 v[26:29], v154 offset0:12 offset1:44
	ds_read2st64_b64 v[30:33], v154 offset0:76 offset1:108
	ds_read2st64_b64 v[34:37], v154 offset0:16 offset1:48
	ds_read2st64_b64 v[38:41], v154 offset0:80 offset1:112
	ds_read2st64_b64 v[42:45], v154 offset0:20 offset1:52
	ds_read2st64_b64 v[46:49], v154 offset0:84 offset1:116
	ds_read2st64_b64 v[50:53], v154 offset0:24 offset1:56
	ds_read2st64_b64 v[54:57], v154 offset0:88 offset1:120
	ds_read2st64_b64 v[58:61], v154 offset0:28 offset1:60
	ds_read2st64_b64 v[62:65], v154 offset0:92 offset1:124
	v_and_b32_e32 v166, 3, v0
	v_lshlrev_b32_e32 v164, 2, v0
	v_mad_i32_i24 v164, v166, -3, v164
	v_sub_u32_e32 v166, v0, v166
	v_cvt_f32_u32_e32 v201, v166
	v_mul_f32_e32 v201, 0x39000000, v201
	v_bfe_i32 v166, v164, 5, 1
	v_bfe_i32 v168, v164, 6, 1
	v_and_b32_e32 v166, 5, v166
	v_and_b32_e32 v168, 26, v168
	v_xor_b32_e32 v166, v166, v168
	v_xor_b32_e32 v166, v166, v164
	v_lshlrev_b32_e32 v156, 3, v166
	v_xor_b32_e32 v158, 32, v156
	v_xor_b32_e32 v160, 64, v156
	v_xor_b32_e32 v162, 0x60, v156
	v_cos_f32_e32 v210, v201
	v_sin_f32_e64 v211, -v201
	s_waitcnt lgkmcnt(14)
	v_pk_add_f32 v[202:203], v[2:3], v[6:7]
	v_pk_add_f32 v[2:3], v[2:3], v[6:7] neg_lo:[0,1] neg_hi:[0,1]
	v_pk_add_f32 v[204:205], v[4:5], v[8:9]
	v_pk_add_f32 v[4:5], v[4:5], v[8:9] neg_lo:[0,1] neg_hi:[0,1]
	v_pk_add_f32 v[6:7], v[202:203], v[204:205]
	v_pk_add_f32 v[8:9], v[202:203], v[204:205] neg_lo:[0,1] neg_hi:[0,1]
	v_pk_add_f32 v[202:203], v[2:3], v[4:5] op_sel:[0,1] op_sel_hi:[1,0] neg_hi:[0,1]
	v_pk_add_f32 v[204:205], v[2:3], v[4:5] op_sel:[0,1] op_sel_hi:[1,0] neg_lo:[0,1]
	v_pk_mul_f32 v[206:207], v[210:211], v[210:211] op_sel:[1,1] op_sel_hi:[1,0]
	v_pk_fma_f32 v[212:213], v[210:211], v[210:211], v[206:207] op_sel_hi:[0,1,1] neg_lo:[0,0,1]
	v_pk_mul_f32 v[206:207], v[210:211], v[212:213] op_sel:[1,1] op_sel_hi:[1,0]
	v_pk_fma_f32 v[220:221], v[210:211], v[212:213], v[206:207] op_sel_hi:[0,1,1] neg_lo:[0,0,1]
	v_pk_mul_f32 v[2:3], v[210:211], v[202:203] op_sel:[1,1] op_sel_hi:[1,0]
	v_pk_fma_f32 v[2:3], v[210:211], v[202:203], v[2:3] op_sel_hi:[0,1,1] neg_lo:[0,0,1]
	v_pk_mul_f32 v[4:5], v[212:213], v[8:9] op_sel:[1,1] op_sel_hi:[1,0]
	v_pk_fma_f32 v[4:5], v[212:213], v[8:9], v[4:5] op_sel_hi:[0,1,1] neg_lo:[0,0,1]
	v_pk_mul_f32 v[8:9], v[220:221], v[204:205] op_sel:[1,1] op_sel_hi:[1,0]
	v_pk_fma_f32 v[8:9], v[220:221], v[204:205], v[8:9] op_sel_hi:[0,1,1] neg_lo:[0,0,1]
	v_add_f32_e32 v214, 0x3d000000, v201
	v_cos_f32_e32 v210, v214
	v_sin_f32_e64 v211, -v214
	s_waitcnt lgkmcnt(12)
; DI f32x2 cmul(f32x2 a, f32x2 b) { return mkf2(a.x * b.x - a.y * b.y, a.x * b.y + a.y * b.x); }
; DI void fft8192(f32x2* buf, const f32x2* __restrict__ tw) {
;     ...
;   for (int ls = 0; ls < 12; ls += 2) {
;     const int s = 1 << ls;
;     f32x2 a[8], b[8], c[8], d[8];
;     __syncthreads();
; #pragma unroll
;     for (int e = 0; e < 8; ++e) {
;       const int i = tid + 256 * e;
;       const int pi = SW(i);
;       a[e] = buf[pi]; b[e] = buf[pi + 2048]; c[e] = buf[pi + 4096]; d[e] = buf[pi + 6144];
;     }
;     __syncthreads();
; #pragma unroll
;     for (int e = 0; e < 8; ++e) {
;       const int i = tid + 256 * e;
;       const int q = i & (s - 1);
;       const int ps = i - q;
;       const float rev = (float)ps * (1.f / 8192.f);
;       const f32x2 w1 = mkf2(__builtin_amdgcn_cosf(rev), -__builtin_amdgcn_sinf(rev));
;       const f32x2 w2 = cmul(w1, w1), w3 = cmul(w1, w2);
;       const f32x2 apc = mkf2(a[e].x + c[e].x, a[e].y + c[e].y), amc = mkf2(a[e].x - c[e].x, a[e].y - c[e].y);
;       const f32x2 bpd = mkf2(b[e].x + d[e].x, b[e].y + d[e].y), bmd = mkf2(b[e].x - d[e].x, b[e].y - d[e].y);
;       const int o = 4 * i - 3 * q;
;       buf[SW(o)] = mkf2(apc.x + bpd.x, apc.y + bpd.y);
;       buf[SW(o + s)] = cmul(w1, mkf2(amc.x + bmd.y, amc.y - bmd.x));
;       buf[SW(o + 2 * s)] = cmul(w2, mkf2(apc.x - bpd.x, apc.y - bpd.y));
;       buf[SW(o + 3 * s)] = cmul(w3, mkf2(amc.x - bmd.y, amc.y + bmd.x));
;     }
	v_pk_add_f32 v[202:203], v[10:11], v[14:15]
	v_pk_add_f32 v[10:11], v[10:11], v[14:15] neg_lo:[0,1] neg_hi:[0,1]
	v_pk_add_f32 v[204:205], v[12:13], v[16:17]
	v_pk_add_f32 v[12:13], v[12:13], v[16:17] neg_lo:[0,1] neg_hi:[0,1]
	v_pk_add_f32 v[14:15], v[202:203], v[204:205]
	v_pk_add_f32 v[16:17], v[202:203], v[204:205] neg_lo:[0,1] neg_hi:[0,1]
	v_pk_add_f32 v[202:203], v[10:11], v[12:13] op_sel:[0,1] op_sel_hi:[1,0] neg_hi:[0,1]
	v_pk_add_f32 v[204:205], v[10:11], v[12:13] op_sel:[0,1] op_sel_hi:[1,0] neg_lo:[0,1]
	v_pk_mul_f32 v[206:207], v[210:211], v[210:211] op_sel:[1,1] op_sel_hi:[1,0]
	v_pk_fma_f32 v[212:213], v[210:211], v[210:211], v[206:207] op_sel_hi:[0,1,1] neg_lo:[0,0,1]
	v_pk_mul_f32 v[206:207], v[210:211], v[212:213] op_sel:[1,1] op_sel_hi:[1,0]
	v_pk_fma_f32 v[220:221], v[210:211], v[212:213], v[206:207] op_sel_hi:[0,1,1] neg_lo:[0,0,1]
	v_pk_mul_f32 v[10:11], v[210:211], v[202:203] op_sel:[1,1] op_sel_hi:[1,0]
	v_pk_fma_f32 v[10:11], v[210:211], v[202:203], v[10:11] op_sel_hi:[0,1,1] neg_lo:[0,0,1]
	v_pk_mul_f32 v[12:13], v[212:213], v[16:17] op_sel:[1,1] op_sel_hi:[1,0]
	v_pk_fma_f32 v[12:13], v[212:213], v[16:17], v[12:13] op_sel_hi:[0,1,1] neg_lo:[0,0,1]
	v_pk_mul_f32 v[16:17], v[220:221], v[204:205] op_sel:[1,1] op_sel_hi:[1,0]
	v_pk_fma_f32 v[16:17], v[220:221], v[204:205], v[16:17] op_sel_hi:[0,1,1] neg_lo:[0,0,1]
	v_add_f32_e32 v214, 0x3d800000, v201
	v_cos_f32_e32 v210, v214
	v_sin_f32_e64 v211, -v214
	s_waitcnt lgkmcnt(10)
	v_pk_add_f32 v[202:203], v[18:19], v[22:23]
	v_pk_add_f32 v[18:19], v[18:19], v[22:23] neg_lo:[0,1] neg_hi:[0,1]
	v_pk_add_f32 v[204:205], v[20:21], v[24:25]
	v_pk_add_f32 v[20:21], v[20:21], v[24:25] neg_lo:[0,1] neg_hi:[0,1]
	v_pk_add_f32 v[22:23], v[202:203], v[204:205]
	v_pk_add_f32 v[24:25], v[202:203], v[204:205] neg_lo:[0,1] neg_hi:[0,1]
	v_pk_add_f32 v[202:203], v[18:19], v[20:21] op_sel:[0,1] op_sel_hi:[1,0] neg_hi:[0,1]
	v_pk_add_f32 v[204:205], v[18:19], v[20:21] op_sel:[0,1] op_sel_hi:[1,0] neg_lo:[0,1]
	v_pk_mul_f32 v[206:207], v[210:211], v[210:211] op_sel:[1,1] op_sel_hi:[1,0]
	v_pk_fma_f32 v[212:213], v[210:211], v[210:211], v[206:207] op_sel_hi:[0,1,1] neg_lo:[0,0,1]
	v_pk_mul_f32 v[206:207], v[210:211], v[212:213] op_sel:[1,1] op_sel_hi:[1,0]
	v_pk_fma_f32 v[220:221], v[210:211], v[212:213], v[206:207] op_sel_hi:[0,1,1] neg_lo:[0,0,1]
	v_pk_mul_f32 v[18:19], v[210:211], v[202:203] op_sel:[1,1] op_sel_hi:[1,0]
	v_pk_fma_f32 v[18:19], v[210:211], v[202:203], v[18:19] op_sel_hi:[0,1,1] neg_lo:[0,0,1]
	v_pk_mul_f32 v[20:21], v[212:213], v[24:25] op_sel:[1,1] op_sel_hi:[1,0]
	v_pk_fma_f32 v[20:21], v[212:213], v[24:25], v[20:21] op_sel_hi:[0,1,1] neg_lo:[0,0,1]
	v_pk_mul_f32 v[24:25], v[220:221], v[204:205] op_sel:[1,1] op_sel_hi:[1,0]
	v_pk_fma_f32 v[24:25], v[220:221], v[204:205], v[24:25] op_sel_hi:[0,1,1] neg_lo:[0,0,1]
	v_add_f32_e32 v214, 0x3dc00000, v201
	v_cos_f32_e32 v210, v214
	v_sin_f32_e64 v211, -v214
	s_waitcnt lgkmcnt(8)
	v_pk_add_f32 v[202:203], v[26:27], v[30:31]
	v_pk_add_f32 v[26:27], v[26:27], v[30:31] neg_lo:[0,1] neg_hi:[0,1]
	v_pk_add_f32 v[204:205], v[28:29], v[32:33]
	v_pk_add_f32 v[28:29], v[28:29], v[32:33] neg_lo:[0,1] neg_hi:[0,1]
	v_pk_add_f32 v[30:31], v[202:203], v[204:205]
	v_pk_add_f32 v[32:33], v[202:203], v[204:205] neg_lo:[0,1] neg_hi:[0,1]
	v_pk_add_f32 v[202:203], v[26:27], v[28:29] op_sel:[0,1] op_sel_hi:[1,0] neg_hi:[0,1]
	v_pk_add_f32 v[204:205], v[26:27], v[28:29] op_sel:[0,1] op_sel_hi:[1,0] neg_lo:[0,1]
	v_pk_mul_f32 v[206:207], v[210:211], v[210:211] op_sel:[1,1] op_sel_hi:[1,0]
	v_pk_fma_f32 v[212:213], v[210:211], v[210:211], v[206:207] op_sel_hi:[0,1,1] neg_lo:[0,0,1]
	v_pk_mul_f32 v[206:207], v[210:211], v[212:213] op_sel:[1,1] op_sel_hi:[1,0]
	v_pk_fma_f32 v[220:221], v[210:211], v[212:213], v[206:207] op_sel_hi:[0,1,1] neg_lo:[0,0,1]
	v_pk_mul_f32 v[26:27], v[210:211], v[202:203] op_sel:[1,1] op_sel_hi:[1,0]
	v_pk_fma_f32 v[26:27], v[210:211], v[202:203], v[26:27] op_sel_hi:[0,1,1] neg_lo:[0,0,1]
	v_pk_mul_f32 v[28:29], v[212:213], v[32:33] op_sel:[1,1] op_sel_hi:[1,0]
	v_pk_fma_f32 v[28:29], v[212:213], v[32:33], v[28:29] op_sel_hi:[0,1,1] neg_lo:[0,0,1]
	v_pk_mul_f32 v[32:33], v[220:221], v[204:205] op_sel:[1,1] op_sel_hi:[1,0]
	v_pk_fma_f32 v[32:33], v[220:221], v[204:205], v[32:33] op_sel_hi:[0,1,1] neg_lo:[0,0,1]
	v_add_f32_e32 v214, 0x3e000000, v201
	v_cos_f32_e32 v210, v214
	v_sin_f32_e64 v211, -v214
	s_waitcnt lgkmcnt(6)
	v_pk_add_f32 v[202:203], v[34:35], v[38:39]
	v_pk_add_f32 v[34:35], v[34:35], v[38:39] neg_lo:[0,1] neg_hi:[0,1]
	v_pk_add_f32 v[204:205], v[36:37], v[40:41]
	v_pk_add_f32 v[36:37], v[36:37], v[40:41] neg_lo:[0,1] neg_hi:[0,1]
	v_pk_add_f32 v[38:39], v[202:203], v[204:205]
	v_pk_add_f32 v[40:41], v[202:203], v[204:205] neg_lo:[0,1] neg_hi:[0,1]
	v_pk_add_f32 v[202:203], v[34:35], v[36:37] op_sel:[0,1] op_sel_hi:[1,0] neg_hi:[0,1]
	v_pk_add_f32 v[204:205], v[34:35], v[36:37] op_sel:[0,1] op_sel_hi:[1,0] neg_lo:[0,1]
	v_pk_mul_f32 v[206:207], v[210:211], v[210:211] op_sel:[1,1] op_sel_hi:[1,0]
	v_pk_fma_f32 v[212:213], v[210:211], v[210:211], v[206:207] op_sel_hi:[0,1,1] neg_lo:[0,0,1]
	v_pk_mul_f32 v[206:207], v[210:211], v[212:213] op_sel:[1,1] op_sel_hi:[1,0]
	v_pk_fma_f32 v[220:221], v[210:211], v[212:213], v[206:207] op_sel_hi:[0,1,1] neg_lo:[0,0,1]
	v_pk_mul_f32 v[34:35], v[210:211], v[202:203] op_sel:[1,1] op_sel_hi:[1,0]
	v_pk_fma_f32 v[34:35], v[210:211], v[202:203], v[34:35] op_sel_hi:[0,1,1] neg_lo:[0,0,1]
	v_pk_mul_f32 v[36:37], v[212:213], v[40:41] op_sel:[1,1] op_sel_hi:[1,0]
	v_pk_fma_f32 v[36:37], v[212:213], v[40:41], v[36:37] op_sel_hi:[0,1,1] neg_lo:[0,0,1]
	v_pk_mul_f32 v[40:41], v[220:221], v[204:205] op_sel:[1,1] op_sel_hi:[1,0]
	v_pk_fma_f32 v[40:41], v[220:221], v[204:205], v[40:41] op_sel_hi:[0,1,1] neg_lo:[0,0,1]
	v_add_f32_e32 v214, 0x3e200000, v201
	v_cos_f32_e32 v210, v214
	v_sin_f32_e64 v211, -v214
	s_waitcnt lgkmcnt(4)
; DI f32x2 cmul(f32x2 a, f32x2 b) { return mkf2(a.x * b.x - a.y * b.y, a.x * b.y + a.y * b.x); }
; DI void fft8192(f32x2* buf, const f32x2* __restrict__ tw) {
;     ...
;   for (int ls = 0; ls < 12; ls += 2) {
;     const int s = 1 << ls;
;     f32x2 a[8], b[8], c[8], d[8];
;     __syncthreads();
; #pragma unroll
;     for (int e = 0; e < 8; ++e) {
;       const int i = tid + 256 * e;
;       const int pi = SW(i);
;       a[e] = buf[pi]; b[e] = buf[pi + 2048]; c[e] = buf[pi + 4096]; d[e] = buf[pi + 6144];
;     }
;     __syncthreads();
; #pragma unroll
;     for (int e = 0; e < 8; ++e) {
;       const int i = tid + 256 * e;
;       const int q = i & (s - 1);
;       const int ps = i - q;
;       const float rev = (float)ps * (1.f / 8192.f);
;       const f32x2 w1 = mkf2(__builtin_amdgcn_cosf(rev), -__builtin_amdgcn_sinf(rev));
;       const f32x2 w2 = cmul(w1, w1), w3 = cmul(w1, w2);
;       const f32x2 apc = mkf2(a[e].x + c[e].x, a[e].y + c[e].y), amc = mkf2(a[e].x - c[e].x, a[e].y - c[e].y);
;       const f32x2 bpd = mkf2(b[e].x + d[e].x, b[e].y + d[e].y), bmd = mkf2(b[e].x - d[e].x, b[e].y - d[e].y);
;       const int o = 4 * i - 3 * q;
;       buf[SW(o)] = mkf2(apc.x + bpd.x, apc.y + bpd.y);
;       buf[SW(o + s)] = cmul(w1, mkf2(amc.x + bmd.y, amc.y - bmd.x));
;       buf[SW(o + 2 * s)] = cmul(w2, mkf2(apc.x - bpd.x, apc.y - bpd.y));
;       buf[SW(o + 3 * s)] = cmul(w3, mkf2(amc.x - bmd.y, amc.y + bmd.x));
;     }
	v_pk_add_f32 v[202:203], v[42:43], v[46:47]
	v_pk_add_f32 v[42:43], v[42:43], v[46:47] neg_lo:[0,1] neg_hi:[0,1]
	v_pk_add_f32 v[204:205], v[44:45], v[48:49]
	v_pk_add_f32 v[44:45], v[44:45], v[48:49] neg_lo:[0,1] neg_hi:[0,1]
	v_pk_add_f32 v[46:47], v[202:203], v[204:205]
	v_pk_add_f32 v[48:49], v[202:203], v[204:205] neg_lo:[0,1] neg_hi:[0,1]
	v_pk_add_f32 v[202:203], v[42:43], v[44:45] op_sel:[0,1] op_sel_hi:[1,0] neg_hi:[0,1]
	v_pk_add_f32 v[204:205], v[42:43], v[44:45] op_sel:[0,1] op_sel_hi:[1,0] neg_lo:[0,1]
	v_pk_mul_f32 v[206:207], v[210:211], v[210:211] op_sel:[1,1] op_sel_hi:[1,0]
	v_pk_fma_f32 v[212:213], v[210:211], v[210:211], v[206:207] op_sel_hi:[0,1,1] neg_lo:[0,0,1]
	v_pk_mul_f32 v[206:207], v[210:211], v[212:213] op_sel:[1,1] op_sel_hi:[1,0]
	v_pk_fma_f32 v[220:221], v[210:211], v[212:213], v[206:207] op_sel_hi:[0,1,1] neg_lo:[0,0,1]
	v_pk_mul_f32 v[42:43], v[210:211], v[202:203] op_sel:[1,1] op_sel_hi:[1,0]
	v_pk_fma_f32 v[42:43], v[210:211], v[202:203], v[42:43] op_sel_hi:[0,1,1] neg_lo:[0,0,1]
	v_pk_mul_f32 v[44:45], v[212:213], v[48:49] op_sel:[1,1] op_sel_hi:[1,0]
	v_pk_fma_f32 v[44:45], v[212:213], v[48:49], v[44:45] op_sel_hi:[0,1,1] neg_lo:[0,0,1]
	v_pk_mul_f32 v[48:49], v[220:221], v[204:205] op_sel:[1,1] op_sel_hi:[1,0]
	v_pk_fma_f32 v[48:49], v[220:221], v[204:205], v[48:49] op_sel_hi:[0,1,1] neg_lo:[0,0,1]
	v_add_f32_e32 v214, 0x3e400000, v201
	v_cos_f32_e32 v210, v214
	v_sin_f32_e64 v211, -v214
	s_waitcnt lgkmcnt(2)
	v_pk_add_f32 v[202:203], v[50:51], v[54:55]
	v_pk_add_f32 v[50:51], v[50:51], v[54:55] neg_lo:[0,1] neg_hi:[0,1]
	v_pk_add_f32 v[204:205], v[52:53], v[56:57]
	v_pk_add_f32 v[52:53], v[52:53], v[56:57] neg_lo:[0,1] neg_hi:[0,1]
	v_pk_add_f32 v[54:55], v[202:203], v[204:205]
	v_pk_add_f32 v[56:57], v[202:203], v[204:205] neg_lo:[0,1] neg_hi:[0,1]
	v_pk_add_f32 v[202:203], v[50:51], v[52:53] op_sel:[0,1] op_sel_hi:[1,0] neg_hi:[0,1]
	v_pk_add_f32 v[204:205], v[50:51], v[52:53] op_sel:[0,1] op_sel_hi:[1,0] neg_lo:[0,1]
	v_pk_mul_f32 v[206:207], v[210:211], v[210:211] op_sel:[1,1] op_sel_hi:[1,0]
	v_pk_fma_f32 v[212:213], v[210:211], v[210:211], v[206:207] op_sel_hi:[0,1,1] neg_lo:[0,0,1]
	v_pk_mul_f32 v[206:207], v[210:211], v[212:213] op_sel:[1,1] op_sel_hi:[1,0]
	v_pk_fma_f32 v[220:221], v[210:211], v[212:213], v[206:207] op_sel_hi:[0,1,1] neg_lo:[0,0,1]
	v_pk_mul_f32 v[50:51], v[210:211], v[202:203] op_sel:[1,1] op_sel_hi:[1,0]
	v_pk_fma_f32 v[50:51], v[210:211], v[202:203], v[50:51] op_sel_hi:[0,1,1] neg_lo:[0,0,1]
	v_pk_mul_f32 v[52:53], v[212:213], v[56:57] op_sel:[1,1] op_sel_hi:[1,0]
	v_pk_fma_f32 v[52:53], v[212:213], v[56:57], v[52:53] op_sel_hi:[0,1,1] neg_lo:[0,0,1]
	v_pk_mul_f32 v[56:57], v[220:221], v[204:205] op_sel:[1,1] op_sel_hi:[1,0]
	v_pk_fma_f32 v[56:57], v[220:221], v[204:205], v[56:57] op_sel_hi:[0,1,1] neg_lo:[0,0,1]
	v_add_f32_e32 v214, 0x3e600000, v201
	v_cos_f32_e32 v210, v214
	v_sin_f32_e64 v211, -v214
	s_waitcnt lgkmcnt(0)
	v_pk_add_f32 v[202:203], v[58:59], v[62:63]
	v_pk_add_f32 v[58:59], v[58:59], v[62:63] neg_lo:[0,1] neg_hi:[0,1]
	v_pk_add_f32 v[204:205], v[60:61], v[64:65]
	v_pk_add_f32 v[60:61], v[60:61], v[64:65] neg_lo:[0,1] neg_hi:[0,1]
	v_pk_add_f32 v[62:63], v[202:203], v[204:205]
	v_pk_add_f32 v[64:65], v[202:203], v[204:205] neg_lo:[0,1] neg_hi:[0,1]
	v_pk_add_f32 v[202:203], v[58:59], v[60:61] op_sel:[0,1] op_sel_hi:[1,0] neg_hi:[0,1]
	v_pk_add_f32 v[204:205], v[58:59], v[60:61] op_sel:[0,1] op_sel_hi:[1,0] neg_lo:[0,1]
	v_pk_mul_f32 v[206:207], v[210:211], v[210:211] op_sel:[1,1] op_sel_hi:[1,0]
	v_pk_fma_f32 v[212:213], v[210:211], v[210:211], v[206:207] op_sel_hi:[0,1,1] neg_lo:[0,0,1]
	v_pk_mul_f32 v[206:207], v[210:211], v[212:213] op_sel:[1,1] op_sel_hi:[1,0]
	v_pk_fma_f32 v[220:221], v[210:211], v[212:213], v[206:207] op_sel_hi:[0,1,1] neg_lo:[0,0,1]
	v_pk_mul_f32 v[58:59], v[210:211], v[202:203] op_sel:[1,1] op_sel_hi:[1,0]
	v_pk_fma_f32 v[58:59], v[210:211], v[202:203], v[58:59] op_sel_hi:[0,1,1] neg_lo:[0,0,1]
	v_pk_mul_f32 v[60:61], v[212:213], v[64:65] op_sel:[1,1] op_sel_hi:[1,0]
	v_pk_fma_f32 v[60:61], v[212:213], v[64:65], v[60:61] op_sel_hi:[0,1,1] neg_lo:[0,0,1]
	v_pk_mul_f32 v[64:65], v[220:221], v[204:205] op_sel:[1,1] op_sel_hi:[1,0]
	v_pk_fma_f32 v[64:65], v[220:221], v[204:205], v[64:65] op_sel_hi:[0,1,1] neg_lo:[0,0,1]
	s_barrier
	ds_write_b64 v156, v[6:7] offset:0
	ds_write_b64 v158, v[2:3] offset:0
	ds_write_b64 v160, v[4:5] offset:0
	ds_write_b64 v162, v[8:9] offset:0
	ds_write_b64 v156, v[14:15] offset:8192
	ds_write_b64 v158, v[10:11] offset:8192
	ds_write_b64 v160, v[12:13] offset:8192
	ds_write_b64 v162, v[16:17] offset:8192
	ds_write_b64 v156, v[22:23] offset:16384
	ds_write_b64 v158, v[18:19] offset:16384
	ds_write_b64 v160, v[20:21] offset:16384
	ds_write_b64 v162, v[24:25] offset:16384
	ds_write_b64 v156, v[30:31] offset:24576
	ds_write_b64 v158, v[26:27] offset:24576
	ds_write_b64 v160, v[28:29] offset:24576
	ds_write_b64 v162, v[32:33] offset:24576
	ds_write_b64 v156, v[38:39] offset:32768
	ds_write_b64 v158, v[34:35] offset:32768
	ds_write_b64 v160, v[36:37] offset:32768
	ds_write_b64 v162, v[40:41] offset:32768
	ds_write_b64 v156, v[46:47] offset:40960
	ds_write_b64 v158, v[42:43] offset:40960
	ds_write_b64 v160, v[44:45] offset:40960
	ds_write_b64 v162, v[48:49] offset:40960
	ds_write_b64 v156, v[54:55] offset:49152
	ds_write_b64 v158, v[50:51] offset:49152
	ds_write_b64 v160, v[52:53] offset:49152
	ds_write_b64 v162, v[56:57] offset:49152
	ds_write_b64 v156, v[62:63] offset:57344
	ds_write_b64 v158, v[58:59] offset:57344
	ds_write_b64 v160, v[60:61] offset:57344
	ds_write_b64 v162, v[64:65] offset:57344
	s_waitcnt lgkmcnt(0)
	s_barrier
; DI f32x2 cmul(f32x2 a, f32x2 b) { return mkf2(a.x * b.x - a.y * b.y, a.x * b.y + a.y * b.x); }
; DI void fft8192(f32x2* buf, const f32x2* __restrict__ tw) {
;     ...
;   for (int ls = 0; ls < 12; ls += 2) {
;     const int s = 1 << ls;
;     f32x2 a[8], b[8], c[8], d[8];
;     __syncthreads();
; #pragma unroll
;     for (int e = 0; e < 8; ++e) {
;       const int i = tid + 256 * e;
;       const int pi = SW(i);
;       a[e] = buf[pi]; b[e] = buf[pi + 2048]; c[e] = buf[pi + 4096]; d[e] = buf[pi + 6144];
;     }
;     __syncthreads();
; #pragma unroll
;     for (int e = 0; e < 8; ++e) {
;       const int i = tid + 256 * e;
;       const int q = i & (s - 1);
;       const int ps = i - q;
;       const float rev = (float)ps * (1.f / 8192.f);
;       const f32x2 w1 = mkf2(__builtin_amdgcn_cosf(rev), -__builtin_amdgcn_sinf(rev));
;       const f32x2 w2 = cmul(w1, w1), w3 = cmul(w1, w2);
;       const f32x2 apc = mkf2(a[e].x + c[e].x, a[e].y + c[e].y), amc = mkf2(a[e].x - c[e].x, a[e].y - c[e].y);
;       const f32x2 bpd = mkf2(b[e].x + d[e].x, b[e].y + d[e].y), bmd = mkf2(b[e].x - d[e].x, b[e].y - d[e].y);
;       const int o = 4 * i - 3 * q;
;       buf[SW(o)] = mkf2(apc.x + bpd.x, apc.y + bpd.y);
;       buf[SW(o + s)] = cmul(w1, mkf2(amc.x + bmd.y, amc.y - bmd.x));
;       buf[SW(o + 2 * s)] = cmul(w2, mkf2(apc.x - bpd.x, apc.y - bpd.y));
;       buf[SW(o + 3 * s)] = cmul(w3, mkf2(amc.x - bmd.y, amc.y + bmd.x));
;     }
	ds_read2st64_b64 v[2:5], v154 offset0:0 offset1:32
	ds_read2st64_b64 v[6:9], v154 offset0:64 offset1:96
	ds_read2st64_b64 v[10:13], v154 offset0:4 offset1:36
	ds_read2st64_b64 v[14:17], v154 offset0:68 offset1:100
	ds_read2st64_b64 v[18:21], v154 offset0:8 offset1:40
	ds_read2st64_b64 v[22:25], v154 offset0:72 offset1:104
	ds_read2st64_b64 v[26:29], v154 offset0:12 offset1:44
	ds_read2st64_b64 v[30:33], v154 offset0:76 offset1:108
	ds_read2st64_b64 v[34:37], v154 offset0:16 offset1:48
	ds_read2st64_b64 v[38:41], v154 offset0:80 offset1:112
	ds_read2st64_b64 v[42:45], v154 offset0:20 offset1:52
	ds_read2st64_b64 v[46:49], v154 offset0:84 offset1:116
	ds_read2st64_b64 v[50:53], v154 offset0:24 offset1:56
	ds_read2st64_b64 v[54:57], v154 offset0:88 offset1:120
	ds_read2st64_b64 v[58:61], v154 offset0:28 offset1:60
	ds_read2st64_b64 v[62:65], v154 offset0:92 offset1:124
	v_and_b32_e32 v166, 15, v0
	v_lshlrev_b32_e32 v164, 2, v0
	v_mad_i32_i24 v164, v166, -3, v164
	v_sub_u32_e32 v166, v0, v166
	v_cvt_f32_u32_e32 v201, v166
	v_mul_f32_e32 v201, 0x39000000, v201
	v_bfe_i32 v166, v164, 5, 1
	v_bfe_i32 v168, v164, 6, 1
	v_and_b32_e32 v166, 5, v166
	v_and_b32_e32 v168, 26, v168
	v_xor_b32_e32 v166, v166, v168
	v_xor_b32_e32 v166, v166, v164
	v_lshlrev_b32_e32 v156, 3, v166
	v_xor_b32_e32 v158, 0x80, v156
	v_xor_b32_e32 v160, 0x128, v156
	v_xor_b32_e32 v162, 0x1a8, v156
	v_cos_f32_e32 v210, v201
	v_sin_f32_e64 v211, -v201
	s_waitcnt lgkmcnt(14)
	v_pk_add_f32 v[202:203], v[2:3], v[6:7]
	v_pk_add_f32 v[2:3], v[2:3], v[6:7] neg_lo:[0,1] neg_hi:[0,1]
	v_pk_add_f32 v[204:205], v[4:5], v[8:9]
	v_pk_add_f32 v[4:5], v[4:5], v[8:9] neg_lo:[0,1] neg_hi:[0,1]
	v_pk_add_f32 v[6:7], v[202:203], v[204:205]
	v_pk_add_f32 v[8:9], v[202:203], v[204:205] neg_lo:[0,1] neg_hi:[0,1]
	v_pk_add_f32 v[202:203], v[2:3], v[4:5] op_sel:[0,1] op_sel_hi:[1,0] neg_hi:[0,1]
	v_pk_add_f32 v[204:205], v[2:3], v[4:5] op_sel:[0,1] op_sel_hi:[1,0] neg_lo:[0,1]
	v_pk_mul_f32 v[206:207], v[210:211], v[210:211] op_sel:[1,1] op_sel_hi:[1,0]
	v_pk_fma_f32 v[212:213], v[210:211], v[210:211], v[206:207] op_sel_hi:[0,1,1] neg_lo:[0,0,1]
	v_pk_mul_f32 v[206:207], v[210:211], v[212:213] op_sel:[1,1] op_sel_hi:[1,0]
	v_pk_fma_f32 v[220:221], v[210:211], v[212:213], v[206:207] op_sel_hi:[0,1,1] neg_lo:[0,0,1]
	v_pk_mul_f32 v[2:3], v[210:211], v[202:203] op_sel:[1,1] op_sel_hi:[1,0]
	v_pk_fma_f32 v[2:3], v[210:211], v[202:203], v[2:3] op_sel_hi:[0,1,1] neg_lo:[0,0,1]
	v_pk_mul_f32 v[4:5], v[212:213], v[8:9] op_sel:[1,1] op_sel_hi:[1,0]
	v_pk_fma_f32 v[4:5], v[212:213], v[8:9], v[4:5] op_sel_hi:[0,1,1] neg_lo:[0,0,1]
	v_pk_mul_f32 v[8:9], v[220:221], v[204:205] op_sel:[1,1] op_sel_hi:[1,0]
	v_pk_fma_f32 v[8:9], v[220:221], v[204:205], v[8:9] op_sel_hi:[0,1,1] neg_lo:[0,0,1]
	v_add_f32_e32 v214, 0x3d000000, v201
	v_cos_f32_e32 v210, v214
	v_sin_f32_e64 v211, -v214
	s_waitcnt lgkmcnt(12)
	v_pk_add_f32 v[202:203], v[10:11], v[14:15]
	v_pk_add_f32 v[10:11], v[10:11], v[14:15] neg_lo:[0,1] neg_hi:[0,1]
	v_pk_add_f32 v[204:205], v[12:13], v[16:17]
	v_pk_add_f32 v[12:13], v[12:13], v[16:17] neg_lo:[0,1] neg_hi:[0,1]
	v_pk_add_f32 v[14:15], v[202:203], v[204:205]
	v_pk_add_f32 v[16:17], v[202:203], v[204:205] neg_lo:[0,1] neg_hi:[0,1]
	v_pk_add_f32 v[202:203], v[10:11], v[12:13] op_sel:[0,1] op_sel_hi:[1,0] neg_hi:[0,1]
	v_pk_add_f32 v[204:205], v[10:11], v[12:13] op_sel:[0,1] op_sel_hi:[1,0] neg_lo:[0,1]
	v_pk_mul_f32 v[206:207], v[210:211], v[210:211] op_sel:[1,1] op_sel_hi:[1,0]
	v_pk_fma_f32 v[212:213], v[210:211], v[210:211], v[206:207] op_sel_hi:[0,1,1] neg_lo:[0,0,1]
	v_pk_mul_f32 v[206:207], v[210:211], v[212:213] op_sel:[1,1] op_sel_hi:[1,0]
	v_pk_fma_f32 v[220:221], v[210:211], v[212:213], v[206:207] op_sel_hi:[0,1,1] neg_lo:[0,0,1]
	v_pk_mul_f32 v[10:11], v[210:211], v[202:203] op_sel:[1,1] op_sel_hi:[1,0]
	v_pk_fma_f32 v[10:11], v[210:211], v[202:203], v[10:11] op_sel_hi:[0,1,1] neg_lo:[0,0,1]
	v_pk_mul_f32 v[12:13], v[212:213], v[16:17] op_sel:[1,1] op_sel_hi:[1,0]
	v_pk_fma_f32 v[12:13], v[212:213], v[16:17], v[12:13] op_sel_hi:[0,1,1] neg_lo:[0,0,1]
	v_pk_mul_f32 v[16:17], v[220:221], v[204:205] op_sel:[1,1] op_sel_hi:[1,0]
	v_pk_fma_f32 v[16:17], v[220:221], v[204:205], v[16:17] op_sel_hi:[0,1,1] neg_lo:[0,0,1]
	v_add_f32_e32 v214, 0x3d800000, v201
	v_cos_f32_e32 v210, v214
	v_sin_f32_e64 v211, -v214
	s_waitcnt lgkmcnt(10)
	v_pk_add_f32 v[202:203], v[18:19], v[22:23]
	v_pk_add_f32 v[18:19], v[18:19], v[22:23] neg_lo:[0,1] neg_hi:[0,1]
	v_pk_add_f32 v[204:205], v[20:21], v[24:25]
	v_pk_add_f32 v[20:21], v[20:21], v[24:25] neg_lo:[0,1] neg_hi:[0,1]
	v_pk_add_f32 v[22:23], v[202:203], v[204:205]
	v_pk_add_f32 v[24:25], v[202:203], v[204:205] neg_lo:[0,1] neg_hi:[0,1]
	v_pk_add_f32 v[202:203], v[18:19], v[20:21] op_sel:[0,1] op_sel_hi:[1,0] neg_hi:[0,1]
	v_pk_add_f32 v[204:205], v[18:19], v[20:21] op_sel:[0,1] op_sel_hi:[1,0] neg_lo:[0,1]
	v_pk_mul_f32 v[206:207], v[210:211], v[210:211] op_sel:[1,1] op_sel_hi:[1,0]
	v_pk_fma_f32 v[212:213], v[210:211], v[210:211], v[206:207] op_sel_hi:[0,1,1] neg_lo:[0,0,1]
	v_pk_mul_f32 v[206:207], v[210:211], v[212:213] op_sel:[1,1] op_sel_hi:[1,0]
	v_pk_fma_f32 v[220:221], v[210:211], v[212:213], v[206:207] op_sel_hi:[0,1,1] neg_lo:[0,0,1]
	v_pk_mul_f32 v[18:19], v[210:211], v[202:203] op_sel:[1,1] op_sel_hi:[1,0]
	v_pk_fma_f32 v[18:19], v[210:211], v[202:203], v[18:19] op_sel_hi:[0,1,1] neg_lo:[0,0,1]
	v_pk_mul_f32 v[20:21], v[212:213], v[24:25] op_sel:[1,1] op_sel_hi:[1,0]
	v_pk_fma_f32 v[20:21], v[212:213], v[24:25], v[20:21] op_sel_hi:[0,1,1] neg_lo:[0,0,1]
	v_pk_mul_f32 v[24:25], v[220:221], v[204:205] op_sel:[1,1] op_sel_hi:[1,0]
	v_pk_fma_f32 v[24:25], v[220:221], v[204:205], v[24:25] op_sel_hi:[0,1,1] neg_lo:[0,0,1]
	v_add_f32_e32 v214, 0x3dc00000, v201
	v_cos_f32_e32 v210, v214
	v_sin_f32_e64 v211, -v214
	s_waitcnt lgkmcnt(8)
; DI f32x2 cmul(f32x2 a, f32x2 b) { return mkf2(a.x * b.x - a.y * b.y, a.x * b.y + a.y * b.x); }
; DI void fft8192(f32x2* buf, const f32x2* __restrict__ tw) {
;     ...
;   for (int ls = 0; ls < 12; ls += 2) {
;     const int s = 1 << ls;
;     f32x2 a[8], b[8], c[8], d[8];
;     __syncthreads();
; #pragma unroll
;     for (int e = 0; e < 8; ++e) {
;       const int i = tid + 256 * e;
;       const int pi = SW(i);
;       a[e] = buf[pi]; b[e] = buf[pi + 2048]; c[e] = buf[pi + 4096]; d[e] = buf[pi + 6144];
;     }
;     __syncthreads();
; #pragma unroll
;     for (int e = 0; e < 8; ++e) {
;       const int i = tid + 256 * e;
;       const int q = i & (s - 1);
;       const int ps = i - q;
;       const float rev = (float)ps * (1.f / 8192.f);
;       const f32x2 w1 = mkf2(__builtin_amdgcn_cosf(rev), -__builtin_amdgcn_sinf(rev));
;       const f32x2 w2 = cmul(w1, w1), w3 = cmul(w1, w2);
;       const f32x2 apc = mkf2(a[e].x + c[e].x, a[e].y + c[e].y), amc = mkf2(a[e].x - c[e].x, a[e].y - c[e].y);
;       const f32x2 bpd = mkf2(b[e].x + d[e].x, b[e].y + d[e].y), bmd = mkf2(b[e].x - d[e].x, b[e].y - d[e].y);
;       const int o = 4 * i - 3 * q;
;       buf[SW(o)] = mkf2(apc.x + bpd.x, apc.y + bpd.y);
;       buf[SW(o + s)] = cmul(w1, mkf2(amc.x + bmd.y, amc.y - bmd.x));
;       buf[SW(o + 2 * s)] = cmul(w2, mkf2(apc.x - bpd.x, apc.y - bpd.y));
;       buf[SW(o + 3 * s)] = cmul(w3, mkf2(amc.x - bmd.y, amc.y + bmd.x));
;     }
	v_pk_add_f32 v[202:203], v[26:27], v[30:31]
	v_pk_add_f32 v[26:27], v[26:27], v[30:31] neg_lo:[0,1] neg_hi:[0,1]
	v_pk_add_f32 v[204:205], v[28:29], v[32:33]
	v_pk_add_f32 v[28:29], v[28:29], v[32:33] neg_lo:[0,1] neg_hi:[0,1]
	v_pk_add_f32 v[30:31], v[202:203], v[204:205]
	v_pk_add_f32 v[32:33], v[202:203], v[204:205] neg_lo:[0,1] neg_hi:[0,1]
	v_pk_add_f32 v[202:203], v[26:27], v[28:29] op_sel:[0,1] op_sel_hi:[1,0] neg_hi:[0,1]
	v_pk_add_f32 v[204:205], v[26:27], v[28:29] op_sel:[0,1] op_sel_hi:[1,0] neg_lo:[0,1]
	v_pk_mul_f32 v[206:207], v[210:211], v[210:211] op_sel:[1,1] op_sel_hi:[1,0]
	v_pk_fma_f32 v[212:213], v[210:211], v[210:211], v[206:207] op_sel_hi:[0,1,1] neg_lo:[0,0,1]
	v_pk_mul_f32 v[206:207], v[210:211], v[212:213] op_sel:[1,1] op_sel_hi:[1,0]
	v_pk_fma_f32 v[220:221], v[210:211], v[212:213], v[206:207] op_sel_hi:[0,1,1] neg_lo:[0,0,1]
	v_pk_mul_f32 v[26:27], v[210:211], v[202:203] op_sel:[1,1] op_sel_hi:[1,0]
	v_pk_fma_f32 v[26:27], v[210:211], v[202:203], v[26:27] op_sel_hi:[0,1,1] neg_lo:[0,0,1]
	v_pk_mul_f32 v[28:29], v[212:213], v[32:33] op_sel:[1,1] op_sel_hi:[1,0]
	v_pk_fma_f32 v[28:29], v[212:213], v[32:33], v[28:29] op_sel_hi:[0,1,1] neg_lo:[0,0,1]
	v_pk_mul_f32 v[32:33], v[220:221], v[204:205] op_sel:[1,1] op_sel_hi:[1,0]
	v_pk_fma_f32 v[32:33], v[220:221], v[204:205], v[32:33] op_sel_hi:[0,1,1] neg_lo:[0,0,1]
	v_add_f32_e32 v214, 0x3e000000, v201
	v_cos_f32_e32 v210, v214
	v_sin_f32_e64 v211, -v214
	s_waitcnt lgkmcnt(6)
	v_pk_add_f32 v[202:203], v[34:35], v[38:39]
	v_pk_add_f32 v[34:35], v[34:35], v[38:39] neg_lo:[0,1] neg_hi:[0,1]
	v_pk_add_f32 v[204:205], v[36:37], v[40:41]
	v_pk_add_f32 v[36:37], v[36:37], v[40:41] neg_lo:[0,1] neg_hi:[0,1]
	v_pk_add_f32 v[38:39], v[202:203], v[204:205]
	v_pk_add_f32 v[40:41], v[202:203], v[204:205] neg_lo:[0,1] neg_hi:[0,1]
	v_pk_add_f32 v[202:203], v[34:35], v[36:37] op_sel:[0,1] op_sel_hi:[1,0] neg_hi:[0,1]
	v_pk_add_f32 v[204:205], v[34:35], v[36:37] op_sel:[0,1] op_sel_hi:[1,0] neg_lo:[0,1]
	v_pk_mul_f32 v[206:207], v[210:211], v[210:211] op_sel:[1,1] op_sel_hi:[1,0]
	v_pk_fma_f32 v[212:213], v[210:211], v[210:211], v[206:207] op_sel_hi:[0,1,1] neg_lo:[0,0,1]
	v_pk_mul_f32 v[206:207], v[210:211], v[212:213] op_sel:[1,1] op_sel_hi:[1,0]
	v_pk_fma_f32 v[220:221], v[210:211], v[212:213], v[206:207] op_sel_hi:[0,1,1] neg_lo:[0,0,1]
	v_pk_mul_f32 v[34:35], v[210:211], v[202:203] op_sel:[1,1] op_sel_hi:[1,0]
	v_pk_fma_f32 v[34:35], v[210:211], v[202:203], v[34:35] op_sel_hi:[0,1,1] neg_lo:[0,0,1]
	v_pk_mul_f32 v[36:37], v[212:213], v[40:41] op_sel:[1,1] op_sel_hi:[1,0]
	v_pk_fma_f32 v[36:37], v[212:213], v[40:41], v[36:37] op_sel_hi:[0,1,1] neg_lo:[0,0,1]
	v_pk_mul_f32 v[40:41], v[220:221], v[204:205] op_sel:[1,1] op_sel_hi:[1,0]
	v_pk_fma_f32 v[40:41], v[220:221], v[204:205], v[40:41] op_sel_hi:[0,1,1] neg_lo:[0,0,1]
	v_add_f32_e32 v214, 0x3e200000, v201
	v_cos_f32_e32 v210, v214
	v_sin_f32_e64 v211, -v214
	s_waitcnt lgkmcnt(4)
	v_pk_add_f32 v[202:203], v[42:43], v[46:47]
	v_pk_add_f32 v[42:43], v[42:43], v[46:47] neg_lo:[0,1] neg_hi:[0,1]
	v_pk_add_f32 v[204:205], v[44:45], v[48:49]
	v_pk_add_f32 v[44:45], v[44:45], v[48:49] neg_lo:[0,1] neg_hi:[0,1]
	v_pk_add_f32 v[46:47], v[202:203], v[204:205]
	v_pk_add_f32 v[48:49], v[202:203], v[204:205] neg_lo:[0,1] neg_hi:[0,1]
	v_pk_add_f32 v[202:203], v[42:43], v[44:45] op_sel:[0,1] op_sel_hi:[1,0] neg_hi:[0,1]
	v_pk_add_f32 v[204:205], v[42:43], v[44:45] op_sel:[0,1] op_sel_hi:[1,0] neg_lo:[0,1]
	v_pk_mul_f32 v[206:207], v[210:211], v[210:211] op_sel:[1,1] op_sel_hi:[1,0]
	v_pk_fma_f32 v[212:213], v[210:211], v[210:211], v[206:207] op_sel_hi:[0,1,1] neg_lo:[0,0,1]
	v_pk_mul_f32 v[206:207], v[210:211], v[212:213] op_sel:[1,1] op_sel_hi:[1,0]
	v_pk_fma_f32 v[220:221], v[210:211], v[212:213], v[206:207] op_sel_hi:[0,1,1] neg_lo:[0,0,1]
	v_pk_mul_f32 v[42:43], v[210:211], v[202:203] op_sel:[1,1] op_sel_hi:[1,0]
	v_pk_fma_f32 v[42:43], v[210:211], v[202:203], v[42:43] op_sel_hi:[0,1,1] neg_lo:[0,0,1]
	v_pk_mul_f32 v[44:45], v[212:213], v[48:49] op_sel:[1,1] op_sel_hi:[1,0]
	v_pk_fma_f32 v[44:45], v[212:213], v[48:49], v[44:45] op_sel_hi:[0,1,1] neg_lo:[0,0,1]
	v_pk_mul_f32 v[48:49], v[220:221], v[204:205] op_sel:[1,1] op_sel_hi:[1,0]
	v_pk_fma_f32 v[48:49], v[220:221], v[204:205], v[48:49] op_sel_hi:[0,1,1] neg_lo:[0,0,1]
	v_add_f32_e32 v214, 0x3e400000, v201
	v_cos_f32_e32 v210, v214
	v_sin_f32_e64 v211, -v214
	s_waitcnt lgkmcnt(2)
	v_pk_add_f32 v[202:203], v[50:51], v[54:55]
	v_pk_add_f32 v[50:51], v[50:51], v[54:55] neg_lo:[0,1] neg_hi:[0,1]
	v_pk_add_f32 v[204:205], v[52:53], v[56:57]
	v_pk_add_f32 v[52:53], v[52:53], v[56:57] neg_lo:[0,1] neg_hi:[0,1]
	v_pk_add_f32 v[54:55], v[202:203], v[204:205]
	v_pk_add_f32 v[56:57], v[202:203], v[204:205] neg_lo:[0,1] neg_hi:[0,1]
	v_pk_add_f32 v[202:203], v[50:51], v[52:53] op_sel:[0,1] op_sel_hi:[1,0] neg_hi:[0,1]
	v_pk_add_f32 v[204:205], v[50:51], v[52:53] op_sel:[0,1] op_sel_hi:[1,0] neg_lo:[0,1]
	v_pk_mul_f32 v[206:207], v[210:211], v[210:211] op_sel:[1,1] op_sel_hi:[1,0]
	v_pk_fma_f32 v[212:213], v[210:211], v[210:211], v[206:207] op_sel_hi:[0,1,1] neg_lo:[0,0,1]
	v_pk_mul_f32 v[206:207], v[210:211], v[212:213] op_sel:[1,1] op_sel_hi:[1,0]
	v_pk_fma_f32 v[220:221], v[210:211], v[212:213], v[206:207] op_sel_hi:[0,1,1] neg_lo:[0,0,1]
	v_pk_mul_f32 v[50:51], v[210:211], v[202:203] op_sel:[1,1] op_sel_hi:[1,0]
	v_pk_fma_f32 v[50:51], v[210:211], v[202:203], v[50:51] op_sel_hi:[0,1,1] neg_lo:[0,0,1]
	v_pk_mul_f32 v[52:53], v[212:213], v[56:57] op_sel:[1,1] op_sel_hi:[1,0]
	v_pk_fma_f32 v[52:53], v[212:213], v[56:57], v[52:53] op_sel_hi:[0,1,1] neg_lo:[0,0,1]
	v_pk_mul_f32 v[56:57], v[220:221], v[204:205] op_sel:[1,1] op_sel_hi:[1,0]
	v_pk_fma_f32 v[56:57], v[220:221], v[204:205], v[56:57] op_sel_hi:[0,1,1] neg_lo:[0,0,1]
	v_add_f32_e32 v214, 0x3e600000, v201
	v_cos_f32_e32 v210, v214
	v_sin_f32_e64 v211, -v214
	s_waitcnt lgkmcnt(0)
; DI f32x2 cmul(f32x2 a, f32x2 b) { return mkf2(a.x * b.x - a.y * b.y, a.x * b.y + a.y * b.x); }
; DI void fft8192(f32x2* buf, const f32x2* __restrict__ tw) {
;     ...
;   for (int ls = 0; ls < 12; ls += 2) {
;     const int s = 1 << ls;
;     f32x2 a[8], b[8], c[8], d[8];
;     __syncthreads();
; #pragma unroll
;     for (int e = 0; e < 8; ++e) {
;       const int i = tid + 256 * e;
;       const int pi = SW(i);
;       a[e] = buf[pi]; b[e] = buf[pi + 2048]; c[e] = buf[pi + 4096]; d[e] = buf[pi + 6144];
;     }
;     __syncthreads();
; #pragma unroll
;     for (int e = 0; e < 8; ++e) {
;       const int i = tid + 256 * e;
;       const int q = i & (s - 1);
;       const int ps = i - q;
;       const float rev = (float)ps * (1.f / 8192.f);
;       const f32x2 w1 = mkf2(__builtin_amdgcn_cosf(rev), -__builtin_amdgcn_sinf(rev));
;       const f32x2 w2 = cmul(w1, w1), w3 = cmul(w1, w2);
;       const f32x2 apc = mkf2(a[e].x + c[e].x, a[e].y + c[e].y), amc = mkf2(a[e].x - c[e].x, a[e].y - c[e].y);
;       const f32x2 bpd = mkf2(b[e].x + d[e].x, b[e].y + d[e].y), bmd = mkf2(b[e].x - d[e].x, b[e].y - d[e].y);
;       const int o = 4 * i - 3 * q;
;       buf[SW(o)] = mkf2(apc.x + bpd.x, apc.y + bpd.y);
;       buf[SW(o + s)] = cmul(w1, mkf2(amc.x + bmd.y, amc.y - bmd.x));
;       buf[SW(o + 2 * s)] = cmul(w2, mkf2(apc.x - bpd.x, apc.y - bpd.y));
;       buf[SW(o + 3 * s)] = cmul(w3, mkf2(amc.x - bmd.y, amc.y + bmd.x));
;     }
	v_pk_add_f32 v[202:203], v[58:59], v[62:63]
	v_pk_add_f32 v[58:59], v[58:59], v[62:63] neg_lo:[0,1] neg_hi:[0,1]
	v_pk_add_f32 v[204:205], v[60:61], v[64:65]
	v_pk_add_f32 v[60:61], v[60:61], v[64:65] neg_lo:[0,1] neg_hi:[0,1]
	v_pk_add_f32 v[62:63], v[202:203], v[204:205]
	v_pk_add_f32 v[64:65], v[202:203], v[204:205] neg_lo:[0,1] neg_hi:[0,1]
	v_pk_add_f32 v[202:203], v[58:59], v[60:61] op_sel:[0,1] op_sel_hi:[1,0] neg_hi:[0,1]
	v_pk_add_f32 v[204:205], v[58:59], v[60:61] op_sel:[0,1] op_sel_hi:[1,0] neg_lo:[0,1]
	v_pk_mul_f32 v[206:207], v[210:211], v[210:211] op_sel:[1,1] op_sel_hi:[1,0]
	v_pk_fma_f32 v[212:213], v[210:211], v[210:211], v[206:207] op_sel_hi:[0,1,1] neg_lo:[0,0,1]
	v_pk_mul_f32 v[206:207], v[210:211], v[212:213] op_sel:[1,1] op_sel_hi:[1,0]
	v_pk_fma_f32 v[220:221], v[210:211], v[212:213], v[206:207] op_sel_hi:[0,1,1] neg_lo:[0,0,1]
	v_pk_mul_f32 v[58:59], v[210:211], v[202:203] op_sel:[1,1] op_sel_hi:[1,0]
	v_pk_fma_f32 v[58:59], v[210:211], v[202:203], v[58:59] op_sel_hi:[0,1,1] neg_lo:[0,0,1]
	v_pk_mul_f32 v[60:61], v[212:213], v[64:65] op_sel:[1,1] op_sel_hi:[1,0]
	v_pk_fma_f32 v[60:61], v[212:213], v[64:65], v[60:61] op_sel_hi:[0,1,1] neg_lo:[0,0,1]
	v_pk_mul_f32 v[64:65], v[220:221], v[204:205] op_sel:[1,1] op_sel_hi:[1,0]
	v_pk_fma_f32 v[64:65], v[220:221], v[204:205], v[64:65] op_sel_hi:[0,1,1] neg_lo:[0,0,1]
	s_barrier
	ds_write_b64 v156, v[6:7] offset:0
	ds_write_b64 v158, v[2:3] offset:0
	ds_write_b64 v160, v[4:5] offset:0
	ds_write_b64 v162, v[8:9] offset:0
	ds_write_b64 v156, v[14:15] offset:8192
	ds_write_b64 v158, v[10:11] offset:8192
	ds_write_b64 v160, v[12:13] offset:8192
	ds_write_b64 v162, v[16:17] offset:8192
	ds_write_b64 v156, v[22:23] offset:16384
	ds_write_b64 v158, v[18:19] offset:16384
	ds_write_b64 v160, v[20:21] offset:16384
	ds_write_b64 v162, v[24:25] offset:16384
	ds_write_b64 v156, v[30:31] offset:24576
	ds_write_b64 v158, v[26:27] offset:24576
	ds_write_b64 v160, v[28:29] offset:24576
	ds_write_b64 v162, v[32:33] offset:24576
	ds_write_b64 v156, v[38:39] offset:32768
	ds_write_b64 v158, v[34:35] offset:32768
	ds_write_b64 v160, v[36:37] offset:32768
	ds_write_b64 v162, v[40:41] offset:32768
	ds_write_b64 v156, v[46:47] offset:40960
	ds_write_b64 v158, v[42:43] offset:40960
	ds_write_b64 v160, v[44:45] offset:40960
	ds_write_b64 v162, v[48:49] offset:40960
	ds_write_b64 v156, v[54:55] offset:49152
	ds_write_b64 v158, v[50:51] offset:49152
	ds_write_b64 v160, v[52:53] offset:49152
	ds_write_b64 v162, v[56:57] offset:49152
	ds_write_b64 v156, v[62:63] offset:57344
	ds_write_b64 v158, v[58:59] offset:57344
	ds_write_b64 v160, v[60:61] offset:57344
	ds_write_b64 v162, v[64:65] offset:57344
	s_waitcnt lgkmcnt(0)
	s_barrier
	ds_read2st64_b64 v[2:5], v154 offset0:0 offset1:32
	ds_read2st64_b64 v[6:9], v154 offset0:64 offset1:96
	ds_read2st64_b64 v[10:13], v154 offset0:4 offset1:36
	ds_read2st64_b64 v[14:17], v154 offset0:68 offset1:100
	ds_read2st64_b64 v[18:21], v154 offset0:8 offset1:40
	ds_read2st64_b64 v[22:25], v154 offset0:72 offset1:104
	ds_read2st64_b64 v[26:29], v154 offset0:12 offset1:44
	ds_read2st64_b64 v[30:33], v154 offset0:76 offset1:108
	ds_read2st64_b64 v[34:37], v154 offset0:16 offset1:48
	ds_read2st64_b64 v[38:41], v154 offset0:80 offset1:112
	ds_read2st64_b64 v[42:45], v154 offset0:20 offset1:52
	ds_read2st64_b64 v[46:49], v154 offset0:84 offset1:116
	ds_read2st64_b64 v[50:53], v154 offset0:24 offset1:56
	ds_read2st64_b64 v[54:57], v154 offset0:88 offset1:120
	ds_read2st64_b64 v[58:61], v154 offset0:28 offset1:60
	ds_read2st64_b64 v[62:65], v154 offset0:92 offset1:124
	v_and_b32_e32 v166, 63, v0
	v_lshlrev_b32_e32 v164, 2, v0
	v_mad_i32_i24 v164, v166, -3, v164
	v_sub_u32_e32 v166, v0, v166
	v_cvt_f32_u32_e32 v201, v166
	v_mul_f32_e32 v201, 0x39000000, v201
	v_bfe_i32 v166, v164, 5, 1
	v_bfe_i32 v168, v164, 6, 1
	v_and_b32_e32 v166, 5, v166
	v_and_b32_e32 v168, 26, v168
	v_xor_b32_e32 v166, v166, v168
	v_xor_b32_e32 v166, v166, v164
	v_lshlrev_b32_e32 v156, 3, v166
	v_xor_b32_e32 v158, 0x2d0, v156
	v_xor_b32_e32 v160, 0x400, v156
	v_xor_b32_e32 v162, 0x6d0, v156
	v_cos_f32_e32 v210, v201
	v_sin_f32_e64 v211, -v201
	s_waitcnt lgkmcnt(14)
	v_pk_add_f32 v[202:203], v[2:3], v[6:7]
	v_pk_add_f32 v[2:3], v[2:3], v[6:7] neg_lo:[0,1] neg_hi:[0,1]
	v_pk_add_f32 v[204:205], v[4:5], v[8:9]
	v_pk_add_f32 v[4:5], v[4:5], v[8:9] neg_lo:[0,1] neg_hi:[0,1]
	v_pk_add_f32 v[6:7], v[202:203], v[204:205]
	v_pk_add_f32 v[8:9], v[202:203], v[204:205] neg_lo:[0,1] neg_hi:[0,1]
	v_pk_add_f32 v[202:203], v[2:3], v[4:5] op_sel:[0,1] op_sel_hi:[1,0] neg_hi:[0,1]
	v_pk_add_f32 v[204:205], v[2:3], v[4:5] op_sel:[0,1] op_sel_hi:[1,0] neg_lo:[0,1]
	v_pk_mul_f32 v[206:207], v[210:211], v[210:211] op_sel:[1,1] op_sel_hi:[1,0]
	v_pk_fma_f32 v[212:213], v[210:211], v[210:211], v[206:207] op_sel_hi:[0,1,1] neg_lo:[0,0,1]
	v_pk_mul_f32 v[206:207], v[210:211], v[212:213] op_sel:[1,1] op_sel_hi:[1,0]
	v_pk_fma_f32 v[220:221], v[210:211], v[212:213], v[206:207] op_sel_hi:[0,1,1] neg_lo:[0,0,1]
	v_pk_mul_f32 v[2:3], v[210:211], v[202:203] op_sel:[1,1] op_sel_hi:[1,0]
	v_pk_fma_f32 v[2:3], v[210:211], v[202:203], v[2:3] op_sel_hi:[0,1,1] neg_lo:[0,0,1]
	v_pk_mul_f32 v[4:5], v[212:213], v[8:9] op_sel:[1,1] op_sel_hi:[1,0]
	v_pk_fma_f32 v[4:5], v[212:213], v[8:9], v[4:5] op_sel_hi:[0,1,1] neg_lo:[0,0,1]
	v_pk_mul_f32 v[8:9], v[220:221], v[204:205] op_sel:[1,1] op_sel_hi:[1,0]
	v_pk_fma_f32 v[8:9], v[220:221], v[204:205], v[8:9] op_sel_hi:[0,1,1] neg_lo:[0,0,1]
	v_add_f32_e32 v214, 0x3d000000, v201
	v_cos_f32_e32 v210, v214
	v_sin_f32_e64 v211, -v214
	s_waitcnt lgkmcnt(12)
; DI f32x2 cmul(f32x2 a, f32x2 b) { return mkf2(a.x * b.x - a.y * b.y, a.x * b.y + a.y * b.x); }
; DI void fft8192(f32x2* buf, const f32x2* __restrict__ tw) {
;     ...
;   for (int ls = 0; ls < 12; ls += 2) {
;     const int s = 1 << ls;
;     f32x2 a[8], b[8], c[8], d[8];
;     __syncthreads();
; #pragma unroll
;     for (int e = 0; e < 8; ++e) {
;       const int i = tid + 256 * e;
;       const int pi = SW(i);
;       a[e] = buf[pi]; b[e] = buf[pi + 2048]; c[e] = buf[pi + 4096]; d[e] = buf[pi + 6144];
;     }
;     __syncthreads();
; #pragma unroll
;     for (int e = 0; e < 8; ++e) {
;       const int i = tid + 256 * e;
;       const int q = i & (s - 1);
;       const int ps = i - q;
;       const float rev = (float)ps * (1.f / 8192.f);
;       const f32x2 w1 = mkf2(__builtin_amdgcn_cosf(rev), -__builtin_amdgcn_sinf(rev));
;       const f32x2 w2 = cmul(w1, w1), w3 = cmul(w1, w2);
;       const f32x2 apc = mkf2(a[e].x + c[e].x, a[e].y + c[e].y), amc = mkf2(a[e].x - c[e].x, a[e].y - c[e].y);
;       const f32x2 bpd = mkf2(b[e].x + d[e].x, b[e].y + d[e].y), bmd = mkf2(b[e].x - d[e].x, b[e].y - d[e].y);
;       const int o = 4 * i - 3 * q;
;       buf[SW(o)] = mkf2(apc.x + bpd.x, apc.y + bpd.y);
;       buf[SW(o + s)] = cmul(w1, mkf2(amc.x + bmd.y, amc.y - bmd.x));
;       buf[SW(o + 2 * s)] = cmul(w2, mkf2(apc.x - bpd.x, apc.y - bpd.y));
;       buf[SW(o + 3 * s)] = cmul(w3, mkf2(amc.x - bmd.y, amc.y + bmd.x));
;     }
	v_pk_add_f32 v[202:203], v[10:11], v[14:15]
	v_pk_add_f32 v[10:11], v[10:11], v[14:15] neg_lo:[0,1] neg_hi:[0,1]
	v_pk_add_f32 v[204:205], v[12:13], v[16:17]
	v_pk_add_f32 v[12:13], v[12:13], v[16:17] neg_lo:[0,1] neg_hi:[0,1]
	v_pk_add_f32 v[14:15], v[202:203], v[204:205]
	v_pk_add_f32 v[16:17], v[202:203], v[204:205] neg_lo:[0,1] neg_hi:[0,1]
	v_pk_add_f32 v[202:203], v[10:11], v[12:13] op_sel:[0,1] op_sel_hi:[1,0] neg_hi:[0,1]
	v_pk_add_f32 v[204:205], v[10:11], v[12:13] op_sel:[0,1] op_sel_hi:[1,0] neg_lo:[0,1]
	v_pk_mul_f32 v[206:207], v[210:211], v[210:211] op_sel:[1,1] op_sel_hi:[1,0]
	v_pk_fma_f32 v[212:213], v[210:211], v[210:211], v[206:207] op_sel_hi:[0,1,1] neg_lo:[0,0,1]
	v_pk_mul_f32 v[206:207], v[210:211], v[212:213] op_sel:[1,1] op_sel_hi:[1,0]
	v_pk_fma_f32 v[220:221], v[210:211], v[212:213], v[206:207] op_sel_hi:[0,1,1] neg_lo:[0,0,1]
	v_pk_mul_f32 v[10:11], v[210:211], v[202:203] op_sel:[1,1] op_sel_hi:[1,0]
	v_pk_fma_f32 v[10:11], v[210:211], v[202:203], v[10:11] op_sel_hi:[0,1,1] neg_lo:[0,0,1]
	v_pk_mul_f32 v[12:13], v[212:213], v[16:17] op_sel:[1,1] op_sel_hi:[1,0]
	v_pk_fma_f32 v[12:13], v[212:213], v[16:17], v[12:13] op_sel_hi:[0,1,1] neg_lo:[0,0,1]
	v_pk_mul_f32 v[16:17], v[220:221], v[204:205] op_sel:[1,1] op_sel_hi:[1,0]
	v_pk_fma_f32 v[16:17], v[220:221], v[204:205], v[16:17] op_sel_hi:[0,1,1] neg_lo:[0,0,1]
	v_add_f32_e32 v214, 0x3d800000, v201
	v_cos_f32_e32 v210, v214
	v_sin_f32_e64 v211, -v214
	s_waitcnt lgkmcnt(10)
	v_pk_add_f32 v[202:203], v[18:19], v[22:23]
	v_pk_add_f32 v[18:19], v[18:19], v[22:23] neg_lo:[0,1] neg_hi:[0,1]
	v_pk_add_f32 v[204:205], v[20:21], v[24:25]
	v_pk_add_f32 v[20:21], v[20:21], v[24:25] neg_lo:[0,1] neg_hi:[0,1]
	v_pk_add_f32 v[22:23], v[202:203], v[204:205]
	v_pk_add_f32 v[24:25], v[202:203], v[204:205] neg_lo:[0,1] neg_hi:[0,1]
	v_pk_add_f32 v[202:203], v[18:19], v[20:21] op_sel:[0,1] op_sel_hi:[1,0] neg_hi:[0,1]
	v_pk_add_f32 v[204:205], v[18:19], v[20:21] op_sel:[0,1] op_sel_hi:[1,0] neg_lo:[0,1]
	v_pk_mul_f32 v[206:207], v[210:211], v[210:211] op_sel:[1,1] op_sel_hi:[1,0]
	v_pk_fma_f32 v[212:213], v[210:211], v[210:211], v[206:207] op_sel_hi:[0,1,1] neg_lo:[0,0,1]
	v_pk_mul_f32 v[206:207], v[210:211], v[212:213] op_sel:[1,1] op_sel_hi:[1,0]
	v_pk_fma_f32 v[220:221], v[210:211], v[212:213], v[206:207] op_sel_hi:[0,1,1] neg_lo:[0,0,1]
	v_pk_mul_f32 v[18:19], v[210:211], v[202:203] op_sel:[1,1] op_sel_hi:[1,0]
	v_pk_fma_f32 v[18:19], v[210:211], v[202:203], v[18:19] op_sel_hi:[0,1,1] neg_lo:[0,0,1]
	v_pk_mul_f32 v[20:21], v[212:213], v[24:25] op_sel:[1,1] op_sel_hi:[1,0]
	v_pk_fma_f32 v[20:21], v[212:213], v[24:25], v[20:21] op_sel_hi:[0,1,1] neg_lo:[0,0,1]
	v_pk_mul_f32 v[24:25], v[220:221], v[204:205] op_sel:[1,1] op_sel_hi:[1,0]
	v_pk_fma_f32 v[24:25], v[220:221], v[204:205], v[24:25] op_sel_hi:[0,1,1] neg_lo:[0,0,1]
	v_add_f32_e32 v214, 0x3dc00000, v201
	v_cos_f32_e32 v210, v214
	v_sin_f32_e64 v211, -v214
	s_waitcnt lgkmcnt(8)
	v_pk_add_f32 v[202:203], v[26:27], v[30:31]
	v_pk_add_f32 v[26:27], v[26:27], v[30:31] neg_lo:[0,1] neg_hi:[0,1]
	v_pk_add_f32 v[204:205], v[28:29], v[32:33]
	v_pk_add_f32 v[28:29], v[28:29], v[32:33] neg_lo:[0,1] neg_hi:[0,1]
	v_pk_add_f32 v[30:31], v[202:203], v[204:205]
	v_pk_add_f32 v[32:33], v[202:203], v[204:205] neg_lo:[0,1] neg_hi:[0,1]
	v_pk_add_f32 v[202:203], v[26:27], v[28:29] op_sel:[0,1] op_sel_hi:[1,0] neg_hi:[0,1]
	v_pk_add_f32 v[204:205], v[26:27], v[28:29] op_sel:[0,1] op_sel_hi:[1,0] neg_lo:[0,1]
	v_pk_mul_f32 v[206:207], v[210:211], v[210:211] op_sel:[1,1] op_sel_hi:[1,0]
	v_pk_fma_f32 v[212:213], v[210:211], v[210:211], v[206:207] op_sel_hi:[0,1,1] neg_lo:[0,0,1]
	v_pk_mul_f32 v[206:207], v[210:211], v[212:213] op_sel:[1,1] op_sel_hi:[1,0]
	v_pk_fma_f32 v[220:221], v[210:211], v[212:213], v[206:207] op_sel_hi:[0,1,1] neg_lo:[0,0,1]
	v_pk_mul_f32 v[26:27], v[210:211], v[202:203] op_sel:[1,1] op_sel_hi:[1,0]
	v_pk_fma_f32 v[26:27], v[210:211], v[202:203], v[26:27] op_sel_hi:[0,1,1] neg_lo:[0,0,1]
	v_pk_mul_f32 v[28:29], v[212:213], v[32:33] op_sel:[1,1] op_sel_hi:[1,0]
	v_pk_fma_f32 v[28:29], v[212:213], v[32:33], v[28:29] op_sel_hi:[0,1,1] neg_lo:[0,0,1]
	v_pk_mul_f32 v[32:33], v[220:221], v[204:205] op_sel:[1,1] op_sel_hi:[1,0]
	v_pk_fma_f32 v[32:33], v[220:221], v[204:205], v[32:33] op_sel_hi:[0,1,1] neg_lo:[0,0,1]
	v_add_f32_e32 v214, 0x3e000000, v201
	v_cos_f32_e32 v210, v214
	v_sin_f32_e64 v211, -v214
	s_waitcnt lgkmcnt(6)
	v_pk_add_f32 v[202:203], v[34:35], v[38:39]
	v_pk_add_f32 v[34:35], v[34:35], v[38:39] neg_lo:[0,1] neg_hi:[0,1]
	v_pk_add_f32 v[204:205], v[36:37], v[40:41]
	v_pk_add_f32 v[36:37], v[36:37], v[40:41] neg_lo:[0,1] neg_hi:[0,1]
	v_pk_add_f32 v[38:39], v[202:203], v[204:205]
	v_pk_add_f32 v[40:41], v[202:203], v[204:205] neg_lo:[0,1] neg_hi:[0,1]
	v_pk_add_f32 v[202:203], v[34:35], v[36:37] op_sel:[0,1] op_sel_hi:[1,0] neg_hi:[0,1]
	v_pk_add_f32 v[204:205], v[34:35], v[36:37] op_sel:[0,1] op_sel_hi:[1,0] neg_lo:[0,1]
	v_pk_mul_f32 v[206:207], v[210:211], v[210:211] op_sel:[1,1] op_sel_hi:[1,0]
	v_pk_fma_f32 v[212:213], v[210:211], v[210:211], v[206:207] op_sel_hi:[0,1,1] neg_lo:[0,0,1]
	v_pk_mul_f32 v[206:207], v[210:211], v[212:213] op_sel:[1,1] op_sel_hi:[1,0]
	v_pk_fma_f32 v[220:221], v[210:211], v[212:213], v[206:207] op_sel_hi:[0,1,1] neg_lo:[0,0,1]
	v_pk_mul_f32 v[34:35], v[210:211], v[202:203] op_sel:[1,1] op_sel_hi:[1,0]
	v_pk_fma_f32 v[34:35], v[210:211], v[202:203], v[34:35] op_sel_hi:[0,1,1] neg_lo:[0,0,1]
	v_pk_mul_f32 v[36:37], v[212:213], v[40:41] op_sel:[1,1] op_sel_hi:[1,0]
	v_pk_fma_f32 v[36:37], v[212:213], v[40:41], v[36:37] op_sel_hi:[0,1,1] neg_lo:[0,0,1]
	v_pk_mul_f32 v[40:41], v[220:221], v[204:205] op_sel:[1,1] op_sel_hi:[1,0]
	v_pk_fma_f32 v[40:41], v[220:221], v[204:205], v[40:41] op_sel_hi:[0,1,1] neg_lo:[0,0,1]
	v_add_f32_e32 v214, 0x3e200000, v201
	v_cos_f32_e32 v210, v214
	v_sin_f32_e64 v211, -v214
	s_waitcnt lgkmcnt(4)
; DI f32x2 cmul(f32x2 a, f32x2 b) { return mkf2(a.x * b.x - a.y * b.y, a.x * b.y + a.y * b.x); }
; DI void fft8192(f32x2* buf, const f32x2* __restrict__ tw) {
;     ...
;   for (int ls = 0; ls < 12; ls += 2) {
;     const int s = 1 << ls;
;     f32x2 a[8], b[8], c[8], d[8];
;     __syncthreads();
; #pragma unroll
;     for (int e = 0; e < 8; ++e) {
;       const int i = tid + 256 * e;
;       const int pi = SW(i);
;       a[e] = buf[pi]; b[e] = buf[pi + 2048]; c[e] = buf[pi + 4096]; d[e] = buf[pi + 6144];
;     }
;     __syncthreads();
; #pragma unroll
;     for (int e = 0; e < 8; ++e) {
;       const int i = tid + 256 * e;
;       const int q = i & (s - 1);
;       const int ps = i - q;
;       const float rev = (float)ps * (1.f / 8192.f);
;       const f32x2 w1 = mkf2(__builtin_amdgcn_cosf(rev), -__builtin_amdgcn_sinf(rev));
;       const f32x2 w2 = cmul(w1, w1), w3 = cmul(w1, w2);
;       const f32x2 apc = mkf2(a[e].x + c[e].x, a[e].y + c[e].y), amc = mkf2(a[e].x - c[e].x, a[e].y - c[e].y);
;       const f32x2 bpd = mkf2(b[e].x + d[e].x, b[e].y + d[e].y), bmd = mkf2(b[e].x - d[e].x, b[e].y - d[e].y);
;       const int o = 4 * i - 3 * q;
;       buf[SW(o)] = mkf2(apc.x + bpd.x, apc.y + bpd.y);
;       buf[SW(o + s)] = cmul(w1, mkf2(amc.x + bmd.y, amc.y - bmd.x));
;       buf[SW(o + 2 * s)] = cmul(w2, mkf2(apc.x - bpd.x, apc.y - bpd.y));
;       buf[SW(o + 3 * s)] = cmul(w3, mkf2(amc.x - bmd.y, amc.y + bmd.x));
;     }
	v_pk_add_f32 v[202:203], v[42:43], v[46:47]
	v_pk_add_f32 v[42:43], v[42:43], v[46:47] neg_lo:[0,1] neg_hi:[0,1]
	v_pk_add_f32 v[204:205], v[44:45], v[48:49]
	v_pk_add_f32 v[44:45], v[44:45], v[48:49] neg_lo:[0,1] neg_hi:[0,1]
	v_pk_add_f32 v[46:47], v[202:203], v[204:205]
	v_pk_add_f32 v[48:49], v[202:203], v[204:205] neg_lo:[0,1] neg_hi:[0,1]
	v_pk_add_f32 v[202:203], v[42:43], v[44:45] op_sel:[0,1] op_sel_hi:[1,0] neg_hi:[0,1]
	v_pk_add_f32 v[204:205], v[42:43], v[44:45] op_sel:[0,1] op_sel_hi:[1,0] neg_lo:[0,1]
	v_pk_mul_f32 v[206:207], v[210:211], v[210:211] op_sel:[1,1] op_sel_hi:[1,0]
	v_pk_fma_f32 v[212:213], v[210:211], v[210:211], v[206:207] op_sel_hi:[0,1,1] neg_lo:[0,0,1]
	v_pk_mul_f32 v[206:207], v[210:211], v[212:213] op_sel:[1,1] op_sel_hi:[1,0]
	v_pk_fma_f32 v[220:221], v[210:211], v[212:213], v[206:207] op_sel_hi:[0,1,1] neg_lo:[0,0,1]
	v_pk_mul_f32 v[42:43], v[210:211], v[202:203] op_sel:[1,1] op_sel_hi:[1,0]
	v_pk_fma_f32 v[42:43], v[210:211], v[202:203], v[42:43] op_sel_hi:[0,1,1] neg_lo:[0,0,1]
	v_pk_mul_f32 v[44:45], v[212:213], v[48:49] op_sel:[1,1] op_sel_hi:[1,0]
	v_pk_fma_f32 v[44:45], v[212:213], v[48:49], v[44:45] op_sel_hi:[0,1,1] neg_lo:[0,0,1]
	v_pk_mul_f32 v[48:49], v[220:221], v[204:205] op_sel:[1,1] op_sel_hi:[1,0]
	v_pk_fma_f32 v[48:49], v[220:221], v[204:205], v[48:49] op_sel_hi:[0,1,1] neg_lo:[0,0,1]
	v_add_f32_e32 v214, 0x3e400000, v201
	v_cos_f32_e32 v210, v214
	v_sin_f32_e64 v211, -v214
	s_waitcnt lgkmcnt(2)
	v_pk_add_f32 v[202:203], v[50:51], v[54:55]
	v_pk_add_f32 v[50:51], v[50:51], v[54:55] neg_lo:[0,1] neg_hi:[0,1]
	v_pk_add_f32 v[204:205], v[52:53], v[56:57]
	v_pk_add_f32 v[52:53], v[52:53], v[56:57] neg_lo:[0,1] neg_hi:[0,1]
	v_pk_add_f32 v[54:55], v[202:203], v[204:205]
	v_pk_add_f32 v[56:57], v[202:203], v[204:205] neg_lo:[0,1] neg_hi:[0,1]
	v_pk_add_f32 v[202:203], v[50:51], v[52:53] op_sel:[0,1] op_sel_hi:[1,0] neg_hi:[0,1]
	v_pk_add_f32 v[204:205], v[50:51], v[52:53] op_sel:[0,1] op_sel_hi:[1,0] neg_lo:[0,1]
	v_pk_mul_f32 v[206:207], v[210:211], v[210:211] op_sel:[1,1] op_sel_hi:[1,0]
	v_pk_fma_f32 v[212:213], v[210:211], v[210:211], v[206:207] op_sel_hi:[0,1,1] neg_lo:[0,0,1]
	v_pk_mul_f32 v[206:207], v[210:211], v[212:213] op_sel:[1,1] op_sel_hi:[1,0]
	v_pk_fma_f32 v[220:221], v[210:211], v[212:213], v[206:207] op_sel_hi:[0,1,1] neg_lo:[0,0,1]
	v_pk_mul_f32 v[50:51], v[210:211], v[202:203] op_sel:[1,1] op_sel_hi:[1,0]
	v_pk_fma_f32 v[50:51], v[210:211], v[202:203], v[50:51] op_sel_hi:[0,1,1] neg_lo:[0,0,1]
	v_pk_mul_f32 v[52:53], v[212:213], v[56:57] op_sel:[1,1] op_sel_hi:[1,0]
	v_pk_fma_f32 v[52:53], v[212:213], v[56:57], v[52:53] op_sel_hi:[0,1,1] neg_lo:[0,0,1]
	v_pk_mul_f32 v[56:57], v[220:221], v[204:205] op_sel:[1,1] op_sel_hi:[1,0]
	v_pk_fma_f32 v[56:57], v[220:221], v[204:205], v[56:57] op_sel_hi:[0,1,1] neg_lo:[0,0,1]
	v_add_f32_e32 v214, 0x3e600000, v201
	v_cos_f32_e32 v210, v214
	v_sin_f32_e64 v211, -v214
	s_waitcnt lgkmcnt(0)
	v_pk_add_f32 v[202:203], v[58:59], v[62:63]
	v_pk_add_f32 v[58:59], v[58:59], v[62:63] neg_lo:[0,1] neg_hi:[0,1]
	v_pk_add_f32 v[204:205], v[60:61], v[64:65]
	v_pk_add_f32 v[60:61], v[60:61], v[64:65] neg_lo:[0,1] neg_hi:[0,1]
	v_pk_add_f32 v[62:63], v[202:203], v[204:205]
	v_pk_add_f32 v[64:65], v[202:203], v[204:205] neg_lo:[0,1] neg_hi:[0,1]
	v_pk_add_f32 v[202:203], v[58:59], v[60:61] op_sel:[0,1] op_sel_hi:[1,0] neg_hi:[0,1]
	v_pk_add_f32 v[204:205], v[58:59], v[60:61] op_sel:[0,1] op_sel_hi:[1,0] neg_lo:[0,1]
	v_pk_mul_f32 v[206:207], v[210:211], v[210:211] op_sel:[1,1] op_sel_hi:[1,0]
	v_pk_fma_f32 v[212:213], v[210:211], v[210:211], v[206:207] op_sel_hi:[0,1,1] neg_lo:[0,0,1]
	v_pk_mul_f32 v[206:207], v[210:211], v[212:213] op_sel:[1,1] op_sel_hi:[1,0]
	v_pk_fma_f32 v[220:221], v[210:211], v[212:213], v[206:207] op_sel_hi:[0,1,1] neg_lo:[0,0,1]
	v_pk_mul_f32 v[58:59], v[210:211], v[202:203] op_sel:[1,1] op_sel_hi:[1,0]
	v_pk_fma_f32 v[58:59], v[210:211], v[202:203], v[58:59] op_sel_hi:[0,1,1] neg_lo:[0,0,1]
	v_pk_mul_f32 v[60:61], v[212:213], v[64:65] op_sel:[1,1] op_sel_hi:[1,0]
	v_pk_fma_f32 v[60:61], v[212:213], v[64:65], v[60:61] op_sel_hi:[0,1,1] neg_lo:[0,0,1]
	v_pk_mul_f32 v[64:65], v[220:221], v[204:205] op_sel:[1,1] op_sel_hi:[1,0]
	v_pk_fma_f32 v[64:65], v[220:221], v[204:205], v[64:65] op_sel_hi:[0,1,1] neg_lo:[0,0,1]
	s_barrier
	ds_write_b64 v156, v[6:7] offset:0
	ds_write_b64 v158, v[2:3] offset:0
	ds_write_b64 v160, v[4:5] offset:0
	ds_write_b64 v162, v[8:9] offset:0
	ds_write_b64 v156, v[14:15] offset:8192
	ds_write_b64 v158, v[10:11] offset:8192
	ds_write_b64 v160, v[12:13] offset:8192
	ds_write_b64 v162, v[16:17] offset:8192
	ds_write_b64 v156, v[22:23] offset:16384
	ds_write_b64 v158, v[18:19] offset:16384
	ds_write_b64 v160, v[20:21] offset:16384
	ds_write_b64 v162, v[24:25] offset:16384
	ds_write_b64 v156, v[30:31] offset:24576
	ds_write_b64 v158, v[26:27] offset:24576
	ds_write_b64 v160, v[28:29] offset:24576
	ds_write_b64 v162, v[32:33] offset:24576
	ds_write_b64 v156, v[38:39] offset:32768
	ds_write_b64 v158, v[34:35] offset:32768
	ds_write_b64 v160, v[36:37] offset:32768
	ds_write_b64 v162, v[40:41] offset:32768
	ds_write_b64 v156, v[46:47] offset:40960
	ds_write_b64 v158, v[42:43] offset:40960
	ds_write_b64 v160, v[44:45] offset:40960
	ds_write_b64 v162, v[48:49] offset:40960
	ds_write_b64 v156, v[54:55] offset:49152
	ds_write_b64 v158, v[50:51] offset:49152
	ds_write_b64 v160, v[52:53] offset:49152
	ds_write_b64 v162, v[56:57] offset:49152
	ds_write_b64 v156, v[62:63] offset:57344
	ds_write_b64 v158, v[58:59] offset:57344
	ds_write_b64 v160, v[60:61] offset:57344
	ds_write_b64 v162, v[64:65] offset:57344
	s_waitcnt lgkmcnt(0)
	s_barrier
; DI f32x2 cmul(f32x2 a, f32x2 b) { return mkf2(a.x * b.x - a.y * b.y, a.x * b.y + a.y * b.x); }
; DI void fft8192(f32x2* buf, const f32x2* __restrict__ tw) {
;     ...
;   for (int ls = 0; ls < 12; ls += 2) {
;     const int s = 1 << ls;
;     f32x2 a[8], b[8], c[8], d[8];
;     __syncthreads();
; #pragma unroll
;     for (int e = 0; e < 8; ++e) {
;       const int i = tid + 256 * e;
;       const int pi = SW(i);
;       a[e] = buf[pi]; b[e] = buf[pi + 2048]; c[e] = buf[pi + 4096]; d[e] = buf[pi + 6144];
;     }
;     __syncthreads();
; #pragma unroll
;     for (int e = 0; e < 8; ++e) {
;       const int i = tid + 256 * e;
;       const int q = i & (s - 1);
;       const int ps = i - q;
;       const float rev = (float)ps * (1.f / 8192.f);
;       const f32x2 w1 = mkf2(__builtin_amdgcn_cosf(rev), -__builtin_amdgcn_sinf(rev));
;       const f32x2 w2 = cmul(w1, w1), w3 = cmul(w1, w2);
;       const f32x2 apc = mkf2(a[e].x + c[e].x, a[e].y + c[e].y), amc = mkf2(a[e].x - c[e].x, a[e].y - c[e].y);
;       const f32x2 bpd = mkf2(b[e].x + d[e].x, b[e].y + d[e].y), bmd = mkf2(b[e].x - d[e].x, b[e].y - d[e].y);
;       const int o = 4 * i - 3 * q;
;       buf[SW(o)] = mkf2(apc.x + bpd.x, apc.y + bpd.y);
;       buf[SW(o + s)] = cmul(w1, mkf2(amc.x + bmd.y, amc.y - bmd.x));
;       buf[SW(o + 2 * s)] = cmul(w2, mkf2(apc.x - bpd.x, apc.y - bpd.y));
;       buf[SW(o + 3 * s)] = cmul(w3, mkf2(amc.x - bmd.y, amc.y + bmd.x));
	ds_read2st64_b64 v[2:5], v154 offset0:0 offset1:32
	ds_read2st64_b64 v[6:9], v154 offset0:64 offset1:96
	ds_read2st64_b64 v[10:13], v154 offset0:4 offset1:36
	ds_read2st64_b64 v[14:17], v154 offset0:68 offset1:100
	ds_read2st64_b64 v[18:21], v154 offset0:8 offset1:40
	ds_read2st64_b64 v[22:25], v154 offset0:72 offset1:104
	ds_read2st64_b64 v[26:29], v154 offset0:12 offset1:44
	ds_read2st64_b64 v[30:33], v154 offset0:76 offset1:108
	ds_read2st64_b64 v[34:37], v154 offset0:16 offset1:48
	ds_read2st64_b64 v[38:41], v154 offset0:80 offset1:112
	ds_read2st64_b64 v[42:45], v154 offset0:20 offset1:52
	ds_read2st64_b64 v[46:49], v154 offset0:84 offset1:116
	ds_read2st64_b64 v[50:53], v154 offset0:24 offset1:56
	ds_read2st64_b64 v[54:57], v154 offset0:88 offset1:120
	ds_read2st64_b64 v[58:61], v154 offset0:28 offset1:60
	ds_read2st64_b64 v[62:65], v154 offset0:92 offset1:124
	s_waitcnt lgkmcnt(14)
	v_pk_add_f32 v[202:203], v[2:3], v[6:7]
	v_pk_add_f32 v[2:3], v[2:3], v[6:7] neg_lo:[0,1] neg_hi:[0,1]
	v_pk_add_f32 v[204:205], v[4:5], v[8:9]
	v_pk_add_f32 v[4:5], v[4:5], v[8:9] neg_lo:[0,1] neg_hi:[0,1]
	v_pk_add_f32 v[6:7], v[202:203], v[204:205]
	v_pk_add_f32 v[8:9], v[202:203], v[204:205] neg_lo:[0,1] neg_hi:[0,1]
	v_pk_add_f32 v[202:203], v[2:3], v[4:5] op_sel:[0,1] op_sel_hi:[1,0] neg_hi:[0,1]
	v_pk_add_f32 v[4:5], v[2:3], v[4:5] op_sel:[0,1] op_sel_hi:[1,0] neg_lo:[0,1]
	v_pk_mov_b32 v[2:3], v[202:203], v[202:203] op_sel:[0,1]
	v_cos_f32_e32 v210, 0x3d000000
	v_sin_f32_e32 v211, 0xbd000000
	s_waitcnt lgkmcnt(12)
	v_pk_add_f32 v[202:203], v[10:11], v[14:15]
	v_pk_add_f32 v[10:11], v[10:11], v[14:15] neg_lo:[0,1] neg_hi:[0,1]
	v_pk_add_f32 v[204:205], v[12:13], v[16:17]
	v_pk_add_f32 v[12:13], v[12:13], v[16:17] neg_lo:[0,1] neg_hi:[0,1]
	v_pk_add_f32 v[14:15], v[202:203], v[204:205]
	v_pk_add_f32 v[16:17], v[202:203], v[204:205] neg_lo:[0,1] neg_hi:[0,1]
	v_pk_add_f32 v[202:203], v[10:11], v[12:13] op_sel:[0,1] op_sel_hi:[1,0] neg_hi:[0,1]
	v_pk_add_f32 v[204:205], v[10:11], v[12:13] op_sel:[0,1] op_sel_hi:[1,0] neg_lo:[0,1]
	v_pk_mul_f32 v[206:207], v[210:211], v[210:211] op_sel:[1,1] op_sel_hi:[1,0]
	v_pk_fma_f32 v[212:213], v[210:211], v[210:211], v[206:207] op_sel_hi:[0,1,1] neg_lo:[0,0,1]
	v_pk_mul_f32 v[206:207], v[210:211], v[212:213] op_sel:[1,1] op_sel_hi:[1,0]
	v_pk_fma_f32 v[220:221], v[210:211], v[212:213], v[206:207] op_sel_hi:[0,1,1] neg_lo:[0,0,1]
	v_pk_mul_f32 v[10:11], v[210:211], v[202:203] op_sel:[1,1] op_sel_hi:[1,0]
	v_pk_fma_f32 v[10:11], v[210:211], v[202:203], v[10:11] op_sel_hi:[0,1,1] neg_lo:[0,0,1]
	v_pk_mul_f32 v[12:13], v[212:213], v[16:17] op_sel:[1,1] op_sel_hi:[1,0]
	v_pk_fma_f32 v[12:13], v[212:213], v[16:17], v[12:13] op_sel_hi:[0,1,1] neg_lo:[0,0,1]
	v_pk_mul_f32 v[16:17], v[220:221], v[204:205] op_sel:[1,1] op_sel_hi:[1,0]
	v_pk_fma_f32 v[16:17], v[220:221], v[204:205], v[16:17] op_sel_hi:[0,1,1] neg_lo:[0,0,1]
	v_cos_f32_e32 v210, 0x3d800000
	v_sin_f32_e32 v211, 0xbd800000
	s_waitcnt lgkmcnt(10)
	v_pk_add_f32 v[202:203], v[18:19], v[22:23]
	v_pk_add_f32 v[18:19], v[18:19], v[22:23] neg_lo:[0,1] neg_hi:[0,1]
	v_pk_add_f32 v[204:205], v[20:21], v[24:25]
	v_pk_add_f32 v[20:21], v[20:21], v[24:25] neg_lo:[0,1] neg_hi:[0,1]
	v_pk_add_f32 v[22:23], v[202:203], v[204:205]
	v_pk_add_f32 v[24:25], v[202:203], v[204:205] neg_lo:[0,1] neg_hi:[0,1]
	v_pk_add_f32 v[202:203], v[18:19], v[20:21] op_sel:[0,1] op_sel_hi:[1,0] neg_hi:[0,1]
	v_pk_add_f32 v[204:205], v[18:19], v[20:21] op_sel:[0,1] op_sel_hi:[1,0] neg_lo:[0,1]
	v_pk_mul_f32 v[206:207], v[210:211], v[210:211] op_sel:[1,1] op_sel_hi:[1,0]
	v_pk_fma_f32 v[212:213], v[210:211], v[210:211], v[206:207] op_sel_hi:[0,1,1] neg_lo:[0,0,1]
	v_pk_mul_f32 v[206:207], v[210:211], v[212:213] op_sel:[1,1] op_sel_hi:[1,0]
	v_pk_fma_f32 v[220:221], v[210:211], v[212:213], v[206:207] op_sel_hi:[0,1,1] neg_lo:[0,0,1]
	v_pk_mul_f32 v[18:19], v[210:211], v[202:203] op_sel:[1,1] op_sel_hi:[1,0]
	v_pk_fma_f32 v[18:19], v[210:211], v[202:203], v[18:19] op_sel_hi:[0,1,1] neg_lo:[0,0,1]
	v_pk_mul_f32 v[20:21], v[212:213], v[24:25] op_sel:[1,1] op_sel_hi:[1,0]
	v_pk_fma_f32 v[20:21], v[212:213], v[24:25], v[20:21] op_sel_hi:[0,1,1] neg_lo:[0,0,1]
	v_pk_mul_f32 v[24:25], v[220:221], v[204:205] op_sel:[1,1] op_sel_hi:[1,0]
	v_pk_fma_f32 v[24:25], v[220:221], v[204:205], v[24:25] op_sel_hi:[0,1,1] neg_lo:[0,0,1]
	v_cos_f32_e32 v210, 0x3dc00000
	v_sin_f32_e32 v211, 0xbdc00000
	s_waitcnt lgkmcnt(8)
	v_pk_add_f32 v[202:203], v[26:27], v[30:31]
	v_pk_add_f32 v[26:27], v[26:27], v[30:31] neg_lo:[0,1] neg_hi:[0,1]
	v_pk_add_f32 v[204:205], v[28:29], v[32:33]
	v_pk_add_f32 v[28:29], v[28:29], v[32:33] neg_lo:[0,1] neg_hi:[0,1]
	v_pk_add_f32 v[30:31], v[202:203], v[204:205]
	v_pk_add_f32 v[32:33], v[202:203], v[204:205] neg_lo:[0,1] neg_hi:[0,1]
	v_pk_add_f32 v[202:203], v[26:27], v[28:29] op_sel:[0,1] op_sel_hi:[1,0] neg_hi:[0,1]
	v_pk_add_f32 v[204:205], v[26:27], v[28:29] op_sel:[0,1] op_sel_hi:[1,0] neg_lo:[0,1]
	v_pk_mul_f32 v[206:207], v[210:211], v[210:211] op_sel:[1,1] op_sel_hi:[1,0]
	v_pk_fma_f32 v[212:213], v[210:211], v[210:211], v[206:207] op_sel_hi:[0,1,1] neg_lo:[0,0,1]
	v_pk_mul_f32 v[206:207], v[210:211], v[212:213] op_sel:[1,1] op_sel_hi:[1,0]
	v_pk_fma_f32 v[220:221], v[210:211], v[212:213], v[206:207] op_sel_hi:[0,1,1] neg_lo:[0,0,1]
	v_pk_mul_f32 v[26:27], v[210:211], v[202:203] op_sel:[1,1] op_sel_hi:[1,0]
	v_pk_fma_f32 v[26:27], v[210:211], v[202:203], v[26:27] op_sel_hi:[0,1,1] neg_lo:[0,0,1]
	v_pk_mul_f32 v[28:29], v[212:213], v[32:33] op_sel:[1,1] op_sel_hi:[1,0]
	v_pk_fma_f32 v[28:29], v[212:213], v[32:33], v[28:29] op_sel_hi:[0,1,1] neg_lo:[0,0,1]
	v_pk_mul_f32 v[32:33], v[220:221], v[204:205] op_sel:[1,1] op_sel_hi:[1,0]
	v_pk_fma_f32 v[32:33], v[220:221], v[204:205], v[32:33] op_sel_hi:[0,1,1] neg_lo:[0,0,1]
	v_cos_f32_e32 v210, 0x3e000000
	v_sin_f32_e32 v211, 0xbe000000
	s_waitcnt lgkmcnt(6)
; DI f32x2 cmul(f32x2 a, f32x2 b) { return mkf2(a.x * b.x - a.y * b.y, a.x * b.y + a.y * b.x); }
; DI void fft8192(f32x2* buf, const f32x2* __restrict__ tw) {
;     ...
; #pragma unroll
;     for (int e = 0; e < 8; ++e) {
;       const int i = tid + 256 * e;
;       const int q = i & (s - 1);
;       const int ps = i - q;
;       const float rev = (float)ps * (1.f / 8192.f);
;       const f32x2 w1 = mkf2(__builtin_amdgcn_cosf(rev), -__builtin_amdgcn_sinf(rev));
;       const f32x2 w2 = cmul(w1, w1), w3 = cmul(w1, w2);
;       const f32x2 apc = mkf2(a[e].x + c[e].x, a[e].y + c[e].y), amc = mkf2(a[e].x - c[e].x, a[e].y - c[e].y);
;       const f32x2 bpd = mkf2(b[e].x + d[e].x, b[e].y + d[e].y), bmd = mkf2(b[e].x - d[e].x, b[e].y - d[e].y);
;       const int o = 4 * i - 3 * q;
;       buf[SW(o)] = mkf2(apc.x + bpd.x, apc.y + bpd.y);
;       buf[SW(o + s)] = cmul(w1, mkf2(amc.x + bmd.y, amc.y - bmd.x));
;       buf[SW(o + 2 * s)] = cmul(w2, mkf2(apc.x - bpd.x, apc.y - bpd.y));
;       buf[SW(o + 3 * s)] = cmul(w3, mkf2(amc.x - bmd.y, amc.y + bmd.x));
	v_pk_add_f32 v[202:203], v[34:35], v[38:39]
	v_pk_add_f32 v[34:35], v[34:35], v[38:39] neg_lo:[0,1] neg_hi:[0,1]
	v_pk_add_f32 v[204:205], v[36:37], v[40:41]
	v_pk_add_f32 v[36:37], v[36:37], v[40:41] neg_lo:[0,1] neg_hi:[0,1]
	v_pk_add_f32 v[38:39], v[202:203], v[204:205]
	v_pk_add_f32 v[40:41], v[202:203], v[204:205] neg_lo:[0,1] neg_hi:[0,1]
	v_pk_add_f32 v[202:203], v[34:35], v[36:37] op_sel:[0,1] op_sel_hi:[1,0] neg_hi:[0,1]
	v_pk_add_f32 v[204:205], v[34:35], v[36:37] op_sel:[0,1] op_sel_hi:[1,0] neg_lo:[0,1]
	v_pk_mul_f32 v[206:207], v[210:211], v[210:211] op_sel:[1,1] op_sel_hi:[1,0]
	v_pk_fma_f32 v[212:213], v[210:211], v[210:211], v[206:207] op_sel_hi:[0,1,1] neg_lo:[0,0,1]
	v_pk_mul_f32 v[206:207], v[210:211], v[212:213] op_sel:[1,1] op_sel_hi:[1,0]
	v_pk_fma_f32 v[220:221], v[210:211], v[212:213], v[206:207] op_sel_hi:[0,1,1] neg_lo:[0,0,1]
	v_pk_mul_f32 v[34:35], v[210:211], v[202:203] op_sel:[1,1] op_sel_hi:[1,0]
	v_pk_fma_f32 v[34:35], v[210:211], v[202:203], v[34:35] op_sel_hi:[0,1,1] neg_lo:[0,0,1]
	v_pk_mul_f32 v[36:37], v[212:213], v[40:41] op_sel:[1,1] op_sel_hi:[1,0]
	v_pk_fma_f32 v[36:37], v[212:213], v[40:41], v[36:37] op_sel_hi:[0,1,1] neg_lo:[0,0,1]
	v_pk_mul_f32 v[40:41], v[220:221], v[204:205] op_sel:[1,1] op_sel_hi:[1,0]
	v_pk_fma_f32 v[40:41], v[220:221], v[204:205], v[40:41] op_sel_hi:[0,1,1] neg_lo:[0,0,1]
	v_cos_f32_e32 v210, 0x3e200000
	v_sin_f32_e32 v211, 0xbe200000
	s_waitcnt lgkmcnt(4)
	v_pk_add_f32 v[202:203], v[42:43], v[46:47]
	v_pk_add_f32 v[42:43], v[42:43], v[46:47] neg_lo:[0,1] neg_hi:[0,1]
	v_pk_add_f32 v[204:205], v[44:45], v[48:49]
	v_pk_add_f32 v[44:45], v[44:45], v[48:49] neg_lo:[0,1] neg_hi:[0,1]
	v_pk_add_f32 v[46:47], v[202:203], v[204:205]
	v_pk_add_f32 v[48:49], v[202:203], v[204:205] neg_lo:[0,1] neg_hi:[0,1]
	v_pk_add_f32 v[202:203], v[42:43], v[44:45] op_sel:[0,1] op_sel_hi:[1,0] neg_hi:[0,1]
	v_pk_add_f32 v[204:205], v[42:43], v[44:45] op_sel:[0,1] op_sel_hi:[1,0] neg_lo:[0,1]
	v_pk_mul_f32 v[206:207], v[210:211], v[210:211] op_sel:[1,1] op_sel_hi:[1,0]
	v_pk_fma_f32 v[212:213], v[210:211], v[210:211], v[206:207] op_sel_hi:[0,1,1] neg_lo:[0,0,1]
	v_pk_mul_f32 v[206:207], v[210:211], v[212:213] op_sel:[1,1] op_sel_hi:[1,0]
	v_pk_fma_f32 v[220:221], v[210:211], v[212:213], v[206:207] op_sel_hi:[0,1,1] neg_lo:[0,0,1]
	v_pk_mul_f32 v[42:43], v[210:211], v[202:203] op_sel:[1,1] op_sel_hi:[1,0]
	v_pk_fma_f32 v[42:43], v[210:211], v[202:203], v[42:43] op_sel_hi:[0,1,1] neg_lo:[0,0,1]
	v_pk_mul_f32 v[44:45], v[212:213], v[48:49] op_sel:[1,1] op_sel_hi:[1,0]
	v_pk_fma_f32 v[44:45], v[212:213], v[48:49], v[44:45] op_sel_hi:[0,1,1] neg_lo:[0,0,1]
	v_pk_mul_f32 v[48:49], v[220:221], v[204:205] op_sel:[1,1] op_sel_hi:[1,0]
	v_pk_fma_f32 v[48:49], v[220:221], v[204:205], v[48:49] op_sel_hi:[0,1,1] neg_lo:[0,0,1]
	v_cos_f32_e32 v210, 0x3e400000
	v_sin_f32_e32 v211, 0xbe400000
	s_waitcnt lgkmcnt(2)
	v_pk_add_f32 v[202:203], v[50:51], v[54:55]
	v_pk_add_f32 v[50:51], v[50:51], v[54:55] neg_lo:[0,1] neg_hi:[0,1]
	v_pk_add_f32 v[204:205], v[52:53], v[56:57]
	v_pk_add_f32 v[52:53], v[52:53], v[56:57] neg_lo:[0,1] neg_hi:[0,1]
	v_pk_add_f32 v[54:55], v[202:203], v[204:205]
	v_pk_add_f32 v[56:57], v[202:203], v[204:205] neg_lo:[0,1] neg_hi:[0,1]
	v_pk_add_f32 v[202:203], v[50:51], v[52:53] op_sel:[0,1] op_sel_hi:[1,0] neg_hi:[0,1]
	v_pk_add_f32 v[204:205], v[50:51], v[52:53] op_sel:[0,1] op_sel_hi:[1,0] neg_lo:[0,1]
	v_pk_mul_f32 v[206:207], v[210:211], v[210:211] op_sel:[1,1] op_sel_hi:[1,0]
	v_pk_fma_f32 v[212:213], v[210:211], v[210:211], v[206:207] op_sel_hi:[0,1,1] neg_lo:[0,0,1]
	v_pk_mul_f32 v[206:207], v[210:211], v[212:213] op_sel:[1,1] op_sel_hi:[1,0]
	v_pk_fma_f32 v[220:221], v[210:211], v[212:213], v[206:207] op_sel_hi:[0,1,1] neg_lo:[0,0,1]
	v_pk_mul_f32 v[50:51], v[210:211], v[202:203] op_sel:[1,1] op_sel_hi:[1,0]
	v_pk_fma_f32 v[50:51], v[210:211], v[202:203], v[50:51] op_sel_hi:[0,1,1] neg_lo:[0,0,1]
	v_pk_mul_f32 v[52:53], v[212:213], v[56:57] op_sel:[1,1] op_sel_hi:[1,0]
	v_pk_fma_f32 v[52:53], v[212:213], v[56:57], v[52:53] op_sel_hi:[0,1,1] neg_lo:[0,0,1]
	v_pk_mul_f32 v[56:57], v[220:221], v[204:205] op_sel:[1,1] op_sel_hi:[1,0]
	v_pk_fma_f32 v[56:57], v[220:221], v[204:205], v[56:57] op_sel_hi:[0,1,1] neg_lo:[0,0,1]
	v_cos_f32_e32 v210, 0x3e600000
	v_sin_f32_e32 v211, 0xbe600000
	s_waitcnt lgkmcnt(0)
	v_pk_add_f32 v[202:203], v[58:59], v[62:63]
	v_pk_add_f32 v[58:59], v[58:59], v[62:63] neg_lo:[0,1] neg_hi:[0,1]
	v_pk_add_f32 v[204:205], v[60:61], v[64:65]
	v_pk_add_f32 v[60:61], v[60:61], v[64:65] neg_lo:[0,1] neg_hi:[0,1]
	v_pk_add_f32 v[62:63], v[202:203], v[204:205]
	v_pk_add_f32 v[64:65], v[202:203], v[204:205] neg_lo:[0,1] neg_hi:[0,1]
	v_pk_add_f32 v[202:203], v[58:59], v[60:61] op_sel:[0,1] op_sel_hi:[1,0] neg_hi:[0,1]
	v_pk_add_f32 v[204:205], v[58:59], v[60:61] op_sel:[0,1] op_sel_hi:[1,0] neg_lo:[0,1]
	v_pk_mul_f32 v[206:207], v[210:211], v[210:211] op_sel:[1,1] op_sel_hi:[1,0]
	v_pk_fma_f32 v[212:213], v[210:211], v[210:211], v[206:207] op_sel_hi:[0,1,1] neg_lo:[0,0,1]
	v_pk_mul_f32 v[206:207], v[210:211], v[212:213] op_sel:[1,1] op_sel_hi:[1,0]
	v_pk_fma_f32 v[220:221], v[210:211], v[212:213], v[206:207] op_sel_hi:[0,1,1] neg_lo:[0,0,1]
	v_pk_mul_f32 v[58:59], v[210:211], v[202:203] op_sel:[1,1] op_sel_hi:[1,0]
	v_pk_fma_f32 v[58:59], v[210:211], v[202:203], v[58:59] op_sel_hi:[0,1,1] neg_lo:[0,0,1]
	v_pk_mul_f32 v[60:61], v[212:213], v[64:65] op_sel:[1,1] op_sel_hi:[1,0]
	v_pk_fma_f32 v[60:61], v[212:213], v[64:65], v[60:61] op_sel_hi:[0,1,1] neg_lo:[0,0,1]
	v_pk_mul_f32 v[64:65], v[220:221], v[204:205] op_sel:[1,1] op_sel_hi:[1,0]
	v_pk_fma_f32 v[64:65], v[220:221], v[204:205], v[64:65] op_sel_hi:[0,1,1] neg_lo:[0,0,1]
	s_barrier
; DI f32x2 cmul(f32x2 a, f32x2 b) { return mkf2(a.x * b.x - a.y * b.y, a.x * b.y + a.y * b.x); }
; DI void fft8192(f32x2* buf, const f32x2* __restrict__ tw) {
;     ...
;   for (int ls = 0; ls < 12; ls += 2) {
;     const int s = 1 << ls;
;     f32x2 a[8], b[8], c[8], d[8];
;     __syncthreads();
; #pragma unroll
;     for (int e = 0; e < 8; ++e) {
;       const int i = tid + 256 * e;
;       const int pi = SW(i);
;       a[e] = buf[pi]; b[e] = buf[pi + 2048]; c[e] = buf[pi + 4096]; d[e] = buf[pi + 6144];
;     }
;     __syncthreads();
; #pragma unroll
;     for (int e = 0; e < 8; ++e) {
;       const int i = tid + 256 * e;
;       const int q = i & (s - 1);
;       const int ps = i - q;
;       const float rev = (float)ps * (1.f / 8192.f);
;       const f32x2 w1 = mkf2(__builtin_amdgcn_cosf(rev), -__builtin_amdgcn_sinf(rev));
;       const f32x2 w2 = cmul(w1, w1), w3 = cmul(w1, w2);
;       const f32x2 apc = mkf2(a[e].x + c[e].x, a[e].y + c[e].y), amc = mkf2(a[e].x - c[e].x, a[e].y - c[e].y);
;       const f32x2 bpd = mkf2(b[e].x + d[e].x, b[e].y + d[e].y), bmd = mkf2(b[e].x - d[e].x, b[e].y - d[e].y);
;       const int o = 4 * i - 3 * q;
;       buf[SW(o)] = mkf2(apc.x + bpd.x, apc.y + bpd.y);
;       buf[SW(o + s)] = cmul(w1, mkf2(amc.x + bmd.y, amc.y - bmd.x));
;       buf[SW(o + 2 * s)] = cmul(w2, mkf2(apc.x - bpd.x, apc.y - bpd.y));
;       buf[SW(o + 3 * s)] = cmul(w3, mkf2(amc.x - bmd.y, amc.y + bmd.x));
;     }
	ds_write_b64 v154, v[6:7] offset:0
	ds_write_b64 v154, v[2:3] offset:2048
	ds_write_b64 v154, v[8:9] offset:4096
	ds_write_b64 v154, v[4:5] offset:6144
	ds_write_b64 v154, v[14:15] offset:8192
	ds_write_b64 v154, v[10:11] offset:10240
	ds_write_b64 v154, v[12:13] offset:12288
	ds_write_b64 v154, v[16:17] offset:14336
	ds_write_b64 v154, v[22:23] offset:16384
	ds_write_b64 v154, v[18:19] offset:18432
	ds_write_b64 v154, v[20:21] offset:20480
	ds_write_b64 v154, v[24:25] offset:22528
	ds_write_b64 v154, v[30:31] offset:24576
	ds_write_b64 v154, v[26:27] offset:26624
	ds_write_b64 v154, v[28:29] offset:28672
	ds_write_b64 v154, v[32:33] offset:30720
	ds_write_b64 v154, v[38:39] offset:32768
	ds_write_b64 v154, v[34:35] offset:34816
	ds_write_b64 v154, v[36:37] offset:36864
	ds_write_b64 v154, v[40:41] offset:38912
	ds_write_b64 v154, v[46:47] offset:40960
	ds_write_b64 v154, v[42:43] offset:43008
	ds_write_b64 v154, v[44:45] offset:45056
	ds_write_b64 v154, v[48:49] offset:47104
	ds_write_b64 v154, v[54:55] offset:49152
	ds_write_b64 v154, v[50:51] offset:51200
	ds_write_b64 v154, v[52:53] offset:53248
	ds_write_b64 v154, v[56:57] offset:55296
	ds_write_b64 v154, v[62:63] offset:57344
	ds_write_b64 v154, v[58:59] offset:59392
	ds_write_b64 v154, v[60:61] offset:61440
	ds_write_b64 v154, v[64:65] offset:63488
	s_waitcnt lgkmcnt(0)
	s_barrier
	ds_read2st64_b64 v[2:5], v154 offset0:0 offset1:32
	ds_read2st64_b64 v[6:9], v154 offset0:64 offset1:96
	ds_read2st64_b64 v[10:13], v154 offset0:4 offset1:36
	ds_read2st64_b64 v[14:17], v154 offset0:68 offset1:100
	ds_read2st64_b64 v[18:21], v154 offset0:8 offset1:40
	ds_read2st64_b64 v[22:25], v154 offset0:72 offset1:104
	ds_read2st64_b64 v[26:29], v154 offset0:12 offset1:44
	ds_read2st64_b64 v[30:33], v154 offset0:76 offset1:108
	ds_read2st64_b64 v[34:37], v154 offset0:16 offset1:48
	ds_read2st64_b64 v[38:41], v154 offset0:80 offset1:112
	ds_read2st64_b64 v[42:45], v154 offset0:20 offset1:52
	ds_read2st64_b64 v[46:49], v154 offset0:84 offset1:116
	ds_read2st64_b64 v[50:53], v154 offset0:24 offset1:56
	ds_read2st64_b64 v[54:57], v154 offset0:88 offset1:120
	ds_read2st64_b64 v[58:61], v154 offset0:28 offset1:60
	ds_read2st64_b64 v[62:65], v154 offset0:92 offset1:124
	s_waitcnt lgkmcnt(14)
	v_pk_add_f32 v[202:203], v[2:3], v[6:7]
	v_pk_add_f32 v[2:3], v[2:3], v[6:7] neg_lo:[0,1] neg_hi:[0,1]
	v_pk_add_f32 v[204:205], v[4:5], v[8:9]
	v_pk_add_f32 v[4:5], v[4:5], v[8:9] neg_lo:[0,1] neg_hi:[0,1]
	v_pk_add_f32 v[6:7], v[202:203], v[204:205]
	v_pk_add_f32 v[8:9], v[202:203], v[204:205] neg_lo:[0,1] neg_hi:[0,1]
	v_pk_add_f32 v[202:203], v[2:3], v[4:5] op_sel:[0,1] op_sel_hi:[1,0] neg_hi:[0,1]
	v_pk_add_f32 v[4:5], v[2:3], v[4:5] op_sel:[0,1] op_sel_hi:[1,0] neg_lo:[0,1]
	v_pk_mov_b32 v[2:3], v[202:203], v[202:203] op_sel:[0,1]
	s_waitcnt lgkmcnt(12)
	v_pk_add_f32 v[202:203], v[10:11], v[14:15]
	v_pk_add_f32 v[10:11], v[10:11], v[14:15] neg_lo:[0,1] neg_hi:[0,1]
	v_pk_add_f32 v[204:205], v[12:13], v[16:17]
	v_pk_add_f32 v[12:13], v[12:13], v[16:17] neg_lo:[0,1] neg_hi:[0,1]
	v_pk_add_f32 v[14:15], v[202:203], v[204:205]
	v_pk_add_f32 v[16:17], v[202:203], v[204:205] neg_lo:[0,1] neg_hi:[0,1]
	v_pk_add_f32 v[202:203], v[10:11], v[12:13] op_sel:[0,1] op_sel_hi:[1,0] neg_hi:[0,1]
	v_pk_add_f32 v[12:13], v[10:11], v[12:13] op_sel:[0,1] op_sel_hi:[1,0] neg_lo:[0,1]
	v_pk_mov_b32 v[10:11], v[202:203], v[202:203] op_sel:[0,1]
	s_waitcnt lgkmcnt(10)
	v_pk_add_f32 v[202:203], v[18:19], v[22:23]
	v_pk_add_f32 v[18:19], v[18:19], v[22:23] neg_lo:[0,1] neg_hi:[0,1]
	v_pk_add_f32 v[204:205], v[20:21], v[24:25]
	v_pk_add_f32 v[20:21], v[20:21], v[24:25] neg_lo:[0,1] neg_hi:[0,1]
	v_pk_add_f32 v[22:23], v[202:203], v[204:205]
	v_pk_add_f32 v[24:25], v[202:203], v[204:205] neg_lo:[0,1] neg_hi:[0,1]
	v_pk_add_f32 v[202:203], v[18:19], v[20:21] op_sel:[0,1] op_sel_hi:[1,0] neg_hi:[0,1]
	v_pk_add_f32 v[20:21], v[18:19], v[20:21] op_sel:[0,1] op_sel_hi:[1,0] neg_lo:[0,1]
	v_pk_mov_b32 v[18:19], v[202:203], v[202:203] op_sel:[0,1]
	s_waitcnt lgkmcnt(8)
	v_pk_add_f32 v[202:203], v[26:27], v[30:31]
	v_pk_add_f32 v[26:27], v[26:27], v[30:31] neg_lo:[0,1] neg_hi:[0,1]
	v_pk_add_f32 v[204:205], v[28:29], v[32:33]
	v_pk_add_f32 v[28:29], v[28:29], v[32:33] neg_lo:[0,1] neg_hi:[0,1]
	v_pk_add_f32 v[30:31], v[202:203], v[204:205]
	v_pk_add_f32 v[32:33], v[202:203], v[204:205] neg_lo:[0,1] neg_hi:[0,1]
	v_pk_add_f32 v[202:203], v[26:27], v[28:29] op_sel:[0,1] op_sel_hi:[1,0] neg_hi:[0,1]
	v_pk_add_f32 v[28:29], v[26:27], v[28:29] op_sel:[0,1] op_sel_hi:[1,0] neg_lo:[0,1]
	v_pk_mov_b32 v[26:27], v[202:203], v[202:203] op_sel:[0,1]
	v_cos_f32_e32 v210, 0x3e000000
	v_sin_f32_e32 v211, 0xbe000000
	s_waitcnt lgkmcnt(6)
	v_pk_add_f32 v[202:203], v[34:35], v[38:39]
	v_pk_add_f32 v[34:35], v[34:35], v[38:39] neg_lo:[0,1] neg_hi:[0,1]
	v_pk_add_f32 v[204:205], v[36:37], v[40:41]
	v_pk_add_f32 v[36:37], v[36:37], v[40:41] neg_lo:[0,1] neg_hi:[0,1]
	v_pk_add_f32 v[38:39], v[202:203], v[204:205]
	v_pk_add_f32 v[40:41], v[202:203], v[204:205] neg_lo:[0,1] neg_hi:[0,1]
	v_pk_add_f32 v[202:203], v[34:35], v[36:37] op_sel:[0,1] op_sel_hi:[1,0] neg_hi:[0,1]
	v_pk_add_f32 v[204:205], v[34:35], v[36:37] op_sel:[0,1] op_sel_hi:[1,0] neg_lo:[0,1]
	v_pk_mul_f32 v[206:207], v[210:211], v[210:211] op_sel:[1,1] op_sel_hi:[1,0]
	v_pk_fma_f32 v[212:213], v[210:211], v[210:211], v[206:207] op_sel_hi:[0,1,1] neg_lo:[0,0,1]
	v_pk_mul_f32 v[206:207], v[210:211], v[212:213] op_sel:[1,1] op_sel_hi:[1,0]
	v_pk_fma_f32 v[220:221], v[210:211], v[212:213], v[206:207] op_sel_hi:[0,1,1] neg_lo:[0,0,1]
	v_pk_mul_f32 v[34:35], v[210:211], v[202:203] op_sel:[1,1] op_sel_hi:[1,0]
	v_pk_fma_f32 v[34:35], v[210:211], v[202:203], v[34:35] op_sel_hi:[0,1,1] neg_lo:[0,0,1]
	v_pk_mul_f32 v[36:37], v[212:213], v[40:41] op_sel:[1,1] op_sel_hi:[1,0]
	v_pk_fma_f32 v[36:37], v[212:213], v[40:41], v[36:37] op_sel_hi:[0,1,1] neg_lo:[0,0,1]
	v_pk_mul_f32 v[40:41], v[220:221], v[204:205] op_sel:[1,1] op_sel_hi:[1,0]
	v_pk_fma_f32 v[40:41], v[220:221], v[204:205], v[40:41] op_sel_hi:[0,1,1] neg_lo:[0,0,1]
	v_cos_f32_e32 v210, 0x3e000000
	v_sin_f32_e32 v211, 0xbe000000
	s_waitcnt lgkmcnt(4)
; DI f32x2 cmul(f32x2 a, f32x2 b) { return mkf2(a.x * b.x - a.y * b.y, a.x * b.y + a.y * b.x); }
; DI void fft8192(f32x2* buf, const f32x2* __restrict__ tw) {
;     ...
; #pragma unroll
;     for (int e = 0; e < 8; ++e) {
;       const int i = tid + 256 * e;
;       const int q = i & (s - 1);
;       const int ps = i - q;
;       const float rev = (float)ps * (1.f / 8192.f);
;       const f32x2 w1 = mkf2(__builtin_amdgcn_cosf(rev), -__builtin_amdgcn_sinf(rev));
;       const f32x2 w2 = cmul(w1, w1), w3 = cmul(w1, w2);
;       const f32x2 apc = mkf2(a[e].x + c[e].x, a[e].y + c[e].y), amc = mkf2(a[e].x - c[e].x, a[e].y - c[e].y);
;       const f32x2 bpd = mkf2(b[e].x + d[e].x, b[e].y + d[e].y), bmd = mkf2(b[e].x - d[e].x, b[e].y - d[e].y);
;       const int o = 4 * i - 3 * q;
;       buf[SW(o)] = mkf2(apc.x + bpd.x, apc.y + bpd.y);
;       buf[SW(o + s)] = cmul(w1, mkf2(amc.x + bmd.y, amc.y - bmd.x));
;       buf[SW(o + 2 * s)] = cmul(w2, mkf2(apc.x - bpd.x, apc.y - bpd.y));
;       buf[SW(o + 3 * s)] = cmul(w3, mkf2(amc.x - bmd.y, amc.y + bmd.x));
;     }
	v_pk_add_f32 v[202:203], v[42:43], v[46:47]
	v_pk_add_f32 v[42:43], v[42:43], v[46:47] neg_lo:[0,1] neg_hi:[0,1]
	v_pk_add_f32 v[204:205], v[44:45], v[48:49]
	v_pk_add_f32 v[44:45], v[44:45], v[48:49] neg_lo:[0,1] neg_hi:[0,1]
	v_pk_add_f32 v[46:47], v[202:203], v[204:205]
	v_pk_add_f32 v[48:49], v[202:203], v[204:205] neg_lo:[0,1] neg_hi:[0,1]
	v_pk_add_f32 v[202:203], v[42:43], v[44:45] op_sel:[0,1] op_sel_hi:[1,0] neg_hi:[0,1]
	v_pk_add_f32 v[204:205], v[42:43], v[44:45] op_sel:[0,1] op_sel_hi:[1,0] neg_lo:[0,1]
	v_pk_mul_f32 v[206:207], v[210:211], v[210:211] op_sel:[1,1] op_sel_hi:[1,0]
	v_pk_fma_f32 v[212:213], v[210:211], v[210:211], v[206:207] op_sel_hi:[0,1,1] neg_lo:[0,0,1]
	v_pk_mul_f32 v[206:207], v[210:211], v[212:213] op_sel:[1,1] op_sel_hi:[1,0]
	v_pk_fma_f32 v[220:221], v[210:211], v[212:213], v[206:207] op_sel_hi:[0,1,1] neg_lo:[0,0,1]
	v_pk_mul_f32 v[42:43], v[210:211], v[202:203] op_sel:[1,1] op_sel_hi:[1,0]
	v_pk_fma_f32 v[42:43], v[210:211], v[202:203], v[42:43] op_sel_hi:[0,1,1] neg_lo:[0,0,1]
	v_pk_mul_f32 v[44:45], v[212:213], v[48:49] op_sel:[1,1] op_sel_hi:[1,0]
	v_pk_fma_f32 v[44:45], v[212:213], v[48:49], v[44:45] op_sel_hi:[0,1,1] neg_lo:[0,0,1]
	v_pk_mul_f32 v[48:49], v[220:221], v[204:205] op_sel:[1,1] op_sel_hi:[1,0]
	v_pk_fma_f32 v[48:49], v[220:221], v[204:205], v[48:49] op_sel_hi:[0,1,1] neg_lo:[0,0,1]
	v_cos_f32_e32 v210, 0x3e000000
	v_sin_f32_e32 v211, 0xbe000000
	s_waitcnt lgkmcnt(2)
	v_pk_add_f32 v[202:203], v[50:51], v[54:55]
	v_pk_add_f32 v[50:51], v[50:51], v[54:55] neg_lo:[0,1] neg_hi:[0,1]
	v_pk_add_f32 v[204:205], v[52:53], v[56:57]
	v_pk_add_f32 v[52:53], v[52:53], v[56:57] neg_lo:[0,1] neg_hi:[0,1]
	v_pk_add_f32 v[54:55], v[202:203], v[204:205]
	v_pk_add_f32 v[56:57], v[202:203], v[204:205] neg_lo:[0,1] neg_hi:[0,1]
	v_pk_add_f32 v[202:203], v[50:51], v[52:53] op_sel:[0,1] op_sel_hi:[1,0] neg_hi:[0,1]
	v_pk_add_f32 v[204:205], v[50:51], v[52:53] op_sel:[0,1] op_sel_hi:[1,0] neg_lo:[0,1]
	v_pk_mul_f32 v[206:207], v[210:211], v[210:211] op_sel:[1,1] op_sel_hi:[1,0]
	v_pk_fma_f32 v[212:213], v[210:211], v[210:211], v[206:207] op_sel_hi:[0,1,1] neg_lo:[0,0,1]
	v_pk_mul_f32 v[206:207], v[210:211], v[212:213] op_sel:[1,1] op_sel_hi:[1,0]
	v_pk_fma_f32 v[220:221], v[210:211], v[212:213], v[206:207] op_sel_hi:[0,1,1] neg_lo:[0,0,1]
	v_pk_mul_f32 v[50:51], v[210:211], v[202:203] op_sel:[1,1] op_sel_hi:[1,0]
	v_pk_fma_f32 v[50:51], v[210:211], v[202:203], v[50:51] op_sel_hi:[0,1,1] neg_lo:[0,0,1]
	v_pk_mul_f32 v[52:53], v[212:213], v[56:57] op_sel:[1,1] op_sel_hi:[1,0]
	v_pk_fma_f32 v[52:53], v[212:213], v[56:57], v[52:53] op_sel_hi:[0,1,1] neg_lo:[0,0,1]
	v_pk_mul_f32 v[56:57], v[220:221], v[204:205] op_sel:[1,1] op_sel_hi:[1,0]
	v_pk_fma_f32 v[56:57], v[220:221], v[204:205], v[56:57] op_sel_hi:[0,1,1] neg_lo:[0,0,1]
	v_cos_f32_e32 v210, 0x3e000000
	v_sin_f32_e32 v211, 0xbe000000
	s_waitcnt lgkmcnt(0)
	v_pk_add_f32 v[202:203], v[58:59], v[62:63]
	v_pk_add_f32 v[58:59], v[58:59], v[62:63] neg_lo:[0,1] neg_hi:[0,1]
	v_pk_add_f32 v[204:205], v[60:61], v[64:65]
	v_pk_add_f32 v[60:61], v[60:61], v[64:65] neg_lo:[0,1] neg_hi:[0,1]
	v_pk_add_f32 v[62:63], v[202:203], v[204:205]
	v_pk_add_f32 v[64:65], v[202:203], v[204:205] neg_lo:[0,1] neg_hi:[0,1]
	v_pk_add_f32 v[202:203], v[58:59], v[60:61] op_sel:[0,1] op_sel_hi:[1,0] neg_hi:[0,1]
	v_pk_add_f32 v[204:205], v[58:59], v[60:61] op_sel:[0,1] op_sel_hi:[1,0] neg_lo:[0,1]
	v_pk_mul_f32 v[206:207], v[210:211], v[210:211] op_sel:[1,1] op_sel_hi:[1,0]
	v_pk_fma_f32 v[212:213], v[210:211], v[210:211], v[206:207] op_sel_hi:[0,1,1] neg_lo:[0,0,1]
	v_pk_mul_f32 v[206:207], v[210:211], v[212:213] op_sel:[1,1] op_sel_hi:[1,0]
	v_pk_fma_f32 v[220:221], v[210:211], v[212:213], v[206:207] op_sel_hi:[0,1,1] neg_lo:[0,0,1]
	v_pk_mul_f32 v[58:59], v[210:211], v[202:203] op_sel:[1,1] op_sel_hi:[1,0]
	v_pk_fma_f32 v[58:59], v[210:211], v[202:203], v[58:59] op_sel_hi:[0,1,1] neg_lo:[0,0,1]
	v_pk_mul_f32 v[60:61], v[212:213], v[64:65] op_sel:[1,1] op_sel_hi:[1,0]
	v_pk_fma_f32 v[60:61], v[212:213], v[64:65], v[60:61] op_sel_hi:[0,1,1] neg_lo:[0,0,1]
	v_pk_mul_f32 v[64:65], v[220:221], v[204:205] op_sel:[1,1] op_sel_hi:[1,0]
	v_pk_fma_f32 v[64:65], v[220:221], v[204:205], v[64:65] op_sel_hi:[0,1,1] neg_lo:[0,0,1]
	s_barrier
	ds_write_b64 v154, v[6:7] offset:0
	ds_write_b64 v154, v[2:3] offset:8192
	ds_write_b64 v154, v[8:9] offset:16384
	ds_write_b64 v154, v[4:5] offset:24576
	ds_write_b64 v154, v[14:15] offset:2048
	ds_write_b64 v154, v[10:11] offset:10240
	ds_write_b64 v154, v[16:17] offset:18432
	ds_write_b64 v154, v[12:13] offset:26624
	ds_write_b64 v154, v[22:23] offset:4096
	ds_write_b64 v154, v[18:19] offset:12288
	ds_write_b64 v154, v[24:25] offset:20480
	ds_write_b64 v154, v[20:21] offset:28672
	ds_write_b64 v154, v[30:31] offset:6144
	ds_write_b64 v154, v[26:27] offset:14336
	ds_write_b64 v154, v[32:33] offset:22528
	ds_write_b64 v154, v[28:29] offset:30720
	ds_write_b64 v154, v[38:39] offset:32768
	ds_write_b64 v154, v[34:35] offset:40960
	ds_write_b64 v154, v[36:37] offset:49152
	ds_write_b64 v154, v[40:41] offset:57344
	ds_write_b64 v154, v[46:47] offset:34816
	ds_write_b64 v154, v[42:43] offset:43008
	ds_write_b64 v154, v[44:45] offset:51200
	ds_write_b64 v154, v[48:49] offset:59392
	ds_write_b64 v154, v[54:55] offset:36864
	ds_write_b64 v154, v[50:51] offset:45056
	ds_write_b64 v154, v[52:53] offset:53248
	ds_write_b64 v154, v[56:57] offset:61440
	ds_write_b64 v154, v[62:63] offset:38912
	ds_write_b64 v154, v[58:59] offset:47104
	ds_write_b64 v154, v[60:61] offset:55296
	ds_write_b64 v154, v[64:65] offset:63488
	s_waitcnt lgkmcnt(0)
	s_barrier
; DI void fft8192(f32x2* buf, const f32x2* __restrict__ tw) {
;     ...
;   {
;     f32x2 a[16], b[16];
;     __syncthreads();
; #pragma unroll
;     for (int e = 0; e < 16; ++e) { const int pi = SW(tid + 256 * e); a[e] = buf[pi]; b[e] = buf[pi + 4096]; }
;     __syncthreads();
; #pragma unroll
;     for (int e = 0; e < 16; ++e) {
;       const int pi = SW(tid + 256 * e);
;       buf[pi] = mkf2(a[e].x + b[e].x, a[e].y + b[e].y);
;       buf[pi + 4096] = mkf2(a[e].x - b[e].x, a[e].y - b[e].y);
;     }
;     __syncthreads();
;   }
; DI void hyena_unit(KP p, int l, int c, char* smem) {
;     ...
;     for (int j = 0; j < 32; ++j) KF[j] = buf[SW(tid + 256 * j)];
;     const int gcol = (o == 0 ? 512 : 1024) + c;
;     const float gw0 = cw[gcol], gw1 = cw[1536 + gcol], gw2 = cw[3072 + gcol], gb = cb[gcol];
;     const float vw0 = cw[c], vw1 = cw[1536 + c], vw2 = cw[3072 + c], vb = cb[c];
	ds_read2st64_b64 v[2:5], v154 offset0:0 offset1:64
	ds_read2st64_b64 v[6:9], v154 offset0:4 offset1:68
	ds_read2st64_b64 v[10:13], v154 offset0:8 offset1:72
	ds_read2st64_b64 v[14:17], v154 offset0:12 offset1:76
	ds_read2st64_b64 v[18:21], v154 offset0:16 offset1:80
	ds_read2st64_b64 v[22:25], v154 offset0:20 offset1:84
	ds_read2st64_b64 v[26:29], v154 offset0:24 offset1:88
	ds_read2st64_b64 v[30:33], v154 offset0:28 offset1:92
	ds_read2st64_b64 v[34:37], v154 offset0:32 offset1:96
	ds_read2st64_b64 v[38:41], v154 offset0:36 offset1:100
	ds_read2st64_b64 v[42:45], v154 offset0:40 offset1:104
	ds_read2st64_b64 v[46:49], v154 offset0:44 offset1:108
	ds_read2st64_b64 v[50:53], v154 offset0:48 offset1:112
	ds_read2st64_b64 v[54:57], v154 offset0:52 offset1:116
	ds_read2st64_b64 v[58:61], v154 offset0:56 offset1:120
	ds_read2st64_b64 v[62:65], v154 offset0:60 offset1:124
	s_waitcnt lgkmcnt(15)
	v_pk_add_f32 v[202:203], v[2:3], v[4:5]
	v_pk_add_f32 v[4:5], v[2:3], v[4:5] neg_lo:[0,1] neg_hi:[0,1]
	s_waitcnt lgkmcnt(14)
	v_pk_add_f32 v[204:205], v[6:7], v[8:9]
	v_pk_add_f32 v[8:9], v[6:7], v[8:9] neg_lo:[0,1] neg_hi:[0,1]
	s_waitcnt lgkmcnt(13)
	v_pk_add_f32 v[206:207], v[10:11], v[12:13]
	v_pk_add_f32 v[12:13], v[10:11], v[12:13] neg_lo:[0,1] neg_hi:[0,1]
	s_waitcnt lgkmcnt(12)
	v_pk_add_f32 v[208:209], v[14:15], v[16:17]
	v_pk_add_f32 v[16:17], v[14:15], v[16:17] neg_lo:[0,1] neg_hi:[0,1]
	s_waitcnt lgkmcnt(11)
	v_pk_add_f32 v[210:211], v[18:19], v[20:21]
	v_pk_add_f32 v[20:21], v[18:19], v[20:21] neg_lo:[0,1] neg_hi:[0,1]
	s_waitcnt lgkmcnt(10)
	v_pk_add_f32 v[212:213], v[22:23], v[24:25]
	v_pk_add_f32 v[24:25], v[22:23], v[24:25] neg_lo:[0,1] neg_hi:[0,1]
	s_waitcnt lgkmcnt(9)
	v_pk_add_f32 v[220:221], v[26:27], v[28:29]
	v_pk_add_f32 v[28:29], v[26:27], v[28:29] neg_lo:[0,1] neg_hi:[0,1]
	s_waitcnt lgkmcnt(8)
	v_pk_add_f32 v[224:225], v[30:31], v[32:33]
	v_pk_add_f32 v[32:33], v[30:31], v[32:33] neg_lo:[0,1] neg_hi:[0,1]
	s_waitcnt lgkmcnt(7)
	v_pk_add_f32 v[226:227], v[34:35], v[36:37]
	v_pk_add_f32 v[36:37], v[34:35], v[36:37] neg_lo:[0,1] neg_hi:[0,1]
	s_waitcnt lgkmcnt(6)
	v_pk_add_f32 v[230:231], v[38:39], v[40:41]
	v_pk_add_f32 v[40:41], v[38:39], v[40:41] neg_lo:[0,1] neg_hi:[0,1]
	s_waitcnt lgkmcnt(5)
	v_pk_add_f32 v[232:233], v[42:43], v[44:45]
	v_pk_add_f32 v[44:45], v[42:43], v[44:45] neg_lo:[0,1] neg_hi:[0,1]
	s_waitcnt lgkmcnt(4)
	v_pk_add_f32 v[236:237], v[46:47], v[48:49]
	v_pk_add_f32 v[48:49], v[46:47], v[48:49] neg_lo:[0,1] neg_hi:[0,1]
	s_waitcnt lgkmcnt(3)
	v_pk_add_f32 v[238:239], v[50:51], v[52:53]
	v_pk_add_f32 v[52:53], v[50:51], v[52:53] neg_lo:[0,1] neg_hi:[0,1]
	s_waitcnt lgkmcnt(2)
	v_pk_add_f32 v[240:241], v[54:55], v[56:57]
	v_pk_add_f32 v[56:57], v[54:55], v[56:57] neg_lo:[0,1] neg_hi:[0,1]
	s_waitcnt lgkmcnt(1)
	v_pk_add_f32 v[244:245], v[58:59], v[60:61]
	v_pk_add_f32 v[60:61], v[58:59], v[60:61] neg_lo:[0,1] neg_hi:[0,1]
	s_waitcnt lgkmcnt(0)
	v_pk_add_f32 v[246:247], v[62:63], v[64:65]
	v_pk_add_f32 v[64:65], v[62:63], v[64:65] neg_lo:[0,1] neg_hi:[0,1]
	s_barrier
	ds_write2st64_b64 v154, v[202:203], v[4:5] offset0:0 offset1:64
	ds_write2st64_b64 v154, v[204:205], v[8:9] offset0:4 offset1:68
	ds_write2st64_b64 v154, v[206:207], v[12:13] offset0:8 offset1:72
	ds_write2st64_b64 v154, v[208:209], v[16:17] offset0:12 offset1:76
	ds_write2st64_b64 v154, v[210:211], v[20:21] offset0:16 offset1:80
	ds_write2st64_b64 v154, v[212:213], v[24:25] offset0:20 offset1:84
	ds_write2st64_b64 v154, v[220:221], v[28:29] offset0:24 offset1:88
	ds_write2st64_b64 v154, v[224:225], v[32:33] offset0:28 offset1:92
	ds_write2st64_b64 v154, v[226:227], v[36:37] offset0:32 offset1:96
	ds_write2st64_b64 v154, v[230:231], v[40:41] offset0:36 offset1:100
	ds_write2st64_b64 v154, v[232:233], v[44:45] offset0:40 offset1:104
	ds_write2st64_b64 v154, v[236:237], v[48:49] offset0:44 offset1:108
	ds_write2st64_b64 v154, v[238:239], v[52:53] offset0:48 offset1:112
	ds_write2st64_b64 v154, v[240:241], v[56:57] offset0:52 offset1:116
	ds_write2st64_b64 v154, v[244:245], v[60:61] offset0:56 offset1:120
	ds_write2st64_b64 v154, v[246:247], v[64:65] offset0:60 offset1:124
	s_and_b64 s[2:3], s[96:97], exec
	s_cselect_b32 s4, 0x200, s62
	s_add_i32 s21, s4, s86
	s_lshl_b32 s5, s4, 2
	s_add_u32 s2, s88, s5
	v_mov_b32_e32 v2, s5
	s_waitcnt lgkmcnt(0)
	s_barrier
	s_addc_u32 s3, s89, 0
	global_load_dword v74, v2, s[88:89]
	global_load_dword v195, v2, s[94:95]
	global_load_dword v196, v235, s[2:3] offset:2048
	global_load_dword v75, v229, s[2:3]
	global_load_dword v76, v199, s[88:89]
	global_load_dword v197, v199, s[90:91]
	global_load_dword v77, v199, s[92:93]
	global_load_dword v200, v199, s[94:95]
	ds_read_b64 v[78:79], v157
	ds_read_b64 v[80:81], v159
	ds_read_b64 v[82:83], v161
	ds_read_b64 v[84:85], v163
	ds_read_b64 v[86:87], v165
	ds_read_b64 v[88:89], v167
	ds_read_b64 v[90:91], v169
	ds_read_b64 v[92:93], v170
	ds_read_b64 v[94:95], v171
	ds_read_b64 v[96:97], v172
	ds_read_b64 v[98:99], v173
	ds_read_b64 v[100:101], v174
	ds_read_b64 v[102:103], v175
	ds_read_b64 v[104:105], v176
	ds_read_b64 v[106:107], v177
	ds_read_b64 v[108:109], v178
	ds_read_b64 v[110:111], v179
	ds_read_b64 v[112:113], v180
	ds_read_b64 v[114:115], v181
	ds_read_b64 v[116:117], v182
	ds_read_b64 v[118:119], v183
	ds_read_b64 v[120:121], v184
	ds_read_b64 v[122:123], v185
	ds_read_b64 v[124:125], v186
	ds_read_b64 v[126:127], v187
	ds_read_b64 v[128:129], v188
	ds_read_b64 v[130:131], v189
	ds_read_b64 v[132:133], v190
	ds_read_b64 v[134:135], v191
	ds_read_b64 v[136:137], v192
	ds_read_b64 v[138:139], v193
	ds_read_b64 v[140:141], v194
	s_waitcnt lgkmcnt(5)
	v_pk_mov_b32 v[142:143], v[130:131], v[130:131] op_sel:[1,0]
	s_waitcnt lgkmcnt(4)
	v_pk_mov_b32 v[144:145], v[132:133], v[132:133] op_sel:[1,0]
	s_waitcnt lgkmcnt(3)
	v_pk_mov_b32 v[146:147], v[134:135], v[134:135] op_sel:[1,0]
	s_waitcnt lgkmcnt(2)
	v_pk_mov_b32 v[148:149], v[136:137], v[136:137] op_sel:[1,0]
	s_waitcnt lgkmcnt(1)
	v_pk_mov_b32 v[150:151], v[138:139], v[138:139] op_sel:[1,0]
	s_waitcnt lgkmcnt(0)
	v_pk_mov_b32 v[152:153], v[140:141], v[140:141] op_sel:[1,0]
	s_add_i32 s77, s40, s4
	s_mov_b32 s83, 0
	s_mov_b64 s[6:7], -1
	s_branch .LBB0_937

; DI f32x2 cmul(f32x2 a, f32x2 b) { return mkf2(a.x * b.x - a.y * b.y, a.x * b.y + a.y * b.x); }
; DI void fft8192(f32x2* buf, const f32x2* __restrict__ tw) {
;     ...
;   for (int ls = 0; ls < 12; ls += 2) {
;     const int s = 1 << ls;
;     f32x2 a[8], b[8], c[8], d[8];
;     __syncthreads();
; #pragma unroll
;     for (int e = 0; e < 8; ++e) {
;       const int i = tid + 256 * e;
;       const int pi = SW(i);
;       a[e] = buf[pi]; b[e] = buf[pi + 2048]; c[e] = buf[pi + 4096]; d[e] = buf[pi + 6144];
;     }
;     __syncthreads();
; #pragma unroll
;     for (int e = 0; e < 8; ++e) {
;       const int i = tid + 256 * e;
;       const int q = i & (s - 1);
;       const int ps = i - q;
;       const float rev = (float)ps * (1.f / 8192.f);
;       const f32x2 w1 = mkf2(__builtin_amdgcn_cosf(rev), -__builtin_amdgcn_sinf(rev));
;       const f32x2 w2 = cmul(w1, w1), w3 = cmul(w1, w2);
;       const f32x2 apc = mkf2(a[e].x + c[e].x, a[e].y + c[e].y), amc = mkf2(a[e].x - c[e].x, a[e].y - c[e].y);
;       const f32x2 bpd = mkf2(b[e].x + d[e].x, b[e].y + d[e].y), bmd = mkf2(b[e].x - d[e].x, b[e].y - d[e].y);
;       const int o = 4 * i - 3 * q;
;       buf[SW(o)] = mkf2(apc.x + bpd.x, apc.y + bpd.y);
;       buf[SW(o + s)] = cmul(w1, mkf2(amc.x + bmd.y, amc.y - bmd.x));
;       buf[SW(o + 2 * s)] = cmul(w2, mkf2(apc.x - bpd.x, apc.y - bpd.y));
;       buf[SW(o + 3 * s)] = cmul(w3, mkf2(amc.x - bmd.y, amc.y + bmd.x));
.Lhy_inA_done:
.LBB0_987:
	v_bfe_i32 v166, v0, 5, 1
	v_bfe_i32 v168, v0, 6, 1
	v_and_b32_e32 v166, 5, v166
	v_and_b32_e32 v168, 26, v168
	v_xor_b32_e32 v166, v166, v168
	v_xor_b32_e32 v166, v166, v0
	v_lshlrev_b32_e32 v154, 3, v166
	s_waitcnt lgkmcnt(0)
	s_barrier
	ds_read2st64_b64 v[2:5], v154 offset0:0 offset1:32
	ds_read2st64_b64 v[6:9], v154 offset0:64 offset1:96
	ds_read2st64_b64 v[10:13], v154 offset0:4 offset1:36
	ds_read2st64_b64 v[14:17], v154 offset0:68 offset1:100
	ds_read2st64_b64 v[18:21], v154 offset0:8 offset1:40
	ds_read2st64_b64 v[22:25], v154 offset0:72 offset1:104
	ds_read2st64_b64 v[26:29], v154 offset0:12 offset1:44
	ds_read2st64_b64 v[30:33], v154 offset0:76 offset1:108
	ds_read2st64_b64 v[34:37], v154 offset0:16 offset1:48
	ds_read2st64_b64 v[38:41], v154 offset0:80 offset1:112
	ds_read2st64_b64 v[42:45], v154 offset0:20 offset1:52
	ds_read2st64_b64 v[46:49], v154 offset0:84 offset1:116
	ds_read2st64_b64 v[50:53], v154 offset0:24 offset1:56
	ds_read2st64_b64 v[54:57], v154 offset0:88 offset1:120
	ds_read2st64_b64 v[58:61], v154 offset0:28 offset1:60
	ds_read2st64_b64 v[62:65], v154 offset0:92 offset1:124
	v_lshlrev_b32_e32 v164, 2, v0
	v_cvt_f32_u32_e32 v201, v0
	v_mul_f32_e32 v201, 0x39000000, v201
	v_bfe_i32 v166, v164, 5, 1
	v_bfe_i32 v168, v164, 6, 1
	v_and_b32_e32 v166, 5, v166
	v_and_b32_e32 v168, 26, v168
	v_xor_b32_e32 v166, v166, v168
	v_xor_b32_e32 v166, v166, v164
	v_lshlrev_b32_e32 v156, 3, v166
	v_xor_b32_e32 v158, 8, v156
	v_xor_b32_e32 v160, 16, v156
	v_xor_b32_e32 v162, 24, v156
	v_cos_f32_e32 v210, v201
	v_sin_f32_e64 v211, -v201
	s_waitcnt lgkmcnt(14)
	v_pk_add_f32 v[202:203], v[2:3], v[6:7]
	v_pk_add_f32 v[2:3], v[2:3], v[6:7] neg_lo:[0,1] neg_hi:[0,1]
	v_pk_add_f32 v[204:205], v[4:5], v[8:9]
	v_pk_add_f32 v[4:5], v[4:5], v[8:9] neg_lo:[0,1] neg_hi:[0,1]
	v_pk_add_f32 v[6:7], v[202:203], v[204:205]
	v_pk_add_f32 v[8:9], v[202:203], v[204:205] neg_lo:[0,1] neg_hi:[0,1]
	v_pk_add_f32 v[202:203], v[2:3], v[4:5] op_sel:[0,1] op_sel_hi:[1,0] neg_hi:[0,1]
	v_pk_add_f32 v[204:205], v[2:3], v[4:5] op_sel:[0,1] op_sel_hi:[1,0] neg_lo:[0,1]
	v_pk_mul_f32 v[206:207], v[210:211], v[210:211] op_sel:[1,1] op_sel_hi:[1,0]
	v_pk_fma_f32 v[212:213], v[210:211], v[210:211], v[206:207] op_sel_hi:[0,1,1] neg_lo:[0,0,1]
	v_pk_mul_f32 v[206:207], v[210:211], v[212:213] op_sel:[1,1] op_sel_hi:[1,0]
	v_pk_fma_f32 v[220:221], v[210:211], v[212:213], v[206:207] op_sel_hi:[0,1,1] neg_lo:[0,0,1]
	v_pk_mul_f32 v[2:3], v[210:211], v[202:203] op_sel:[1,1] op_sel_hi:[1,0]
	v_pk_fma_f32 v[2:3], v[210:211], v[202:203], v[2:3] op_sel_hi:[0,1,1] neg_lo:[0,0,1]
	v_pk_mul_f32 v[4:5], v[212:213], v[8:9] op_sel:[1,1] op_sel_hi:[1,0]
	v_pk_fma_f32 v[4:5], v[212:213], v[8:9], v[4:5] op_sel_hi:[0,1,1] neg_lo:[0,0,1]
	v_pk_mul_f32 v[8:9], v[220:221], v[204:205] op_sel:[1,1] op_sel_hi:[1,0]
	v_pk_fma_f32 v[8:9], v[220:221], v[204:205], v[8:9] op_sel_hi:[0,1,1] neg_lo:[0,0,1]
	v_add_f32_e32 v214, 0x3d000000, v201
	v_cos_f32_e32 v210, v214
	v_sin_f32_e64 v211, -v214
	s_waitcnt lgkmcnt(12)
	v_pk_add_f32 v[202:203], v[10:11], v[14:15]
	v_pk_add_f32 v[10:11], v[10:11], v[14:15] neg_lo:[0,1] neg_hi:[0,1]
	v_pk_add_f32 v[204:205], v[12:13], v[16:17]
	v_pk_add_f32 v[12:13], v[12:13], v[16:17] neg_lo:[0,1] neg_hi:[0,1]
	v_pk_add_f32 v[14:15], v[202:203], v[204:205]
	v_pk_add_f32 v[16:17], v[202:203], v[204:205] neg_lo:[0,1] neg_hi:[0,1]
	v_pk_add_f32 v[202:203], v[10:11], v[12:13] op_sel:[0,1] op_sel_hi:[1,0] neg_hi:[0,1]
	v_pk_add_f32 v[204:205], v[10:11], v[12:13] op_sel:[0,1] op_sel_hi:[1,0] neg_lo:[0,1]
	v_pk_mul_f32 v[206:207], v[210:211], v[210:211] op_sel:[1,1] op_sel_hi:[1,0]
	v_pk_fma_f32 v[212:213], v[210:211], v[210:211], v[206:207] op_sel_hi:[0,1,1] neg_lo:[0,0,1]
	v_pk_mul_f32 v[206:207], v[210:211], v[212:213] op_sel:[1,1] op_sel_hi:[1,0]
	v_pk_fma_f32 v[220:221], v[210:211], v[212:213], v[206:207] op_sel_hi:[0,1,1] neg_lo:[0,0,1]
	v_pk_mul_f32 v[10:11], v[210:211], v[202:203] op_sel:[1,1] op_sel_hi:[1,0]
	v_pk_fma_f32 v[10:11], v[210:211], v[202:203], v[10:11] op_sel_hi:[0,1,1] neg_lo:[0,0,1]
	v_pk_mul_f32 v[12:13], v[212:213], v[16:17] op_sel:[1,1] op_sel_hi:[1,0]
	v_pk_fma_f32 v[12:13], v[212:213], v[16:17], v[12:13] op_sel_hi:[0,1,1] neg_lo:[0,0,1]
	v_pk_mul_f32 v[16:17], v[220:221], v[204:205] op_sel:[1,1] op_sel_hi:[1,0]
	v_pk_fma_f32 v[16:17], v[220:221], v[204:205], v[16:17] op_sel_hi:[0,1,1] neg_lo:[0,0,1]
	v_add_f32_e32 v214, 0x3d800000, v201
	v_cos_f32_e32 v210, v214
	v_sin_f32_e64 v211, -v214
	s_waitcnt lgkmcnt(10)
	v_pk_add_f32 v[202:203], v[18:19], v[22:23]
	v_pk_add_f32 v[18:19], v[18:19], v[22:23] neg_lo:[0,1] neg_hi:[0,1]
	v_pk_add_f32 v[204:205], v[20:21], v[24:25]
	v_pk_add_f32 v[20:21], v[20:21], v[24:25] neg_lo:[0,1] neg_hi:[0,1]
	v_pk_add_f32 v[22:23], v[202:203], v[204:205]
	v_pk_add_f32 v[24:25], v[202:203], v[204:205] neg_lo:[0,1] neg_hi:[0,1]
	v_pk_add_f32 v[202:203], v[18:19], v[20:21] op_sel:[0,1] op_sel_hi:[1,0] neg_hi:[0,1]
	v_pk_add_f32 v[204:205], v[18:19], v[20:21] op_sel:[0,1] op_sel_hi:[1,0] neg_lo:[0,1]
	v_pk_mul_f32 v[206:207], v[210:211], v[210:211] op_sel:[1,1] op_sel_hi:[1,0]
	v_pk_fma_f32 v[212:213], v[210:211], v[210:211], v[206:207] op_sel_hi:[0,1,1] neg_lo:[0,0,1]
	v_pk_mul_f32 v[206:207], v[210:211], v[212:213] op_sel:[1,1] op_sel_hi:[1,0]
	v_pk_fma_f32 v[220:221], v[210:211], v[212:213], v[206:207] op_sel_hi:[0,1,1] neg_lo:[0,0,1]
	v_pk_mul_f32 v[18:19], v[210:211], v[202:203] op_sel:[1,1] op_sel_hi:[1,0]
	v_pk_fma_f32 v[18:19], v[210:211], v[202:203], v[18:19] op_sel_hi:[0,1,1] neg_lo:[0,0,1]
	v_pk_mul_f32 v[20:21], v[212:213], v[24:25] op_sel:[1,1] op_sel_hi:[1,0]
	v_pk_fma_f32 v[20:21], v[212:213], v[24:25], v[20:21] op_sel_hi:[0,1,1] neg_lo:[0,0,1]
	v_pk_mul_f32 v[24:25], v[220:221], v[204:205] op_sel:[1,1] op_sel_hi:[1,0]
	v_pk_fma_f32 v[24:25], v[220:221], v[204:205], v[24:25] op_sel_hi:[0,1,1] neg_lo:[0,0,1]
	v_add_f32_e32 v214, 0x3dc00000, v201
	v_cos_f32_e32 v210, v214
	v_sin_f32_e64 v211, -v214
	s_waitcnt lgkmcnt(8)
; DI f32x2 cmul(f32x2 a, f32x2 b) { return mkf2(a.x * b.x - a.y * b.y, a.x * b.y + a.y * b.x); }
; DI void fft8192(f32x2* buf, const f32x2* __restrict__ tw) {
;     ...
; #pragma unroll
;     for (int e = 0; e < 8; ++e) {
;       const int i = tid + 256 * e;
;       const int q = i & (s - 1);
;       const int ps = i - q;
;       const float rev = (float)ps * (1.f / 8192.f);
;       const f32x2 w1 = mkf2(__builtin_amdgcn_cosf(rev), -__builtin_amdgcn_sinf(rev));
;       const f32x2 w2 = cmul(w1, w1), w3 = cmul(w1, w2);
;       const f32x2 apc = mkf2(a[e].x + c[e].x, a[e].y + c[e].y), amc = mkf2(a[e].x - c[e].x, a[e].y - c[e].y);
;       const f32x2 bpd = mkf2(b[e].x + d[e].x, b[e].y + d[e].y), bmd = mkf2(b[e].x - d[e].x, b[e].y - d[e].y);
;       const int o = 4 * i - 3 * q;
;       buf[SW(o)] = mkf2(apc.x + bpd.x, apc.y + bpd.y);
;       buf[SW(o + s)] = cmul(w1, mkf2(amc.x + bmd.y, amc.y - bmd.x));
;       buf[SW(o + 2 * s)] = cmul(w2, mkf2(apc.x - bpd.x, apc.y - bpd.y));
;       buf[SW(o + 3 * s)] = cmul(w3, mkf2(amc.x - bmd.y, amc.y + bmd.x));
	v_pk_add_f32 v[202:203], v[26:27], v[30:31]
	v_pk_add_f32 v[26:27], v[26:27], v[30:31] neg_lo:[0,1] neg_hi:[0,1]
	v_pk_add_f32 v[204:205], v[28:29], v[32:33]
	v_pk_add_f32 v[28:29], v[28:29], v[32:33] neg_lo:[0,1] neg_hi:[0,1]
	v_pk_add_f32 v[30:31], v[202:203], v[204:205]
	v_pk_add_f32 v[32:33], v[202:203], v[204:205] neg_lo:[0,1] neg_hi:[0,1]
	v_pk_add_f32 v[202:203], v[26:27], v[28:29] op_sel:[0,1] op_sel_hi:[1,0] neg_hi:[0,1]
	v_pk_add_f32 v[204:205], v[26:27], v[28:29] op_sel:[0,1] op_sel_hi:[1,0] neg_lo:[0,1]
	v_pk_mul_f32 v[206:207], v[210:211], v[210:211] op_sel:[1,1] op_sel_hi:[1,0]
	v_pk_fma_f32 v[212:213], v[210:211], v[210:211], v[206:207] op_sel_hi:[0,1,1] neg_lo:[0,0,1]
	v_pk_mul_f32 v[206:207], v[210:211], v[212:213] op_sel:[1,1] op_sel_hi:[1,0]
	v_pk_fma_f32 v[220:221], v[210:211], v[212:213], v[206:207] op_sel_hi:[0,1,1] neg_lo:[0,0,1]
	v_pk_mul_f32 v[26:27], v[210:211], v[202:203] op_sel:[1,1] op_sel_hi:[1,0]
	v_pk_fma_f32 v[26:27], v[210:211], v[202:203], v[26:27] op_sel_hi:[0,1,1] neg_lo:[0,0,1]
	v_pk_mul_f32 v[28:29], v[212:213], v[32:33] op_sel:[1,1] op_sel_hi:[1,0]
	v_pk_fma_f32 v[28:29], v[212:213], v[32:33], v[28:29] op_sel_hi:[0,1,1] neg_lo:[0,0,1]
	v_pk_mul_f32 v[32:33], v[220:221], v[204:205] op_sel:[1,1] op_sel_hi:[1,0]
	v_pk_fma_f32 v[32:33], v[220:221], v[204:205], v[32:33] op_sel_hi:[0,1,1] neg_lo:[0,0,1]
	v_add_f32_e32 v214, 0x3e000000, v201
	v_cos_f32_e32 v210, v214
	v_sin_f32_e64 v211, -v214
	s_waitcnt lgkmcnt(6)
	v_pk_add_f32 v[202:203], v[34:35], v[38:39]
	v_pk_add_f32 v[34:35], v[34:35], v[38:39] neg_lo:[0,1] neg_hi:[0,1]
	v_pk_add_f32 v[204:205], v[36:37], v[40:41]
	v_pk_add_f32 v[36:37], v[36:37], v[40:41] neg_lo:[0,1] neg_hi:[0,1]
	v_pk_add_f32 v[38:39], v[202:203], v[204:205]
	v_pk_add_f32 v[40:41], v[202:203], v[204:205] neg_lo:[0,1] neg_hi:[0,1]
	v_pk_add_f32 v[202:203], v[34:35], v[36:37] op_sel:[0,1] op_sel_hi:[1,0] neg_hi:[0,1]
	v_pk_add_f32 v[204:205], v[34:35], v[36:37] op_sel:[0,1] op_sel_hi:[1,0] neg_lo:[0,1]
	v_pk_mul_f32 v[206:207], v[210:211], v[210:211] op_sel:[1,1] op_sel_hi:[1,0]
	v_pk_fma_f32 v[212:213], v[210:211], v[210:211], v[206:207] op_sel_hi:[0,1,1] neg_lo:[0,0,1]
	v_pk_mul_f32 v[206:207], v[210:211], v[212:213] op_sel:[1,1] op_sel_hi:[1,0]
	v_pk_fma_f32 v[220:221], v[210:211], v[212:213], v[206:207] op_sel_hi:[0,1,1] neg_lo:[0,0,1]
	v_pk_mul_f32 v[34:35], v[210:211], v[202:203] op_sel:[1,1] op_sel_hi:[1,0]
	v_pk_fma_f32 v[34:35], v[210:211], v[202:203], v[34:35] op_sel_hi:[0,1,1] neg_lo:[0,0,1]
	v_pk_mul_f32 v[36:37], v[212:213], v[40:41] op_sel:[1,1] op_sel_hi:[1,0]
	v_pk_fma_f32 v[36:37], v[212:213], v[40:41], v[36:37] op_sel_hi:[0,1,1] neg_lo:[0,0,1]
	v_pk_mul_f32 v[40:41], v[220:221], v[204:205] op_sel:[1,1] op_sel_hi:[1,0]
	v_pk_fma_f32 v[40:41], v[220:221], v[204:205], v[40:41] op_sel_hi:[0,1,1] neg_lo:[0,0,1]
	v_add_f32_e32 v214, 0x3e200000, v201
	v_cos_f32_e32 v210, v214
	v_sin_f32_e64 v211, -v214
	s_waitcnt lgkmcnt(4)
	v_pk_add_f32 v[202:203], v[42:43], v[46:47]
	v_pk_add_f32 v[42:43], v[42:43], v[46:47] neg_lo:[0,1] neg_hi:[0,1]
	v_pk_add_f32 v[204:205], v[44:45], v[48:49]
	v_pk_add_f32 v[44:45], v[44:45], v[48:49] neg_lo:[0,1] neg_hi:[0,1]
	v_pk_add_f32 v[46:47], v[202:203], v[204:205]
	v_pk_add_f32 v[48:49], v[202:203], v[204:205] neg_lo:[0,1] neg_hi:[0,1]
	v_pk_add_f32 v[202:203], v[42:43], v[44:45] op_sel:[0,1] op_sel_hi:[1,0] neg_hi:[0,1]
	v_pk_add_f32 v[204:205], v[42:43], v[44:45] op_sel:[0,1] op_sel_hi:[1,0] neg_lo:[0,1]
	v_pk_mul_f32 v[206:207], v[210:211], v[210:211] op_sel:[1,1] op_sel_hi:[1,0]
	v_pk_fma_f32 v[212:213], v[210:211], v[210:211], v[206:207] op_sel_hi:[0,1,1] neg_lo:[0,0,1]
	v_pk_mul_f32 v[206:207], v[210:211], v[212:213] op_sel:[1,1] op_sel_hi:[1,0]
	v_pk_fma_f32 v[220:221], v[210:211], v[212:213], v[206:207] op_sel_hi:[0,1,1] neg_lo:[0,0,1]
	v_pk_mul_f32 v[42:43], v[210:211], v[202:203] op_sel:[1,1] op_sel_hi:[1,0]
	v_pk_fma_f32 v[42:43], v[210:211], v[202:203], v[42:43] op_sel_hi:[0,1,1] neg_lo:[0,0,1]
	v_pk_mul_f32 v[44:45], v[212:213], v[48:49] op_sel:[1,1] op_sel_hi:[1,0]
	v_pk_fma_f32 v[44:45], v[212:213], v[48:49], v[44:45] op_sel_hi:[0,1,1] neg_lo:[0,0,1]
	v_pk_mul_f32 v[48:49], v[220:221], v[204:205] op_sel:[1,1] op_sel_hi:[1,0]
	v_pk_fma_f32 v[48:49], v[220:221], v[204:205], v[48:49] op_sel_hi:[0,1,1] neg_lo:[0,0,1]
	v_add_f32_e32 v214, 0x3e400000, v201
	v_cos_f32_e32 v210, v214
	v_sin_f32_e64 v211, -v214
	s_waitcnt lgkmcnt(2)
	v_pk_add_f32 v[202:203], v[50:51], v[54:55]
	v_pk_add_f32 v[50:51], v[50:51], v[54:55] neg_lo:[0,1] neg_hi:[0,1]
	v_pk_add_f32 v[204:205], v[52:53], v[56:57]
	v_pk_add_f32 v[52:53], v[52:53], v[56:57] neg_lo:[0,1] neg_hi:[0,1]
	v_pk_add_f32 v[54:55], v[202:203], v[204:205]
	v_pk_add_f32 v[56:57], v[202:203], v[204:205] neg_lo:[0,1] neg_hi:[0,1]
	v_pk_add_f32 v[202:203], v[50:51], v[52:53] op_sel:[0,1] op_sel_hi:[1,0] neg_hi:[0,1]
	v_pk_add_f32 v[204:205], v[50:51], v[52:53] op_sel:[0,1] op_sel_hi:[1,0] neg_lo:[0,1]
	v_pk_mul_f32 v[206:207], v[210:211], v[210:211] op_sel:[1,1] op_sel_hi:[1,0]
	v_pk_fma_f32 v[212:213], v[210:211], v[210:211], v[206:207] op_sel_hi:[0,1,1] neg_lo:[0,0,1]
	v_pk_mul_f32 v[206:207], v[210:211], v[212:213] op_sel:[1,1] op_sel_hi:[1,0]
	v_pk_fma_f32 v[220:221], v[210:211], v[212:213], v[206:207] op_sel_hi:[0,1,1] neg_lo:[0,0,1]
	v_pk_mul_f32 v[50:51], v[210:211], v[202:203] op_sel:[1,1] op_sel_hi:[1,0]
	v_pk_fma_f32 v[50:51], v[210:211], v[202:203], v[50:51] op_sel_hi:[0,1,1] neg_lo:[0,0,1]
	v_pk_mul_f32 v[52:53], v[212:213], v[56:57] op_sel:[1,1] op_sel_hi:[1,0]
	v_pk_fma_f32 v[52:53], v[212:213], v[56:57], v[52:53] op_sel_hi:[0,1,1] neg_lo:[0,0,1]
	v_pk_mul_f32 v[56:57], v[220:221], v[204:205] op_sel:[1,1] op_sel_hi:[1,0]
	v_pk_fma_f32 v[56:57], v[220:221], v[204:205], v[56:57] op_sel_hi:[0,1,1] neg_lo:[0,0,1]
	v_add_f32_e32 v214, 0x3e600000, v201
	v_cos_f32_e32 v210, v214
	v_sin_f32_e64 v211, -v214
	s_waitcnt lgkmcnt(0)
; DI f32x2 cmul(f32x2 a, f32x2 b) { return mkf2(a.x * b.x - a.y * b.y, a.x * b.y + a.y * b.x); }
; DI void fft8192(f32x2* buf, const f32x2* __restrict__ tw) {
;     ...
;     __syncthreads();
; #pragma unroll
;     for (int e = 0; e < 8; ++e) {
;       const int i = tid + 256 * e;
;       const int pi = SW(i);
;       a[e] = buf[pi]; b[e] = buf[pi + 2048]; c[e] = buf[pi + 4096]; d[e] = buf[pi + 6144];
;     }
;     __syncthreads();
; #pragma unroll
;     for (int e = 0; e < 8; ++e) {
;       const int i = tid + 256 * e;
;       const int q = i & (s - 1);
;       const int ps = i - q;
;       const float rev = (float)ps * (1.f / 8192.f);
;       const f32x2 w1 = mkf2(__builtin_amdgcn_cosf(rev), -__builtin_amdgcn_sinf(rev));
;       const f32x2 w2 = cmul(w1, w1), w3 = cmul(w1, w2);
;       const f32x2 apc = mkf2(a[e].x + c[e].x, a[e].y + c[e].y), amc = mkf2(a[e].x - c[e].x, a[e].y - c[e].y);
;       const f32x2 bpd = mkf2(b[e].x + d[e].x, b[e].y + d[e].y), bmd = mkf2(b[e].x - d[e].x, b[e].y - d[e].y);
;       const int o = 4 * i - 3 * q;
;       buf[SW(o)] = mkf2(apc.x + bpd.x, apc.y + bpd.y);
;       buf[SW(o + s)] = cmul(w1, mkf2(amc.x + bmd.y, amc.y - bmd.x));
;       buf[SW(o + 2 * s)] = cmul(w2, mkf2(apc.x - bpd.x, apc.y - bpd.y));
;       buf[SW(o + 3 * s)] = cmul(w3, mkf2(amc.x - bmd.y, amc.y + bmd.x));
;     }
	v_pk_add_f32 v[202:203], v[58:59], v[62:63]
	v_pk_add_f32 v[58:59], v[58:59], v[62:63] neg_lo:[0,1] neg_hi:[0,1]
	v_pk_add_f32 v[204:205], v[60:61], v[64:65]
	v_pk_add_f32 v[60:61], v[60:61], v[64:65] neg_lo:[0,1] neg_hi:[0,1]
	v_pk_add_f32 v[62:63], v[202:203], v[204:205]
	v_pk_add_f32 v[64:65], v[202:203], v[204:205] neg_lo:[0,1] neg_hi:[0,1]
	v_pk_add_f32 v[202:203], v[58:59], v[60:61] op_sel:[0,1] op_sel_hi:[1,0] neg_hi:[0,1]
	v_pk_add_f32 v[204:205], v[58:59], v[60:61] op_sel:[0,1] op_sel_hi:[1,0] neg_lo:[0,1]
	v_pk_mul_f32 v[206:207], v[210:211], v[210:211] op_sel:[1,1] op_sel_hi:[1,0]
	v_pk_fma_f32 v[212:213], v[210:211], v[210:211], v[206:207] op_sel_hi:[0,1,1] neg_lo:[0,0,1]
	v_pk_mul_f32 v[206:207], v[210:211], v[212:213] op_sel:[1,1] op_sel_hi:[1,0]
	v_pk_fma_f32 v[220:221], v[210:211], v[212:213], v[206:207] op_sel_hi:[0,1,1] neg_lo:[0,0,1]
	v_pk_mul_f32 v[58:59], v[210:211], v[202:203] op_sel:[1,1] op_sel_hi:[1,0]
	v_pk_fma_f32 v[58:59], v[210:211], v[202:203], v[58:59] op_sel_hi:[0,1,1] neg_lo:[0,0,1]
	v_pk_mul_f32 v[60:61], v[212:213], v[64:65] op_sel:[1,1] op_sel_hi:[1,0]
	v_pk_fma_f32 v[60:61], v[212:213], v[64:65], v[60:61] op_sel_hi:[0,1,1] neg_lo:[0,0,1]
	v_pk_mul_f32 v[64:65], v[220:221], v[204:205] op_sel:[1,1] op_sel_hi:[1,0]
	v_pk_fma_f32 v[64:65], v[220:221], v[204:205], v[64:65] op_sel_hi:[0,1,1] neg_lo:[0,0,1]
	s_barrier
	ds_write_b64 v156, v[6:7] offset:0
	ds_write_b64 v158, v[2:3] offset:0
	ds_write_b64 v160, v[4:5] offset:0
	ds_write_b64 v162, v[8:9] offset:0
	ds_write_b64 v156, v[14:15] offset:8192
	ds_write_b64 v158, v[10:11] offset:8192
	ds_write_b64 v160, v[12:13] offset:8192
	ds_write_b64 v162, v[16:17] offset:8192
	ds_write_b64 v156, v[22:23] offset:16384
	ds_write_b64 v158, v[18:19] offset:16384
	ds_write_b64 v160, v[20:21] offset:16384
	ds_write_b64 v162, v[24:25] offset:16384
	ds_write_b64 v156, v[30:31] offset:24576
	ds_write_b64 v158, v[26:27] offset:24576
	ds_write_b64 v160, v[28:29] offset:24576
	ds_write_b64 v162, v[32:33] offset:24576
	ds_write_b64 v156, v[38:39] offset:32768
	ds_write_b64 v158, v[34:35] offset:32768
	ds_write_b64 v160, v[36:37] offset:32768
	ds_write_b64 v162, v[40:41] offset:32768
	ds_write_b64 v156, v[46:47] offset:40960
	ds_write_b64 v158, v[42:43] offset:40960
	ds_write_b64 v160, v[44:45] offset:40960
	ds_write_b64 v162, v[48:49] offset:40960
	ds_write_b64 v156, v[54:55] offset:49152
	ds_write_b64 v158, v[50:51] offset:49152
	ds_write_b64 v160, v[52:53] offset:49152
	ds_write_b64 v162, v[56:57] offset:49152
	ds_write_b64 v156, v[62:63] offset:57344
	ds_write_b64 v158, v[58:59] offset:57344
	ds_write_b64 v160, v[60:61] offset:57344
	ds_write_b64 v162, v[64:65] offset:57344
	s_waitcnt lgkmcnt(0)
	s_barrier
	ds_read2st64_b64 v[2:5], v154 offset0:0 offset1:32
	ds_read2st64_b64 v[6:9], v154 offset0:64 offset1:96
	ds_read2st64_b64 v[10:13], v154 offset0:4 offset1:36
	ds_read2st64_b64 v[14:17], v154 offset0:68 offset1:100
	ds_read2st64_b64 v[18:21], v154 offset0:8 offset1:40
	ds_read2st64_b64 v[22:25], v154 offset0:72 offset1:104
	ds_read2st64_b64 v[26:29], v154 offset0:12 offset1:44
	ds_read2st64_b64 v[30:33], v154 offset0:76 offset1:108
	ds_read2st64_b64 v[34:37], v154 offset0:16 offset1:48
	ds_read2st64_b64 v[38:41], v154 offset0:80 offset1:112
	ds_read2st64_b64 v[42:45], v154 offset0:20 offset1:52
	ds_read2st64_b64 v[46:49], v154 offset0:84 offset1:116
	ds_read2st64_b64 v[50:53], v154 offset0:24 offset1:56
	ds_read2st64_b64 v[54:57], v154 offset0:88 offset1:120
	ds_read2st64_b64 v[58:61], v154 offset0:28 offset1:60
	ds_read2st64_b64 v[62:65], v154 offset0:92 offset1:124
	v_and_b32_e32 v166, 3, v0
	v_lshlrev_b32_e32 v164, 2, v0
	v_mad_i32_i24 v164, v166, -3, v164
	v_sub_u32_e32 v166, v0, v166
	v_cvt_f32_u32_e32 v201, v166
	v_mul_f32_e32 v201, 0x39000000, v201
	v_bfe_i32 v166, v164, 5, 1
	v_bfe_i32 v168, v164, 6, 1
	v_and_b32_e32 v166, 5, v166
	v_and_b32_e32 v168, 26, v168
	v_xor_b32_e32 v166, v166, v168
	v_xor_b32_e32 v166, v166, v164
	v_lshlrev_b32_e32 v156, 3, v166
	v_xor_b32_e32 v158, 32, v156
	v_xor_b32_e32 v160, 64, v156
	v_xor_b32_e32 v162, 0x60, v156
	v_cos_f32_e32 v210, v201
	v_sin_f32_e64 v211, -v201
	s_waitcnt lgkmcnt(14)
	v_pk_add_f32 v[202:203], v[2:3], v[6:7]
	v_pk_add_f32 v[2:3], v[2:3], v[6:7] neg_lo:[0,1] neg_hi:[0,1]
	v_pk_add_f32 v[204:205], v[4:5], v[8:9]
	v_pk_add_f32 v[4:5], v[4:5], v[8:9] neg_lo:[0,1] neg_hi:[0,1]
	v_pk_add_f32 v[6:7], v[202:203], v[204:205]
	v_pk_add_f32 v[8:9], v[202:203], v[204:205] neg_lo:[0,1] neg_hi:[0,1]
	v_pk_add_f32 v[202:203], v[2:3], v[4:5] op_sel:[0,1] op_sel_hi:[1,0] neg_hi:[0,1]
	v_pk_add_f32 v[204:205], v[2:3], v[4:5] op_sel:[0,1] op_sel_hi:[1,0] neg_lo:[0,1]
	v_pk_mul_f32 v[206:207], v[210:211], v[210:211] op_sel:[1,1] op_sel_hi:[1,0]
	v_pk_fma_f32 v[212:213], v[210:211], v[210:211], v[206:207] op_sel_hi:[0,1,1] neg_lo:[0,0,1]
	v_pk_mul_f32 v[206:207], v[210:211], v[212:213] op_sel:[1,1] op_sel_hi:[1,0]
	v_pk_fma_f32 v[220:221], v[210:211], v[212:213], v[206:207] op_sel_hi:[0,1,1] neg_lo:[0,0,1]
	v_pk_mul_f32 v[2:3], v[210:211], v[202:203] op_sel:[1,1] op_sel_hi:[1,0]
	v_pk_fma_f32 v[2:3], v[210:211], v[202:203], v[2:3] op_sel_hi:[0,1,1] neg_lo:[0,0,1]
	v_pk_mul_f32 v[4:5], v[212:213], v[8:9] op_sel:[1,1] op_sel_hi:[1,0]
	v_pk_fma_f32 v[4:5], v[212:213], v[8:9], v[4:5] op_sel_hi:[0,1,1] neg_lo:[0,0,1]
	v_pk_mul_f32 v[8:9], v[220:221], v[204:205] op_sel:[1,1] op_sel_hi:[1,0]
	v_pk_fma_f32 v[8:9], v[220:221], v[204:205], v[8:9] op_sel_hi:[0,1,1] neg_lo:[0,0,1]
	v_add_f32_e32 v214, 0x3d000000, v201
	v_cos_f32_e32 v210, v214
	v_sin_f32_e64 v211, -v214
	s_waitcnt lgkmcnt(12)
; DI f32x2 cmul(f32x2 a, f32x2 b) { return mkf2(a.x * b.x - a.y * b.y, a.x * b.y + a.y * b.x); }
; DI void fft8192(f32x2* buf, const f32x2* __restrict__ tw) {
;     ...
; #pragma unroll
;     for (int e = 0; e < 8; ++e) {
;       const int i = tid + 256 * e;
;       const int q = i & (s - 1);
;       const int ps = i - q;
;       const float rev = (float)ps * (1.f / 8192.f);
;       const f32x2 w1 = mkf2(__builtin_amdgcn_cosf(rev), -__builtin_amdgcn_sinf(rev));
;       const f32x2 w2 = cmul(w1, w1), w3 = cmul(w1, w2);
;       const f32x2 apc = mkf2(a[e].x + c[e].x, a[e].y + c[e].y), amc = mkf2(a[e].x - c[e].x, a[e].y - c[e].y);
;       const f32x2 bpd = mkf2(b[e].x + d[e].x, b[e].y + d[e].y), bmd = mkf2(b[e].x - d[e].x, b[e].y - d[e].y);
;       const int o = 4 * i - 3 * q;
;       buf[SW(o)] = mkf2(apc.x + bpd.x, apc.y + bpd.y);
;       buf[SW(o + s)] = cmul(w1, mkf2(amc.x + bmd.y, amc.y - bmd.x));
;       buf[SW(o + 2 * s)] = cmul(w2, mkf2(apc.x - bpd.x, apc.y - bpd.y));
;       buf[SW(o + 3 * s)] = cmul(w3, mkf2(amc.x - bmd.y, amc.y + bmd.x));
	v_pk_add_f32 v[202:203], v[10:11], v[14:15]
	v_pk_add_f32 v[10:11], v[10:11], v[14:15] neg_lo:[0,1] neg_hi:[0,1]
	v_pk_add_f32 v[204:205], v[12:13], v[16:17]
	v_pk_add_f32 v[12:13], v[12:13], v[16:17] neg_lo:[0,1] neg_hi:[0,1]
	v_pk_add_f32 v[14:15], v[202:203], v[204:205]
	v_pk_add_f32 v[16:17], v[202:203], v[204:205] neg_lo:[0,1] neg_hi:[0,1]
	v_pk_add_f32 v[202:203], v[10:11], v[12:13] op_sel:[0,1] op_sel_hi:[1,0] neg_hi:[0,1]
	v_pk_add_f32 v[204:205], v[10:11], v[12:13] op_sel:[0,1] op_sel_hi:[1,0] neg_lo:[0,1]
	v_pk_mul_f32 v[206:207], v[210:211], v[210:211] op_sel:[1,1] op_sel_hi:[1,0]
	v_pk_fma_f32 v[212:213], v[210:211], v[210:211], v[206:207] op_sel_hi:[0,1,1] neg_lo:[0,0,1]
	v_pk_mul_f32 v[206:207], v[210:211], v[212:213] op_sel:[1,1] op_sel_hi:[1,0]
	v_pk_fma_f32 v[220:221], v[210:211], v[212:213], v[206:207] op_sel_hi:[0,1,1] neg_lo:[0,0,1]
	v_pk_mul_f32 v[10:11], v[210:211], v[202:203] op_sel:[1,1] op_sel_hi:[1,0]
	v_pk_fma_f32 v[10:11], v[210:211], v[202:203], v[10:11] op_sel_hi:[0,1,1] neg_lo:[0,0,1]
	v_pk_mul_f32 v[12:13], v[212:213], v[16:17] op_sel:[1,1] op_sel_hi:[1,0]
	v_pk_fma_f32 v[12:13], v[212:213], v[16:17], v[12:13] op_sel_hi:[0,1,1] neg_lo:[0,0,1]
	v_pk_mul_f32 v[16:17], v[220:221], v[204:205] op_sel:[1,1] op_sel_hi:[1,0]
	v_pk_fma_f32 v[16:17], v[220:221], v[204:205], v[16:17] op_sel_hi:[0,1,1] neg_lo:[0,0,1]
	v_add_f32_e32 v214, 0x3d800000, v201
	v_cos_f32_e32 v210, v214
	v_sin_f32_e64 v211, -v214
	s_waitcnt lgkmcnt(10)
	v_pk_add_f32 v[202:203], v[18:19], v[22:23]
	v_pk_add_f32 v[18:19], v[18:19], v[22:23] neg_lo:[0,1] neg_hi:[0,1]
	v_pk_add_f32 v[204:205], v[20:21], v[24:25]
	v_pk_add_f32 v[20:21], v[20:21], v[24:25] neg_lo:[0,1] neg_hi:[0,1]
	v_pk_add_f32 v[22:23], v[202:203], v[204:205]
	v_pk_add_f32 v[24:25], v[202:203], v[204:205] neg_lo:[0,1] neg_hi:[0,1]
	v_pk_add_f32 v[202:203], v[18:19], v[20:21] op_sel:[0,1] op_sel_hi:[1,0] neg_hi:[0,1]
	v_pk_add_f32 v[204:205], v[18:19], v[20:21] op_sel:[0,1] op_sel_hi:[1,0] neg_lo:[0,1]
	v_pk_mul_f32 v[206:207], v[210:211], v[210:211] op_sel:[1,1] op_sel_hi:[1,0]
	v_pk_fma_f32 v[212:213], v[210:211], v[210:211], v[206:207] op_sel_hi:[0,1,1] neg_lo:[0,0,1]
	v_pk_mul_f32 v[206:207], v[210:211], v[212:213] op_sel:[1,1] op_sel_hi:[1,0]
	v_pk_fma_f32 v[220:221], v[210:211], v[212:213], v[206:207] op_sel_hi:[0,1,1] neg_lo:[0,0,1]
	v_pk_mul_f32 v[18:19], v[210:211], v[202:203] op_sel:[1,1] op_sel_hi:[1,0]
	v_pk_fma_f32 v[18:19], v[210:211], v[202:203], v[18:19] op_sel_hi:[0,1,1] neg_lo:[0,0,1]
	v_pk_mul_f32 v[20:21], v[212:213], v[24:25] op_sel:[1,1] op_sel_hi:[1,0]
	v_pk_fma_f32 v[20:21], v[212:213], v[24:25], v[20:21] op_sel_hi:[0,1,1] neg_lo:[0,0,1]
	v_pk_mul_f32 v[24:25], v[220:221], v[204:205] op_sel:[1,1] op_sel_hi:[1,0]
	v_pk_fma_f32 v[24:25], v[220:221], v[204:205], v[24:25] op_sel_hi:[0,1,1] neg_lo:[0,0,1]
	v_add_f32_e32 v214, 0x3dc00000, v201
	v_cos_f32_e32 v210, v214
	v_sin_f32_e64 v211, -v214
	s_waitcnt lgkmcnt(8)
	v_pk_add_f32 v[202:203], v[26:27], v[30:31]
	v_pk_add_f32 v[26:27], v[26:27], v[30:31] neg_lo:[0,1] neg_hi:[0,1]
	v_pk_add_f32 v[204:205], v[28:29], v[32:33]
	v_pk_add_f32 v[28:29], v[28:29], v[32:33] neg_lo:[0,1] neg_hi:[0,1]
	v_pk_add_f32 v[30:31], v[202:203], v[204:205]
	v_pk_add_f32 v[32:33], v[202:203], v[204:205] neg_lo:[0,1] neg_hi:[0,1]
	v_pk_add_f32 v[202:203], v[26:27], v[28:29] op_sel:[0,1] op_sel_hi:[1,0] neg_hi:[0,1]
	v_pk_add_f32 v[204:205], v[26:27], v[28:29] op_sel:[0,1] op_sel_hi:[1,0] neg_lo:[0,1]
	v_pk_mul_f32 v[206:207], v[210:211], v[210:211] op_sel:[1,1] op_sel_hi:[1,0]
	v_pk_fma_f32 v[212:213], v[210:211], v[210:211], v[206:207] op_sel_hi:[0,1,1] neg_lo:[0,0,1]
	v_pk_mul_f32 v[206:207], v[210:211], v[212:213] op_sel:[1,1] op_sel_hi:[1,0]
	v_pk_fma_f32 v[220:221], v[210:211], v[212:213], v[206:207] op_sel_hi:[0,1,1] neg_lo:[0,0,1]
	v_pk_mul_f32 v[26:27], v[210:211], v[202:203] op_sel:[1,1] op_sel_hi:[1,0]
	v_pk_fma_f32 v[26:27], v[210:211], v[202:203], v[26:27] op_sel_hi:[0,1,1] neg_lo:[0,0,1]
	v_pk_mul_f32 v[28:29], v[212:213], v[32:33] op_sel:[1,1] op_sel_hi:[1,0]
	v_pk_fma_f32 v[28:29], v[212:213], v[32:33], v[28:29] op_sel_hi:[0,1,1] neg_lo:[0,0,1]
	v_pk_mul_f32 v[32:33], v[220:221], v[204:205] op_sel:[1,1] op_sel_hi:[1,0]
	v_pk_fma_f32 v[32:33], v[220:221], v[204:205], v[32:33] op_sel_hi:[0,1,1] neg_lo:[0,0,1]
	v_add_f32_e32 v214, 0x3e000000, v201
	v_cos_f32_e32 v210, v214
	v_sin_f32_e64 v211, -v214
	s_waitcnt lgkmcnt(6)
	v_pk_add_f32 v[202:203], v[34:35], v[38:39]
	v_pk_add_f32 v[34:35], v[34:35], v[38:39] neg_lo:[0,1] neg_hi:[0,1]
	v_pk_add_f32 v[204:205], v[36:37], v[40:41]
	v_pk_add_f32 v[36:37], v[36:37], v[40:41] neg_lo:[0,1] neg_hi:[0,1]
	v_pk_add_f32 v[38:39], v[202:203], v[204:205]
	v_pk_add_f32 v[40:41], v[202:203], v[204:205] neg_lo:[0,1] neg_hi:[0,1]
	v_pk_add_f32 v[202:203], v[34:35], v[36:37] op_sel:[0,1] op_sel_hi:[1,0] neg_hi:[0,1]
	v_pk_add_f32 v[204:205], v[34:35], v[36:37] op_sel:[0,1] op_sel_hi:[1,0] neg_lo:[0,1]
	v_pk_mul_f32 v[206:207], v[210:211], v[210:211] op_sel:[1,1] op_sel_hi:[1,0]
	v_pk_fma_f32 v[212:213], v[210:211], v[210:211], v[206:207] op_sel_hi:[0,1,1] neg_lo:[0,0,1]
	v_pk_mul_f32 v[206:207], v[210:211], v[212:213] op_sel:[1,1] op_sel_hi:[1,0]
	v_pk_fma_f32 v[220:221], v[210:211], v[212:213], v[206:207] op_sel_hi:[0,1,1] neg_lo:[0,0,1]
	v_pk_mul_f32 v[34:35], v[210:211], v[202:203] op_sel:[1,1] op_sel_hi:[1,0]
	v_pk_fma_f32 v[34:35], v[210:211], v[202:203], v[34:35] op_sel_hi:[0,1,1] neg_lo:[0,0,1]
	v_pk_mul_f32 v[36:37], v[212:213], v[40:41] op_sel:[1,1] op_sel_hi:[1,0]
	v_pk_fma_f32 v[36:37], v[212:213], v[40:41], v[36:37] op_sel_hi:[0,1,1] neg_lo:[0,0,1]
	v_pk_mul_f32 v[40:41], v[220:221], v[204:205] op_sel:[1,1] op_sel_hi:[1,0]
	v_pk_fma_f32 v[40:41], v[220:221], v[204:205], v[40:41] op_sel_hi:[0,1,1] neg_lo:[0,0,1]
	v_add_f32_e32 v214, 0x3e200000, v201
	v_cos_f32_e32 v210, v214
	v_sin_f32_e64 v211, -v214
	s_waitcnt lgkmcnt(4)
; DI f32x2 cmul(f32x2 a, f32x2 b) { return mkf2(a.x * b.x - a.y * b.y, a.x * b.y + a.y * b.x); }
; DI void fft8192(f32x2* buf, const f32x2* __restrict__ tw) {
;     ...
; #pragma unroll
;     for (int e = 0; e < 8; ++e) {
;       const int i = tid + 256 * e;
;       const int q = i & (s - 1);
;       const int ps = i - q;
;       const float rev = (float)ps * (1.f / 8192.f);
;       const f32x2 w1 = mkf2(__builtin_amdgcn_cosf(rev), -__builtin_amdgcn_sinf(rev));
;       const f32x2 w2 = cmul(w1, w1), w3 = cmul(w1, w2);
;       const f32x2 apc = mkf2(a[e].x + c[e].x, a[e].y + c[e].y), amc = mkf2(a[e].x - c[e].x, a[e].y - c[e].y);
;       const f32x2 bpd = mkf2(b[e].x + d[e].x, b[e].y + d[e].y), bmd = mkf2(b[e].x - d[e].x, b[e].y - d[e].y);
;       const int o = 4 * i - 3 * q;
;       buf[SW(o)] = mkf2(apc.x + bpd.x, apc.y + bpd.y);
;       buf[SW(o + s)] = cmul(w1, mkf2(amc.x + bmd.y, amc.y - bmd.x));
;       buf[SW(o + 2 * s)] = cmul(w2, mkf2(apc.x - bpd.x, apc.y - bpd.y));
;       buf[SW(o + 3 * s)] = cmul(w3, mkf2(amc.x - bmd.y, amc.y + bmd.x));
;     }
	v_pk_add_f32 v[202:203], v[42:43], v[46:47]
	v_pk_add_f32 v[42:43], v[42:43], v[46:47] neg_lo:[0,1] neg_hi:[0,1]
	v_pk_add_f32 v[204:205], v[44:45], v[48:49]
	v_pk_add_f32 v[44:45], v[44:45], v[48:49] neg_lo:[0,1] neg_hi:[0,1]
	v_pk_add_f32 v[46:47], v[202:203], v[204:205]
	v_pk_add_f32 v[48:49], v[202:203], v[204:205] neg_lo:[0,1] neg_hi:[0,1]
	v_pk_add_f32 v[202:203], v[42:43], v[44:45] op_sel:[0,1] op_sel_hi:[1,0] neg_hi:[0,1]
	v_pk_add_f32 v[204:205], v[42:43], v[44:45] op_sel:[0,1] op_sel_hi:[1,0] neg_lo:[0,1]
	v_pk_mul_f32 v[206:207], v[210:211], v[210:211] op_sel:[1,1] op_sel_hi:[1,0]
	v_pk_fma_f32 v[212:213], v[210:211], v[210:211], v[206:207] op_sel_hi:[0,1,1] neg_lo:[0,0,1]
	v_pk_mul_f32 v[206:207], v[210:211], v[212:213] op_sel:[1,1] op_sel_hi:[1,0]
	v_pk_fma_f32 v[220:221], v[210:211], v[212:213], v[206:207] op_sel_hi:[0,1,1] neg_lo:[0,0,1]
	v_pk_mul_f32 v[42:43], v[210:211], v[202:203] op_sel:[1,1] op_sel_hi:[1,0]
	v_pk_fma_f32 v[42:43], v[210:211], v[202:203], v[42:43] op_sel_hi:[0,1,1] neg_lo:[0,0,1]
	v_pk_mul_f32 v[44:45], v[212:213], v[48:49] op_sel:[1,1] op_sel_hi:[1,0]
	v_pk_fma_f32 v[44:45], v[212:213], v[48:49], v[44:45] op_sel_hi:[0,1,1] neg_lo:[0,0,1]
	v_pk_mul_f32 v[48:49], v[220:221], v[204:205] op_sel:[1,1] op_sel_hi:[1,0]
	v_pk_fma_f32 v[48:49], v[220:221], v[204:205], v[48:49] op_sel_hi:[0,1,1] neg_lo:[0,0,1]
	v_add_f32_e32 v214, 0x3e400000, v201
	v_cos_f32_e32 v210, v214
	v_sin_f32_e64 v211, -v214
	s_waitcnt lgkmcnt(2)
	v_pk_add_f32 v[202:203], v[50:51], v[54:55]
	v_pk_add_f32 v[50:51], v[50:51], v[54:55] neg_lo:[0,1] neg_hi:[0,1]
	v_pk_add_f32 v[204:205], v[52:53], v[56:57]
	v_pk_add_f32 v[52:53], v[52:53], v[56:57] neg_lo:[0,1] neg_hi:[0,1]
	v_pk_add_f32 v[54:55], v[202:203], v[204:205]
	v_pk_add_f32 v[56:57], v[202:203], v[204:205] neg_lo:[0,1] neg_hi:[0,1]
	v_pk_add_f32 v[202:203], v[50:51], v[52:53] op_sel:[0,1] op_sel_hi:[1,0] neg_hi:[0,1]
	v_pk_add_f32 v[204:205], v[50:51], v[52:53] op_sel:[0,1] op_sel_hi:[1,0] neg_lo:[0,1]
	v_pk_mul_f32 v[206:207], v[210:211], v[210:211] op_sel:[1,1] op_sel_hi:[1,0]
	v_pk_fma_f32 v[212:213], v[210:211], v[210:211], v[206:207] op_sel_hi:[0,1,1] neg_lo:[0,0,1]
	v_pk_mul_f32 v[206:207], v[210:211], v[212:213] op_sel:[1,1] op_sel_hi:[1,0]
	v_pk_fma_f32 v[220:221], v[210:211], v[212:213], v[206:207] op_sel_hi:[0,1,1] neg_lo:[0,0,1]
	v_pk_mul_f32 v[50:51], v[210:211], v[202:203] op_sel:[1,1] op_sel_hi:[1,0]
	v_pk_fma_f32 v[50:51], v[210:211], v[202:203], v[50:51] op_sel_hi:[0,1,1] neg_lo:[0,0,1]
	v_pk_mul_f32 v[52:53], v[212:213], v[56:57] op_sel:[1,1] op_sel_hi:[1,0]
	v_pk_fma_f32 v[52:53], v[212:213], v[56:57], v[52:53] op_sel_hi:[0,1,1] neg_lo:[0,0,1]
	v_pk_mul_f32 v[56:57], v[220:221], v[204:205] op_sel:[1,1] op_sel_hi:[1,0]
	v_pk_fma_f32 v[56:57], v[220:221], v[204:205], v[56:57] op_sel_hi:[0,1,1] neg_lo:[0,0,1]
	v_add_f32_e32 v214, 0x3e600000, v201
	v_cos_f32_e32 v210, v214
	v_sin_f32_e64 v211, -v214
	s_waitcnt lgkmcnt(0)
	v_pk_add_f32 v[202:203], v[58:59], v[62:63]
	v_pk_add_f32 v[58:59], v[58:59], v[62:63] neg_lo:[0,1] neg_hi:[0,1]
	v_pk_add_f32 v[204:205], v[60:61], v[64:65]
	v_pk_add_f32 v[60:61], v[60:61], v[64:65] neg_lo:[0,1] neg_hi:[0,1]
	v_pk_add_f32 v[62:63], v[202:203], v[204:205]
	v_pk_add_f32 v[64:65], v[202:203], v[204:205] neg_lo:[0,1] neg_hi:[0,1]
	v_pk_add_f32 v[202:203], v[58:59], v[60:61] op_sel:[0,1] op_sel_hi:[1,0] neg_hi:[0,1]
	v_pk_add_f32 v[204:205], v[58:59], v[60:61] op_sel:[0,1] op_sel_hi:[1,0] neg_lo:[0,1]
	v_pk_mul_f32 v[206:207], v[210:211], v[210:211] op_sel:[1,1] op_sel_hi:[1,0]
	v_pk_fma_f32 v[212:213], v[210:211], v[210:211], v[206:207] op_sel_hi:[0,1,1] neg_lo:[0,0,1]
	v_pk_mul_f32 v[206:207], v[210:211], v[212:213] op_sel:[1,1] op_sel_hi:[1,0]
	v_pk_fma_f32 v[220:221], v[210:211], v[212:213], v[206:207] op_sel_hi:[0,1,1] neg_lo:[0,0,1]
	v_pk_mul_f32 v[58:59], v[210:211], v[202:203] op_sel:[1,1] op_sel_hi:[1,0]
	v_pk_fma_f32 v[58:59], v[210:211], v[202:203], v[58:59] op_sel_hi:[0,1,1] neg_lo:[0,0,1]
	v_pk_mul_f32 v[60:61], v[212:213], v[64:65] op_sel:[1,1] op_sel_hi:[1,0]
	v_pk_fma_f32 v[60:61], v[212:213], v[64:65], v[60:61] op_sel_hi:[0,1,1] neg_lo:[0,0,1]
	v_pk_mul_f32 v[64:65], v[220:221], v[204:205] op_sel:[1,1] op_sel_hi:[1,0]
	v_pk_fma_f32 v[64:65], v[220:221], v[204:205], v[64:65] op_sel_hi:[0,1,1] neg_lo:[0,0,1]
	s_barrier
	ds_write_b64 v156, v[6:7] offset:0
	ds_write_b64 v158, v[2:3] offset:0
	ds_write_b64 v160, v[4:5] offset:0
	ds_write_b64 v162, v[8:9] offset:0
	ds_write_b64 v156, v[14:15] offset:8192
	ds_write_b64 v158, v[10:11] offset:8192
	ds_write_b64 v160, v[12:13] offset:8192
	ds_write_b64 v162, v[16:17] offset:8192
	ds_write_b64 v156, v[22:23] offset:16384
	ds_write_b64 v158, v[18:19] offset:16384
	ds_write_b64 v160, v[20:21] offset:16384
	ds_write_b64 v162, v[24:25] offset:16384
	ds_write_b64 v156, v[30:31] offset:24576
	ds_write_b64 v158, v[26:27] offset:24576
	ds_write_b64 v160, v[28:29] offset:24576
	ds_write_b64 v162, v[32:33] offset:24576
	ds_write_b64 v156, v[38:39] offset:32768
	ds_write_b64 v158, v[34:35] offset:32768
	ds_write_b64 v160, v[36:37] offset:32768
	ds_write_b64 v162, v[40:41] offset:32768
	ds_write_b64 v156, v[46:47] offset:40960
	ds_write_b64 v158, v[42:43] offset:40960
	ds_write_b64 v160, v[44:45] offset:40960
	ds_write_b64 v162, v[48:49] offset:40960
	ds_write_b64 v156, v[54:55] offset:49152
	ds_write_b64 v158, v[50:51] offset:49152
	ds_write_b64 v160, v[52:53] offset:49152
	ds_write_b64 v162, v[56:57] offset:49152
	ds_write_b64 v156, v[62:63] offset:57344
	ds_write_b64 v158, v[58:59] offset:57344
	ds_write_b64 v160, v[60:61] offset:57344
	ds_write_b64 v162, v[64:65] offset:57344
	s_waitcnt lgkmcnt(0)
	s_barrier
; DI f32x2 cmul(f32x2 a, f32x2 b) { return mkf2(a.x * b.x - a.y * b.y, a.x * b.y + a.y * b.x); }
; DI void fft8192(f32x2* buf, const f32x2* __restrict__ tw) {
;     ...
;   for (int ls = 0; ls < 12; ls += 2) {
;     const int s = 1 << ls;
;     f32x2 a[8], b[8], c[8], d[8];
;     __syncthreads();
; #pragma unroll
;     for (int e = 0; e < 8; ++e) {
;       const int i = tid + 256 * e;
;       const int pi = SW(i);
;       a[e] = buf[pi]; b[e] = buf[pi + 2048]; c[e] = buf[pi + 4096]; d[e] = buf[pi + 6144];
;     }
;     __syncthreads();
; #pragma unroll
;     for (int e = 0; e < 8; ++e) {
;       const int i = tid + 256 * e;
;       const int q = i & (s - 1);
;       const int ps = i - q;
;       const float rev = (float)ps * (1.f / 8192.f);
;       const f32x2 w1 = mkf2(__builtin_amdgcn_cosf(rev), -__builtin_amdgcn_sinf(rev));
;       const f32x2 w2 = cmul(w1, w1), w3 = cmul(w1, w2);
;       const f32x2 apc = mkf2(a[e].x + c[e].x, a[e].y + c[e].y), amc = mkf2(a[e].x - c[e].x, a[e].y - c[e].y);
;       const f32x2 bpd = mkf2(b[e].x + d[e].x, b[e].y + d[e].y), bmd = mkf2(b[e].x - d[e].x, b[e].y - d[e].y);
;       const int o = 4 * i - 3 * q;
;       buf[SW(o)] = mkf2(apc.x + bpd.x, apc.y + bpd.y);
;       buf[SW(o + s)] = cmul(w1, mkf2(amc.x + bmd.y, amc.y - bmd.x));
;       buf[SW(o + 2 * s)] = cmul(w2, mkf2(apc.x - bpd.x, apc.y - bpd.y));
;       buf[SW(o + 3 * s)] = cmul(w3, mkf2(amc.x - bmd.y, amc.y + bmd.x));
	ds_read2st64_b64 v[2:5], v154 offset0:0 offset1:32
	ds_read2st64_b64 v[6:9], v154 offset0:64 offset1:96
	ds_read2st64_b64 v[10:13], v154 offset0:4 offset1:36
	ds_read2st64_b64 v[14:17], v154 offset0:68 offset1:100
	ds_read2st64_b64 v[18:21], v154 offset0:8 offset1:40
	ds_read2st64_b64 v[22:25], v154 offset0:72 offset1:104
	ds_read2st64_b64 v[26:29], v154 offset0:12 offset1:44
	ds_read2st64_b64 v[30:33], v154 offset0:76 offset1:108
	ds_read2st64_b64 v[34:37], v154 offset0:16 offset1:48
	ds_read2st64_b64 v[38:41], v154 offset0:80 offset1:112
	ds_read2st64_b64 v[42:45], v154 offset0:20 offset1:52
	ds_read2st64_b64 v[46:49], v154 offset0:84 offset1:116
	ds_read2st64_b64 v[50:53], v154 offset0:24 offset1:56
	ds_read2st64_b64 v[54:57], v154 offset0:88 offset1:120
	ds_read2st64_b64 v[58:61], v154 offset0:28 offset1:60
	ds_read2st64_b64 v[62:65], v154 offset0:92 offset1:124
	v_and_b32_e32 v166, 15, v0
	v_lshlrev_b32_e32 v164, 2, v0
	v_mad_i32_i24 v164, v166, -3, v164
	v_sub_u32_e32 v166, v0, v166
	v_cvt_f32_u32_e32 v201, v166
	v_mul_f32_e32 v201, 0x39000000, v201
	v_bfe_i32 v166, v164, 5, 1
	v_bfe_i32 v168, v164, 6, 1
	v_and_b32_e32 v166, 5, v166
	v_and_b32_e32 v168, 26, v168
	v_xor_b32_e32 v166, v166, v168
	v_xor_b32_e32 v166, v166, v164
	v_lshlrev_b32_e32 v156, 3, v166
	v_xor_b32_e32 v158, 0x80, v156
	v_xor_b32_e32 v160, 0x128, v156
	v_xor_b32_e32 v162, 0x1a8, v156
	v_cos_f32_e32 v210, v201
	v_sin_f32_e64 v211, -v201
	s_waitcnt lgkmcnt(14)
	v_pk_add_f32 v[202:203], v[2:3], v[6:7]
	v_pk_add_f32 v[2:3], v[2:3], v[6:7] neg_lo:[0,1] neg_hi:[0,1]
	v_pk_add_f32 v[204:205], v[4:5], v[8:9]
	v_pk_add_f32 v[4:5], v[4:5], v[8:9] neg_lo:[0,1] neg_hi:[0,1]
	v_pk_add_f32 v[6:7], v[202:203], v[204:205]
	v_pk_add_f32 v[8:9], v[202:203], v[204:205] neg_lo:[0,1] neg_hi:[0,1]
	v_pk_add_f32 v[202:203], v[2:3], v[4:5] op_sel:[0,1] op_sel_hi:[1,0] neg_hi:[0,1]
	v_pk_add_f32 v[204:205], v[2:3], v[4:5] op_sel:[0,1] op_sel_hi:[1,0] neg_lo:[0,1]
	v_pk_mul_f32 v[206:207], v[210:211], v[210:211] op_sel:[1,1] op_sel_hi:[1,0]
	v_pk_fma_f32 v[212:213], v[210:211], v[210:211], v[206:207] op_sel_hi:[0,1,1] neg_lo:[0,0,1]
	v_pk_mul_f32 v[206:207], v[210:211], v[212:213] op_sel:[1,1] op_sel_hi:[1,0]
	v_pk_fma_f32 v[220:221], v[210:211], v[212:213], v[206:207] op_sel_hi:[0,1,1] neg_lo:[0,0,1]
	v_pk_mul_f32 v[2:3], v[210:211], v[202:203] op_sel:[1,1] op_sel_hi:[1,0]
	v_pk_fma_f32 v[2:3], v[210:211], v[202:203], v[2:3] op_sel_hi:[0,1,1] neg_lo:[0,0,1]
	v_pk_mul_f32 v[4:5], v[212:213], v[8:9] op_sel:[1,1] op_sel_hi:[1,0]
	v_pk_fma_f32 v[4:5], v[212:213], v[8:9], v[4:5] op_sel_hi:[0,1,1] neg_lo:[0,0,1]
	v_pk_mul_f32 v[8:9], v[220:221], v[204:205] op_sel:[1,1] op_sel_hi:[1,0]
	v_pk_fma_f32 v[8:9], v[220:221], v[204:205], v[8:9] op_sel_hi:[0,1,1] neg_lo:[0,0,1]
	v_add_f32_e32 v214, 0x3d000000, v201
	v_cos_f32_e32 v210, v214
	v_sin_f32_e64 v211, -v214
	s_waitcnt lgkmcnt(12)
	v_pk_add_f32 v[202:203], v[10:11], v[14:15]
	v_pk_add_f32 v[10:11], v[10:11], v[14:15] neg_lo:[0,1] neg_hi:[0,1]
	v_pk_add_f32 v[204:205], v[12:13], v[16:17]
	v_pk_add_f32 v[12:13], v[12:13], v[16:17] neg_lo:[0,1] neg_hi:[0,1]
	v_pk_add_f32 v[14:15], v[202:203], v[204:205]
	v_pk_add_f32 v[16:17], v[202:203], v[204:205] neg_lo:[0,1] neg_hi:[0,1]
	v_pk_add_f32 v[202:203], v[10:11], v[12:13] op_sel:[0,1] op_sel_hi:[1,0] neg_hi:[0,1]
	v_pk_add_f32 v[204:205], v[10:11], v[12:13] op_sel:[0,1] op_sel_hi:[1,0] neg_lo:[0,1]
	v_pk_mul_f32 v[206:207], v[210:211], v[210:211] op_sel:[1,1] op_sel_hi:[1,0]
	v_pk_fma_f32 v[212:213], v[210:211], v[210:211], v[206:207] op_sel_hi:[0,1,1] neg_lo:[0,0,1]
	v_pk_mul_f32 v[206:207], v[210:211], v[212:213] op_sel:[1,1] op_sel_hi:[1,0]
	v_pk_fma_f32 v[220:221], v[210:211], v[212:213], v[206:207] op_sel_hi:[0,1,1] neg_lo:[0,0,1]
	v_pk_mul_f32 v[10:11], v[210:211], v[202:203] op_sel:[1,1] op_sel_hi:[1,0]
	v_pk_fma_f32 v[10:11], v[210:211], v[202:203], v[10:11] op_sel_hi:[0,1,1] neg_lo:[0,0,1]
	v_pk_mul_f32 v[12:13], v[212:213], v[16:17] op_sel:[1,1] op_sel_hi:[1,0]
	v_pk_fma_f32 v[12:13], v[212:213], v[16:17], v[12:13] op_sel_hi:[0,1,1] neg_lo:[0,0,1]
	v_pk_mul_f32 v[16:17], v[220:221], v[204:205] op_sel:[1,1] op_sel_hi:[1,0]
	v_pk_fma_f32 v[16:17], v[220:221], v[204:205], v[16:17] op_sel_hi:[0,1,1] neg_lo:[0,0,1]
	v_add_f32_e32 v214, 0x3d800000, v201
	v_cos_f32_e32 v210, v214
	v_sin_f32_e64 v211, -v214
	s_waitcnt lgkmcnt(10)
	v_pk_add_f32 v[202:203], v[18:19], v[22:23]
	v_pk_add_f32 v[18:19], v[18:19], v[22:23] neg_lo:[0,1] neg_hi:[0,1]
	v_pk_add_f32 v[204:205], v[20:21], v[24:25]
	v_pk_add_f32 v[20:21], v[20:21], v[24:25] neg_lo:[0,1] neg_hi:[0,1]
	v_pk_add_f32 v[22:23], v[202:203], v[204:205]
	v_pk_add_f32 v[24:25], v[202:203], v[204:205] neg_lo:[0,1] neg_hi:[0,1]
	v_pk_add_f32 v[202:203], v[18:19], v[20:21] op_sel:[0,1] op_sel_hi:[1,0] neg_hi:[0,1]
	v_pk_add_f32 v[204:205], v[18:19], v[20:21] op_sel:[0,1] op_sel_hi:[1,0] neg_lo:[0,1]
	v_pk_mul_f32 v[206:207], v[210:211], v[210:211] op_sel:[1,1] op_sel_hi:[1,0]
	v_pk_fma_f32 v[212:213], v[210:211], v[210:211], v[206:207] op_sel_hi:[0,1,1] neg_lo:[0,0,1]
	v_pk_mul_f32 v[206:207], v[210:211], v[212:213] op_sel:[1,1] op_sel_hi:[1,0]
	v_pk_fma_f32 v[220:221], v[210:211], v[212:213], v[206:207] op_sel_hi:[0,1,1] neg_lo:[0,0,1]
	v_pk_mul_f32 v[18:19], v[210:211], v[202:203] op_sel:[1,1] op_sel_hi:[1,0]
	v_pk_fma_f32 v[18:19], v[210:211], v[202:203], v[18:19] op_sel_hi:[0,1,1] neg_lo:[0,0,1]
	v_pk_mul_f32 v[20:21], v[212:213], v[24:25] op_sel:[1,1] op_sel_hi:[1,0]
	v_pk_fma_f32 v[20:21], v[212:213], v[24:25], v[20:21] op_sel_hi:[0,1,1] neg_lo:[0,0,1]
	v_pk_mul_f32 v[24:25], v[220:221], v[204:205] op_sel:[1,1] op_sel_hi:[1,0]
	v_pk_fma_f32 v[24:25], v[220:221], v[204:205], v[24:25] op_sel_hi:[0,1,1] neg_lo:[0,0,1]
	v_add_f32_e32 v214, 0x3dc00000, v201
	v_cos_f32_e32 v210, v214
	v_sin_f32_e64 v211, -v214
	s_waitcnt lgkmcnt(8)
; DI f32x2 cmul(f32x2 a, f32x2 b) { return mkf2(a.x * b.x - a.y * b.y, a.x * b.y + a.y * b.x); }
; DI void fft8192(f32x2* buf, const f32x2* __restrict__ tw) {
;     ...
; #pragma unroll
;     for (int e = 0; e < 8; ++e) {
;       const int i = tid + 256 * e;
;       const int q = i & (s - 1);
;       const int ps = i - q;
;       const float rev = (float)ps * (1.f / 8192.f);
;       const f32x2 w1 = mkf2(__builtin_amdgcn_cosf(rev), -__builtin_amdgcn_sinf(rev));
;       const f32x2 w2 = cmul(w1, w1), w3 = cmul(w1, w2);
;       const f32x2 apc = mkf2(a[e].x + c[e].x, a[e].y + c[e].y), amc = mkf2(a[e].x - c[e].x, a[e].y - c[e].y);
;       const f32x2 bpd = mkf2(b[e].x + d[e].x, b[e].y + d[e].y), bmd = mkf2(b[e].x - d[e].x, b[e].y - d[e].y);
;       const int o = 4 * i - 3 * q;
;       buf[SW(o)] = mkf2(apc.x + bpd.x, apc.y + bpd.y);
;       buf[SW(o + s)] = cmul(w1, mkf2(amc.x + bmd.y, amc.y - bmd.x));
;       buf[SW(o + 2 * s)] = cmul(w2, mkf2(apc.x - bpd.x, apc.y - bpd.y));
;       buf[SW(o + 3 * s)] = cmul(w3, mkf2(amc.x - bmd.y, amc.y + bmd.x));
	v_pk_add_f32 v[202:203], v[26:27], v[30:31]
	v_pk_add_f32 v[26:27], v[26:27], v[30:31] neg_lo:[0,1] neg_hi:[0,1]
	v_pk_add_f32 v[204:205], v[28:29], v[32:33]
	v_pk_add_f32 v[28:29], v[28:29], v[32:33] neg_lo:[0,1] neg_hi:[0,1]
	v_pk_add_f32 v[30:31], v[202:203], v[204:205]
	v_pk_add_f32 v[32:33], v[202:203], v[204:205] neg_lo:[0,1] neg_hi:[0,1]
	v_pk_add_f32 v[202:203], v[26:27], v[28:29] op_sel:[0,1] op_sel_hi:[1,0] neg_hi:[0,1]
	v_pk_add_f32 v[204:205], v[26:27], v[28:29] op_sel:[0,1] op_sel_hi:[1,0] neg_lo:[0,1]
	v_pk_mul_f32 v[206:207], v[210:211], v[210:211] op_sel:[1,1] op_sel_hi:[1,0]
	v_pk_fma_f32 v[212:213], v[210:211], v[210:211], v[206:207] op_sel_hi:[0,1,1] neg_lo:[0,0,1]
	v_pk_mul_f32 v[206:207], v[210:211], v[212:213] op_sel:[1,1] op_sel_hi:[1,0]
	v_pk_fma_f32 v[220:221], v[210:211], v[212:213], v[206:207] op_sel_hi:[0,1,1] neg_lo:[0,0,1]
	v_pk_mul_f32 v[26:27], v[210:211], v[202:203] op_sel:[1,1] op_sel_hi:[1,0]
	v_pk_fma_f32 v[26:27], v[210:211], v[202:203], v[26:27] op_sel_hi:[0,1,1] neg_lo:[0,0,1]
	v_pk_mul_f32 v[28:29], v[212:213], v[32:33] op_sel:[1,1] op_sel_hi:[1,0]
	v_pk_fma_f32 v[28:29], v[212:213], v[32:33], v[28:29] op_sel_hi:[0,1,1] neg_lo:[0,0,1]
	v_pk_mul_f32 v[32:33], v[220:221], v[204:205] op_sel:[1,1] op_sel_hi:[1,0]
	v_pk_fma_f32 v[32:33], v[220:221], v[204:205], v[32:33] op_sel_hi:[0,1,1] neg_lo:[0,0,1]
	v_add_f32_e32 v214, 0x3e000000, v201
	v_cos_f32_e32 v210, v214
	v_sin_f32_e64 v211, -v214
	s_waitcnt lgkmcnt(6)
	v_pk_add_f32 v[202:203], v[34:35], v[38:39]
	v_pk_add_f32 v[34:35], v[34:35], v[38:39] neg_lo:[0,1] neg_hi:[0,1]
	v_pk_add_f32 v[204:205], v[36:37], v[40:41]
	v_pk_add_f32 v[36:37], v[36:37], v[40:41] neg_lo:[0,1] neg_hi:[0,1]
	v_pk_add_f32 v[38:39], v[202:203], v[204:205]
	v_pk_add_f32 v[40:41], v[202:203], v[204:205] neg_lo:[0,1] neg_hi:[0,1]
	v_pk_add_f32 v[202:203], v[34:35], v[36:37] op_sel:[0,1] op_sel_hi:[1,0] neg_hi:[0,1]
	v_pk_add_f32 v[204:205], v[34:35], v[36:37] op_sel:[0,1] op_sel_hi:[1,0] neg_lo:[0,1]
	v_pk_mul_f32 v[206:207], v[210:211], v[210:211] op_sel:[1,1] op_sel_hi:[1,0]
	v_pk_fma_f32 v[212:213], v[210:211], v[210:211], v[206:207] op_sel_hi:[0,1,1] neg_lo:[0,0,1]
	v_pk_mul_f32 v[206:207], v[210:211], v[212:213] op_sel:[1,1] op_sel_hi:[1,0]
	v_pk_fma_f32 v[220:221], v[210:211], v[212:213], v[206:207] op_sel_hi:[0,1,1] neg_lo:[0,0,1]
	v_pk_mul_f32 v[34:35], v[210:211], v[202:203] op_sel:[1,1] op_sel_hi:[1,0]
	v_pk_fma_f32 v[34:35], v[210:211], v[202:203], v[34:35] op_sel_hi:[0,1,1] neg_lo:[0,0,1]
	v_pk_mul_f32 v[36:37], v[212:213], v[40:41] op_sel:[1,1] op_sel_hi:[1,0]
	v_pk_fma_f32 v[36:37], v[212:213], v[40:41], v[36:37] op_sel_hi:[0,1,1] neg_lo:[0,0,1]
	v_pk_mul_f32 v[40:41], v[220:221], v[204:205] op_sel:[1,1] op_sel_hi:[1,0]
	v_pk_fma_f32 v[40:41], v[220:221], v[204:205], v[40:41] op_sel_hi:[0,1,1] neg_lo:[0,0,1]
	v_add_f32_e32 v214, 0x3e200000, v201
	v_cos_f32_e32 v210, v214
	v_sin_f32_e64 v211, -v214
	s_waitcnt lgkmcnt(4)
	v_pk_add_f32 v[202:203], v[42:43], v[46:47]
	v_pk_add_f32 v[42:43], v[42:43], v[46:47] neg_lo:[0,1] neg_hi:[0,1]
	v_pk_add_f32 v[204:205], v[44:45], v[48:49]
	v_pk_add_f32 v[44:45], v[44:45], v[48:49] neg_lo:[0,1] neg_hi:[0,1]
	v_pk_add_f32 v[46:47], v[202:203], v[204:205]
	v_pk_add_f32 v[48:49], v[202:203], v[204:205] neg_lo:[0,1] neg_hi:[0,1]
	v_pk_add_f32 v[202:203], v[42:43], v[44:45] op_sel:[0,1] op_sel_hi:[1,0] neg_hi:[0,1]
	v_pk_add_f32 v[204:205], v[42:43], v[44:45] op_sel:[0,1] op_sel_hi:[1,0] neg_lo:[0,1]
	v_pk_mul_f32 v[206:207], v[210:211], v[210:211] op_sel:[1,1] op_sel_hi:[1,0]
	v_pk_fma_f32 v[212:213], v[210:211], v[210:211], v[206:207] op_sel_hi:[0,1,1] neg_lo:[0,0,1]
	v_pk_mul_f32 v[206:207], v[210:211], v[212:213] op_sel:[1,1] op_sel_hi:[1,0]
	v_pk_fma_f32 v[220:221], v[210:211], v[212:213], v[206:207] op_sel_hi:[0,1,1] neg_lo:[0,0,1]
	v_pk_mul_f32 v[42:43], v[210:211], v[202:203] op_sel:[1,1] op_sel_hi:[1,0]
	v_pk_fma_f32 v[42:43], v[210:211], v[202:203], v[42:43] op_sel_hi:[0,1,1] neg_lo:[0,0,1]
	v_pk_mul_f32 v[44:45], v[212:213], v[48:49] op_sel:[1,1] op_sel_hi:[1,0]
	v_pk_fma_f32 v[44:45], v[212:213], v[48:49], v[44:45] op_sel_hi:[0,1,1] neg_lo:[0,0,1]
	v_pk_mul_f32 v[48:49], v[220:221], v[204:205] op_sel:[1,1] op_sel_hi:[1,0]
	v_pk_fma_f32 v[48:49], v[220:221], v[204:205], v[48:49] op_sel_hi:[0,1,1] neg_lo:[0,0,1]
	v_add_f32_e32 v214, 0x3e400000, v201
	v_cos_f32_e32 v210, v214
	v_sin_f32_e64 v211, -v214
	s_waitcnt lgkmcnt(2)
	v_pk_add_f32 v[202:203], v[50:51], v[54:55]
	v_pk_add_f32 v[50:51], v[50:51], v[54:55] neg_lo:[0,1] neg_hi:[0,1]
	v_pk_add_f32 v[204:205], v[52:53], v[56:57]
	v_pk_add_f32 v[52:53], v[52:53], v[56:57] neg_lo:[0,1] neg_hi:[0,1]
	v_pk_add_f32 v[54:55], v[202:203], v[204:205]
	v_pk_add_f32 v[56:57], v[202:203], v[204:205] neg_lo:[0,1] neg_hi:[0,1]
	v_pk_add_f32 v[202:203], v[50:51], v[52:53] op_sel:[0,1] op_sel_hi:[1,0] neg_hi:[0,1]
	v_pk_add_f32 v[204:205], v[50:51], v[52:53] op_sel:[0,1] op_sel_hi:[1,0] neg_lo:[0,1]
	v_pk_mul_f32 v[206:207], v[210:211], v[210:211] op_sel:[1,1] op_sel_hi:[1,0]
	v_pk_fma_f32 v[212:213], v[210:211], v[210:211], v[206:207] op_sel_hi:[0,1,1] neg_lo:[0,0,1]
	v_pk_mul_f32 v[206:207], v[210:211], v[212:213] op_sel:[1,1] op_sel_hi:[1,0]
	v_pk_fma_f32 v[220:221], v[210:211], v[212:213], v[206:207] op_sel_hi:[0,1,1] neg_lo:[0,0,1]
	v_pk_mul_f32 v[50:51], v[210:211], v[202:203] op_sel:[1,1] op_sel_hi:[1,0]
	v_pk_fma_f32 v[50:51], v[210:211], v[202:203], v[50:51] op_sel_hi:[0,1,1] neg_lo:[0,0,1]
	v_pk_mul_f32 v[52:53], v[212:213], v[56:57] op_sel:[1,1] op_sel_hi:[1,0]
	v_pk_fma_f32 v[52:53], v[212:213], v[56:57], v[52:53] op_sel_hi:[0,1,1] neg_lo:[0,0,1]
	v_pk_mul_f32 v[56:57], v[220:221], v[204:205] op_sel:[1,1] op_sel_hi:[1,0]
	v_pk_fma_f32 v[56:57], v[220:221], v[204:205], v[56:57] op_sel_hi:[0,1,1] neg_lo:[0,0,1]
	v_add_f32_e32 v214, 0x3e600000, v201
	v_cos_f32_e32 v210, v214
	v_sin_f32_e64 v211, -v214
	s_waitcnt lgkmcnt(0)
; DI f32x2 cmul(f32x2 a, f32x2 b) { return mkf2(a.x * b.x - a.y * b.y, a.x * b.y + a.y * b.x); }
; DI void fft8192(f32x2* buf, const f32x2* __restrict__ tw) {
;     ...
;     __syncthreads();
; #pragma unroll
;     for (int e = 0; e < 8; ++e) {
;       const int i = tid + 256 * e;
;       const int pi = SW(i);
;       a[e] = buf[pi]; b[e] = buf[pi + 2048]; c[e] = buf[pi + 4096]; d[e] = buf[pi + 6144];
;     }
;     __syncthreads();
; #pragma unroll
;     for (int e = 0; e < 8; ++e) {
;       const int i = tid + 256 * e;
;       const int q = i & (s - 1);
;       const int ps = i - q;
;       const float rev = (float)ps * (1.f / 8192.f);
;       const f32x2 w1 = mkf2(__builtin_amdgcn_cosf(rev), -__builtin_amdgcn_sinf(rev));
;       const f32x2 w2 = cmul(w1, w1), w3 = cmul(w1, w2);
;       const f32x2 apc = mkf2(a[e].x + c[e].x, a[e].y + c[e].y), amc = mkf2(a[e].x - c[e].x, a[e].y - c[e].y);
;       const f32x2 bpd = mkf2(b[e].x + d[e].x, b[e].y + d[e].y), bmd = mkf2(b[e].x - d[e].x, b[e].y - d[e].y);
;       const int o = 4 * i - 3 * q;
;       buf[SW(o)] = mkf2(apc.x + bpd.x, apc.y + bpd.y);
;       buf[SW(o + s)] = cmul(w1, mkf2(amc.x + bmd.y, amc.y - bmd.x));
;       buf[SW(o + 2 * s)] = cmul(w2, mkf2(apc.x - bpd.x, apc.y - bpd.y));
;       buf[SW(o + 3 * s)] = cmul(w3, mkf2(amc.x - bmd.y, amc.y + bmd.x));
;     }
	v_pk_add_f32 v[202:203], v[58:59], v[62:63]
	v_pk_add_f32 v[58:59], v[58:59], v[62:63] neg_lo:[0,1] neg_hi:[0,1]
	v_pk_add_f32 v[204:205], v[60:61], v[64:65]
	v_pk_add_f32 v[60:61], v[60:61], v[64:65] neg_lo:[0,1] neg_hi:[0,1]
	v_pk_add_f32 v[62:63], v[202:203], v[204:205]
	v_pk_add_f32 v[64:65], v[202:203], v[204:205] neg_lo:[0,1] neg_hi:[0,1]
	v_pk_add_f32 v[202:203], v[58:59], v[60:61] op_sel:[0,1] op_sel_hi:[1,0] neg_hi:[0,1]
	v_pk_add_f32 v[204:205], v[58:59], v[60:61] op_sel:[0,1] op_sel_hi:[1,0] neg_lo:[0,1]
	v_pk_mul_f32 v[206:207], v[210:211], v[210:211] op_sel:[1,1] op_sel_hi:[1,0]
	v_pk_fma_f32 v[212:213], v[210:211], v[210:211], v[206:207] op_sel_hi:[0,1,1] neg_lo:[0,0,1]
	v_pk_mul_f32 v[206:207], v[210:211], v[212:213] op_sel:[1,1] op_sel_hi:[1,0]
	v_pk_fma_f32 v[220:221], v[210:211], v[212:213], v[206:207] op_sel_hi:[0,1,1] neg_lo:[0,0,1]
	v_pk_mul_f32 v[58:59], v[210:211], v[202:203] op_sel:[1,1] op_sel_hi:[1,0]
	v_pk_fma_f32 v[58:59], v[210:211], v[202:203], v[58:59] op_sel_hi:[0,1,1] neg_lo:[0,0,1]
	v_pk_mul_f32 v[60:61], v[212:213], v[64:65] op_sel:[1,1] op_sel_hi:[1,0]
	v_pk_fma_f32 v[60:61], v[212:213], v[64:65], v[60:61] op_sel_hi:[0,1,1] neg_lo:[0,0,1]
	v_pk_mul_f32 v[64:65], v[220:221], v[204:205] op_sel:[1,1] op_sel_hi:[1,0]
	v_pk_fma_f32 v[64:65], v[220:221], v[204:205], v[64:65] op_sel_hi:[0,1,1] neg_lo:[0,0,1]
	s_barrier
	ds_write_b64 v156, v[6:7] offset:0
	ds_write_b64 v158, v[2:3] offset:0
	ds_write_b64 v160, v[4:5] offset:0
	ds_write_b64 v162, v[8:9] offset:0
	ds_write_b64 v156, v[14:15] offset:8192
	ds_write_b64 v158, v[10:11] offset:8192
	ds_write_b64 v160, v[12:13] offset:8192
	ds_write_b64 v162, v[16:17] offset:8192
	ds_write_b64 v156, v[22:23] offset:16384
	ds_write_b64 v158, v[18:19] offset:16384
	ds_write_b64 v160, v[20:21] offset:16384
	ds_write_b64 v162, v[24:25] offset:16384
	ds_write_b64 v156, v[30:31] offset:24576
	ds_write_b64 v158, v[26:27] offset:24576
	ds_write_b64 v160, v[28:29] offset:24576
	ds_write_b64 v162, v[32:33] offset:24576
	ds_write_b64 v156, v[38:39] offset:32768
	ds_write_b64 v158, v[34:35] offset:32768
	ds_write_b64 v160, v[36:37] offset:32768
	ds_write_b64 v162, v[40:41] offset:32768
	ds_write_b64 v156, v[46:47] offset:40960
	ds_write_b64 v158, v[42:43] offset:40960
	ds_write_b64 v160, v[44:45] offset:40960
	ds_write_b64 v162, v[48:49] offset:40960
	ds_write_b64 v156, v[54:55] offset:49152
	ds_write_b64 v158, v[50:51] offset:49152
	ds_write_b64 v160, v[52:53] offset:49152
	ds_write_b64 v162, v[56:57] offset:49152
	ds_write_b64 v156, v[62:63] offset:57344
	ds_write_b64 v158, v[58:59] offset:57344
	ds_write_b64 v160, v[60:61] offset:57344
	ds_write_b64 v162, v[64:65] offset:57344
	s_waitcnt lgkmcnt(0)
	s_barrier
	ds_read2st64_b64 v[2:5], v154 offset0:0 offset1:32
	ds_read2st64_b64 v[6:9], v154 offset0:64 offset1:96
	ds_read2st64_b64 v[10:13], v154 offset0:4 offset1:36
	ds_read2st64_b64 v[14:17], v154 offset0:68 offset1:100
	ds_read2st64_b64 v[18:21], v154 offset0:8 offset1:40
	ds_read2st64_b64 v[22:25], v154 offset0:72 offset1:104
	ds_read2st64_b64 v[26:29], v154 offset0:12 offset1:44
	ds_read2st64_b64 v[30:33], v154 offset0:76 offset1:108
	ds_read2st64_b64 v[34:37], v154 offset0:16 offset1:48
	ds_read2st64_b64 v[38:41], v154 offset0:80 offset1:112
	ds_read2st64_b64 v[42:45], v154 offset0:20 offset1:52
	ds_read2st64_b64 v[46:49], v154 offset0:84 offset1:116
	ds_read2st64_b64 v[50:53], v154 offset0:24 offset1:56
	ds_read2st64_b64 v[54:57], v154 offset0:88 offset1:120
	ds_read2st64_b64 v[58:61], v154 offset0:28 offset1:60
	ds_read2st64_b64 v[62:65], v154 offset0:92 offset1:124
	v_and_b32_e32 v166, 63, v0
	v_lshlrev_b32_e32 v164, 2, v0
	v_mad_i32_i24 v164, v166, -3, v164
	v_sub_u32_e32 v166, v0, v166
	v_cvt_f32_u32_e32 v201, v166
	v_mul_f32_e32 v201, 0x39000000, v201
	v_bfe_i32 v166, v164, 5, 1
	v_bfe_i32 v168, v164, 6, 1
	v_and_b32_e32 v166, 5, v166
	v_and_b32_e32 v168, 26, v168
	v_xor_b32_e32 v166, v166, v168
	v_xor_b32_e32 v166, v166, v164
	v_lshlrev_b32_e32 v156, 3, v166
	v_xor_b32_e32 v158, 0x2d0, v156
	v_xor_b32_e32 v160, 0x400, v156
	v_xor_b32_e32 v162, 0x6d0, v156
	v_cos_f32_e32 v210, v201
	v_sin_f32_e64 v211, -v201
	s_waitcnt lgkmcnt(14)
	v_pk_add_f32 v[202:203], v[2:3], v[6:7]
	v_pk_add_f32 v[2:3], v[2:3], v[6:7] neg_lo:[0,1] neg_hi:[0,1]
	v_pk_add_f32 v[204:205], v[4:5], v[8:9]
	v_pk_add_f32 v[4:5], v[4:5], v[8:9] neg_lo:[0,1] neg_hi:[0,1]
	v_pk_add_f32 v[6:7], v[202:203], v[204:205]
	v_pk_add_f32 v[8:9], v[202:203], v[204:205] neg_lo:[0,1] neg_hi:[0,1]
	v_pk_add_f32 v[202:203], v[2:3], v[4:5] op_sel:[0,1] op_sel_hi:[1,0] neg_hi:[0,1]
	v_pk_add_f32 v[204:205], v[2:3], v[4:5] op_sel:[0,1] op_sel_hi:[1,0] neg_lo:[0,1]
	v_pk_mul_f32 v[206:207], v[210:211], v[210:211] op_sel:[1,1] op_sel_hi:[1,0]
	v_pk_fma_f32 v[212:213], v[210:211], v[210:211], v[206:207] op_sel_hi:[0,1,1] neg_lo:[0,0,1]
	v_pk_mul_f32 v[206:207], v[210:211], v[212:213] op_sel:[1,1] op_sel_hi:[1,0]
	v_pk_fma_f32 v[220:221], v[210:211], v[212:213], v[206:207] op_sel_hi:[0,1,1] neg_lo:[0,0,1]
	v_pk_mul_f32 v[2:3], v[210:211], v[202:203] op_sel:[1,1] op_sel_hi:[1,0]
	v_pk_fma_f32 v[2:3], v[210:211], v[202:203], v[2:3] op_sel_hi:[0,1,1] neg_lo:[0,0,1]
	v_pk_mul_f32 v[4:5], v[212:213], v[8:9] op_sel:[1,1] op_sel_hi:[1,0]
	v_pk_fma_f32 v[4:5], v[212:213], v[8:9], v[4:5] op_sel_hi:[0,1,1] neg_lo:[0,0,1]
	v_pk_mul_f32 v[8:9], v[220:221], v[204:205] op_sel:[1,1] op_sel_hi:[1,0]
	v_pk_fma_f32 v[8:9], v[220:221], v[204:205], v[8:9] op_sel_hi:[0,1,1] neg_lo:[0,0,1]
	v_add_f32_e32 v214, 0x3d000000, v201
	v_cos_f32_e32 v210, v214
	v_sin_f32_e64 v211, -v214
	s_waitcnt lgkmcnt(12)
; DI f32x2 cmul(f32x2 a, f32x2 b) { return mkf2(a.x * b.x - a.y * b.y, a.x * b.y + a.y * b.x); }
; DI void fft8192(f32x2* buf, const f32x2* __restrict__ tw) {
;     ...
; #pragma unroll
;     for (int e = 0; e < 8; ++e) {
;       const int i = tid + 256 * e;
;       const int q = i & (s - 1);
;       const int ps = i - q;
;       const float rev = (float)ps * (1.f / 8192.f);
;       const f32x2 w1 = mkf2(__builtin_amdgcn_cosf(rev), -__builtin_amdgcn_sinf(rev));
;       const f32x2 w2 = cmul(w1, w1), w3 = cmul(w1, w2);
;       const f32x2 apc = mkf2(a[e].x + c[e].x, a[e].y + c[e].y), amc = mkf2(a[e].x - c[e].x, a[e].y - c[e].y);
;       const f32x2 bpd = mkf2(b[e].x + d[e].x, b[e].y + d[e].y), bmd = mkf2(b[e].x - d[e].x, b[e].y - d[e].y);
;       const int o = 4 * i - 3 * q;
;       buf[SW(o)] = mkf2(apc.x + bpd.x, apc.y + bpd.y);
;       buf[SW(o + s)] = cmul(w1, mkf2(amc.x + bmd.y, amc.y - bmd.x));
;       buf[SW(o + 2 * s)] = cmul(w2, mkf2(apc.x - bpd.x, apc.y - bpd.y));
;       buf[SW(o + 3 * s)] = cmul(w3, mkf2(amc.x - bmd.y, amc.y + bmd.x));
	v_pk_add_f32 v[202:203], v[10:11], v[14:15]
	v_pk_add_f32 v[10:11], v[10:11], v[14:15] neg_lo:[0,1] neg_hi:[0,1]
	v_pk_add_f32 v[204:205], v[12:13], v[16:17]
	v_pk_add_f32 v[12:13], v[12:13], v[16:17] neg_lo:[0,1] neg_hi:[0,1]
	v_pk_add_f32 v[14:15], v[202:203], v[204:205]
	v_pk_add_f32 v[16:17], v[202:203], v[204:205] neg_lo:[0,1] neg_hi:[0,1]
	v_pk_add_f32 v[202:203], v[10:11], v[12:13] op_sel:[0,1] op_sel_hi:[1,0] neg_hi:[0,1]
	v_pk_add_f32 v[204:205], v[10:11], v[12:13] op_sel:[0,1] op_sel_hi:[1,0] neg_lo:[0,1]
	v_pk_mul_f32 v[206:207], v[210:211], v[210:211] op_sel:[1,1] op_sel_hi:[1,0]
	v_pk_fma_f32 v[212:213], v[210:211], v[210:211], v[206:207] op_sel_hi:[0,1,1] neg_lo:[0,0,1]
	v_pk_mul_f32 v[206:207], v[210:211], v[212:213] op_sel:[1,1] op_sel_hi:[1,0]
	v_pk_fma_f32 v[220:221], v[210:211], v[212:213], v[206:207] op_sel_hi:[0,1,1] neg_lo:[0,0,1]
	v_pk_mul_f32 v[10:11], v[210:211], v[202:203] op_sel:[1,1] op_sel_hi:[1,0]
	v_pk_fma_f32 v[10:11], v[210:211], v[202:203], v[10:11] op_sel_hi:[0,1,1] neg_lo:[0,0,1]
	v_pk_mul_f32 v[12:13], v[212:213], v[16:17] op_sel:[1,1] op_sel_hi:[1,0]
	v_pk_fma_f32 v[12:13], v[212:213], v[16:17], v[12:13] op_sel_hi:[0,1,1] neg_lo:[0,0,1]
	v_pk_mul_f32 v[16:17], v[220:221], v[204:205] op_sel:[1,1] op_sel_hi:[1,0]
	v_pk_fma_f32 v[16:17], v[220:221], v[204:205], v[16:17] op_sel_hi:[0,1,1] neg_lo:[0,0,1]
	v_add_f32_e32 v214, 0x3d800000, v201
	v_cos_f32_e32 v210, v214
	v_sin_f32_e64 v211, -v214
	s_waitcnt lgkmcnt(10)
	v_pk_add_f32 v[202:203], v[18:19], v[22:23]
	v_pk_add_f32 v[18:19], v[18:19], v[22:23] neg_lo:[0,1] neg_hi:[0,1]
	v_pk_add_f32 v[204:205], v[20:21], v[24:25]
	v_pk_add_f32 v[20:21], v[20:21], v[24:25] neg_lo:[0,1] neg_hi:[0,1]
	v_pk_add_f32 v[22:23], v[202:203], v[204:205]
	v_pk_add_f32 v[24:25], v[202:203], v[204:205] neg_lo:[0,1] neg_hi:[0,1]
	v_pk_add_f32 v[202:203], v[18:19], v[20:21] op_sel:[0,1] op_sel_hi:[1,0] neg_hi:[0,1]
	v_pk_add_f32 v[204:205], v[18:19], v[20:21] op_sel:[0,1] op_sel_hi:[1,0] neg_lo:[0,1]
	v_pk_mul_f32 v[206:207], v[210:211], v[210:211] op_sel:[1,1] op_sel_hi:[1,0]
	v_pk_fma_f32 v[212:213], v[210:211], v[210:211], v[206:207] op_sel_hi:[0,1,1] neg_lo:[0,0,1]
	v_pk_mul_f32 v[206:207], v[210:211], v[212:213] op_sel:[1,1] op_sel_hi:[1,0]
	v_pk_fma_f32 v[220:221], v[210:211], v[212:213], v[206:207] op_sel_hi:[0,1,1] neg_lo:[0,0,1]
	v_pk_mul_f32 v[18:19], v[210:211], v[202:203] op_sel:[1,1] op_sel_hi:[1,0]
	v_pk_fma_f32 v[18:19], v[210:211], v[202:203], v[18:19] op_sel_hi:[0,1,1] neg_lo:[0,0,1]
	v_pk_mul_f32 v[20:21], v[212:213], v[24:25] op_sel:[1,1] op_sel_hi:[1,0]
	v_pk_fma_f32 v[20:21], v[212:213], v[24:25], v[20:21] op_sel_hi:[0,1,1] neg_lo:[0,0,1]
	v_pk_mul_f32 v[24:25], v[220:221], v[204:205] op_sel:[1,1] op_sel_hi:[1,0]
	v_pk_fma_f32 v[24:25], v[220:221], v[204:205], v[24:25] op_sel_hi:[0,1,1] neg_lo:[0,0,1]
	v_add_f32_e32 v214, 0x3dc00000, v201
	v_cos_f32_e32 v210, v214
	v_sin_f32_e64 v211, -v214
	s_waitcnt lgkmcnt(8)
	v_pk_add_f32 v[202:203], v[26:27], v[30:31]
	v_pk_add_f32 v[26:27], v[26:27], v[30:31] neg_lo:[0,1] neg_hi:[0,1]
	v_pk_add_f32 v[204:205], v[28:29], v[32:33]
	v_pk_add_f32 v[28:29], v[28:29], v[32:33] neg_lo:[0,1] neg_hi:[0,1]
	v_pk_add_f32 v[30:31], v[202:203], v[204:205]
	v_pk_add_f32 v[32:33], v[202:203], v[204:205] neg_lo:[0,1] neg_hi:[0,1]
	v_pk_add_f32 v[202:203], v[26:27], v[28:29] op_sel:[0,1] op_sel_hi:[1,0] neg_hi:[0,1]
	v_pk_add_f32 v[204:205], v[26:27], v[28:29] op_sel:[0,1] op_sel_hi:[1,0] neg_lo:[0,1]
	v_pk_mul_f32 v[206:207], v[210:211], v[210:211] op_sel:[1,1] op_sel_hi:[1,0]
	v_pk_fma_f32 v[212:213], v[210:211], v[210:211], v[206:207] op_sel_hi:[0,1,1] neg_lo:[0,0,1]
	v_pk_mul_f32 v[206:207], v[210:211], v[212:213] op_sel:[1,1] op_sel_hi:[1,0]
	v_pk_fma_f32 v[220:221], v[210:211], v[212:213], v[206:207] op_sel_hi:[0,1,1] neg_lo:[0,0,1]
	v_pk_mul_f32 v[26:27], v[210:211], v[202:203] op_sel:[1,1] op_sel_hi:[1,0]
	v_pk_fma_f32 v[26:27], v[210:211], v[202:203], v[26:27] op_sel_hi:[0,1,1] neg_lo:[0,0,1]
	v_pk_mul_f32 v[28:29], v[212:213], v[32:33] op_sel:[1,1] op_sel_hi:[1,0]
	v_pk_fma_f32 v[28:29], v[212:213], v[32:33], v[28:29] op_sel_hi:[0,1,1] neg_lo:[0,0,1]
	v_pk_mul_f32 v[32:33], v[220:221], v[204:205] op_sel:[1,1] op_sel_hi:[1,0]
	v_pk_fma_f32 v[32:33], v[220:221], v[204:205], v[32:33] op_sel_hi:[0,1,1] neg_lo:[0,0,1]
	v_add_f32_e32 v214, 0x3e000000, v201
	v_cos_f32_e32 v210, v214
	v_sin_f32_e64 v211, -v214
	s_waitcnt lgkmcnt(6)
	v_pk_add_f32 v[202:203], v[34:35], v[38:39]
	v_pk_add_f32 v[34:35], v[34:35], v[38:39] neg_lo:[0,1] neg_hi:[0,1]
	v_pk_add_f32 v[204:205], v[36:37], v[40:41]
	v_pk_add_f32 v[36:37], v[36:37], v[40:41] neg_lo:[0,1] neg_hi:[0,1]
	v_pk_add_f32 v[38:39], v[202:203], v[204:205]
	v_pk_add_f32 v[40:41], v[202:203], v[204:205] neg_lo:[0,1] neg_hi:[0,1]
	v_pk_add_f32 v[202:203], v[34:35], v[36:37] op_sel:[0,1] op_sel_hi:[1,0] neg_hi:[0,1]
	v_pk_add_f32 v[204:205], v[34:35], v[36:37] op_sel:[0,1] op_sel_hi:[1,0] neg_lo:[0,1]
	v_pk_mul_f32 v[206:207], v[210:211], v[210:211] op_sel:[1,1] op_sel_hi:[1,0]
	v_pk_fma_f32 v[212:213], v[210:211], v[210:211], v[206:207] op_sel_hi:[0,1,1] neg_lo:[0,0,1]
	v_pk_mul_f32 v[206:207], v[210:211], v[212:213] op_sel:[1,1] op_sel_hi:[1,0]
	v_pk_fma_f32 v[220:221], v[210:211], v[212:213], v[206:207] op_sel_hi:[0,1,1] neg_lo:[0,0,1]
	v_pk_mul_f32 v[34:35], v[210:211], v[202:203] op_sel:[1,1] op_sel_hi:[1,0]
	v_pk_fma_f32 v[34:35], v[210:211], v[202:203], v[34:35] op_sel_hi:[0,1,1] neg_lo:[0,0,1]
	v_pk_mul_f32 v[36:37], v[212:213], v[40:41] op_sel:[1,1] op_sel_hi:[1,0]
	v_pk_fma_f32 v[36:37], v[212:213], v[40:41], v[36:37] op_sel_hi:[0,1,1] neg_lo:[0,0,1]
	v_pk_mul_f32 v[40:41], v[220:221], v[204:205] op_sel:[1,1] op_sel_hi:[1,0]
	v_pk_fma_f32 v[40:41], v[220:221], v[204:205], v[40:41] op_sel_hi:[0,1,1] neg_lo:[0,0,1]
	v_add_f32_e32 v214, 0x3e200000, v201
	v_cos_f32_e32 v210, v214
	v_sin_f32_e64 v211, -v214
	s_waitcnt lgkmcnt(4)
; DI f32x2 cmul(f32x2 a, f32x2 b) { return mkf2(a.x * b.x - a.y * b.y, a.x * b.y + a.y * b.x); }
; DI void fft8192(f32x2* buf, const f32x2* __restrict__ tw) {
;     ...
; #pragma unroll
;     for (int e = 0; e < 8; ++e) {
;       const int i = tid + 256 * e;
;       const int q = i & (s - 1);
;       const int ps = i - q;
;       const float rev = (float)ps * (1.f / 8192.f);
;       const f32x2 w1 = mkf2(__builtin_amdgcn_cosf(rev), -__builtin_amdgcn_sinf(rev));
;       const f32x2 w2 = cmul(w1, w1), w3 = cmul(w1, w2);
;       const f32x2 apc = mkf2(a[e].x + c[e].x, a[e].y + c[e].y), amc = mkf2(a[e].x - c[e].x, a[e].y - c[e].y);
;       const f32x2 bpd = mkf2(b[e].x + d[e].x, b[e].y + d[e].y), bmd = mkf2(b[e].x - d[e].x, b[e].y - d[e].y);
;       const int o = 4 * i - 3 * q;
;       buf[SW(o)] = mkf2(apc.x + bpd.x, apc.y + bpd.y);
;       buf[SW(o + s)] = cmul(w1, mkf2(amc.x + bmd.y, amc.y - bmd.x));
;       buf[SW(o + 2 * s)] = cmul(w2, mkf2(apc.x - bpd.x, apc.y - bpd.y));
;       buf[SW(o + 3 * s)] = cmul(w3, mkf2(amc.x - bmd.y, amc.y + bmd.x));
;     }
	v_pk_add_f32 v[202:203], v[42:43], v[46:47]
	v_pk_add_f32 v[42:43], v[42:43], v[46:47] neg_lo:[0,1] neg_hi:[0,1]
	v_pk_add_f32 v[204:205], v[44:45], v[48:49]
	v_pk_add_f32 v[44:45], v[44:45], v[48:49] neg_lo:[0,1] neg_hi:[0,1]
	v_pk_add_f32 v[46:47], v[202:203], v[204:205]
	v_pk_add_f32 v[48:49], v[202:203], v[204:205] neg_lo:[0,1] neg_hi:[0,1]
	v_pk_add_f32 v[202:203], v[42:43], v[44:45] op_sel:[0,1] op_sel_hi:[1,0] neg_hi:[0,1]
	v_pk_add_f32 v[204:205], v[42:43], v[44:45] op_sel:[0,1] op_sel_hi:[1,0] neg_lo:[0,1]
	v_pk_mul_f32 v[206:207], v[210:211], v[210:211] op_sel:[1,1] op_sel_hi:[1,0]
	v_pk_fma_f32 v[212:213], v[210:211], v[210:211], v[206:207] op_sel_hi:[0,1,1] neg_lo:[0,0,1]
	v_pk_mul_f32 v[206:207], v[210:211], v[212:213] op_sel:[1,1] op_sel_hi:[1,0]
	v_pk_fma_f32 v[220:221], v[210:211], v[212:213], v[206:207] op_sel_hi:[0,1,1] neg_lo:[0,0,1]
	v_pk_mul_f32 v[42:43], v[210:211], v[202:203] op_sel:[1,1] op_sel_hi:[1,0]
	v_pk_fma_f32 v[42:43], v[210:211], v[202:203], v[42:43] op_sel_hi:[0,1,1] neg_lo:[0,0,1]
	v_pk_mul_f32 v[44:45], v[212:213], v[48:49] op_sel:[1,1] op_sel_hi:[1,0]
	v_pk_fma_f32 v[44:45], v[212:213], v[48:49], v[44:45] op_sel_hi:[0,1,1] neg_lo:[0,0,1]
	v_pk_mul_f32 v[48:49], v[220:221], v[204:205] op_sel:[1,1] op_sel_hi:[1,0]
	v_pk_fma_f32 v[48:49], v[220:221], v[204:205], v[48:49] op_sel_hi:[0,1,1] neg_lo:[0,0,1]
	v_add_f32_e32 v214, 0x3e400000, v201
	v_cos_f32_e32 v210, v214
	v_sin_f32_e64 v211, -v214
	s_waitcnt lgkmcnt(2)
	v_pk_add_f32 v[202:203], v[50:51], v[54:55]
	v_pk_add_f32 v[50:51], v[50:51], v[54:55] neg_lo:[0,1] neg_hi:[0,1]
	v_pk_add_f32 v[204:205], v[52:53], v[56:57]
	v_pk_add_f32 v[52:53], v[52:53], v[56:57] neg_lo:[0,1] neg_hi:[0,1]
	v_pk_add_f32 v[54:55], v[202:203], v[204:205]
	v_pk_add_f32 v[56:57], v[202:203], v[204:205] neg_lo:[0,1] neg_hi:[0,1]
	v_pk_add_f32 v[202:203], v[50:51], v[52:53] op_sel:[0,1] op_sel_hi:[1,0] neg_hi:[0,1]
	v_pk_add_f32 v[204:205], v[50:51], v[52:53] op_sel:[0,1] op_sel_hi:[1,0] neg_lo:[0,1]
	v_pk_mul_f32 v[206:207], v[210:211], v[210:211] op_sel:[1,1] op_sel_hi:[1,0]
	v_pk_fma_f32 v[212:213], v[210:211], v[210:211], v[206:207] op_sel_hi:[0,1,1] neg_lo:[0,0,1]
	v_pk_mul_f32 v[206:207], v[210:211], v[212:213] op_sel:[1,1] op_sel_hi:[1,0]
	v_pk_fma_f32 v[220:221], v[210:211], v[212:213], v[206:207] op_sel_hi:[0,1,1] neg_lo:[0,0,1]
	v_pk_mul_f32 v[50:51], v[210:211], v[202:203] op_sel:[1,1] op_sel_hi:[1,0]
	v_pk_fma_f32 v[50:51], v[210:211], v[202:203], v[50:51] op_sel_hi:[0,1,1] neg_lo:[0,0,1]
	v_pk_mul_f32 v[52:53], v[212:213], v[56:57] op_sel:[1,1] op_sel_hi:[1,0]
	v_pk_fma_f32 v[52:53], v[212:213], v[56:57], v[52:53] op_sel_hi:[0,1,1] neg_lo:[0,0,1]
	v_pk_mul_f32 v[56:57], v[220:221], v[204:205] op_sel:[1,1] op_sel_hi:[1,0]
	v_pk_fma_f32 v[56:57], v[220:221], v[204:205], v[56:57] op_sel_hi:[0,1,1] neg_lo:[0,0,1]
	v_add_f32_e32 v214, 0x3e600000, v201
	v_cos_f32_e32 v210, v214
	v_sin_f32_e64 v211, -v214
	s_waitcnt lgkmcnt(0)
	v_pk_add_f32 v[202:203], v[58:59], v[62:63]
	v_pk_add_f32 v[58:59], v[58:59], v[62:63] neg_lo:[0,1] neg_hi:[0,1]
	v_pk_add_f32 v[204:205], v[60:61], v[64:65]
	v_pk_add_f32 v[60:61], v[60:61], v[64:65] neg_lo:[0,1] neg_hi:[0,1]
	v_pk_add_f32 v[62:63], v[202:203], v[204:205]
	v_pk_add_f32 v[64:65], v[202:203], v[204:205] neg_lo:[0,1] neg_hi:[0,1]
	v_pk_add_f32 v[202:203], v[58:59], v[60:61] op_sel:[0,1] op_sel_hi:[1,0] neg_hi:[0,1]
	v_pk_add_f32 v[204:205], v[58:59], v[60:61] op_sel:[0,1] op_sel_hi:[1,0] neg_lo:[0,1]
	v_pk_mul_f32 v[206:207], v[210:211], v[210:211] op_sel:[1,1] op_sel_hi:[1,0]
	v_pk_fma_f32 v[212:213], v[210:211], v[210:211], v[206:207] op_sel_hi:[0,1,1] neg_lo:[0,0,1]
	v_pk_mul_f32 v[206:207], v[210:211], v[212:213] op_sel:[1,1] op_sel_hi:[1,0]
	v_pk_fma_f32 v[220:221], v[210:211], v[212:213], v[206:207] op_sel_hi:[0,1,1] neg_lo:[0,0,1]
	v_pk_mul_f32 v[58:59], v[210:211], v[202:203] op_sel:[1,1] op_sel_hi:[1,0]
	v_pk_fma_f32 v[58:59], v[210:211], v[202:203], v[58:59] op_sel_hi:[0,1,1] neg_lo:[0,0,1]
	v_pk_mul_f32 v[60:61], v[212:213], v[64:65] op_sel:[1,1] op_sel_hi:[1,0]
	v_pk_fma_f32 v[60:61], v[212:213], v[64:65], v[60:61] op_sel_hi:[0,1,1] neg_lo:[0,0,1]
	v_pk_mul_f32 v[64:65], v[220:221], v[204:205] op_sel:[1,1] op_sel_hi:[1,0]
	v_pk_fma_f32 v[64:65], v[220:221], v[204:205], v[64:65] op_sel_hi:[0,1,1] neg_lo:[0,0,1]
	s_barrier
	ds_write_b64 v156, v[6:7] offset:0
	ds_write_b64 v158, v[2:3] offset:0
	ds_write_b64 v160, v[4:5] offset:0
	ds_write_b64 v162, v[8:9] offset:0
	ds_write_b64 v156, v[14:15] offset:8192
	ds_write_b64 v158, v[10:11] offset:8192
	ds_write_b64 v160, v[12:13] offset:8192
	ds_write_b64 v162, v[16:17] offset:8192
	ds_write_b64 v156, v[22:23] offset:16384
	ds_write_b64 v158, v[18:19] offset:16384
	ds_write_b64 v160, v[20:21] offset:16384
	ds_write_b64 v162, v[24:25] offset:16384
	ds_write_b64 v156, v[30:31] offset:24576
	ds_write_b64 v158, v[26:27] offset:24576
	ds_write_b64 v160, v[28:29] offset:24576
	ds_write_b64 v162, v[32:33] offset:24576
	ds_write_b64 v156, v[38:39] offset:32768
	ds_write_b64 v158, v[34:35] offset:32768
	ds_write_b64 v160, v[36:37] offset:32768
	ds_write_b64 v162, v[40:41] offset:32768
	ds_write_b64 v156, v[46:47] offset:40960
	ds_write_b64 v158, v[42:43] offset:40960
	ds_write_b64 v160, v[44:45] offset:40960
	ds_write_b64 v162, v[48:49] offset:40960
	ds_write_b64 v156, v[54:55] offset:49152
	ds_write_b64 v158, v[50:51] offset:49152
	ds_write_b64 v160, v[52:53] offset:49152
	ds_write_b64 v162, v[56:57] offset:49152
	ds_write_b64 v156, v[62:63] offset:57344
	ds_write_b64 v158, v[58:59] offset:57344
	ds_write_b64 v160, v[60:61] offset:57344
	ds_write_b64 v162, v[64:65] offset:57344
	s_waitcnt lgkmcnt(0)
	s_barrier
; DI f32x2 cmul(f32x2 a, f32x2 b) { return mkf2(a.x * b.x - a.y * b.y, a.x * b.y + a.y * b.x); }
; DI void fft8192(f32x2* buf, const f32x2* __restrict__ tw) {
;     ...
;   for (int ls = 0; ls < 12; ls += 2) {
;     const int s = 1 << ls;
;     f32x2 a[8], b[8], c[8], d[8];
;     __syncthreads();
; #pragma unroll
;     for (int e = 0; e < 8; ++e) {
;       const int i = tid + 256 * e;
;       const int pi = SW(i);
;       a[e] = buf[pi]; b[e] = buf[pi + 2048]; c[e] = buf[pi + 4096]; d[e] = buf[pi + 6144];
;     }
;     __syncthreads();
; #pragma unroll
;     for (int e = 0; e < 8; ++e) {
;       const int i = tid + 256 * e;
;       const int q = i & (s - 1);
;       const int ps = i - q;
;       const float rev = (float)ps * (1.f / 8192.f);
;       const f32x2 w1 = mkf2(__builtin_amdgcn_cosf(rev), -__builtin_amdgcn_sinf(rev));
;       const f32x2 w2 = cmul(w1, w1), w3 = cmul(w1, w2);
;       const f32x2 apc = mkf2(a[e].x + c[e].x, a[e].y + c[e].y), amc = mkf2(a[e].x - c[e].x, a[e].y - c[e].y);
;       const f32x2 bpd = mkf2(b[e].x + d[e].x, b[e].y + d[e].y), bmd = mkf2(b[e].x - d[e].x, b[e].y - d[e].y);
;       const int o = 4 * i - 3 * q;
;       buf[SW(o)] = mkf2(apc.x + bpd.x, apc.y + bpd.y);
;       buf[SW(o + s)] = cmul(w1, mkf2(amc.x + bmd.y, amc.y - bmd.x));
;       buf[SW(o + 2 * s)] = cmul(w2, mkf2(apc.x - bpd.x, apc.y - bpd.y));
;       buf[SW(o + 3 * s)] = cmul(w3, mkf2(amc.x - bmd.y, amc.y + bmd.x));
	ds_read2st64_b64 v[2:5], v154 offset0:0 offset1:32
	ds_read2st64_b64 v[6:9], v154 offset0:64 offset1:96
	ds_read2st64_b64 v[10:13], v154 offset0:4 offset1:36
	ds_read2st64_b64 v[14:17], v154 offset0:68 offset1:100
	ds_read2st64_b64 v[18:21], v154 offset0:8 offset1:40
	ds_read2st64_b64 v[22:25], v154 offset0:72 offset1:104
	ds_read2st64_b64 v[26:29], v154 offset0:12 offset1:44
	ds_read2st64_b64 v[30:33], v154 offset0:76 offset1:108
	ds_read2st64_b64 v[34:37], v154 offset0:16 offset1:48
	ds_read2st64_b64 v[38:41], v154 offset0:80 offset1:112
	ds_read2st64_b64 v[42:45], v154 offset0:20 offset1:52
	ds_read2st64_b64 v[46:49], v154 offset0:84 offset1:116
	ds_read2st64_b64 v[50:53], v154 offset0:24 offset1:56
	ds_read2st64_b64 v[54:57], v154 offset0:88 offset1:120
	ds_read2st64_b64 v[58:61], v154 offset0:28 offset1:60
	ds_read2st64_b64 v[62:65], v154 offset0:92 offset1:124
	s_waitcnt lgkmcnt(14)
	v_pk_add_f32 v[202:203], v[2:3], v[6:7]
	v_pk_add_f32 v[2:3], v[2:3], v[6:7] neg_lo:[0,1] neg_hi:[0,1]
	v_pk_add_f32 v[204:205], v[4:5], v[8:9]
	v_pk_add_f32 v[4:5], v[4:5], v[8:9] neg_lo:[0,1] neg_hi:[0,1]
	v_pk_add_f32 v[6:7], v[202:203], v[204:205]
	v_pk_add_f32 v[8:9], v[202:203], v[204:205] neg_lo:[0,1] neg_hi:[0,1]
	v_pk_add_f32 v[202:203], v[2:3], v[4:5] op_sel:[0,1] op_sel_hi:[1,0] neg_hi:[0,1]
	v_pk_add_f32 v[4:5], v[2:3], v[4:5] op_sel:[0,1] op_sel_hi:[1,0] neg_lo:[0,1]
	v_pk_mov_b32 v[2:3], v[202:203], v[202:203] op_sel:[0,1]
	v_cos_f32_e32 v210, 0x3d000000
	v_sin_f32_e32 v211, 0xbd000000
	s_waitcnt lgkmcnt(12)
	v_pk_add_f32 v[202:203], v[10:11], v[14:15]
	v_pk_add_f32 v[10:11], v[10:11], v[14:15] neg_lo:[0,1] neg_hi:[0,1]
	v_pk_add_f32 v[204:205], v[12:13], v[16:17]
	v_pk_add_f32 v[12:13], v[12:13], v[16:17] neg_lo:[0,1] neg_hi:[0,1]
	v_pk_add_f32 v[14:15], v[202:203], v[204:205]
	v_pk_add_f32 v[16:17], v[202:203], v[204:205] neg_lo:[0,1] neg_hi:[0,1]
	v_pk_add_f32 v[202:203], v[10:11], v[12:13] op_sel:[0,1] op_sel_hi:[1,0] neg_hi:[0,1]
	v_pk_add_f32 v[204:205], v[10:11], v[12:13] op_sel:[0,1] op_sel_hi:[1,0] neg_lo:[0,1]
	v_pk_mul_f32 v[206:207], v[210:211], v[210:211] op_sel:[1,1] op_sel_hi:[1,0]
	v_pk_fma_f32 v[212:213], v[210:211], v[210:211], v[206:207] op_sel_hi:[0,1,1] neg_lo:[0,0,1]
	v_pk_mul_f32 v[206:207], v[210:211], v[212:213] op_sel:[1,1] op_sel_hi:[1,0]
	v_pk_fma_f32 v[220:221], v[210:211], v[212:213], v[206:207] op_sel_hi:[0,1,1] neg_lo:[0,0,1]
	v_pk_mul_f32 v[10:11], v[210:211], v[202:203] op_sel:[1,1] op_sel_hi:[1,0]
	v_pk_fma_f32 v[10:11], v[210:211], v[202:203], v[10:11] op_sel_hi:[0,1,1] neg_lo:[0,0,1]
	v_pk_mul_f32 v[12:13], v[212:213], v[16:17] op_sel:[1,1] op_sel_hi:[1,0]
	v_pk_fma_f32 v[12:13], v[212:213], v[16:17], v[12:13] op_sel_hi:[0,1,1] neg_lo:[0,0,1]
	v_pk_mul_f32 v[16:17], v[220:221], v[204:205] op_sel:[1,1] op_sel_hi:[1,0]
	v_pk_fma_f32 v[16:17], v[220:221], v[204:205], v[16:17] op_sel_hi:[0,1,1] neg_lo:[0,0,1]
	v_cos_f32_e32 v210, 0x3d800000
	v_sin_f32_e32 v211, 0xbd800000
	s_waitcnt lgkmcnt(10)
	v_pk_add_f32 v[202:203], v[18:19], v[22:23]
	v_pk_add_f32 v[18:19], v[18:19], v[22:23] neg_lo:[0,1] neg_hi:[0,1]
	v_pk_add_f32 v[204:205], v[20:21], v[24:25]
	v_pk_add_f32 v[20:21], v[20:21], v[24:25] neg_lo:[0,1] neg_hi:[0,1]
	v_pk_add_f32 v[22:23], v[202:203], v[204:205]
	v_pk_add_f32 v[24:25], v[202:203], v[204:205] neg_lo:[0,1] neg_hi:[0,1]
	v_pk_add_f32 v[202:203], v[18:19], v[20:21] op_sel:[0,1] op_sel_hi:[1,0] neg_hi:[0,1]
	v_pk_add_f32 v[204:205], v[18:19], v[20:21] op_sel:[0,1] op_sel_hi:[1,0] neg_lo:[0,1]
	v_pk_mul_f32 v[206:207], v[210:211], v[210:211] op_sel:[1,1] op_sel_hi:[1,0]
	v_pk_fma_f32 v[212:213], v[210:211], v[210:211], v[206:207] op_sel_hi:[0,1,1] neg_lo:[0,0,1]
	v_pk_mul_f32 v[206:207], v[210:211], v[212:213] op_sel:[1,1] op_sel_hi:[1,0]
	v_pk_fma_f32 v[220:221], v[210:211], v[212:213], v[206:207] op_sel_hi:[0,1,1] neg_lo:[0,0,1]
	v_pk_mul_f32 v[18:19], v[210:211], v[202:203] op_sel:[1,1] op_sel_hi:[1,0]
	v_pk_fma_f32 v[18:19], v[210:211], v[202:203], v[18:19] op_sel_hi:[0,1,1] neg_lo:[0,0,1]
	v_pk_mul_f32 v[20:21], v[212:213], v[24:25] op_sel:[1,1] op_sel_hi:[1,0]
	v_pk_fma_f32 v[20:21], v[212:213], v[24:25], v[20:21] op_sel_hi:[0,1,1] neg_lo:[0,0,1]
	v_pk_mul_f32 v[24:25], v[220:221], v[204:205] op_sel:[1,1] op_sel_hi:[1,0]
	v_pk_fma_f32 v[24:25], v[220:221], v[204:205], v[24:25] op_sel_hi:[0,1,1] neg_lo:[0,0,1]
	v_cos_f32_e32 v210, 0x3dc00000
	v_sin_f32_e32 v211, 0xbdc00000
	s_waitcnt lgkmcnt(8)
	v_pk_add_f32 v[202:203], v[26:27], v[30:31]
	v_pk_add_f32 v[26:27], v[26:27], v[30:31] neg_lo:[0,1] neg_hi:[0,1]
	v_pk_add_f32 v[204:205], v[28:29], v[32:33]
	v_pk_add_f32 v[28:29], v[28:29], v[32:33] neg_lo:[0,1] neg_hi:[0,1]
	v_pk_add_f32 v[30:31], v[202:203], v[204:205]
	v_pk_add_f32 v[32:33], v[202:203], v[204:205] neg_lo:[0,1] neg_hi:[0,1]
	v_pk_add_f32 v[202:203], v[26:27], v[28:29] op_sel:[0,1] op_sel_hi:[1,0] neg_hi:[0,1]
	v_pk_add_f32 v[204:205], v[26:27], v[28:29] op_sel:[0,1] op_sel_hi:[1,0] neg_lo:[0,1]
	v_pk_mul_f32 v[206:207], v[210:211], v[210:211] op_sel:[1,1] op_sel_hi:[1,0]
	v_pk_fma_f32 v[212:213], v[210:211], v[210:211], v[206:207] op_sel_hi:[0,1,1] neg_lo:[0,0,1]
	v_pk_mul_f32 v[206:207], v[210:211], v[212:213] op_sel:[1,1] op_sel_hi:[1,0]
	v_pk_fma_f32 v[220:221], v[210:211], v[212:213], v[206:207] op_sel_hi:[0,1,1] neg_lo:[0,0,1]
	v_pk_mul_f32 v[26:27], v[210:211], v[202:203] op_sel:[1,1] op_sel_hi:[1,0]
	v_pk_fma_f32 v[26:27], v[210:211], v[202:203], v[26:27] op_sel_hi:[0,1,1] neg_lo:[0,0,1]
	v_pk_mul_f32 v[28:29], v[212:213], v[32:33] op_sel:[1,1] op_sel_hi:[1,0]
	v_pk_fma_f32 v[28:29], v[212:213], v[32:33], v[28:29] op_sel_hi:[0,1,1] neg_lo:[0,0,1]
	v_pk_mul_f32 v[32:33], v[220:221], v[204:205] op_sel:[1,1] op_sel_hi:[1,0]
	v_pk_fma_f32 v[32:33], v[220:221], v[204:205], v[32:33] op_sel_hi:[0,1,1] neg_lo:[0,0,1]
	v_cos_f32_e32 v210, 0x3e000000
	v_sin_f32_e32 v211, 0xbe000000
	s_waitcnt lgkmcnt(6)
; DI f32x2 cmul(f32x2 a, f32x2 b) { return mkf2(a.x * b.x - a.y * b.y, a.x * b.y + a.y * b.x); }
; DI void fft8192(f32x2* buf, const f32x2* __restrict__ tw) {
;     ...
; #pragma unroll
;     for (int e = 0; e < 8; ++e) {
;       const int i = tid + 256 * e;
;       const int q = i & (s - 1);
;       const int ps = i - q;
;       const float rev = (float)ps * (1.f / 8192.f);
;       const f32x2 w1 = mkf2(__builtin_amdgcn_cosf(rev), -__builtin_amdgcn_sinf(rev));
;       const f32x2 w2 = cmul(w1, w1), w3 = cmul(w1, w2);
;       const f32x2 apc = mkf2(a[e].x + c[e].x, a[e].y + c[e].y), amc = mkf2(a[e].x - c[e].x, a[e].y - c[e].y);
;       const f32x2 bpd = mkf2(b[e].x + d[e].x, b[e].y + d[e].y), bmd = mkf2(b[e].x - d[e].x, b[e].y - d[e].y);
;       const int o = 4 * i - 3 * q;
;       buf[SW(o)] = mkf2(apc.x + bpd.x, apc.y + bpd.y);
;       buf[SW(o + s)] = cmul(w1, mkf2(amc.x + bmd.y, amc.y - bmd.x));
;       buf[SW(o + 2 * s)] = cmul(w2, mkf2(apc.x - bpd.x, apc.y - bpd.y));
;       buf[SW(o + 3 * s)] = cmul(w3, mkf2(amc.x - bmd.y, amc.y + bmd.x));
	v_pk_add_f32 v[202:203], v[34:35], v[38:39]
	v_pk_add_f32 v[34:35], v[34:35], v[38:39] neg_lo:[0,1] neg_hi:[0,1]
	v_pk_add_f32 v[204:205], v[36:37], v[40:41]
	v_pk_add_f32 v[36:37], v[36:37], v[40:41] neg_lo:[0,1] neg_hi:[0,1]
	v_pk_add_f32 v[38:39], v[202:203], v[204:205]
	v_pk_add_f32 v[40:41], v[202:203], v[204:205] neg_lo:[0,1] neg_hi:[0,1]
	v_pk_add_f32 v[202:203], v[34:35], v[36:37] op_sel:[0,1] op_sel_hi:[1,0] neg_hi:[0,1]
	v_pk_add_f32 v[204:205], v[34:35], v[36:37] op_sel:[0,1] op_sel_hi:[1,0] neg_lo:[0,1]
	v_pk_mul_f32 v[206:207], v[210:211], v[210:211] op_sel:[1,1] op_sel_hi:[1,0]
	v_pk_fma_f32 v[212:213], v[210:211], v[210:211], v[206:207] op_sel_hi:[0,1,1] neg_lo:[0,0,1]
	v_pk_mul_f32 v[206:207], v[210:211], v[212:213] op_sel:[1,1] op_sel_hi:[1,0]
	v_pk_fma_f32 v[220:221], v[210:211], v[212:213], v[206:207] op_sel_hi:[0,1,1] neg_lo:[0,0,1]
	v_pk_mul_f32 v[34:35], v[210:211], v[202:203] op_sel:[1,1] op_sel_hi:[1,0]
	v_pk_fma_f32 v[34:35], v[210:211], v[202:203], v[34:35] op_sel_hi:[0,1,1] neg_lo:[0,0,1]
	v_pk_mul_f32 v[36:37], v[212:213], v[40:41] op_sel:[1,1] op_sel_hi:[1,0]
	v_pk_fma_f32 v[36:37], v[212:213], v[40:41], v[36:37] op_sel_hi:[0,1,1] neg_lo:[0,0,1]
	v_pk_mul_f32 v[40:41], v[220:221], v[204:205] op_sel:[1,1] op_sel_hi:[1,0]
	v_pk_fma_f32 v[40:41], v[220:221], v[204:205], v[40:41] op_sel_hi:[0,1,1] neg_lo:[0,0,1]
	v_cos_f32_e32 v210, 0x3e200000
	v_sin_f32_e32 v211, 0xbe200000
	s_waitcnt lgkmcnt(4)
	v_pk_add_f32 v[202:203], v[42:43], v[46:47]
	v_pk_add_f32 v[42:43], v[42:43], v[46:47] neg_lo:[0,1] neg_hi:[0,1]
	v_pk_add_f32 v[204:205], v[44:45], v[48:49]
	v_pk_add_f32 v[44:45], v[44:45], v[48:49] neg_lo:[0,1] neg_hi:[0,1]
	v_pk_add_f32 v[46:47], v[202:203], v[204:205]
	v_pk_add_f32 v[48:49], v[202:203], v[204:205] neg_lo:[0,1] neg_hi:[0,1]
	v_pk_add_f32 v[202:203], v[42:43], v[44:45] op_sel:[0,1] op_sel_hi:[1,0] neg_hi:[0,1]
	v_pk_add_f32 v[204:205], v[42:43], v[44:45] op_sel:[0,1] op_sel_hi:[1,0] neg_lo:[0,1]
	v_pk_mul_f32 v[206:207], v[210:211], v[210:211] op_sel:[1,1] op_sel_hi:[1,0]
	v_pk_fma_f32 v[212:213], v[210:211], v[210:211], v[206:207] op_sel_hi:[0,1,1] neg_lo:[0,0,1]
	v_pk_mul_f32 v[206:207], v[210:211], v[212:213] op_sel:[1,1] op_sel_hi:[1,0]
	v_pk_fma_f32 v[220:221], v[210:211], v[212:213], v[206:207] op_sel_hi:[0,1,1] neg_lo:[0,0,1]
	v_pk_mul_f32 v[42:43], v[210:211], v[202:203] op_sel:[1,1] op_sel_hi:[1,0]
	v_pk_fma_f32 v[42:43], v[210:211], v[202:203], v[42:43] op_sel_hi:[0,1,1] neg_lo:[0,0,1]
	v_pk_mul_f32 v[44:45], v[212:213], v[48:49] op_sel:[1,1] op_sel_hi:[1,0]
	v_pk_fma_f32 v[44:45], v[212:213], v[48:49], v[44:45] op_sel_hi:[0,1,1] neg_lo:[0,0,1]
	v_pk_mul_f32 v[48:49], v[220:221], v[204:205] op_sel:[1,1] op_sel_hi:[1,0]
	v_pk_fma_f32 v[48:49], v[220:221], v[204:205], v[48:49] op_sel_hi:[0,1,1] neg_lo:[0,0,1]
	v_cos_f32_e32 v210, 0x3e400000
	v_sin_f32_e32 v211, 0xbe400000
	s_waitcnt lgkmcnt(2)
	v_pk_add_f32 v[202:203], v[50:51], v[54:55]
	v_pk_add_f32 v[50:51], v[50:51], v[54:55] neg_lo:[0,1] neg_hi:[0,1]
	v_pk_add_f32 v[204:205], v[52:53], v[56:57]
	v_pk_add_f32 v[52:53], v[52:53], v[56:57] neg_lo:[0,1] neg_hi:[0,1]
	v_pk_add_f32 v[54:55], v[202:203], v[204:205]
	v_pk_add_f32 v[56:57], v[202:203], v[204:205] neg_lo:[0,1] neg_hi:[0,1]
	v_pk_add_f32 v[202:203], v[50:51], v[52:53] op_sel:[0,1] op_sel_hi:[1,0] neg_hi:[0,1]
	v_pk_add_f32 v[204:205], v[50:51], v[52:53] op_sel:[0,1] op_sel_hi:[1,0] neg_lo:[0,1]
	v_pk_mul_f32 v[206:207], v[210:211], v[210:211] op_sel:[1,1] op_sel_hi:[1,0]
	v_pk_fma_f32 v[212:213], v[210:211], v[210:211], v[206:207] op_sel_hi:[0,1,1] neg_lo:[0,0,1]
	v_pk_mul_f32 v[206:207], v[210:211], v[212:213] op_sel:[1,1] op_sel_hi:[1,0]
	v_pk_fma_f32 v[220:221], v[210:211], v[212:213], v[206:207] op_sel_hi:[0,1,1] neg_lo:[0,0,1]
	v_pk_mul_f32 v[50:51], v[210:211], v[202:203] op_sel:[1,1] op_sel_hi:[1,0]
	v_pk_fma_f32 v[50:51], v[210:211], v[202:203], v[50:51] op_sel_hi:[0,1,1] neg_lo:[0,0,1]
	v_pk_mul_f32 v[52:53], v[212:213], v[56:57] op_sel:[1,1] op_sel_hi:[1,0]
	v_pk_fma_f32 v[52:53], v[212:213], v[56:57], v[52:53] op_sel_hi:[0,1,1] neg_lo:[0,0,1]
	v_pk_mul_f32 v[56:57], v[220:221], v[204:205] op_sel:[1,1] op_sel_hi:[1,0]
	v_pk_fma_f32 v[56:57], v[220:221], v[204:205], v[56:57] op_sel_hi:[0,1,1] neg_lo:[0,0,1]
	v_cos_f32_e32 v210, 0x3e600000
	v_sin_f32_e32 v211, 0xbe600000
	s_waitcnt lgkmcnt(0)
	v_pk_add_f32 v[202:203], v[58:59], v[62:63]
	v_pk_add_f32 v[58:59], v[58:59], v[62:63] neg_lo:[0,1] neg_hi:[0,1]
	v_pk_add_f32 v[204:205], v[60:61], v[64:65]
	v_pk_add_f32 v[60:61], v[60:61], v[64:65] neg_lo:[0,1] neg_hi:[0,1]
	v_pk_add_f32 v[62:63], v[202:203], v[204:205]
	v_pk_add_f32 v[64:65], v[202:203], v[204:205] neg_lo:[0,1] neg_hi:[0,1]
	v_pk_add_f32 v[202:203], v[58:59], v[60:61] op_sel:[0,1] op_sel_hi:[1,0] neg_hi:[0,1]
	v_pk_add_f32 v[204:205], v[58:59], v[60:61] op_sel:[0,1] op_sel_hi:[1,0] neg_lo:[0,1]
	v_pk_mul_f32 v[206:207], v[210:211], v[210:211] op_sel:[1,1] op_sel_hi:[1,0]
	v_pk_fma_f32 v[212:213], v[210:211], v[210:211], v[206:207] op_sel_hi:[0,1,1] neg_lo:[0,0,1]
	v_pk_mul_f32 v[206:207], v[210:211], v[212:213] op_sel:[1,1] op_sel_hi:[1,0]
	v_pk_fma_f32 v[220:221], v[210:211], v[212:213], v[206:207] op_sel_hi:[0,1,1] neg_lo:[0,0,1]
	v_pk_mul_f32 v[58:59], v[210:211], v[202:203] op_sel:[1,1] op_sel_hi:[1,0]
	v_pk_fma_f32 v[58:59], v[210:211], v[202:203], v[58:59] op_sel_hi:[0,1,1] neg_lo:[0,0,1]
	v_pk_mul_f32 v[60:61], v[212:213], v[64:65] op_sel:[1,1] op_sel_hi:[1,0]
	v_pk_fma_f32 v[60:61], v[212:213], v[64:65], v[60:61] op_sel_hi:[0,1,1] neg_lo:[0,0,1]
	v_pk_mul_f32 v[64:65], v[220:221], v[204:205] op_sel:[1,1] op_sel_hi:[1,0]
	v_pk_fma_f32 v[64:65], v[220:221], v[204:205], v[64:65] op_sel_hi:[0,1,1] neg_lo:[0,0,1]
	s_barrier
; DI f32x2 cmul(f32x2 a, f32x2 b) { return mkf2(a.x * b.x - a.y * b.y, a.x * b.y + a.y * b.x); }
; DI void fft8192(f32x2* buf, const f32x2* __restrict__ tw) {
;     ...
;   for (int ls = 0; ls < 12; ls += 2) {
;     const int s = 1 << ls;
;     f32x2 a[8], b[8], c[8], d[8];
;     __syncthreads();
; #pragma unroll
;     for (int e = 0; e < 8; ++e) {
;       const int i = tid + 256 * e;
;       const int pi = SW(i);
;       a[e] = buf[pi]; b[e] = buf[pi + 2048]; c[e] = buf[pi + 4096]; d[e] = buf[pi + 6144];
;     }
;     __syncthreads();
; #pragma unroll
;     for (int e = 0; e < 8; ++e) {
;       const int i = tid + 256 * e;
;       const int q = i & (s - 1);
;       const int ps = i - q;
;       const float rev = (float)ps * (1.f / 8192.f);
;       const f32x2 w1 = mkf2(__builtin_amdgcn_cosf(rev), -__builtin_amdgcn_sinf(rev));
;       const f32x2 w2 = cmul(w1, w1), w3 = cmul(w1, w2);
;       const f32x2 apc = mkf2(a[e].x + c[e].x, a[e].y + c[e].y), amc = mkf2(a[e].x - c[e].x, a[e].y - c[e].y);
;       const f32x2 bpd = mkf2(b[e].x + d[e].x, b[e].y + d[e].y), bmd = mkf2(b[e].x - d[e].x, b[e].y - d[e].y);
;       const int o = 4 * i - 3 * q;
;       buf[SW(o)] = mkf2(apc.x + bpd.x, apc.y + bpd.y);
;       buf[SW(o + s)] = cmul(w1, mkf2(amc.x + bmd.y, amc.y - bmd.x));
;       buf[SW(o + 2 * s)] = cmul(w2, mkf2(apc.x - bpd.x, apc.y - bpd.y));
;       buf[SW(o + 3 * s)] = cmul(w3, mkf2(amc.x - bmd.y, amc.y + bmd.x));
;     }
	ds_write_b64 v154, v[6:7] offset:0
	ds_write_b64 v154, v[2:3] offset:2048
	ds_write_b64 v154, v[8:9] offset:4096
	ds_write_b64 v154, v[4:5] offset:6144
	ds_write_b64 v154, v[14:15] offset:8192
	ds_write_b64 v154, v[10:11] offset:10240
	ds_write_b64 v154, v[12:13] offset:12288
	ds_write_b64 v154, v[16:17] offset:14336
	ds_write_b64 v154, v[22:23] offset:16384
	ds_write_b64 v154, v[18:19] offset:18432
	ds_write_b64 v154, v[20:21] offset:20480
	ds_write_b64 v154, v[24:25] offset:22528
	ds_write_b64 v154, v[30:31] offset:24576
	ds_write_b64 v154, v[26:27] offset:26624
	ds_write_b64 v154, v[28:29] offset:28672
	ds_write_b64 v154, v[32:33] offset:30720
	ds_write_b64 v154, v[38:39] offset:32768
	ds_write_b64 v154, v[34:35] offset:34816
	ds_write_b64 v154, v[36:37] offset:36864
	ds_write_b64 v154, v[40:41] offset:38912
	ds_write_b64 v154, v[46:47] offset:40960
	ds_write_b64 v154, v[42:43] offset:43008
	ds_write_b64 v154, v[44:45] offset:45056
	ds_write_b64 v154, v[48:49] offset:47104
	ds_write_b64 v154, v[54:55] offset:49152
	ds_write_b64 v154, v[50:51] offset:51200
	ds_write_b64 v154, v[52:53] offset:53248
	ds_write_b64 v154, v[56:57] offset:55296
	ds_write_b64 v154, v[62:63] offset:57344
	ds_write_b64 v154, v[58:59] offset:59392
	ds_write_b64 v154, v[60:61] offset:61440
	ds_write_b64 v154, v[64:65] offset:63488
	s_waitcnt lgkmcnt(0)
	s_barrier
	ds_read2st64_b64 v[2:5], v154 offset0:0 offset1:32
	ds_read2st64_b64 v[6:9], v154 offset0:64 offset1:96
	ds_read2st64_b64 v[10:13], v154 offset0:4 offset1:36
	ds_read2st64_b64 v[14:17], v154 offset0:68 offset1:100
	ds_read2st64_b64 v[18:21], v154 offset0:8 offset1:40
	ds_read2st64_b64 v[22:25], v154 offset0:72 offset1:104
	ds_read2st64_b64 v[26:29], v154 offset0:12 offset1:44
	ds_read2st64_b64 v[30:33], v154 offset0:76 offset1:108
	ds_read2st64_b64 v[34:37], v154 offset0:16 offset1:48
	ds_read2st64_b64 v[38:41], v154 offset0:80 offset1:112
	ds_read2st64_b64 v[42:45], v154 offset0:20 offset1:52
	ds_read2st64_b64 v[46:49], v154 offset0:84 offset1:116
	ds_read2st64_b64 v[50:53], v154 offset0:24 offset1:56
	ds_read2st64_b64 v[54:57], v154 offset0:88 offset1:120
	ds_read2st64_b64 v[58:61], v154 offset0:28 offset1:60
	ds_read2st64_b64 v[62:65], v154 offset0:92 offset1:124
	s_waitcnt lgkmcnt(14)
	v_pk_add_f32 v[202:203], v[2:3], v[6:7]
	v_pk_add_f32 v[2:3], v[2:3], v[6:7] neg_lo:[0,1] neg_hi:[0,1]
	v_pk_add_f32 v[204:205], v[4:5], v[8:9]
	v_pk_add_f32 v[4:5], v[4:5], v[8:9] neg_lo:[0,1] neg_hi:[0,1]
	v_pk_add_f32 v[6:7], v[202:203], v[204:205]
	v_pk_add_f32 v[8:9], v[202:203], v[204:205] neg_lo:[0,1] neg_hi:[0,1]
	v_pk_add_f32 v[202:203], v[2:3], v[4:5] op_sel:[0,1] op_sel_hi:[1,0] neg_hi:[0,1]
	v_pk_add_f32 v[4:5], v[2:3], v[4:5] op_sel:[0,1] op_sel_hi:[1,0] neg_lo:[0,1]
	v_pk_mov_b32 v[2:3], v[202:203], v[202:203] op_sel:[0,1]
	s_waitcnt lgkmcnt(12)
	v_pk_add_f32 v[202:203], v[10:11], v[14:15]
	v_pk_add_f32 v[10:11], v[10:11], v[14:15] neg_lo:[0,1] neg_hi:[0,1]
	v_pk_add_f32 v[204:205], v[12:13], v[16:17]
	v_pk_add_f32 v[12:13], v[12:13], v[16:17] neg_lo:[0,1] neg_hi:[0,1]
	v_pk_add_f32 v[14:15], v[202:203], v[204:205]
	v_pk_add_f32 v[16:17], v[202:203], v[204:205] neg_lo:[0,1] neg_hi:[0,1]
	v_pk_add_f32 v[202:203], v[10:11], v[12:13] op_sel:[0,1] op_sel_hi:[1,0] neg_hi:[0,1]
	v_pk_add_f32 v[12:13], v[10:11], v[12:13] op_sel:[0,1] op_sel_hi:[1,0] neg_lo:[0,1]
	v_pk_mov_b32 v[10:11], v[202:203], v[202:203] op_sel:[0,1]
	s_waitcnt lgkmcnt(10)
	v_pk_add_f32 v[202:203], v[18:19], v[22:23]
	v_pk_add_f32 v[18:19], v[18:19], v[22:23] neg_lo:[0,1] neg_hi:[0,1]
	v_pk_add_f32 v[204:205], v[20:21], v[24:25]
	v_pk_add_f32 v[20:21], v[20:21], v[24:25] neg_lo:[0,1] neg_hi:[0,1]
	v_pk_add_f32 v[22:23], v[202:203], v[204:205]
	v_pk_add_f32 v[24:25], v[202:203], v[204:205] neg_lo:[0,1] neg_hi:[0,1]
	v_pk_add_f32 v[202:203], v[18:19], v[20:21] op_sel:[0,1] op_sel_hi:[1,0] neg_hi:[0,1]
	v_pk_add_f32 v[20:21], v[18:19], v[20:21] op_sel:[0,1] op_sel_hi:[1,0] neg_lo:[0,1]
	v_pk_mov_b32 v[18:19], v[202:203], v[202:203] op_sel:[0,1]
	s_waitcnt lgkmcnt(8)
	v_pk_add_f32 v[202:203], v[26:27], v[30:31]
	v_pk_add_f32 v[26:27], v[26:27], v[30:31] neg_lo:[0,1] neg_hi:[0,1]
	v_pk_add_f32 v[204:205], v[28:29], v[32:33]
	v_pk_add_f32 v[28:29], v[28:29], v[32:33] neg_lo:[0,1] neg_hi:[0,1]
	v_pk_add_f32 v[30:31], v[202:203], v[204:205]
	v_pk_add_f32 v[32:33], v[202:203], v[204:205] neg_lo:[0,1] neg_hi:[0,1]
	v_pk_add_f32 v[202:203], v[26:27], v[28:29] op_sel:[0,1] op_sel_hi:[1,0] neg_hi:[0,1]
	v_pk_add_f32 v[28:29], v[26:27], v[28:29] op_sel:[0,1] op_sel_hi:[1,0] neg_lo:[0,1]
	v_pk_mov_b32 v[26:27], v[202:203], v[202:203] op_sel:[0,1]
	v_cos_f32_e32 v210, 0x3e000000
	v_sin_f32_e32 v211, 0xbe000000
	s_waitcnt lgkmcnt(6)
	v_pk_add_f32 v[202:203], v[34:35], v[38:39]
	v_pk_add_f32 v[34:35], v[34:35], v[38:39] neg_lo:[0,1] neg_hi:[0,1]
	v_pk_add_f32 v[204:205], v[36:37], v[40:41]
	v_pk_add_f32 v[36:37], v[36:37], v[40:41] neg_lo:[0,1] neg_hi:[0,1]
	v_pk_add_f32 v[38:39], v[202:203], v[204:205]
	v_pk_add_f32 v[40:41], v[202:203], v[204:205] neg_lo:[0,1] neg_hi:[0,1]
	v_pk_add_f32 v[202:203], v[34:35], v[36:37] op_sel:[0,1] op_sel_hi:[1,0] neg_hi:[0,1]
	v_pk_add_f32 v[204:205], v[34:35], v[36:37] op_sel:[0,1] op_sel_hi:[1,0] neg_lo:[0,1]
	v_pk_mul_f32 v[206:207], v[210:211], v[210:211] op_sel:[1,1] op_sel_hi:[1,0]
	v_pk_fma_f32 v[212:213], v[210:211], v[210:211], v[206:207] op_sel_hi:[0,1,1] neg_lo:[0,0,1]
	v_pk_mul_f32 v[206:207], v[210:211], v[212:213] op_sel:[1,1] op_sel_hi:[1,0]
	v_pk_fma_f32 v[220:221], v[210:211], v[212:213], v[206:207] op_sel_hi:[0,1,1] neg_lo:[0,0,1]
	v_pk_mul_f32 v[34:35], v[210:211], v[202:203] op_sel:[1,1] op_sel_hi:[1,0]
	v_pk_fma_f32 v[34:35], v[210:211], v[202:203], v[34:35] op_sel_hi:[0,1,1] neg_lo:[0,0,1]
	v_pk_mul_f32 v[36:37], v[212:213], v[40:41] op_sel:[1,1] op_sel_hi:[1,0]
	v_pk_fma_f32 v[36:37], v[212:213], v[40:41], v[36:37] op_sel_hi:[0,1,1] neg_lo:[0,0,1]
	v_pk_mul_f32 v[40:41], v[220:221], v[204:205] op_sel:[1,1] op_sel_hi:[1,0]
	v_pk_fma_f32 v[40:41], v[220:221], v[204:205], v[40:41] op_sel_hi:[0,1,1] neg_lo:[0,0,1]
	v_cos_f32_e32 v210, 0x3e000000
	v_sin_f32_e32 v211, 0xbe000000
	s_waitcnt lgkmcnt(4)
; DI f32x2 cmul(f32x2 a, f32x2 b) { return mkf2(a.x * b.x - a.y * b.y, a.x * b.y + a.y * b.x); }
; DI void fft8192(f32x2* buf, const f32x2* __restrict__ tw) {
;     ...
; #pragma unroll
;     for (int e = 0; e < 8; ++e) {
;       const int i = tid + 256 * e;
;       const int q = i & (s - 1);
;       const int ps = i - q;
;       const float rev = (float)ps * (1.f / 8192.f);
;       const f32x2 w1 = mkf2(__builtin_amdgcn_cosf(rev), -__builtin_amdgcn_sinf(rev));
;       const f32x2 w2 = cmul(w1, w1), w3 = cmul(w1, w2);
;       const f32x2 apc = mkf2(a[e].x + c[e].x, a[e].y + c[e].y), amc = mkf2(a[e].x - c[e].x, a[e].y - c[e].y);
;       const f32x2 bpd = mkf2(b[e].x + d[e].x, b[e].y + d[e].y), bmd = mkf2(b[e].x - d[e].x, b[e].y - d[e].y);
;       const int o = 4 * i - 3 * q;
;       buf[SW(o)] = mkf2(apc.x + bpd.x, apc.y + bpd.y);
;       buf[SW(o + s)] = cmul(w1, mkf2(amc.x + bmd.y, amc.y - bmd.x));
;       buf[SW(o + 2 * s)] = cmul(w2, mkf2(apc.x - bpd.x, apc.y - bpd.y));
;       buf[SW(o + 3 * s)] = cmul(w3, mkf2(amc.x - bmd.y, amc.y + bmd.x));
;     }
	v_pk_add_f32 v[202:203], v[42:43], v[46:47]
	v_pk_add_f32 v[42:43], v[42:43], v[46:47] neg_lo:[0,1] neg_hi:[0,1]
	v_pk_add_f32 v[204:205], v[44:45], v[48:49]
	v_pk_add_f32 v[44:45], v[44:45], v[48:49] neg_lo:[0,1] neg_hi:[0,1]
	v_pk_add_f32 v[46:47], v[202:203], v[204:205]
	v_pk_add_f32 v[48:49], v[202:203], v[204:205] neg_lo:[0,1] neg_hi:[0,1]
	v_pk_add_f32 v[202:203], v[42:43], v[44:45] op_sel:[0,1] op_sel_hi:[1,0] neg_hi:[0,1]
	v_pk_add_f32 v[204:205], v[42:43], v[44:45] op_sel:[0,1] op_sel_hi:[1,0] neg_lo:[0,1]
	v_pk_mul_f32 v[206:207], v[210:211], v[210:211] op_sel:[1,1] op_sel_hi:[1,0]
	v_pk_fma_f32 v[212:213], v[210:211], v[210:211], v[206:207] op_sel_hi:[0,1,1] neg_lo:[0,0,1]
	v_pk_mul_f32 v[206:207], v[210:211], v[212:213] op_sel:[1,1] op_sel_hi:[1,0]
	v_pk_fma_f32 v[220:221], v[210:211], v[212:213], v[206:207] op_sel_hi:[0,1,1] neg_lo:[0,0,1]
	v_pk_mul_f32 v[42:43], v[210:211], v[202:203] op_sel:[1,1] op_sel_hi:[1,0]
	v_pk_fma_f32 v[42:43], v[210:211], v[202:203], v[42:43] op_sel_hi:[0,1,1] neg_lo:[0,0,1]
	v_pk_mul_f32 v[44:45], v[212:213], v[48:49] op_sel:[1,1] op_sel_hi:[1,0]
	v_pk_fma_f32 v[44:45], v[212:213], v[48:49], v[44:45] op_sel_hi:[0,1,1] neg_lo:[0,0,1]
	v_pk_mul_f32 v[48:49], v[220:221], v[204:205] op_sel:[1,1] op_sel_hi:[1,0]
	v_pk_fma_f32 v[48:49], v[220:221], v[204:205], v[48:49] op_sel_hi:[0,1,1] neg_lo:[0,0,1]
	v_cos_f32_e32 v210, 0x3e000000
	v_sin_f32_e32 v211, 0xbe000000
	s_waitcnt lgkmcnt(2)
	v_pk_add_f32 v[202:203], v[50:51], v[54:55]
	v_pk_add_f32 v[50:51], v[50:51], v[54:55] neg_lo:[0,1] neg_hi:[0,1]
	v_pk_add_f32 v[204:205], v[52:53], v[56:57]
	v_pk_add_f32 v[52:53], v[52:53], v[56:57] neg_lo:[0,1] neg_hi:[0,1]
	v_pk_add_f32 v[54:55], v[202:203], v[204:205]
	v_pk_add_f32 v[56:57], v[202:203], v[204:205] neg_lo:[0,1] neg_hi:[0,1]
	v_pk_add_f32 v[202:203], v[50:51], v[52:53] op_sel:[0,1] op_sel_hi:[1,0] neg_hi:[0,1]
	v_pk_add_f32 v[204:205], v[50:51], v[52:53] op_sel:[0,1] op_sel_hi:[1,0] neg_lo:[0,1]
	v_pk_mul_f32 v[206:207], v[210:211], v[210:211] op_sel:[1,1] op_sel_hi:[1,0]
	v_pk_fma_f32 v[212:213], v[210:211], v[210:211], v[206:207] op_sel_hi:[0,1,1] neg_lo:[0,0,1]
	v_pk_mul_f32 v[206:207], v[210:211], v[212:213] op_sel:[1,1] op_sel_hi:[1,0]
	v_pk_fma_f32 v[220:221], v[210:211], v[212:213], v[206:207] op_sel_hi:[0,1,1] neg_lo:[0,0,1]
	v_pk_mul_f32 v[50:51], v[210:211], v[202:203] op_sel:[1,1] op_sel_hi:[1,0]
	v_pk_fma_f32 v[50:51], v[210:211], v[202:203], v[50:51] op_sel_hi:[0,1,1] neg_lo:[0,0,1]
	v_pk_mul_f32 v[52:53], v[212:213], v[56:57] op_sel:[1,1] op_sel_hi:[1,0]
	v_pk_fma_f32 v[52:53], v[212:213], v[56:57], v[52:53] op_sel_hi:[0,1,1] neg_lo:[0,0,1]
	v_pk_mul_f32 v[56:57], v[220:221], v[204:205] op_sel:[1,1] op_sel_hi:[1,0]
	v_pk_fma_f32 v[56:57], v[220:221], v[204:205], v[56:57] op_sel_hi:[0,1,1] neg_lo:[0,0,1]
	v_cos_f32_e32 v210, 0x3e000000
	v_sin_f32_e32 v211, 0xbe000000
	s_waitcnt lgkmcnt(0)
	v_pk_add_f32 v[202:203], v[58:59], v[62:63]
	v_pk_add_f32 v[58:59], v[58:59], v[62:63] neg_lo:[0,1] neg_hi:[0,1]
	v_pk_add_f32 v[204:205], v[60:61], v[64:65]
	v_pk_add_f32 v[60:61], v[60:61], v[64:65] neg_lo:[0,1] neg_hi:[0,1]
	v_pk_add_f32 v[62:63], v[202:203], v[204:205]
	v_pk_add_f32 v[64:65], v[202:203], v[204:205] neg_lo:[0,1] neg_hi:[0,1]
	v_pk_add_f32 v[202:203], v[58:59], v[60:61] op_sel:[0,1] op_sel_hi:[1,0] neg_hi:[0,1]
	v_pk_add_f32 v[204:205], v[58:59], v[60:61] op_sel:[0,1] op_sel_hi:[1,0] neg_lo:[0,1]
	v_pk_mul_f32 v[206:207], v[210:211], v[210:211] op_sel:[1,1] op_sel_hi:[1,0]
	v_pk_fma_f32 v[212:213], v[210:211], v[210:211], v[206:207] op_sel_hi:[0,1,1] neg_lo:[0,0,1]
	v_pk_mul_f32 v[206:207], v[210:211], v[212:213] op_sel:[1,1] op_sel_hi:[1,0]
	v_pk_fma_f32 v[220:221], v[210:211], v[212:213], v[206:207] op_sel_hi:[0,1,1] neg_lo:[0,0,1]
	v_pk_mul_f32 v[58:59], v[210:211], v[202:203] op_sel:[1,1] op_sel_hi:[1,0]
	v_pk_fma_f32 v[58:59], v[210:211], v[202:203], v[58:59] op_sel_hi:[0,1,1] neg_lo:[0,0,1]
	v_pk_mul_f32 v[60:61], v[212:213], v[64:65] op_sel:[1,1] op_sel_hi:[1,0]
	v_pk_fma_f32 v[60:61], v[212:213], v[64:65], v[60:61] op_sel_hi:[0,1,1] neg_lo:[0,0,1]
	v_pk_mul_f32 v[64:65], v[220:221], v[204:205] op_sel:[1,1] op_sel_hi:[1,0]
	v_pk_fma_f32 v[64:65], v[220:221], v[204:205], v[64:65] op_sel_hi:[0,1,1] neg_lo:[0,0,1]
	s_barrier
	ds_write_b64 v154, v[6:7] offset:0
	ds_write_b64 v154, v[2:3] offset:8192
	ds_write_b64 v154, v[8:9] offset:16384
	ds_write_b64 v154, v[4:5] offset:24576
	ds_write_b64 v154, v[14:15] offset:2048
	ds_write_b64 v154, v[10:11] offset:10240
	ds_write_b64 v154, v[16:17] offset:18432
	ds_write_b64 v154, v[12:13] offset:26624
	ds_write_b64 v154, v[22:23] offset:4096
	ds_write_b64 v154, v[18:19] offset:12288
	ds_write_b64 v154, v[24:25] offset:20480
	ds_write_b64 v154, v[20:21] offset:28672
	ds_write_b64 v154, v[30:31] offset:6144
	ds_write_b64 v154, v[26:27] offset:14336
	ds_write_b64 v154, v[32:33] offset:22528
	ds_write_b64 v154, v[28:29] offset:30720
	ds_write_b64 v154, v[38:39] offset:32768
	ds_write_b64 v154, v[34:35] offset:40960
	ds_write_b64 v154, v[36:37] offset:49152
	ds_write_b64 v154, v[40:41] offset:57344
	ds_write_b64 v154, v[46:47] offset:34816
	ds_write_b64 v154, v[42:43] offset:43008
	ds_write_b64 v154, v[44:45] offset:51200
	ds_write_b64 v154, v[48:49] offset:59392
	ds_write_b64 v154, v[54:55] offset:36864
	ds_write_b64 v154, v[50:51] offset:45056
	ds_write_b64 v154, v[52:53] offset:53248
	ds_write_b64 v154, v[56:57] offset:61440
	ds_write_b64 v154, v[62:63] offset:38912
	ds_write_b64 v154, v[58:59] offset:47104
	ds_write_b64 v154, v[60:61] offset:55296
	ds_write_b64 v154, v[64:65] offset:63488
	s_waitcnt lgkmcnt(0)
	s_barrier
; DI f32x2 cmul(f32x2 a, f32x2 b) { return mkf2(a.x * b.x - a.y * b.y, a.x * b.y + a.y * b.x); }
; DI void fft8192(f32x2* buf, const f32x2* __restrict__ tw) {
;     ...
;   {
;     f32x2 a[16], b[16];
;     __syncthreads();
; #pragma unroll
;     for (int e = 0; e < 16; ++e) { const int pi = SW(tid + 256 * e); a[e] = buf[pi]; b[e] = buf[pi + 4096]; }
;     __syncthreads();
; #pragma unroll
;     for (int e = 0; e < 16; ++e) {
;       const int pi = SW(tid + 256 * e);
;       buf[pi] = mkf2(a[e].x + b[e].x, a[e].y + b[e].y);
;       buf[pi + 4096] = mkf2(a[e].x - b[e].x, a[e].y - b[e].y);
;     }
;     __syncthreads();
;   }
; DI void hyena_unit(KP p, int l, int c, char* smem) {
;     ...
;       for (int j = 0; j < 32; ++j) {
;         const int f = tid + 256 * j;
;         f32x2 z = cmul(buf[SW(f)], KF[j]);
;         buf[SW(f)] = mkf2(z.x, -z.y);
;       }
	ds_read2st64_b64 v[2:5], v154 offset0:0 offset1:64
	ds_read2st64_b64 v[6:9], v154 offset0:4 offset1:68
	ds_read2st64_b64 v[10:13], v154 offset0:8 offset1:72
	ds_read2st64_b64 v[14:17], v154 offset0:12 offset1:76
	ds_read2st64_b64 v[18:21], v154 offset0:16 offset1:80
	ds_read2st64_b64 v[22:25], v154 offset0:20 offset1:84
	ds_read2st64_b64 v[26:29], v154 offset0:24 offset1:88
	ds_read2st64_b64 v[30:33], v154 offset0:28 offset1:92
	ds_read2st64_b64 v[34:37], v154 offset0:32 offset1:96
	ds_read2st64_b64 v[38:41], v154 offset0:36 offset1:100
	ds_read2st64_b64 v[42:45], v154 offset0:40 offset1:104
	ds_read2st64_b64 v[46:49], v154 offset0:44 offset1:108
	ds_read2st64_b64 v[50:53], v154 offset0:48 offset1:112
	ds_read2st64_b64 v[54:57], v154 offset0:52 offset1:116
	ds_read2st64_b64 v[58:61], v154 offset0:56 offset1:120
	ds_read2st64_b64 v[62:65], v154 offset0:60 offset1:124
	s_waitcnt lgkmcnt(15)
	v_pk_add_f32 v[202:203], v[2:3], v[4:5]
	v_pk_add_f32 v[4:5], v[2:3], v[4:5] neg_lo:[0,1] neg_hi:[0,1]
	s_waitcnt lgkmcnt(14)
	v_pk_add_f32 v[204:205], v[6:7], v[8:9]
	v_pk_add_f32 v[8:9], v[6:7], v[8:9] neg_lo:[0,1] neg_hi:[0,1]
	s_waitcnt lgkmcnt(13)
	v_pk_add_f32 v[206:207], v[10:11], v[12:13]
	v_pk_add_f32 v[12:13], v[10:11], v[12:13] neg_lo:[0,1] neg_hi:[0,1]
	s_waitcnt lgkmcnt(12)
	v_pk_add_f32 v[208:209], v[14:15], v[16:17]
	v_pk_add_f32 v[16:17], v[14:15], v[16:17] neg_lo:[0,1] neg_hi:[0,1]
	s_waitcnt lgkmcnt(11)
	v_pk_add_f32 v[210:211], v[18:19], v[20:21]
	v_pk_add_f32 v[20:21], v[18:19], v[20:21] neg_lo:[0,1] neg_hi:[0,1]
	s_waitcnt lgkmcnt(10)
	v_pk_add_f32 v[212:213], v[22:23], v[24:25]
	v_pk_add_f32 v[24:25], v[22:23], v[24:25] neg_lo:[0,1] neg_hi:[0,1]
	s_waitcnt lgkmcnt(9)
	v_pk_add_f32 v[220:221], v[26:27], v[28:29]
	v_pk_add_f32 v[28:29], v[26:27], v[28:29] neg_lo:[0,1] neg_hi:[0,1]
	s_waitcnt lgkmcnt(8)
	v_pk_add_f32 v[224:225], v[30:31], v[32:33]
	v_pk_add_f32 v[32:33], v[30:31], v[32:33] neg_lo:[0,1] neg_hi:[0,1]
	s_waitcnt lgkmcnt(7)
	v_pk_add_f32 v[226:227], v[34:35], v[36:37]
	v_pk_add_f32 v[36:37], v[34:35], v[36:37] neg_lo:[0,1] neg_hi:[0,1]
	s_waitcnt lgkmcnt(6)
	v_pk_add_f32 v[230:231], v[38:39], v[40:41]
	v_pk_add_f32 v[40:41], v[38:39], v[40:41] neg_lo:[0,1] neg_hi:[0,1]
	s_waitcnt lgkmcnt(5)
	v_pk_add_f32 v[232:233], v[42:43], v[44:45]
	v_pk_add_f32 v[44:45], v[42:43], v[44:45] neg_lo:[0,1] neg_hi:[0,1]
	s_waitcnt lgkmcnt(4)
	v_pk_add_f32 v[236:237], v[46:47], v[48:49]
	v_pk_add_f32 v[48:49], v[46:47], v[48:49] neg_lo:[0,1] neg_hi:[0,1]
	s_waitcnt lgkmcnt(3)
	v_pk_add_f32 v[238:239], v[50:51], v[52:53]
	v_pk_add_f32 v[52:53], v[50:51], v[52:53] neg_lo:[0,1] neg_hi:[0,1]
	s_waitcnt lgkmcnt(2)
	v_pk_add_f32 v[240:241], v[54:55], v[56:57]
	v_pk_add_f32 v[56:57], v[54:55], v[56:57] neg_lo:[0,1] neg_hi:[0,1]
	s_waitcnt lgkmcnt(1)
	v_pk_add_f32 v[244:245], v[58:59], v[60:61]
	v_pk_add_f32 v[60:61], v[58:59], v[60:61] neg_lo:[0,1] neg_hi:[0,1]
	s_waitcnt lgkmcnt(0)
	v_pk_add_f32 v[246:247], v[62:63], v[64:65]
	v_pk_add_f32 v[64:65], v[62:63], v[64:65] neg_lo:[0,1] neg_hi:[0,1]
	s_barrier
	ds_write2st64_b64 v154, v[202:203], v[4:5] offset0:0 offset1:64
	ds_write2st64_b64 v154, v[204:205], v[8:9] offset0:4 offset1:68
	ds_write2st64_b64 v154, v[206:207], v[12:13] offset0:8 offset1:72
	ds_write2st64_b64 v154, v[208:209], v[16:17] offset0:12 offset1:76
	ds_write2st64_b64 v154, v[210:211], v[20:21] offset0:16 offset1:80
	ds_write2st64_b64 v154, v[212:213], v[24:25] offset0:20 offset1:84
	ds_write2st64_b64 v154, v[220:221], v[28:29] offset0:24 offset1:88
	ds_write2st64_b64 v154, v[224:225], v[32:33] offset0:28 offset1:92
	ds_write2st64_b64 v154, v[226:227], v[36:37] offset0:32 offset1:96
	ds_write2st64_b64 v154, v[230:231], v[40:41] offset0:36 offset1:100
	ds_write2st64_b64 v154, v[232:233], v[44:45] offset0:40 offset1:104
	ds_write2st64_b64 v154, v[236:237], v[48:49] offset0:44 offset1:108
	ds_write2st64_b64 v154, v[238:239], v[52:53] offset0:48 offset1:112
	ds_write2st64_b64 v154, v[240:241], v[56:57] offset0:52 offset1:116
	ds_write2st64_b64 v154, v[244:245], v[60:61] offset0:56 offset1:120
	ds_write2st64_b64 v154, v[246:247], v[64:65] offset0:60 offset1:124
	s_waitcnt lgkmcnt(0)
	s_barrier
	ds_read_b64 v[2:3], v157
	ds_read_b64 v[4:5], v159
	ds_read_b64 v[6:7], v161
	ds_read_b64 v[8:9], v163
	v_pk_mov_b32 v[10:11], v[78:79], v[78:79] op_sel:[1,0]
	v_mov_b32_e32 v208, v0
	s_waitcnt lgkmcnt(3)
	v_pk_mul_f32 v[10:11], v[10:11], v[2:3]
	s_mov_b32 s7, 0
	v_add_f32_e32 v11, v10, v11
	v_mul_f32_e32 v10, v79, v3
	v_pk_fma_f32 v[2:3], v[78:79], v[2:3], v[10:11] op_sel_hi:[1,1,0] neg_lo:[0,0,1] neg_hi:[0,0,1]
	s_nop 0
	v_xor_b32_e32 v3, 0x80000000, v11
	ds_write_b64 v157, v[2:3]
	v_pk_mov_b32 v[2:3], v[80:81], v[80:81] op_sel:[1,0]
	s_waitcnt lgkmcnt(3)
	v_pk_mul_f32 v[2:3], v[2:3], v[4:5]
	s_nop 0
	v_add_f32_e32 v10, v2, v3
	v_mul_f32_e32 v2, v81, v5
	v_pk_fma_f32 v[2:3], v[80:81], v[4:5], v[2:3] op_sel_hi:[1,1,0] neg_lo:[0,0,1] neg_hi:[0,0,1]
	s_nop 0
	v_xor_b32_e32 v3, 0x80000000, v10
	ds_write_b64 v159, v[2:3]
	v_pk_mov_b32 v[2:3], v[82:83], v[82:83] op_sel:[1,0]
	v_pk_mov_b32 v[10:11], v[86:87], v[86:87] op_sel:[1,0]
	s_waitcnt lgkmcnt(3)
	v_pk_mul_f32 v[2:3], v[2:3], v[6:7]
	s_nop 0
	v_add_f32_e32 v4, v2, v3
	v_mul_f32_e32 v2, v83, v7
	v_pk_fma_f32 v[2:3], v[82:83], v[6:7], v[2:3] op_sel_hi:[1,1,0] neg_lo:[0,0,1] neg_hi:[0,0,1]
	s_nop 0
	v_xor_b32_e32 v3, 0x80000000, v4
	ds_write_b64 v161, v[2:3]
	v_pk_mov_b32 v[2:3], v[84:85], v[84:85] op_sel:[1,0]
	s_waitcnt lgkmcnt(3)
; DI f32x2 cmul(f32x2 a, f32x2 b) { return mkf2(a.x * b.x - a.y * b.y, a.x * b.y + a.y * b.x); }
; DI void hyena_unit(KP p, int l, int c, char* smem) {
;     ...
;       for (int j = 0; j < 32; ++j) {
;         const int f = tid + 256 * j;
;         f32x2 z = cmul(buf[SW(f)], KF[j]);
;         buf[SW(f)] = mkf2(z.x, -z.y);
;       }
	v_pk_mul_f32 v[2:3], v[2:3], v[8:9]
	s_nop 0
	v_add_f32_e32 v4, v2, v3
	v_mul_f32_e32 v2, v85, v9
	v_pk_fma_f32 v[2:3], v[84:85], v[8:9], v[2:3] op_sel_hi:[1,1,0] neg_lo:[0,0,1] neg_hi:[0,0,1]
	s_nop 0
	v_xor_b32_e32 v3, 0x80000000, v4
	ds_read_b64 v[4:5], v165
	ds_write_b64 v163, v[2:3]
	ds_read_b64 v[2:3], v167
	ds_read_b64 v[6:7], v169
	ds_read_b64 v[8:9], v170
	s_waitcnt lgkmcnt(4)
	v_pk_mul_f32 v[10:11], v[10:11], v[4:5]
	s_nop 0
	v_add_f32_e32 v11, v10, v11
	v_mul_f32_e32 v10, v87, v5
	v_pk_fma_f32 v[4:5], v[86:87], v[4:5], v[10:11] op_sel_hi:[1,1,0] neg_lo:[0,0,1] neg_hi:[0,0,1]
	s_nop 0
	v_xor_b32_e32 v5, 0x80000000, v11
	ds_write_b64 v165, v[4:5]
	v_pk_mov_b32 v[4:5], v[88:89], v[88:89] op_sel:[1,0]
	v_pk_mov_b32 v[10:11], v[94:95], v[94:95] op_sel:[1,0]
	s_waitcnt lgkmcnt(3)
	v_pk_mul_f32 v[4:5], v[4:5], v[2:3]
	s_nop 0
	v_add_f32_e32 v5, v4, v5
	v_mul_f32_e32 v4, v89, v3
	v_pk_fma_f32 v[2:3], v[88:89], v[2:3], v[4:5] op_sel_hi:[1,1,0] neg_lo:[0,0,1] neg_hi:[0,0,1]
	s_nop 0
	v_xor_b32_e32 v3, 0x80000000, v5
	ds_write_b64 v167, v[2:3]
	v_pk_mov_b32 v[2:3], v[90:91], v[90:91] op_sel:[1,0]
	s_waitcnt lgkmcnt(3)
	v_pk_mul_f32 v[2:3], v[2:3], v[6:7]
	s_nop 0
	v_add_f32_e32 v4, v2, v3
	v_mul_f32_e32 v2, v91, v7
	v_pk_fma_f32 v[2:3], v[90:91], v[6:7], v[2:3] op_sel_hi:[1,1,0] neg_lo:[0,0,1] neg_hi:[0,0,1]
	s_nop 0
	v_xor_b32_e32 v3, 0x80000000, v4
	ds_write_b64 v169, v[2:3]
	v_pk_mov_b32 v[2:3], v[92:93], v[92:93] op_sel:[1,0]
	s_waitcnt lgkmcnt(3)
	v_pk_mul_f32 v[2:3], v[2:3], v[8:9]
	s_nop 0
	v_add_f32_e32 v4, v2, v3
	v_mul_f32_e32 v2, v93, v9
	v_pk_fma_f32 v[2:3], v[92:93], v[8:9], v[2:3] op_sel_hi:[1,1,0] neg_lo:[0,0,1] neg_hi:[0,0,1]
	s_nop 0
	v_xor_b32_e32 v3, 0x80000000, v4
	ds_read_b64 v[4:5], v171
	ds_write_b64 v170, v[2:3]
	ds_read_b64 v[2:3], v172
	ds_read_b64 v[6:7], v173
	ds_read_b64 v[8:9], v174
	s_waitcnt lgkmcnt(4)
	v_pk_mul_f32 v[10:11], v[10:11], v[4:5]
	s_nop 0
	v_add_f32_e32 v11, v10, v11
	v_mul_f32_e32 v10, v95, v5
	v_pk_fma_f32 v[4:5], v[94:95], v[4:5], v[10:11] op_sel_hi:[1,1,0] neg_lo:[0,0,1] neg_hi:[0,0,1]
	s_nop 0
	v_xor_b32_e32 v5, 0x80000000, v11
	ds_write_b64 v171, v[4:5]
	v_pk_mov_b32 v[4:5], v[96:97], v[96:97] op_sel:[1,0]
	v_pk_mov_b32 v[10:11], v[102:103], v[102:103] op_sel:[1,0]
	s_waitcnt lgkmcnt(3)
	v_pk_mul_f32 v[4:5], v[4:5], v[2:3]
	s_nop 0
	v_add_f32_e32 v5, v4, v5
	v_mul_f32_e32 v4, v97, v3
	v_pk_fma_f32 v[2:3], v[96:97], v[2:3], v[4:5] op_sel_hi:[1,1,0] neg_lo:[0,0,1] neg_hi:[0,0,1]
	s_nop 0
	v_xor_b32_e32 v3, 0x80000000, v5
	ds_write_b64 v172, v[2:3]
	v_pk_mov_b32 v[2:3], v[98:99], v[98:99] op_sel:[1,0]
	s_waitcnt lgkmcnt(3)
	v_pk_mul_f32 v[2:3], v[2:3], v[6:7]
	s_nop 0
	v_add_f32_e32 v4, v2, v3
	v_mul_f32_e32 v2, v99, v7
	v_pk_fma_f32 v[2:3], v[98:99], v[6:7], v[2:3] op_sel_hi:[1,1,0] neg_lo:[0,0,1] neg_hi:[0,0,1]
	s_nop 0
	v_xor_b32_e32 v3, 0x80000000, v4
	ds_write_b64 v173, v[2:3]
	v_pk_mov_b32 v[2:3], v[100:101], v[100:101] op_sel:[1,0]
	s_waitcnt lgkmcnt(3)
	v_pk_mul_f32 v[2:3], v[2:3], v[8:9]
	s_nop 0
	v_add_f32_e32 v4, v2, v3
	v_mul_f32_e32 v2, v101, v9
	v_pk_fma_f32 v[2:3], v[100:101], v[8:9], v[2:3] op_sel_hi:[1,1,0] neg_lo:[0,0,1] neg_hi:[0,0,1]
	s_nop 0
	v_xor_b32_e32 v3, 0x80000000, v4
	ds_read_b64 v[4:5], v175
	ds_write_b64 v174, v[2:3]
	ds_read_b64 v[2:3], v176
	ds_read_b64 v[6:7], v177
	ds_read_b64 v[8:9], v178
	s_waitcnt lgkmcnt(4)
	v_pk_mul_f32 v[10:11], v[10:11], v[4:5]
	s_nop 0
	v_add_f32_e32 v11, v10, v11
	v_mul_f32_e32 v10, v103, v5
	v_pk_fma_f32 v[4:5], v[102:103], v[4:5], v[10:11] op_sel_hi:[1,1,0] neg_lo:[0,0,1] neg_hi:[0,0,1]
	s_nop 0
	v_xor_b32_e32 v5, 0x80000000, v11
	ds_write_b64 v175, v[4:5]
	v_pk_mov_b32 v[4:5], v[104:105], v[104:105] op_sel:[1,0]
	v_pk_mov_b32 v[10:11], v[110:111], v[110:111] op_sel:[1,0]
	s_waitcnt lgkmcnt(3)
	v_pk_mul_f32 v[4:5], v[4:5], v[2:3]
	s_nop 0
	v_add_f32_e32 v5, v4, v5
	v_mul_f32_e32 v4, v105, v3
	v_pk_fma_f32 v[2:3], v[104:105], v[2:3], v[4:5] op_sel_hi:[1,1,0] neg_lo:[0,0,1] neg_hi:[0,0,1]
	s_nop 0
	v_xor_b32_e32 v3, 0x80000000, v5
	ds_write_b64 v176, v[2:3]
	v_pk_mov_b32 v[2:3], v[106:107], v[106:107] op_sel:[1,0]
	s_waitcnt lgkmcnt(3)
	v_pk_mul_f32 v[2:3], v[2:3], v[6:7]
	s_nop 0
	v_add_f32_e32 v4, v2, v3
	v_mul_f32_e32 v2, v107, v7
	v_pk_fma_f32 v[2:3], v[106:107], v[6:7], v[2:3] op_sel_hi:[1,1,0] neg_lo:[0,0,1] neg_hi:[0,0,1]
	s_nop 0
	v_xor_b32_e32 v3, 0x80000000, v4
	ds_write_b64 v177, v[2:3]
	v_pk_mov_b32 v[2:3], v[108:109], v[108:109] op_sel:[1,0]
	s_waitcnt lgkmcnt(3)
	v_pk_mul_f32 v[2:3], v[2:3], v[8:9]
	s_nop 0
	v_add_f32_e32 v4, v2, v3
	v_mul_f32_e32 v2, v109, v9
	v_pk_fma_f32 v[2:3], v[108:109], v[8:9], v[2:3] op_sel_hi:[1,1,0] neg_lo:[0,0,1] neg_hi:[0,0,1]
	s_nop 0
	v_xor_b32_e32 v3, 0x80000000, v4
	ds_read_b64 v[4:5], v179
	ds_write_b64 v178, v[2:3]
	ds_read_b64 v[2:3], v180
	ds_read_b64 v[6:7], v181
	ds_read_b64 v[8:9], v182
	s_waitcnt lgkmcnt(4)
	v_pk_mul_f32 v[10:11], v[10:11], v[4:5]
	s_nop 0
	v_add_f32_e32 v11, v10, v11
	v_mul_f32_e32 v10, v111, v5
	v_pk_fma_f32 v[4:5], v[110:111], v[4:5], v[10:11] op_sel_hi:[1,1,0] neg_lo:[0,0,1] neg_hi:[0,0,1]
	s_nop 0
	v_xor_b32_e32 v5, 0x80000000, v11
	ds_write_b64 v179, v[4:5]
	v_pk_mov_b32 v[4:5], v[112:113], v[112:113] op_sel:[1,0]
	v_pk_mov_b32 v[10:11], v[118:119], v[118:119] op_sel:[1,0]
	s_waitcnt lgkmcnt(3)
	v_pk_mul_f32 v[4:5], v[4:5], v[2:3]
	s_nop 0
	v_add_f32_e32 v5, v4, v5
	v_mul_f32_e32 v4, v113, v3
	v_pk_fma_f32 v[2:3], v[112:113], v[2:3], v[4:5] op_sel_hi:[1,1,0] neg_lo:[0,0,1] neg_hi:[0,0,1]
	s_nop 0
	v_xor_b32_e32 v3, 0x80000000, v5
	ds_write_b64 v180, v[2:3]
	v_pk_mov_b32 v[2:3], v[114:115], v[114:115] op_sel:[1,0]
	s_waitcnt lgkmcnt(3)
; DI f32x2 cmul(f32x2 a, f32x2 b) { return mkf2(a.x * b.x - a.y * b.y, a.x * b.y + a.y * b.x); }
; DI void fft8192(f32x2* buf, const f32x2* __restrict__ tw) {
;     ...
; #pragma unroll 2
;   for (int ls = 0; ls < 12; ls += 2) {
;     const int s = 1 << ls;
;     f32x2 a[8], b[8], c[8], d[8];
;     __syncthreads();
; #pragma unroll
;     for (int e = 0; e < 8; ++e) {
;       const int i = tid + 256 * e;
;       const int pi = SW(i);
;       a[e] = buf[pi]; b[e] = buf[pi + 2048]; c[e] = buf[pi + 4096]; d[e] = buf[pi + 6144];
; DI void hyena_unit(KP p, int l, int c, char* smem) {
;     ...
;       for (int j = 0; j < 32; ++j) {
;         const int f = tid + 256 * j;
;         f32x2 z = cmul(buf[SW(f)], KF[j]);
;         buf[SW(f)] = mkf2(z.x, -z.y);
;       }
	v_pk_mul_f32 v[2:3], v[2:3], v[6:7]
	s_nop 0
	v_add_f32_e32 v4, v2, v3
	v_mul_f32_e32 v2, v115, v7
	v_pk_fma_f32 v[2:3], v[114:115], v[6:7], v[2:3] op_sel_hi:[1,1,0] neg_lo:[0,0,1] neg_hi:[0,0,1]
	s_nop 0
	v_xor_b32_e32 v3, 0x80000000, v4
	ds_write_b64 v181, v[2:3]
	v_pk_mov_b32 v[2:3], v[116:117], v[116:117] op_sel:[1,0]
	s_waitcnt lgkmcnt(3)
	v_pk_mul_f32 v[2:3], v[2:3], v[8:9]
	s_nop 0
	v_add_f32_e32 v4, v2, v3
	v_mul_f32_e32 v2, v117, v9
	v_pk_fma_f32 v[2:3], v[116:117], v[8:9], v[2:3] op_sel_hi:[1,1,0] neg_lo:[0,0,1] neg_hi:[0,0,1]
	s_nop 0
	v_xor_b32_e32 v3, 0x80000000, v4
	ds_read_b64 v[4:5], v183
	ds_write_b64 v182, v[2:3]
	ds_read_b64 v[2:3], v184
	ds_read_b64 v[6:7], v185
	ds_read_b64 v[8:9], v186
	s_waitcnt lgkmcnt(4)
	v_pk_mul_f32 v[10:11], v[10:11], v[4:5]
	s_nop 0
	v_add_f32_e32 v11, v10, v11
	v_mul_f32_e32 v10, v119, v5
	v_pk_fma_f32 v[4:5], v[118:119], v[4:5], v[10:11] op_sel_hi:[1,1,0] neg_lo:[0,0,1] neg_hi:[0,0,1]
	s_nop 0
	v_xor_b32_e32 v5, 0x80000000, v11
	ds_write_b64 v183, v[4:5]
	v_pk_mov_b32 v[4:5], v[120:121], v[120:121] op_sel:[1,0]
	v_pk_mov_b32 v[10:11], v[126:127], v[126:127] op_sel:[1,0]
	s_waitcnt lgkmcnt(3)
	v_pk_mul_f32 v[4:5], v[4:5], v[2:3]
	s_nop 0
	v_add_f32_e32 v5, v4, v5
	v_mul_f32_e32 v4, v121, v3
	v_pk_fma_f32 v[2:3], v[120:121], v[2:3], v[4:5] op_sel_hi:[1,1,0] neg_lo:[0,0,1] neg_hi:[0,0,1]
	s_nop 0
	v_xor_b32_e32 v3, 0x80000000, v5
	ds_write_b64 v184, v[2:3]
	v_pk_mov_b32 v[2:3], v[122:123], v[122:123] op_sel:[1,0]
	s_waitcnt lgkmcnt(3)
	v_pk_mul_f32 v[2:3], v[2:3], v[6:7]
	s_nop 0
	v_add_f32_e32 v4, v2, v3
	v_mul_f32_e32 v2, v123, v7
	v_pk_fma_f32 v[2:3], v[122:123], v[6:7], v[2:3] op_sel_hi:[1,1,0] neg_lo:[0,0,1] neg_hi:[0,0,1]
	s_nop 0
	v_xor_b32_e32 v3, 0x80000000, v4
	ds_write_b64 v185, v[2:3]
	v_pk_mov_b32 v[2:3], v[124:125], v[124:125] op_sel:[1,0]
	s_waitcnt lgkmcnt(3)
	v_pk_mul_f32 v[2:3], v[2:3], v[8:9]
	s_nop 0
	v_add_f32_e32 v4, v2, v3
	v_mul_f32_e32 v2, v125, v9
	v_pk_fma_f32 v[2:3], v[124:125], v[8:9], v[2:3] op_sel_hi:[1,1,0] neg_lo:[0,0,1] neg_hi:[0,0,1]
	s_nop 0
	v_xor_b32_e32 v3, 0x80000000, v4
	ds_read_b64 v[4:5], v187
	ds_write_b64 v186, v[2:3]
	ds_read_b64 v[2:3], v188
	ds_read_b64 v[6:7], v189
	ds_read_b64 v[8:9], v190
	s_waitcnt lgkmcnt(4)
	v_pk_mul_f32 v[10:11], v[10:11], v[4:5]
	s_nop 0
	v_add_f32_e32 v11, v10, v11
	v_mul_f32_e32 v10, v127, v5
	v_pk_fma_f32 v[4:5], v[126:127], v[4:5], v[10:11] op_sel_hi:[1,1,0] neg_lo:[0,0,1] neg_hi:[0,0,1]
	s_nop 0
	v_xor_b32_e32 v5, 0x80000000, v11
	ds_write_b64 v187, v[4:5]
	v_pk_mov_b32 v[4:5], v[128:129], v[128:129] op_sel:[1,0]
	s_waitcnt lgkmcnt(3)
	v_pk_mul_f32 v[4:5], v[4:5], v[2:3]
	s_nop 0
	v_add_f32_e32 v5, v4, v5
	v_mul_f32_e32 v4, v129, v3
	v_pk_fma_f32 v[2:3], v[128:129], v[2:3], v[4:5] op_sel_hi:[1,1,0] neg_lo:[0,0,1] neg_hi:[0,0,1]
	s_nop 0
	v_xor_b32_e32 v3, 0x80000000, v5
	ds_write_b64 v188, v[2:3]
	s_waitcnt lgkmcnt(3)
	v_pk_mul_f32 v[2:3], v[142:143], v[6:7]
	s_nop 0
	v_add_f32_e32 v4, v2, v3
	v_mul_f32_e32 v2, v131, v7
	v_pk_fma_f32 v[2:3], v[130:131], v[6:7], v[2:3] op_sel_hi:[1,1,0] neg_lo:[0,0,1] neg_hi:[0,0,1]
	s_nop 0
	v_xor_b32_e32 v3, 0x80000000, v4
	ds_write_b64 v189, v[2:3]
	s_waitcnt lgkmcnt(3)
	v_pk_mul_f32 v[2:3], v[144:145], v[8:9]
	s_nop 0
	v_add_f32_e32 v4, v2, v3
	v_mul_f32_e32 v2, v133, v9
	v_pk_fma_f32 v[2:3], v[132:133], v[8:9], v[2:3] op_sel_hi:[1,1,0] neg_lo:[0,0,1] neg_hi:[0,0,1]
	s_nop 0
	v_xor_b32_e32 v3, 0x80000000, v4
	ds_read_b64 v[4:5], v191
	ds_write_b64 v190, v[2:3]
	ds_read_b64 v[2:3], v192
	ds_read_b64 v[6:7], v193
	ds_read_b64 v[8:9], v194
	s_waitcnt lgkmcnt(4)
	v_pk_mul_f32 v[10:11], v[146:147], v[4:5]
	s_nop 0
	v_add_f32_e32 v11, v10, v11
	v_mul_f32_e32 v10, v135, v5
	v_pk_fma_f32 v[4:5], v[134:135], v[4:5], v[10:11] op_sel_hi:[1,1,0] neg_lo:[0,0,1] neg_hi:[0,0,1]
	s_nop 0
	v_xor_b32_e32 v5, 0x80000000, v11
	ds_write_b64 v191, v[4:5]
	s_waitcnt lgkmcnt(3)
	v_pk_mul_f32 v[4:5], v[148:149], v[2:3]
	s_nop 0
	v_add_f32_e32 v5, v4, v5
	v_mul_f32_e32 v4, v137, v3
	v_pk_fma_f32 v[2:3], v[136:137], v[2:3], v[4:5] op_sel_hi:[1,1,0] neg_lo:[0,0,1] neg_hi:[0,0,1]
	s_nop 0
	v_xor_b32_e32 v3, 0x80000000, v5
	ds_write_b64 v192, v[2:3]
	s_waitcnt lgkmcnt(3)
	v_pk_mul_f32 v[2:3], v[150:151], v[6:7]
	s_nop 0
	v_add_f32_e32 v4, v2, v3
	v_mul_f32_e32 v2, v139, v7
	v_pk_fma_f32 v[2:3], v[138:139], v[6:7], v[2:3] op_sel_hi:[1,1,0] neg_lo:[0,0,1] neg_hi:[0,0,1]
	s_nop 0
	v_xor_b32_e32 v3, 0x80000000, v4
	ds_write_b64 v193, v[2:3]
	s_waitcnt lgkmcnt(3)
	v_pk_mul_f32 v[2:3], v[152:153], v[8:9]
	s_nop 0
	v_add_f32_e32 v4, v2, v3
	v_mul_f32_e32 v2, v141, v9
	v_pk_fma_f32 v[2:3], v[140:141], v[8:9], v[2:3] op_sel_hi:[1,1,0] neg_lo:[0,0,1] neg_hi:[0,0,1]
	s_nop 0
	v_xor_b32_e32 v3, 0x80000000, v4
	ds_write_b64 v194, v[2:3]
	v_bfe_i32 v166, v0, 5, 1
	v_bfe_i32 v168, v0, 6, 1
	v_and_b32_e32 v166, 5, v166
	v_and_b32_e32 v168, 26, v168
	v_xor_b32_e32 v166, v166, v168
	v_xor_b32_e32 v166, v166, v0
	v_lshlrev_b32_e32 v154, 3, v166
	s_waitcnt lgkmcnt(0)
	s_barrier
; DI f32x2 cmul(f32x2 a, f32x2 b) { return mkf2(a.x * b.x - a.y * b.y, a.x * b.y + a.y * b.x); }
; DI void fft8192(f32x2* buf, const f32x2* __restrict__ tw) {
;     ...
; #pragma unroll 2
;   for (int ls = 0; ls < 12; ls += 2) {
;     const int s = 1 << ls;
;     f32x2 a[8], b[8], c[8], d[8];
;     __syncthreads();
; #pragma unroll
;     for (int e = 0; e < 8; ++e) {
;       const int i = tid + 256 * e;
;       const int pi = SW(i);
;       a[e] = buf[pi]; b[e] = buf[pi + 2048]; c[e] = buf[pi + 4096]; d[e] = buf[pi + 6144];
;     }
;     __syncthreads();
; #pragma unroll
;     for (int e = 0; e < 8; ++e) {
;       const int i = tid + 256 * e;
;       const int q = i & (s - 1);
;       const int ps = i - q;
;       const float rev = (float)ps * (1.f / 8192.f);
;       const f32x2 w1 = mkf2(__builtin_amdgcn_cosf(rev), -__builtin_amdgcn_sinf(rev));
;       const f32x2 w2 = cmul(w1, w1), w3 = cmul(w1, w2);
;       const f32x2 apc = mkf2(a[e].x + c[e].x, a[e].y + c[e].y), amc = mkf2(a[e].x - c[e].x, a[e].y - c[e].y);
;       const f32x2 bpd = mkf2(b[e].x + d[e].x, b[e].y + d[e].y), bmd = mkf2(b[e].x - d[e].x, b[e].y - d[e].y);
;       const int o = 4 * i - 3 * q;
;       buf[SW(o)] = mkf2(apc.x + bpd.x, apc.y + bpd.y);
;       buf[SW(o + s)] = cmul(w1, mkf2(amc.x + bmd.y, amc.y - bmd.x));
;       buf[SW(o + 2 * s)] = cmul(w2, mkf2(apc.x - bpd.x, apc.y - bpd.y));
;       buf[SW(o + 3 * s)] = cmul(w3, mkf2(amc.x - bmd.y, amc.y + bmd.x));
;     }
	ds_read2st64_b64 v[2:5], v154 offset0:0 offset1:32
	ds_read2st64_b64 v[6:9], v154 offset0:64 offset1:96
	ds_read2st64_b64 v[10:13], v154 offset0:4 offset1:36
	ds_read2st64_b64 v[14:17], v154 offset0:68 offset1:100
	ds_read2st64_b64 v[18:21], v154 offset0:8 offset1:40
	ds_read2st64_b64 v[22:25], v154 offset0:72 offset1:104
	ds_read2st64_b64 v[26:29], v154 offset0:12 offset1:44
	ds_read2st64_b64 v[30:33], v154 offset0:76 offset1:108
	ds_read2st64_b64 v[34:37], v154 offset0:16 offset1:48
	ds_read2st64_b64 v[38:41], v154 offset0:80 offset1:112
	ds_read2st64_b64 v[42:45], v154 offset0:20 offset1:52
	ds_read2st64_b64 v[46:49], v154 offset0:84 offset1:116
	ds_read2st64_b64 v[50:53], v154 offset0:24 offset1:56
	ds_read2st64_b64 v[54:57], v154 offset0:88 offset1:120
	ds_read2st64_b64 v[58:61], v154 offset0:28 offset1:60
	ds_read2st64_b64 v[62:65], v154 offset0:92 offset1:124
	v_lshlrev_b32_e32 v164, 2, v0
	v_cvt_f32_u32_e32 v201, v0
	v_mul_f32_e32 v201, 0x39000000, v201
	v_bfe_i32 v166, v164, 5, 1
	v_bfe_i32 v168, v164, 6, 1
	v_and_b32_e32 v166, 5, v166
	v_and_b32_e32 v168, 26, v168
	v_xor_b32_e32 v166, v166, v168
	v_xor_b32_e32 v166, v166, v164
	v_lshlrev_b32_e32 v156, 3, v166
	v_xor_b32_e32 v158, 8, v156
	v_xor_b32_e32 v160, 16, v156
	v_xor_b32_e32 v162, 24, v156
	v_cos_f32_e32 v210, v201
	v_sin_f32_e64 v211, -v201
	s_waitcnt lgkmcnt(14)
	v_pk_add_f32 v[202:203], v[2:3], v[6:7]
	v_pk_add_f32 v[2:3], v[2:3], v[6:7] neg_lo:[0,1] neg_hi:[0,1]
	v_pk_add_f32 v[204:205], v[4:5], v[8:9]
	v_pk_add_f32 v[4:5], v[4:5], v[8:9] neg_lo:[0,1] neg_hi:[0,1]
	v_pk_add_f32 v[6:7], v[202:203], v[204:205]
	v_pk_add_f32 v[8:9], v[202:203], v[204:205] neg_lo:[0,1] neg_hi:[0,1]
	v_pk_add_f32 v[202:203], v[2:3], v[4:5] op_sel:[0,1] op_sel_hi:[1,0] neg_hi:[0,1]
	v_pk_add_f32 v[204:205], v[2:3], v[4:5] op_sel:[0,1] op_sel_hi:[1,0] neg_lo:[0,1]
	v_pk_mul_f32 v[206:207], v[210:211], v[210:211] op_sel:[1,1] op_sel_hi:[1,0]
	v_pk_fma_f32 v[212:213], v[210:211], v[210:211], v[206:207] op_sel_hi:[0,1,1] neg_lo:[0,0,1]
	v_pk_mul_f32 v[206:207], v[210:211], v[212:213] op_sel:[1,1] op_sel_hi:[1,0]
	v_pk_fma_f32 v[220:221], v[210:211], v[212:213], v[206:207] op_sel_hi:[0,1,1] neg_lo:[0,0,1]
	v_pk_mul_f32 v[2:3], v[210:211], v[202:203] op_sel:[1,1] op_sel_hi:[1,0]
	v_pk_fma_f32 v[2:3], v[210:211], v[202:203], v[2:3] op_sel_hi:[0,1,1] neg_lo:[0,0,1]
	v_pk_mul_f32 v[4:5], v[212:213], v[8:9] op_sel:[1,1] op_sel_hi:[1,0]
	v_pk_fma_f32 v[4:5], v[212:213], v[8:9], v[4:5] op_sel_hi:[0,1,1] neg_lo:[0,0,1]
	v_pk_mul_f32 v[8:9], v[220:221], v[204:205] op_sel:[1,1] op_sel_hi:[1,0]
	v_pk_fma_f32 v[8:9], v[220:221], v[204:205], v[8:9] op_sel_hi:[0,1,1] neg_lo:[0,0,1]
	v_add_f32_e32 v214, 0x3d000000, v201
	v_cos_f32_e32 v210, v214
	v_sin_f32_e64 v211, -v214
	s_waitcnt lgkmcnt(12)
	v_pk_add_f32 v[202:203], v[10:11], v[14:15]
	v_pk_add_f32 v[10:11], v[10:11], v[14:15] neg_lo:[0,1] neg_hi:[0,1]
	v_pk_add_f32 v[204:205], v[12:13], v[16:17]
	v_pk_add_f32 v[12:13], v[12:13], v[16:17] neg_lo:[0,1] neg_hi:[0,1]
	v_pk_add_f32 v[14:15], v[202:203], v[204:205]
	v_pk_add_f32 v[16:17], v[202:203], v[204:205] neg_lo:[0,1] neg_hi:[0,1]
	v_pk_add_f32 v[202:203], v[10:11], v[12:13] op_sel:[0,1] op_sel_hi:[1,0] neg_hi:[0,1]
	v_pk_add_f32 v[204:205], v[10:11], v[12:13] op_sel:[0,1] op_sel_hi:[1,0] neg_lo:[0,1]
	v_pk_mul_f32 v[206:207], v[210:211], v[210:211] op_sel:[1,1] op_sel_hi:[1,0]
	v_pk_fma_f32 v[212:213], v[210:211], v[210:211], v[206:207] op_sel_hi:[0,1,1] neg_lo:[0,0,1]
	v_pk_mul_f32 v[206:207], v[210:211], v[212:213] op_sel:[1,1] op_sel_hi:[1,0]
	v_pk_fma_f32 v[220:221], v[210:211], v[212:213], v[206:207] op_sel_hi:[0,1,1] neg_lo:[0,0,1]
	v_pk_mul_f32 v[10:11], v[210:211], v[202:203] op_sel:[1,1] op_sel_hi:[1,0]
	v_pk_fma_f32 v[10:11], v[210:211], v[202:203], v[10:11] op_sel_hi:[0,1,1] neg_lo:[0,0,1]
	v_pk_mul_f32 v[12:13], v[212:213], v[16:17] op_sel:[1,1] op_sel_hi:[1,0]
	v_pk_fma_f32 v[12:13], v[212:213], v[16:17], v[12:13] op_sel_hi:[0,1,1] neg_lo:[0,0,1]
	v_pk_mul_f32 v[16:17], v[220:221], v[204:205] op_sel:[1,1] op_sel_hi:[1,0]
	v_pk_fma_f32 v[16:17], v[220:221], v[204:205], v[16:17] op_sel_hi:[0,1,1] neg_lo:[0,0,1]
	v_add_f32_e32 v214, 0x3d800000, v201
	v_cos_f32_e32 v210, v214
	v_sin_f32_e64 v211, -v214
	s_waitcnt lgkmcnt(10)
	v_pk_add_f32 v[202:203], v[18:19], v[22:23]
	v_pk_add_f32 v[18:19], v[18:19], v[22:23] neg_lo:[0,1] neg_hi:[0,1]
	v_pk_add_f32 v[204:205], v[20:21], v[24:25]
	v_pk_add_f32 v[20:21], v[20:21], v[24:25] neg_lo:[0,1] neg_hi:[0,1]
	v_pk_add_f32 v[22:23], v[202:203], v[204:205]
	v_pk_add_f32 v[24:25], v[202:203], v[204:205] neg_lo:[0,1] neg_hi:[0,1]
	v_pk_add_f32 v[202:203], v[18:19], v[20:21] op_sel:[0,1] op_sel_hi:[1,0] neg_hi:[0,1]
	v_pk_add_f32 v[204:205], v[18:19], v[20:21] op_sel:[0,1] op_sel_hi:[1,0] neg_lo:[0,1]
	v_pk_mul_f32 v[206:207], v[210:211], v[210:211] op_sel:[1,1] op_sel_hi:[1,0]
	v_pk_fma_f32 v[212:213], v[210:211], v[210:211], v[206:207] op_sel_hi:[0,1,1] neg_lo:[0,0,1]
	v_pk_mul_f32 v[206:207], v[210:211], v[212:213] op_sel:[1,1] op_sel_hi:[1,0]
	v_pk_fma_f32 v[220:221], v[210:211], v[212:213], v[206:207] op_sel_hi:[0,1,1] neg_lo:[0,0,1]
	v_pk_mul_f32 v[18:19], v[210:211], v[202:203] op_sel:[1,1] op_sel_hi:[1,0]
	v_pk_fma_f32 v[18:19], v[210:211], v[202:203], v[18:19] op_sel_hi:[0,1,1] neg_lo:[0,0,1]
	v_pk_mul_f32 v[20:21], v[212:213], v[24:25] op_sel:[1,1] op_sel_hi:[1,0]
	v_pk_fma_f32 v[20:21], v[212:213], v[24:25], v[20:21] op_sel_hi:[0,1,1] neg_lo:[0,0,1]
	v_pk_mul_f32 v[24:25], v[220:221], v[204:205] op_sel:[1,1] op_sel_hi:[1,0]
	v_pk_fma_f32 v[24:25], v[220:221], v[204:205], v[24:25] op_sel_hi:[0,1,1] neg_lo:[0,0,1]
	v_add_f32_e32 v214, 0x3dc00000, v201
	v_cos_f32_e32 v210, v214
	v_sin_f32_e64 v211, -v214
	s_waitcnt lgkmcnt(8)
; DI f32x2 cmul(f32x2 a, f32x2 b) { return mkf2(a.x * b.x - a.y * b.y, a.x * b.y + a.y * b.x); }
; DI void fft8192(f32x2* buf, const f32x2* __restrict__ tw) {
;     ...
; #pragma unroll
;     for (int e = 0; e < 8; ++e) {
;       const int i = tid + 256 * e;
;       const int q = i & (s - 1);
;       const int ps = i - q;
;       const float rev = (float)ps * (1.f / 8192.f);
;       const f32x2 w1 = mkf2(__builtin_amdgcn_cosf(rev), -__builtin_amdgcn_sinf(rev));
;       const f32x2 w2 = cmul(w1, w1), w3 = cmul(w1, w2);
;       const f32x2 apc = mkf2(a[e].x + c[e].x, a[e].y + c[e].y), amc = mkf2(a[e].x - c[e].x, a[e].y - c[e].y);
;       const f32x2 bpd = mkf2(b[e].x + d[e].x, b[e].y + d[e].y), bmd = mkf2(b[e].x - d[e].x, b[e].y - d[e].y);
;       const int o = 4 * i - 3 * q;
;       buf[SW(o)] = mkf2(apc.x + bpd.x, apc.y + bpd.y);
;       buf[SW(o + s)] = cmul(w1, mkf2(amc.x + bmd.y, amc.y - bmd.x));
;       buf[SW(o + 2 * s)] = cmul(w2, mkf2(apc.x - bpd.x, apc.y - bpd.y));
;       buf[SW(o + 3 * s)] = cmul(w3, mkf2(amc.x - bmd.y, amc.y + bmd.x));
;     }
	v_pk_add_f32 v[202:203], v[26:27], v[30:31]
	v_pk_add_f32 v[26:27], v[26:27], v[30:31] neg_lo:[0,1] neg_hi:[0,1]
	v_pk_add_f32 v[204:205], v[28:29], v[32:33]
	v_pk_add_f32 v[28:29], v[28:29], v[32:33] neg_lo:[0,1] neg_hi:[0,1]
	v_pk_add_f32 v[30:31], v[202:203], v[204:205]
	v_pk_add_f32 v[32:33], v[202:203], v[204:205] neg_lo:[0,1] neg_hi:[0,1]
	v_pk_add_f32 v[202:203], v[26:27], v[28:29] op_sel:[0,1] op_sel_hi:[1,0] neg_hi:[0,1]
	v_pk_add_f32 v[204:205], v[26:27], v[28:29] op_sel:[0,1] op_sel_hi:[1,0] neg_lo:[0,1]
	v_pk_mul_f32 v[206:207], v[210:211], v[210:211] op_sel:[1,1] op_sel_hi:[1,0]
	v_pk_fma_f32 v[212:213], v[210:211], v[210:211], v[206:207] op_sel_hi:[0,1,1] neg_lo:[0,0,1]
	v_pk_mul_f32 v[206:207], v[210:211], v[212:213] op_sel:[1,1] op_sel_hi:[1,0]
	v_pk_fma_f32 v[220:221], v[210:211], v[212:213], v[206:207] op_sel_hi:[0,1,1] neg_lo:[0,0,1]
	v_pk_mul_f32 v[26:27], v[210:211], v[202:203] op_sel:[1,1] op_sel_hi:[1,0]
	v_pk_fma_f32 v[26:27], v[210:211], v[202:203], v[26:27] op_sel_hi:[0,1,1] neg_lo:[0,0,1]
	v_pk_mul_f32 v[28:29], v[212:213], v[32:33] op_sel:[1,1] op_sel_hi:[1,0]
	v_pk_fma_f32 v[28:29], v[212:213], v[32:33], v[28:29] op_sel_hi:[0,1,1] neg_lo:[0,0,1]
	v_pk_mul_f32 v[32:33], v[220:221], v[204:205] op_sel:[1,1] op_sel_hi:[1,0]
	v_pk_fma_f32 v[32:33], v[220:221], v[204:205], v[32:33] op_sel_hi:[0,1,1] neg_lo:[0,0,1]
	v_add_f32_e32 v214, 0x3e000000, v201
	v_cos_f32_e32 v210, v214
	v_sin_f32_e64 v211, -v214
	s_waitcnt lgkmcnt(6)
	v_pk_add_f32 v[202:203], v[34:35], v[38:39]
	v_pk_add_f32 v[34:35], v[34:35], v[38:39] neg_lo:[0,1] neg_hi:[0,1]
	v_pk_add_f32 v[204:205], v[36:37], v[40:41]
	v_pk_add_f32 v[36:37], v[36:37], v[40:41] neg_lo:[0,1] neg_hi:[0,1]
	v_pk_add_f32 v[38:39], v[202:203], v[204:205]
	v_pk_add_f32 v[40:41], v[202:203], v[204:205] neg_lo:[0,1] neg_hi:[0,1]
	v_pk_add_f32 v[202:203], v[34:35], v[36:37] op_sel:[0,1] op_sel_hi:[1,0] neg_hi:[0,1]
	v_pk_add_f32 v[204:205], v[34:35], v[36:37] op_sel:[0,1] op_sel_hi:[1,0] neg_lo:[0,1]
	v_pk_mul_f32 v[206:207], v[210:211], v[210:211] op_sel:[1,1] op_sel_hi:[1,0]
	v_pk_fma_f32 v[212:213], v[210:211], v[210:211], v[206:207] op_sel_hi:[0,1,1] neg_lo:[0,0,1]
	v_pk_mul_f32 v[206:207], v[210:211], v[212:213] op_sel:[1,1] op_sel_hi:[1,0]
	v_pk_fma_f32 v[220:221], v[210:211], v[212:213], v[206:207] op_sel_hi:[0,1,1] neg_lo:[0,0,1]
	v_pk_mul_f32 v[34:35], v[210:211], v[202:203] op_sel:[1,1] op_sel_hi:[1,0]
	v_pk_fma_f32 v[34:35], v[210:211], v[202:203], v[34:35] op_sel_hi:[0,1,1] neg_lo:[0,0,1]
	v_pk_mul_f32 v[36:37], v[212:213], v[40:41] op_sel:[1,1] op_sel_hi:[1,0]
	v_pk_fma_f32 v[36:37], v[212:213], v[40:41], v[36:37] op_sel_hi:[0,1,1] neg_lo:[0,0,1]
	v_pk_mul_f32 v[40:41], v[220:221], v[204:205] op_sel:[1,1] op_sel_hi:[1,0]
	v_pk_fma_f32 v[40:41], v[220:221], v[204:205], v[40:41] op_sel_hi:[0,1,1] neg_lo:[0,0,1]
	v_add_f32_e32 v214, 0x3e200000, v201
	v_cos_f32_e32 v210, v214
	v_sin_f32_e64 v211, -v214
	s_waitcnt lgkmcnt(4)
	v_pk_add_f32 v[202:203], v[42:43], v[46:47]
	v_pk_add_f32 v[42:43], v[42:43], v[46:47] neg_lo:[0,1] neg_hi:[0,1]
	v_pk_add_f32 v[204:205], v[44:45], v[48:49]
	v_pk_add_f32 v[44:45], v[44:45], v[48:49] neg_lo:[0,1] neg_hi:[0,1]
	v_pk_add_f32 v[46:47], v[202:203], v[204:205]
	v_pk_add_f32 v[48:49], v[202:203], v[204:205] neg_lo:[0,1] neg_hi:[0,1]
	v_pk_add_f32 v[202:203], v[42:43], v[44:45] op_sel:[0,1] op_sel_hi:[1,0] neg_hi:[0,1]
	v_pk_add_f32 v[204:205], v[42:43], v[44:45] op_sel:[0,1] op_sel_hi:[1,0] neg_lo:[0,1]
	v_pk_mul_f32 v[206:207], v[210:211], v[210:211] op_sel:[1,1] op_sel_hi:[1,0]
	v_pk_fma_f32 v[212:213], v[210:211], v[210:211], v[206:207] op_sel_hi:[0,1,1] neg_lo:[0,0,1]
	v_pk_mul_f32 v[206:207], v[210:211], v[212:213] op_sel:[1,1] op_sel_hi:[1,0]
	v_pk_fma_f32 v[220:221], v[210:211], v[212:213], v[206:207] op_sel_hi:[0,1,1] neg_lo:[0,0,1]
	v_pk_mul_f32 v[42:43], v[210:211], v[202:203] op_sel:[1,1] op_sel_hi:[1,0]
	v_pk_fma_f32 v[42:43], v[210:211], v[202:203], v[42:43] op_sel_hi:[0,1,1] neg_lo:[0,0,1]
	v_pk_mul_f32 v[44:45], v[212:213], v[48:49] op_sel:[1,1] op_sel_hi:[1,0]
	v_pk_fma_f32 v[44:45], v[212:213], v[48:49], v[44:45] op_sel_hi:[0,1,1] neg_lo:[0,0,1]
	v_pk_mul_f32 v[48:49], v[220:221], v[204:205] op_sel:[1,1] op_sel_hi:[1,0]
	v_pk_fma_f32 v[48:49], v[220:221], v[204:205], v[48:49] op_sel_hi:[0,1,1] neg_lo:[0,0,1]
	v_add_f32_e32 v214, 0x3e400000, v201
	v_cos_f32_e32 v210, v214
	v_sin_f32_e64 v211, -v214
	s_waitcnt lgkmcnt(2)
	v_pk_add_f32 v[202:203], v[50:51], v[54:55]
	v_pk_add_f32 v[50:51], v[50:51], v[54:55] neg_lo:[0,1] neg_hi:[0,1]
	v_pk_add_f32 v[204:205], v[52:53], v[56:57]
	v_pk_add_f32 v[52:53], v[52:53], v[56:57] neg_lo:[0,1] neg_hi:[0,1]
	v_pk_add_f32 v[54:55], v[202:203], v[204:205]
	v_pk_add_f32 v[56:57], v[202:203], v[204:205] neg_lo:[0,1] neg_hi:[0,1]
	v_pk_add_f32 v[202:203], v[50:51], v[52:53] op_sel:[0,1] op_sel_hi:[1,0] neg_hi:[0,1]
	v_pk_add_f32 v[204:205], v[50:51], v[52:53] op_sel:[0,1] op_sel_hi:[1,0] neg_lo:[0,1]
	v_pk_mul_f32 v[206:207], v[210:211], v[210:211] op_sel:[1,1] op_sel_hi:[1,0]
	v_pk_fma_f32 v[212:213], v[210:211], v[210:211], v[206:207] op_sel_hi:[0,1,1] neg_lo:[0,0,1]
	v_pk_mul_f32 v[206:207], v[210:211], v[212:213] op_sel:[1,1] op_sel_hi:[1,0]
	v_pk_fma_f32 v[220:221], v[210:211], v[212:213], v[206:207] op_sel_hi:[0,1,1] neg_lo:[0,0,1]
	v_pk_mul_f32 v[50:51], v[210:211], v[202:203] op_sel:[1,1] op_sel_hi:[1,0]
	v_pk_fma_f32 v[50:51], v[210:211], v[202:203], v[50:51] op_sel_hi:[0,1,1] neg_lo:[0,0,1]
	v_pk_mul_f32 v[52:53], v[212:213], v[56:57] op_sel:[1,1] op_sel_hi:[1,0]
	v_pk_fma_f32 v[52:53], v[212:213], v[56:57], v[52:53] op_sel_hi:[0,1,1] neg_lo:[0,0,1]
	v_pk_mul_f32 v[56:57], v[220:221], v[204:205] op_sel:[1,1] op_sel_hi:[1,0]
	v_pk_fma_f32 v[56:57], v[220:221], v[204:205], v[56:57] op_sel_hi:[0,1,1] neg_lo:[0,0,1]
	v_add_f32_e32 v214, 0x3e600000, v201
	v_cos_f32_e32 v210, v214
	v_sin_f32_e64 v211, -v214
	s_waitcnt lgkmcnt(0)
; DI f32x2 cmul(f32x2 a, f32x2 b) { return mkf2(a.x * b.x - a.y * b.y, a.x * b.y + a.y * b.x); }
; DI void fft8192(f32x2* buf, const f32x2* __restrict__ tw) {
;     ...
;     __syncthreads();
; #pragma unroll
;     for (int e = 0; e < 8; ++e) {
;       const int i = tid + 256 * e;
;       const int pi = SW(i);
;       a[e] = buf[pi]; b[e] = buf[pi + 2048]; c[e] = buf[pi + 4096]; d[e] = buf[pi + 6144];
;     }
;     __syncthreads();
; #pragma unroll
;     for (int e = 0; e < 8; ++e) {
;       const int i = tid + 256 * e;
;       const int q = i & (s - 1);
;       const int ps = i - q;
;       const float rev = (float)ps * (1.f / 8192.f);
;       const f32x2 w1 = mkf2(__builtin_amdgcn_cosf(rev), -__builtin_amdgcn_sinf(rev));
;       const f32x2 w2 = cmul(w1, w1), w3 = cmul(w1, w2);
;       const f32x2 apc = mkf2(a[e].x + c[e].x, a[e].y + c[e].y), amc = mkf2(a[e].x - c[e].x, a[e].y - c[e].y);
;       const f32x2 bpd = mkf2(b[e].x + d[e].x, b[e].y + d[e].y), bmd = mkf2(b[e].x - d[e].x, b[e].y - d[e].y);
;       const int o = 4 * i - 3 * q;
;       buf[SW(o)] = mkf2(apc.x + bpd.x, apc.y + bpd.y);
;       buf[SW(o + s)] = cmul(w1, mkf2(amc.x + bmd.y, amc.y - bmd.x));
;       buf[SW(o + 2 * s)] = cmul(w2, mkf2(apc.x - bpd.x, apc.y - bpd.y));
;       buf[SW(o + 3 * s)] = cmul(w3, mkf2(amc.x - bmd.y, amc.y + bmd.x));
;     }
	v_pk_add_f32 v[202:203], v[58:59], v[62:63]
	v_pk_add_f32 v[58:59], v[58:59], v[62:63] neg_lo:[0,1] neg_hi:[0,1]
	v_pk_add_f32 v[204:205], v[60:61], v[64:65]
	v_pk_add_f32 v[60:61], v[60:61], v[64:65] neg_lo:[0,1] neg_hi:[0,1]
	v_pk_add_f32 v[62:63], v[202:203], v[204:205]
	v_pk_add_f32 v[64:65], v[202:203], v[204:205] neg_lo:[0,1] neg_hi:[0,1]
	v_pk_add_f32 v[202:203], v[58:59], v[60:61] op_sel:[0,1] op_sel_hi:[1,0] neg_hi:[0,1]
	v_pk_add_f32 v[204:205], v[58:59], v[60:61] op_sel:[0,1] op_sel_hi:[1,0] neg_lo:[0,1]
	v_pk_mul_f32 v[206:207], v[210:211], v[210:211] op_sel:[1,1] op_sel_hi:[1,0]
	v_pk_fma_f32 v[212:213], v[210:211], v[210:211], v[206:207] op_sel_hi:[0,1,1] neg_lo:[0,0,1]
	v_pk_mul_f32 v[206:207], v[210:211], v[212:213] op_sel:[1,1] op_sel_hi:[1,0]
	v_pk_fma_f32 v[220:221], v[210:211], v[212:213], v[206:207] op_sel_hi:[0,1,1] neg_lo:[0,0,1]
	v_pk_mul_f32 v[58:59], v[210:211], v[202:203] op_sel:[1,1] op_sel_hi:[1,0]
	v_pk_fma_f32 v[58:59], v[210:211], v[202:203], v[58:59] op_sel_hi:[0,1,1] neg_lo:[0,0,1]
	v_pk_mul_f32 v[60:61], v[212:213], v[64:65] op_sel:[1,1] op_sel_hi:[1,0]
	v_pk_fma_f32 v[60:61], v[212:213], v[64:65], v[60:61] op_sel_hi:[0,1,1] neg_lo:[0,0,1]
	v_pk_mul_f32 v[64:65], v[220:221], v[204:205] op_sel:[1,1] op_sel_hi:[1,0]
	v_pk_fma_f32 v[64:65], v[220:221], v[204:205], v[64:65] op_sel_hi:[0,1,1] neg_lo:[0,0,1]
	s_barrier
	ds_write_b64 v156, v[6:7] offset:0
	ds_write_b64 v158, v[2:3] offset:0
	ds_write_b64 v160, v[4:5] offset:0
	ds_write_b64 v162, v[8:9] offset:0
	ds_write_b64 v156, v[14:15] offset:8192
	ds_write_b64 v158, v[10:11] offset:8192
	ds_write_b64 v160, v[12:13] offset:8192
	ds_write_b64 v162, v[16:17] offset:8192
	ds_write_b64 v156, v[22:23] offset:16384
	ds_write_b64 v158, v[18:19] offset:16384
	ds_write_b64 v160, v[20:21] offset:16384
	ds_write_b64 v162, v[24:25] offset:16384
	ds_write_b64 v156, v[30:31] offset:24576
	ds_write_b64 v158, v[26:27] offset:24576
	ds_write_b64 v160, v[28:29] offset:24576
	ds_write_b64 v162, v[32:33] offset:24576
	ds_write_b64 v156, v[38:39] offset:32768
	ds_write_b64 v158, v[34:35] offset:32768
	ds_write_b64 v160, v[36:37] offset:32768
	ds_write_b64 v162, v[40:41] offset:32768
	ds_write_b64 v156, v[46:47] offset:40960
	ds_write_b64 v158, v[42:43] offset:40960
	ds_write_b64 v160, v[44:45] offset:40960
	ds_write_b64 v162, v[48:49] offset:40960
	ds_write_b64 v156, v[54:55] offset:49152
	ds_write_b64 v158, v[50:51] offset:49152
	ds_write_b64 v160, v[52:53] offset:49152
	ds_write_b64 v162, v[56:57] offset:49152
	ds_write_b64 v156, v[62:63] offset:57344
	ds_write_b64 v158, v[58:59] offset:57344
	ds_write_b64 v160, v[60:61] offset:57344
	ds_write_b64 v162, v[64:65] offset:57344
	s_waitcnt lgkmcnt(0)
	s_barrier
	ds_read2st64_b64 v[2:5], v154 offset0:0 offset1:32
	ds_read2st64_b64 v[6:9], v154 offset0:64 offset1:96
	ds_read2st64_b64 v[10:13], v154 offset0:4 offset1:36
	ds_read2st64_b64 v[14:17], v154 offset0:68 offset1:100
	ds_read2st64_b64 v[18:21], v154 offset0:8 offset1:40
	ds_read2st64_b64 v[22:25], v154 offset0:72 offset1:104
	ds_read2st64_b64 v[26:29], v154 offset0:12 offset1:44
	ds_read2st64_b64 v[30:33], v154 offset0:76 offset1:108
	ds_read2st64_b64 v[34:37], v154 offset0:16 offset1:48
	ds_read2st64_b64 v[38:41], v154 offset0:80 offset1:112
	ds_read2st64_b64 v[42:45], v154 offset0:20 offset1:52
	ds_read2st64_b64 v[46:49], v154 offset0:84 offset1:116
	ds_read2st64_b64 v[50:53], v154 offset0:24 offset1:56
	ds_read2st64_b64 v[54:57], v154 offset0:88 offset1:120
	ds_read2st64_b64 v[58:61], v154 offset0:28 offset1:60
	ds_read2st64_b64 v[62:65], v154 offset0:92 offset1:124
	v_and_b32_e32 v166, 3, v0
	v_lshlrev_b32_e32 v164, 2, v0
	v_mad_i32_i24 v164, v166, -3, v164
	v_sub_u32_e32 v166, v0, v166
	v_cvt_f32_u32_e32 v201, v166
	v_mul_f32_e32 v201, 0x39000000, v201
	v_bfe_i32 v166, v164, 5, 1
	v_bfe_i32 v168, v164, 6, 1
	v_and_b32_e32 v166, 5, v166
	v_and_b32_e32 v168, 26, v168
	v_xor_b32_e32 v166, v166, v168
	v_xor_b32_e32 v166, v166, v164
	v_lshlrev_b32_e32 v156, 3, v166
	v_xor_b32_e32 v158, 32, v156
	v_xor_b32_e32 v160, 64, v156
	v_xor_b32_e32 v162, 0x60, v156
	v_cos_f32_e32 v210, v201
	v_sin_f32_e64 v211, -v201
	s_waitcnt lgkmcnt(14)
	v_pk_add_f32 v[202:203], v[2:3], v[6:7]
	v_pk_add_f32 v[2:3], v[2:3], v[6:7] neg_lo:[0,1] neg_hi:[0,1]
	v_pk_add_f32 v[204:205], v[4:5], v[8:9]
	v_pk_add_f32 v[4:5], v[4:5], v[8:9] neg_lo:[0,1] neg_hi:[0,1]
	v_pk_add_f32 v[6:7], v[202:203], v[204:205]
	v_pk_add_f32 v[8:9], v[202:203], v[204:205] neg_lo:[0,1] neg_hi:[0,1]
	v_pk_add_f32 v[202:203], v[2:3], v[4:5] op_sel:[0,1] op_sel_hi:[1,0] neg_hi:[0,1]
	v_pk_add_f32 v[204:205], v[2:3], v[4:5] op_sel:[0,1] op_sel_hi:[1,0] neg_lo:[0,1]
	v_pk_mul_f32 v[206:207], v[210:211], v[210:211] op_sel:[1,1] op_sel_hi:[1,0]
	v_pk_fma_f32 v[212:213], v[210:211], v[210:211], v[206:207] op_sel_hi:[0,1,1] neg_lo:[0,0,1]
	v_pk_mul_f32 v[206:207], v[210:211], v[212:213] op_sel:[1,1] op_sel_hi:[1,0]
	v_pk_fma_f32 v[220:221], v[210:211], v[212:213], v[206:207] op_sel_hi:[0,1,1] neg_lo:[0,0,1]
	v_pk_mul_f32 v[2:3], v[210:211], v[202:203] op_sel:[1,1] op_sel_hi:[1,0]
	v_pk_fma_f32 v[2:3], v[210:211], v[202:203], v[2:3] op_sel_hi:[0,1,1] neg_lo:[0,0,1]
	v_pk_mul_f32 v[4:5], v[212:213], v[8:9] op_sel:[1,1] op_sel_hi:[1,0]
	v_pk_fma_f32 v[4:5], v[212:213], v[8:9], v[4:5] op_sel_hi:[0,1,1] neg_lo:[0,0,1]
	v_pk_mul_f32 v[8:9], v[220:221], v[204:205] op_sel:[1,1] op_sel_hi:[1,0]
	v_pk_fma_f32 v[8:9], v[220:221], v[204:205], v[8:9] op_sel_hi:[0,1,1] neg_lo:[0,0,1]
	v_add_f32_e32 v214, 0x3d000000, v201
	v_cos_f32_e32 v210, v214
	v_sin_f32_e64 v211, -v214
	s_waitcnt lgkmcnt(12)
; DI f32x2 cmul(f32x2 a, f32x2 b) { return mkf2(a.x * b.x - a.y * b.y, a.x * b.y + a.y * b.x); }
; DI void fft8192(f32x2* buf, const f32x2* __restrict__ tw) {
;     ...
; #pragma unroll
;     for (int e = 0; e < 8; ++e) {
;       const int i = tid + 256 * e;
;       const int q = i & (s - 1);
;       const int ps = i - q;
;       const float rev = (float)ps * (1.f / 8192.f);
;       const f32x2 w1 = mkf2(__builtin_amdgcn_cosf(rev), -__builtin_amdgcn_sinf(rev));
;       const f32x2 w2 = cmul(w1, w1), w3 = cmul(w1, w2);
;       const f32x2 apc = mkf2(a[e].x + c[e].x, a[e].y + c[e].y), amc = mkf2(a[e].x - c[e].x, a[e].y - c[e].y);
;       const f32x2 bpd = mkf2(b[e].x + d[e].x, b[e].y + d[e].y), bmd = mkf2(b[e].x - d[e].x, b[e].y - d[e].y);
;       const int o = 4 * i - 3 * q;
;       buf[SW(o)] = mkf2(apc.x + bpd.x, apc.y + bpd.y);
;       buf[SW(o + s)] = cmul(w1, mkf2(amc.x + bmd.y, amc.y - bmd.x));
;       buf[SW(o + 2 * s)] = cmul(w2, mkf2(apc.x - bpd.x, apc.y - bpd.y));
;       buf[SW(o + 3 * s)] = cmul(w3, mkf2(amc.x - bmd.y, amc.y + bmd.x));
;     }
	v_pk_add_f32 v[202:203], v[10:11], v[14:15]
	v_pk_add_f32 v[10:11], v[10:11], v[14:15] neg_lo:[0,1] neg_hi:[0,1]
	v_pk_add_f32 v[204:205], v[12:13], v[16:17]
	v_pk_add_f32 v[12:13], v[12:13], v[16:17] neg_lo:[0,1] neg_hi:[0,1]
	v_pk_add_f32 v[14:15], v[202:203], v[204:205]
	v_pk_add_f32 v[16:17], v[202:203], v[204:205] neg_lo:[0,1] neg_hi:[0,1]
	v_pk_add_f32 v[202:203], v[10:11], v[12:13] op_sel:[0,1] op_sel_hi:[1,0] neg_hi:[0,1]
	v_pk_add_f32 v[204:205], v[10:11], v[12:13] op_sel:[0,1] op_sel_hi:[1,0] neg_lo:[0,1]
	v_pk_mul_f32 v[206:207], v[210:211], v[210:211] op_sel:[1,1] op_sel_hi:[1,0]
	v_pk_fma_f32 v[212:213], v[210:211], v[210:211], v[206:207] op_sel_hi:[0,1,1] neg_lo:[0,0,1]
	v_pk_mul_f32 v[206:207], v[210:211], v[212:213] op_sel:[1,1] op_sel_hi:[1,0]
	v_pk_fma_f32 v[220:221], v[210:211], v[212:213], v[206:207] op_sel_hi:[0,1,1] neg_lo:[0,0,1]
	v_pk_mul_f32 v[10:11], v[210:211], v[202:203] op_sel:[1,1] op_sel_hi:[1,0]
	v_pk_fma_f32 v[10:11], v[210:211], v[202:203], v[10:11] op_sel_hi:[0,1,1] neg_lo:[0,0,1]
	v_pk_mul_f32 v[12:13], v[212:213], v[16:17] op_sel:[1,1] op_sel_hi:[1,0]
	v_pk_fma_f32 v[12:13], v[212:213], v[16:17], v[12:13] op_sel_hi:[0,1,1] neg_lo:[0,0,1]
	v_pk_mul_f32 v[16:17], v[220:221], v[204:205] op_sel:[1,1] op_sel_hi:[1,0]
	v_pk_fma_f32 v[16:17], v[220:221], v[204:205], v[16:17] op_sel_hi:[0,1,1] neg_lo:[0,0,1]
	v_add_f32_e32 v214, 0x3d800000, v201
	v_cos_f32_e32 v210, v214
	v_sin_f32_e64 v211, -v214
	s_waitcnt lgkmcnt(10)
	v_pk_add_f32 v[202:203], v[18:19], v[22:23]
	v_pk_add_f32 v[18:19], v[18:19], v[22:23] neg_lo:[0,1] neg_hi:[0,1]
	v_pk_add_f32 v[204:205], v[20:21], v[24:25]
	v_pk_add_f32 v[20:21], v[20:21], v[24:25] neg_lo:[0,1] neg_hi:[0,1]
	v_pk_add_f32 v[22:23], v[202:203], v[204:205]
	v_pk_add_f32 v[24:25], v[202:203], v[204:205] neg_lo:[0,1] neg_hi:[0,1]
	v_pk_add_f32 v[202:203], v[18:19], v[20:21] op_sel:[0,1] op_sel_hi:[1,0] neg_hi:[0,1]
	v_pk_add_f32 v[204:205], v[18:19], v[20:21] op_sel:[0,1] op_sel_hi:[1,0] neg_lo:[0,1]
	v_pk_mul_f32 v[206:207], v[210:211], v[210:211] op_sel:[1,1] op_sel_hi:[1,0]
	v_pk_fma_f32 v[212:213], v[210:211], v[210:211], v[206:207] op_sel_hi:[0,1,1] neg_lo:[0,0,1]
	v_pk_mul_f32 v[206:207], v[210:211], v[212:213] op_sel:[1,1] op_sel_hi:[1,0]
	v_pk_fma_f32 v[220:221], v[210:211], v[212:213], v[206:207] op_sel_hi:[0,1,1] neg_lo:[0,0,1]
	v_pk_mul_f32 v[18:19], v[210:211], v[202:203] op_sel:[1,1] op_sel_hi:[1,0]
	v_pk_fma_f32 v[18:19], v[210:211], v[202:203], v[18:19] op_sel_hi:[0,1,1] neg_lo:[0,0,1]
	v_pk_mul_f32 v[20:21], v[212:213], v[24:25] op_sel:[1,1] op_sel_hi:[1,0]
	v_pk_fma_f32 v[20:21], v[212:213], v[24:25], v[20:21] op_sel_hi:[0,1,1] neg_lo:[0,0,1]
	v_pk_mul_f32 v[24:25], v[220:221], v[204:205] op_sel:[1,1] op_sel_hi:[1,0]
	v_pk_fma_f32 v[24:25], v[220:221], v[204:205], v[24:25] op_sel_hi:[0,1,1] neg_lo:[0,0,1]
	v_add_f32_e32 v214, 0x3dc00000, v201
	v_cos_f32_e32 v210, v214
	v_sin_f32_e64 v211, -v214
	s_waitcnt lgkmcnt(8)
	v_pk_add_f32 v[202:203], v[26:27], v[30:31]
	v_pk_add_f32 v[26:27], v[26:27], v[30:31] neg_lo:[0,1] neg_hi:[0,1]
	v_pk_add_f32 v[204:205], v[28:29], v[32:33]
	v_pk_add_f32 v[28:29], v[28:29], v[32:33] neg_lo:[0,1] neg_hi:[0,1]
	v_pk_add_f32 v[30:31], v[202:203], v[204:205]
	v_pk_add_f32 v[32:33], v[202:203], v[204:205] neg_lo:[0,1] neg_hi:[0,1]
	v_pk_add_f32 v[202:203], v[26:27], v[28:29] op_sel:[0,1] op_sel_hi:[1,0] neg_hi:[0,1]
	v_pk_add_f32 v[204:205], v[26:27], v[28:29] op_sel:[0,1] op_sel_hi:[1,0] neg_lo:[0,1]
	v_pk_mul_f32 v[206:207], v[210:211], v[210:211] op_sel:[1,1] op_sel_hi:[1,0]
	v_pk_fma_f32 v[212:213], v[210:211], v[210:211], v[206:207] op_sel_hi:[0,1,1] neg_lo:[0,0,1]
	v_pk_mul_f32 v[206:207], v[210:211], v[212:213] op_sel:[1,1] op_sel_hi:[1,0]
	v_pk_fma_f32 v[220:221], v[210:211], v[212:213], v[206:207] op_sel_hi:[0,1,1] neg_lo:[0,0,1]
	v_pk_mul_f32 v[26:27], v[210:211], v[202:203] op_sel:[1,1] op_sel_hi:[1,0]
	v_pk_fma_f32 v[26:27], v[210:211], v[202:203], v[26:27] op_sel_hi:[0,1,1] neg_lo:[0,0,1]
	v_pk_mul_f32 v[28:29], v[212:213], v[32:33] op_sel:[1,1] op_sel_hi:[1,0]
	v_pk_fma_f32 v[28:29], v[212:213], v[32:33], v[28:29] op_sel_hi:[0,1,1] neg_lo:[0,0,1]
	v_pk_mul_f32 v[32:33], v[220:221], v[204:205] op_sel:[1,1] op_sel_hi:[1,0]
	v_pk_fma_f32 v[32:33], v[220:221], v[204:205], v[32:33] op_sel_hi:[0,1,1] neg_lo:[0,0,1]
	v_add_f32_e32 v214, 0x3e000000, v201
	v_cos_f32_e32 v210, v214
	v_sin_f32_e64 v211, -v214
	s_waitcnt lgkmcnt(6)
	v_pk_add_f32 v[202:203], v[34:35], v[38:39]
	v_pk_add_f32 v[34:35], v[34:35], v[38:39] neg_lo:[0,1] neg_hi:[0,1]
	v_pk_add_f32 v[204:205], v[36:37], v[40:41]
	v_pk_add_f32 v[36:37], v[36:37], v[40:41] neg_lo:[0,1] neg_hi:[0,1]
	v_pk_add_f32 v[38:39], v[202:203], v[204:205]
	v_pk_add_f32 v[40:41], v[202:203], v[204:205] neg_lo:[0,1] neg_hi:[0,1]
	v_pk_add_f32 v[202:203], v[34:35], v[36:37] op_sel:[0,1] op_sel_hi:[1,0] neg_hi:[0,1]
	v_pk_add_f32 v[204:205], v[34:35], v[36:37] op_sel:[0,1] op_sel_hi:[1,0] neg_lo:[0,1]
	v_pk_mul_f32 v[206:207], v[210:211], v[210:211] op_sel:[1,1] op_sel_hi:[1,0]
	v_pk_fma_f32 v[212:213], v[210:211], v[210:211], v[206:207] op_sel_hi:[0,1,1] neg_lo:[0,0,1]
	v_pk_mul_f32 v[206:207], v[210:211], v[212:213] op_sel:[1,1] op_sel_hi:[1,0]
	v_pk_fma_f32 v[220:221], v[210:211], v[212:213], v[206:207] op_sel_hi:[0,1,1] neg_lo:[0,0,1]
	v_pk_mul_f32 v[34:35], v[210:211], v[202:203] op_sel:[1,1] op_sel_hi:[1,0]
	v_pk_fma_f32 v[34:35], v[210:211], v[202:203], v[34:35] op_sel_hi:[0,1,1] neg_lo:[0,0,1]
	v_pk_mul_f32 v[36:37], v[212:213], v[40:41] op_sel:[1,1] op_sel_hi:[1,0]
	v_pk_fma_f32 v[36:37], v[212:213], v[40:41], v[36:37] op_sel_hi:[0,1,1] neg_lo:[0,0,1]
	v_pk_mul_f32 v[40:41], v[220:221], v[204:205] op_sel:[1,1] op_sel_hi:[1,0]
	v_pk_fma_f32 v[40:41], v[220:221], v[204:205], v[40:41] op_sel_hi:[0,1,1] neg_lo:[0,0,1]
	v_add_f32_e32 v214, 0x3e200000, v201
	v_cos_f32_e32 v210, v214
	v_sin_f32_e64 v211, -v214
	s_waitcnt lgkmcnt(4)
; DI f32x2 cmul(f32x2 a, f32x2 b) { return mkf2(a.x * b.x - a.y * b.y, a.x * b.y + a.y * b.x); }
; DI void fft8192(f32x2* buf, const f32x2* __restrict__ tw) {
;     ...
; #pragma unroll
;     for (int e = 0; e < 8; ++e) {
;       const int i = tid + 256 * e;
;       const int q = i & (s - 1);
;       const int ps = i - q;
;       const float rev = (float)ps * (1.f / 8192.f);
;       const f32x2 w1 = mkf2(__builtin_amdgcn_cosf(rev), -__builtin_amdgcn_sinf(rev));
;       const f32x2 w2 = cmul(w1, w1), w3 = cmul(w1, w2);
;       const f32x2 apc = mkf2(a[e].x + c[e].x, a[e].y + c[e].y), amc = mkf2(a[e].x - c[e].x, a[e].y - c[e].y);
;       const f32x2 bpd = mkf2(b[e].x + d[e].x, b[e].y + d[e].y), bmd = mkf2(b[e].x - d[e].x, b[e].y - d[e].y);
;       const int o = 4 * i - 3 * q;
;       buf[SW(o)] = mkf2(apc.x + bpd.x, apc.y + bpd.y);
;       buf[SW(o + s)] = cmul(w1, mkf2(amc.x + bmd.y, amc.y - bmd.x));
;       buf[SW(o + 2 * s)] = cmul(w2, mkf2(apc.x - bpd.x, apc.y - bpd.y));
;       buf[SW(o + 3 * s)] = cmul(w3, mkf2(amc.x - bmd.y, amc.y + bmd.x));
;     }
	v_pk_add_f32 v[202:203], v[42:43], v[46:47]
	v_pk_add_f32 v[42:43], v[42:43], v[46:47] neg_lo:[0,1] neg_hi:[0,1]
	v_pk_add_f32 v[204:205], v[44:45], v[48:49]
	v_pk_add_f32 v[44:45], v[44:45], v[48:49] neg_lo:[0,1] neg_hi:[0,1]
	v_pk_add_f32 v[46:47], v[202:203], v[204:205]
	v_pk_add_f32 v[48:49], v[202:203], v[204:205] neg_lo:[0,1] neg_hi:[0,1]
	v_pk_add_f32 v[202:203], v[42:43], v[44:45] op_sel:[0,1] op_sel_hi:[1,0] neg_hi:[0,1]
	v_pk_add_f32 v[204:205], v[42:43], v[44:45] op_sel:[0,1] op_sel_hi:[1,0] neg_lo:[0,1]
	v_pk_mul_f32 v[206:207], v[210:211], v[210:211] op_sel:[1,1] op_sel_hi:[1,0]
	v_pk_fma_f32 v[212:213], v[210:211], v[210:211], v[206:207] op_sel_hi:[0,1,1] neg_lo:[0,0,1]
	v_pk_mul_f32 v[206:207], v[210:211], v[212:213] op_sel:[1,1] op_sel_hi:[1,0]
	v_pk_fma_f32 v[220:221], v[210:211], v[212:213], v[206:207] op_sel_hi:[0,1,1] neg_lo:[0,0,1]
	v_pk_mul_f32 v[42:43], v[210:211], v[202:203] op_sel:[1,1] op_sel_hi:[1,0]
	v_pk_fma_f32 v[42:43], v[210:211], v[202:203], v[42:43] op_sel_hi:[0,1,1] neg_lo:[0,0,1]
	v_pk_mul_f32 v[44:45], v[212:213], v[48:49] op_sel:[1,1] op_sel_hi:[1,0]
	v_pk_fma_f32 v[44:45], v[212:213], v[48:49], v[44:45] op_sel_hi:[0,1,1] neg_lo:[0,0,1]
	v_pk_mul_f32 v[48:49], v[220:221], v[204:205] op_sel:[1,1] op_sel_hi:[1,0]
	v_pk_fma_f32 v[48:49], v[220:221], v[204:205], v[48:49] op_sel_hi:[0,1,1] neg_lo:[0,0,1]
	v_add_f32_e32 v214, 0x3e400000, v201
	v_cos_f32_e32 v210, v214
	v_sin_f32_e64 v211, -v214
	s_waitcnt lgkmcnt(2)
	v_pk_add_f32 v[202:203], v[50:51], v[54:55]
	v_pk_add_f32 v[50:51], v[50:51], v[54:55] neg_lo:[0,1] neg_hi:[0,1]
	v_pk_add_f32 v[204:205], v[52:53], v[56:57]
	v_pk_add_f32 v[52:53], v[52:53], v[56:57] neg_lo:[0,1] neg_hi:[0,1]
	v_pk_add_f32 v[54:55], v[202:203], v[204:205]
	v_pk_add_f32 v[56:57], v[202:203], v[204:205] neg_lo:[0,1] neg_hi:[0,1]
	v_pk_add_f32 v[202:203], v[50:51], v[52:53] op_sel:[0,1] op_sel_hi:[1,0] neg_hi:[0,1]
	v_pk_add_f32 v[204:205], v[50:51], v[52:53] op_sel:[0,1] op_sel_hi:[1,0] neg_lo:[0,1]
	v_pk_mul_f32 v[206:207], v[210:211], v[210:211] op_sel:[1,1] op_sel_hi:[1,0]
	v_pk_fma_f32 v[212:213], v[210:211], v[210:211], v[206:207] op_sel_hi:[0,1,1] neg_lo:[0,0,1]
	v_pk_mul_f32 v[206:207], v[210:211], v[212:213] op_sel:[1,1] op_sel_hi:[1,0]
	v_pk_fma_f32 v[220:221], v[210:211], v[212:213], v[206:207] op_sel_hi:[0,1,1] neg_lo:[0,0,1]
	v_pk_mul_f32 v[50:51], v[210:211], v[202:203] op_sel:[1,1] op_sel_hi:[1,0]
	v_pk_fma_f32 v[50:51], v[210:211], v[202:203], v[50:51] op_sel_hi:[0,1,1] neg_lo:[0,0,1]
	v_pk_mul_f32 v[52:53], v[212:213], v[56:57] op_sel:[1,1] op_sel_hi:[1,0]
	v_pk_fma_f32 v[52:53], v[212:213], v[56:57], v[52:53] op_sel_hi:[0,1,1] neg_lo:[0,0,1]
	v_pk_mul_f32 v[56:57], v[220:221], v[204:205] op_sel:[1,1] op_sel_hi:[1,0]
	v_pk_fma_f32 v[56:57], v[220:221], v[204:205], v[56:57] op_sel_hi:[0,1,1] neg_lo:[0,0,1]
	v_add_f32_e32 v214, 0x3e600000, v201
	v_cos_f32_e32 v210, v214
	v_sin_f32_e64 v211, -v214
	s_waitcnt lgkmcnt(0)
	v_pk_add_f32 v[202:203], v[58:59], v[62:63]
	v_pk_add_f32 v[58:59], v[58:59], v[62:63] neg_lo:[0,1] neg_hi:[0,1]
	v_pk_add_f32 v[204:205], v[60:61], v[64:65]
	v_pk_add_f32 v[60:61], v[60:61], v[64:65] neg_lo:[0,1] neg_hi:[0,1]
	v_pk_add_f32 v[62:63], v[202:203], v[204:205]
	v_pk_add_f32 v[64:65], v[202:203], v[204:205] neg_lo:[0,1] neg_hi:[0,1]
	v_pk_add_f32 v[202:203], v[58:59], v[60:61] op_sel:[0,1] op_sel_hi:[1,0] neg_hi:[0,1]
	v_pk_add_f32 v[204:205], v[58:59], v[60:61] op_sel:[0,1] op_sel_hi:[1,0] neg_lo:[0,1]
	v_pk_mul_f32 v[206:207], v[210:211], v[210:211] op_sel:[1,1] op_sel_hi:[1,0]
	v_pk_fma_f32 v[212:213], v[210:211], v[210:211], v[206:207] op_sel_hi:[0,1,1] neg_lo:[0,0,1]
	v_pk_mul_f32 v[206:207], v[210:211], v[212:213] op_sel:[1,1] op_sel_hi:[1,0]
	v_pk_fma_f32 v[220:221], v[210:211], v[212:213], v[206:207] op_sel_hi:[0,1,1] neg_lo:[0,0,1]
	v_pk_mul_f32 v[58:59], v[210:211], v[202:203] op_sel:[1,1] op_sel_hi:[1,0]
	v_pk_fma_f32 v[58:59], v[210:211], v[202:203], v[58:59] op_sel_hi:[0,1,1] neg_lo:[0,0,1]
	v_pk_mul_f32 v[60:61], v[212:213], v[64:65] op_sel:[1,1] op_sel_hi:[1,0]
	v_pk_fma_f32 v[60:61], v[212:213], v[64:65], v[60:61] op_sel_hi:[0,1,1] neg_lo:[0,0,1]
	v_pk_mul_f32 v[64:65], v[220:221], v[204:205] op_sel:[1,1] op_sel_hi:[1,0]
	v_pk_fma_f32 v[64:65], v[220:221], v[204:205], v[64:65] op_sel_hi:[0,1,1] neg_lo:[0,0,1]
	s_barrier
	ds_write_b64 v156, v[6:7] offset:0
	ds_write_b64 v158, v[2:3] offset:0
	ds_write_b64 v160, v[4:5] offset:0
	ds_write_b64 v162, v[8:9] offset:0
	ds_write_b64 v156, v[14:15] offset:8192
	ds_write_b64 v158, v[10:11] offset:8192
	ds_write_b64 v160, v[12:13] offset:8192
	ds_write_b64 v162, v[16:17] offset:8192
	ds_write_b64 v156, v[22:23] offset:16384
	ds_write_b64 v158, v[18:19] offset:16384
	ds_write_b64 v160, v[20:21] offset:16384
	ds_write_b64 v162, v[24:25] offset:16384
	ds_write_b64 v156, v[30:31] offset:24576
	ds_write_b64 v158, v[26:27] offset:24576
	ds_write_b64 v160, v[28:29] offset:24576
	ds_write_b64 v162, v[32:33] offset:24576
	ds_write_b64 v156, v[38:39] offset:32768
	ds_write_b64 v158, v[34:35] offset:32768
	ds_write_b64 v160, v[36:37] offset:32768
	ds_write_b64 v162, v[40:41] offset:32768
	ds_write_b64 v156, v[46:47] offset:40960
	ds_write_b64 v158, v[42:43] offset:40960
	ds_write_b64 v160, v[44:45] offset:40960
	ds_write_b64 v162, v[48:49] offset:40960
	ds_write_b64 v156, v[54:55] offset:49152
	ds_write_b64 v158, v[50:51] offset:49152
	ds_write_b64 v160, v[52:53] offset:49152
	ds_write_b64 v162, v[56:57] offset:49152
	ds_write_b64 v156, v[62:63] offset:57344
	ds_write_b64 v158, v[58:59] offset:57344
	ds_write_b64 v160, v[60:61] offset:57344
	ds_write_b64 v162, v[64:65] offset:57344
	s_waitcnt lgkmcnt(0)
	s_barrier
; DI f32x2 cmul(f32x2 a, f32x2 b) { return mkf2(a.x * b.x - a.y * b.y, a.x * b.y + a.y * b.x); }
; DI void fft8192(f32x2* buf, const f32x2* __restrict__ tw) {
;     ...
; #pragma unroll 2
;   for (int ls = 0; ls < 12; ls += 2) {
;     const int s = 1 << ls;
;     f32x2 a[8], b[8], c[8], d[8];
;     __syncthreads();
; #pragma unroll
;     for (int e = 0; e < 8; ++e) {
;       const int i = tid + 256 * e;
;       const int pi = SW(i);
;       a[e] = buf[pi]; b[e] = buf[pi + 2048]; c[e] = buf[pi + 4096]; d[e] = buf[pi + 6144];
;     }
;     __syncthreads();
; #pragma unroll
;     for (int e = 0; e < 8; ++e) {
;       const int i = tid + 256 * e;
;       const int q = i & (s - 1);
;       const int ps = i - q;
;       const float rev = (float)ps * (1.f / 8192.f);
;       const f32x2 w1 = mkf2(__builtin_amdgcn_cosf(rev), -__builtin_amdgcn_sinf(rev));
;       const f32x2 w2 = cmul(w1, w1), w3 = cmul(w1, w2);
;       const f32x2 apc = mkf2(a[e].x + c[e].x, a[e].y + c[e].y), amc = mkf2(a[e].x - c[e].x, a[e].y - c[e].y);
;       const f32x2 bpd = mkf2(b[e].x + d[e].x, b[e].y + d[e].y), bmd = mkf2(b[e].x - d[e].x, b[e].y - d[e].y);
;       const int o = 4 * i - 3 * q;
;       buf[SW(o)] = mkf2(apc.x + bpd.x, apc.y + bpd.y);
;       buf[SW(o + s)] = cmul(w1, mkf2(amc.x + bmd.y, amc.y - bmd.x));
;       buf[SW(o + 2 * s)] = cmul(w2, mkf2(apc.x - bpd.x, apc.y - bpd.y));
;       buf[SW(o + 3 * s)] = cmul(w3, mkf2(amc.x - bmd.y, amc.y + bmd.x));
;     }
	ds_read2st64_b64 v[2:5], v154 offset0:0 offset1:32
	ds_read2st64_b64 v[6:9], v154 offset0:64 offset1:96
	ds_read2st64_b64 v[10:13], v154 offset0:4 offset1:36
	ds_read2st64_b64 v[14:17], v154 offset0:68 offset1:100
	ds_read2st64_b64 v[18:21], v154 offset0:8 offset1:40
	ds_read2st64_b64 v[22:25], v154 offset0:72 offset1:104
	ds_read2st64_b64 v[26:29], v154 offset0:12 offset1:44
	ds_read2st64_b64 v[30:33], v154 offset0:76 offset1:108
	ds_read2st64_b64 v[34:37], v154 offset0:16 offset1:48
	ds_read2st64_b64 v[38:41], v154 offset0:80 offset1:112
	ds_read2st64_b64 v[42:45], v154 offset0:20 offset1:52
	ds_read2st64_b64 v[46:49], v154 offset0:84 offset1:116
	ds_read2st64_b64 v[50:53], v154 offset0:24 offset1:56
	ds_read2st64_b64 v[54:57], v154 offset0:88 offset1:120
	ds_read2st64_b64 v[58:61], v154 offset0:28 offset1:60
	ds_read2st64_b64 v[62:65], v154 offset0:92 offset1:124
	v_and_b32_e32 v166, 15, v0
	v_lshlrev_b32_e32 v164, 2, v0
	v_mad_i32_i24 v164, v166, -3, v164
	v_sub_u32_e32 v166, v0, v166
	v_cvt_f32_u32_e32 v201, v166
	v_mul_f32_e32 v201, 0x39000000, v201
	v_bfe_i32 v166, v164, 5, 1
	v_bfe_i32 v168, v164, 6, 1
	v_and_b32_e32 v166, 5, v166
	v_and_b32_e32 v168, 26, v168
	v_xor_b32_e32 v166, v166, v168
	v_xor_b32_e32 v166, v166, v164
	v_lshlrev_b32_e32 v156, 3, v166
	v_xor_b32_e32 v158, 0x80, v156
	v_xor_b32_e32 v160, 0x128, v156
	v_xor_b32_e32 v162, 0x1a8, v156
	v_cos_f32_e32 v210, v201
	v_sin_f32_e64 v211, -v201
	s_waitcnt lgkmcnt(14)
	v_pk_add_f32 v[202:203], v[2:3], v[6:7]
	v_pk_add_f32 v[2:3], v[2:3], v[6:7] neg_lo:[0,1] neg_hi:[0,1]
	v_pk_add_f32 v[204:205], v[4:5], v[8:9]
	v_pk_add_f32 v[4:5], v[4:5], v[8:9] neg_lo:[0,1] neg_hi:[0,1]
	v_pk_add_f32 v[6:7], v[202:203], v[204:205]
	v_pk_add_f32 v[8:9], v[202:203], v[204:205] neg_lo:[0,1] neg_hi:[0,1]
	v_pk_add_f32 v[202:203], v[2:3], v[4:5] op_sel:[0,1] op_sel_hi:[1,0] neg_hi:[0,1]
	v_pk_add_f32 v[204:205], v[2:3], v[4:5] op_sel:[0,1] op_sel_hi:[1,0] neg_lo:[0,1]
	v_pk_mul_f32 v[206:207], v[210:211], v[210:211] op_sel:[1,1] op_sel_hi:[1,0]
	v_pk_fma_f32 v[212:213], v[210:211], v[210:211], v[206:207] op_sel_hi:[0,1,1] neg_lo:[0,0,1]
	v_pk_mul_f32 v[206:207], v[210:211], v[212:213] op_sel:[1,1] op_sel_hi:[1,0]
	v_pk_fma_f32 v[220:221], v[210:211], v[212:213], v[206:207] op_sel_hi:[0,1,1] neg_lo:[0,0,1]
	v_pk_mul_f32 v[2:3], v[210:211], v[202:203] op_sel:[1,1] op_sel_hi:[1,0]
	v_pk_fma_f32 v[2:3], v[210:211], v[202:203], v[2:3] op_sel_hi:[0,1,1] neg_lo:[0,0,1]
	v_pk_mul_f32 v[4:5], v[212:213], v[8:9] op_sel:[1,1] op_sel_hi:[1,0]
	v_pk_fma_f32 v[4:5], v[212:213], v[8:9], v[4:5] op_sel_hi:[0,1,1] neg_lo:[0,0,1]
	v_pk_mul_f32 v[8:9], v[220:221], v[204:205] op_sel:[1,1] op_sel_hi:[1,0]
	v_pk_fma_f32 v[8:9], v[220:221], v[204:205], v[8:9] op_sel_hi:[0,1,1] neg_lo:[0,0,1]
	v_add_f32_e32 v214, 0x3d000000, v201
	v_cos_f32_e32 v210, v214
	v_sin_f32_e64 v211, -v214
	s_waitcnt lgkmcnt(12)
	v_pk_add_f32 v[202:203], v[10:11], v[14:15]
	v_pk_add_f32 v[10:11], v[10:11], v[14:15] neg_lo:[0,1] neg_hi:[0,1]
	v_pk_add_f32 v[204:205], v[12:13], v[16:17]
	v_pk_add_f32 v[12:13], v[12:13], v[16:17] neg_lo:[0,1] neg_hi:[0,1]
	v_pk_add_f32 v[14:15], v[202:203], v[204:205]
	v_pk_add_f32 v[16:17], v[202:203], v[204:205] neg_lo:[0,1] neg_hi:[0,1]
	v_pk_add_f32 v[202:203], v[10:11], v[12:13] op_sel:[0,1] op_sel_hi:[1,0] neg_hi:[0,1]
	v_pk_add_f32 v[204:205], v[10:11], v[12:13] op_sel:[0,1] op_sel_hi:[1,0] neg_lo:[0,1]
	v_pk_mul_f32 v[206:207], v[210:211], v[210:211] op_sel:[1,1] op_sel_hi:[1,0]
	v_pk_fma_f32 v[212:213], v[210:211], v[210:211], v[206:207] op_sel_hi:[0,1,1] neg_lo:[0,0,1]
	v_pk_mul_f32 v[206:207], v[210:211], v[212:213] op_sel:[1,1] op_sel_hi:[1,0]
	v_pk_fma_f32 v[220:221], v[210:211], v[212:213], v[206:207] op_sel_hi:[0,1,1] neg_lo:[0,0,1]
	v_pk_mul_f32 v[10:11], v[210:211], v[202:203] op_sel:[1,1] op_sel_hi:[1,0]
	v_pk_fma_f32 v[10:11], v[210:211], v[202:203], v[10:11] op_sel_hi:[0,1,1] neg_lo:[0,0,1]
	v_pk_mul_f32 v[12:13], v[212:213], v[16:17] op_sel:[1,1] op_sel_hi:[1,0]
	v_pk_fma_f32 v[12:13], v[212:213], v[16:17], v[12:13] op_sel_hi:[0,1,1] neg_lo:[0,0,1]
	v_pk_mul_f32 v[16:17], v[220:221], v[204:205] op_sel:[1,1] op_sel_hi:[1,0]
	v_pk_fma_f32 v[16:17], v[220:221], v[204:205], v[16:17] op_sel_hi:[0,1,1] neg_lo:[0,0,1]
	v_add_f32_e32 v214, 0x3d800000, v201
	v_cos_f32_e32 v210, v214
	v_sin_f32_e64 v211, -v214
	s_waitcnt lgkmcnt(10)
	v_pk_add_f32 v[202:203], v[18:19], v[22:23]
	v_pk_add_f32 v[18:19], v[18:19], v[22:23] neg_lo:[0,1] neg_hi:[0,1]
	v_pk_add_f32 v[204:205], v[20:21], v[24:25]
	v_pk_add_f32 v[20:21], v[20:21], v[24:25] neg_lo:[0,1] neg_hi:[0,1]
	v_pk_add_f32 v[22:23], v[202:203], v[204:205]
	v_pk_add_f32 v[24:25], v[202:203], v[204:205] neg_lo:[0,1] neg_hi:[0,1]
	v_pk_add_f32 v[202:203], v[18:19], v[20:21] op_sel:[0,1] op_sel_hi:[1,0] neg_hi:[0,1]
	v_pk_add_f32 v[204:205], v[18:19], v[20:21] op_sel:[0,1] op_sel_hi:[1,0] neg_lo:[0,1]
	v_pk_mul_f32 v[206:207], v[210:211], v[210:211] op_sel:[1,1] op_sel_hi:[1,0]
	v_pk_fma_f32 v[212:213], v[210:211], v[210:211], v[206:207] op_sel_hi:[0,1,1] neg_lo:[0,0,1]
	v_pk_mul_f32 v[206:207], v[210:211], v[212:213] op_sel:[1,1] op_sel_hi:[1,0]
	v_pk_fma_f32 v[220:221], v[210:211], v[212:213], v[206:207] op_sel_hi:[0,1,1] neg_lo:[0,0,1]
	v_pk_mul_f32 v[18:19], v[210:211], v[202:203] op_sel:[1,1] op_sel_hi:[1,0]
	v_pk_fma_f32 v[18:19], v[210:211], v[202:203], v[18:19] op_sel_hi:[0,1,1] neg_lo:[0,0,1]
	v_pk_mul_f32 v[20:21], v[212:213], v[24:25] op_sel:[1,1] op_sel_hi:[1,0]
	v_pk_fma_f32 v[20:21], v[212:213], v[24:25], v[20:21] op_sel_hi:[0,1,1] neg_lo:[0,0,1]
	v_pk_mul_f32 v[24:25], v[220:221], v[204:205] op_sel:[1,1] op_sel_hi:[1,0]
	v_pk_fma_f32 v[24:25], v[220:221], v[204:205], v[24:25] op_sel_hi:[0,1,1] neg_lo:[0,0,1]
	v_add_f32_e32 v214, 0x3dc00000, v201
	v_cos_f32_e32 v210, v214
	v_sin_f32_e64 v211, -v214
	s_waitcnt lgkmcnt(8)
; DI f32x2 cmul(f32x2 a, f32x2 b) { return mkf2(a.x * b.x - a.y * b.y, a.x * b.y + a.y * b.x); }
; DI void fft8192(f32x2* buf, const f32x2* __restrict__ tw) {
;     ...
; #pragma unroll
;     for (int e = 0; e < 8; ++e) {
;       const int i = tid + 256 * e;
;       const int q = i & (s - 1);
;       const int ps = i - q;
;       const float rev = (float)ps * (1.f / 8192.f);
;       const f32x2 w1 = mkf2(__builtin_amdgcn_cosf(rev), -__builtin_amdgcn_sinf(rev));
;       const f32x2 w2 = cmul(w1, w1), w3 = cmul(w1, w2);
;       const f32x2 apc = mkf2(a[e].x + c[e].x, a[e].y + c[e].y), amc = mkf2(a[e].x - c[e].x, a[e].y - c[e].y);
;       const f32x2 bpd = mkf2(b[e].x + d[e].x, b[e].y + d[e].y), bmd = mkf2(b[e].x - d[e].x, b[e].y - d[e].y);
;       const int o = 4 * i - 3 * q;
;       buf[SW(o)] = mkf2(apc.x + bpd.x, apc.y + bpd.y);
;       buf[SW(o + s)] = cmul(w1, mkf2(amc.x + bmd.y, amc.y - bmd.x));
;       buf[SW(o + 2 * s)] = cmul(w2, mkf2(apc.x - bpd.x, apc.y - bpd.y));
;       buf[SW(o + 3 * s)] = cmul(w3, mkf2(amc.x - bmd.y, amc.y + bmd.x));
;     }
	v_pk_add_f32 v[202:203], v[26:27], v[30:31]
	v_pk_add_f32 v[26:27], v[26:27], v[30:31] neg_lo:[0,1] neg_hi:[0,1]
	v_pk_add_f32 v[204:205], v[28:29], v[32:33]
	v_pk_add_f32 v[28:29], v[28:29], v[32:33] neg_lo:[0,1] neg_hi:[0,1]
	v_pk_add_f32 v[30:31], v[202:203], v[204:205]
	v_pk_add_f32 v[32:33], v[202:203], v[204:205] neg_lo:[0,1] neg_hi:[0,1]
	v_pk_add_f32 v[202:203], v[26:27], v[28:29] op_sel:[0,1] op_sel_hi:[1,0] neg_hi:[0,1]
	v_pk_add_f32 v[204:205], v[26:27], v[28:29] op_sel:[0,1] op_sel_hi:[1,0] neg_lo:[0,1]
	v_pk_mul_f32 v[206:207], v[210:211], v[210:211] op_sel:[1,1] op_sel_hi:[1,0]
	v_pk_fma_f32 v[212:213], v[210:211], v[210:211], v[206:207] op_sel_hi:[0,1,1] neg_lo:[0,0,1]
	v_pk_mul_f32 v[206:207], v[210:211], v[212:213] op_sel:[1,1] op_sel_hi:[1,0]
	v_pk_fma_f32 v[220:221], v[210:211], v[212:213], v[206:207] op_sel_hi:[0,1,1] neg_lo:[0,0,1]
	v_pk_mul_f32 v[26:27], v[210:211], v[202:203] op_sel:[1,1] op_sel_hi:[1,0]
	v_pk_fma_f32 v[26:27], v[210:211], v[202:203], v[26:27] op_sel_hi:[0,1,1] neg_lo:[0,0,1]
	v_pk_mul_f32 v[28:29], v[212:213], v[32:33] op_sel:[1,1] op_sel_hi:[1,0]
	v_pk_fma_f32 v[28:29], v[212:213], v[32:33], v[28:29] op_sel_hi:[0,1,1] neg_lo:[0,0,1]
	v_pk_mul_f32 v[32:33], v[220:221], v[204:205] op_sel:[1,1] op_sel_hi:[1,0]
	v_pk_fma_f32 v[32:33], v[220:221], v[204:205], v[32:33] op_sel_hi:[0,1,1] neg_lo:[0,0,1]
	v_add_f32_e32 v214, 0x3e000000, v201
	v_cos_f32_e32 v210, v214
	v_sin_f32_e64 v211, -v214
	s_waitcnt lgkmcnt(6)
	v_pk_add_f32 v[202:203], v[34:35], v[38:39]
	v_pk_add_f32 v[34:35], v[34:35], v[38:39] neg_lo:[0,1] neg_hi:[0,1]
	v_pk_add_f32 v[204:205], v[36:37], v[40:41]
	v_pk_add_f32 v[36:37], v[36:37], v[40:41] neg_lo:[0,1] neg_hi:[0,1]
	v_pk_add_f32 v[38:39], v[202:203], v[204:205]
	v_pk_add_f32 v[40:41], v[202:203], v[204:205] neg_lo:[0,1] neg_hi:[0,1]
	v_pk_add_f32 v[202:203], v[34:35], v[36:37] op_sel:[0,1] op_sel_hi:[1,0] neg_hi:[0,1]
	v_pk_add_f32 v[204:205], v[34:35], v[36:37] op_sel:[0,1] op_sel_hi:[1,0] neg_lo:[0,1]
	v_pk_mul_f32 v[206:207], v[210:211], v[210:211] op_sel:[1,1] op_sel_hi:[1,0]
	v_pk_fma_f32 v[212:213], v[210:211], v[210:211], v[206:207] op_sel_hi:[0,1,1] neg_lo:[0,0,1]
	v_pk_mul_f32 v[206:207], v[210:211], v[212:213] op_sel:[1,1] op_sel_hi:[1,0]
	v_pk_fma_f32 v[220:221], v[210:211], v[212:213], v[206:207] op_sel_hi:[0,1,1] neg_lo:[0,0,1]
	v_pk_mul_f32 v[34:35], v[210:211], v[202:203] op_sel:[1,1] op_sel_hi:[1,0]
	v_pk_fma_f32 v[34:35], v[210:211], v[202:203], v[34:35] op_sel_hi:[0,1,1] neg_lo:[0,0,1]
	v_pk_mul_f32 v[36:37], v[212:213], v[40:41] op_sel:[1,1] op_sel_hi:[1,0]
	v_pk_fma_f32 v[36:37], v[212:213], v[40:41], v[36:37] op_sel_hi:[0,1,1] neg_lo:[0,0,1]
	v_pk_mul_f32 v[40:41], v[220:221], v[204:205] op_sel:[1,1] op_sel_hi:[1,0]
	v_pk_fma_f32 v[40:41], v[220:221], v[204:205], v[40:41] op_sel_hi:[0,1,1] neg_lo:[0,0,1]
	v_add_f32_e32 v214, 0x3e200000, v201
	v_cos_f32_e32 v210, v214
	v_sin_f32_e64 v211, -v214
	s_waitcnt lgkmcnt(4)
	v_pk_add_f32 v[202:203], v[42:43], v[46:47]
	v_pk_add_f32 v[42:43], v[42:43], v[46:47] neg_lo:[0,1] neg_hi:[0,1]
	v_pk_add_f32 v[204:205], v[44:45], v[48:49]
	v_pk_add_f32 v[44:45], v[44:45], v[48:49] neg_lo:[0,1] neg_hi:[0,1]
	v_pk_add_f32 v[46:47], v[202:203], v[204:205]
	v_pk_add_f32 v[48:49], v[202:203], v[204:205] neg_lo:[0,1] neg_hi:[0,1]
	v_pk_add_f32 v[202:203], v[42:43], v[44:45] op_sel:[0,1] op_sel_hi:[1,0] neg_hi:[0,1]
	v_pk_add_f32 v[204:205], v[42:43], v[44:45] op_sel:[0,1] op_sel_hi:[1,0] neg_lo:[0,1]
	v_pk_mul_f32 v[206:207], v[210:211], v[210:211] op_sel:[1,1] op_sel_hi:[1,0]
	v_pk_fma_f32 v[212:213], v[210:211], v[210:211], v[206:207] op_sel_hi:[0,1,1] neg_lo:[0,0,1]
	v_pk_mul_f32 v[206:207], v[210:211], v[212:213] op_sel:[1,1] op_sel_hi:[1,0]
	v_pk_fma_f32 v[220:221], v[210:211], v[212:213], v[206:207] op_sel_hi:[0,1,1] neg_lo:[0,0,1]
	v_pk_mul_f32 v[42:43], v[210:211], v[202:203] op_sel:[1,1] op_sel_hi:[1,0]
	v_pk_fma_f32 v[42:43], v[210:211], v[202:203], v[42:43] op_sel_hi:[0,1,1] neg_lo:[0,0,1]
	v_pk_mul_f32 v[44:45], v[212:213], v[48:49] op_sel:[1,1] op_sel_hi:[1,0]
	v_pk_fma_f32 v[44:45], v[212:213], v[48:49], v[44:45] op_sel_hi:[0,1,1] neg_lo:[0,0,1]
	v_pk_mul_f32 v[48:49], v[220:221], v[204:205] op_sel:[1,1] op_sel_hi:[1,0]
	v_pk_fma_f32 v[48:49], v[220:221], v[204:205], v[48:49] op_sel_hi:[0,1,1] neg_lo:[0,0,1]
	v_add_f32_e32 v214, 0x3e400000, v201
	v_cos_f32_e32 v210, v214
	v_sin_f32_e64 v211, -v214
	s_waitcnt lgkmcnt(2)
	v_pk_add_f32 v[202:203], v[50:51], v[54:55]
	v_pk_add_f32 v[50:51], v[50:51], v[54:55] neg_lo:[0,1] neg_hi:[0,1]
	v_pk_add_f32 v[204:205], v[52:53], v[56:57]
	v_pk_add_f32 v[52:53], v[52:53], v[56:57] neg_lo:[0,1] neg_hi:[0,1]
	v_pk_add_f32 v[54:55], v[202:203], v[204:205]
	v_pk_add_f32 v[56:57], v[202:203], v[204:205] neg_lo:[0,1] neg_hi:[0,1]
	v_pk_add_f32 v[202:203], v[50:51], v[52:53] op_sel:[0,1] op_sel_hi:[1,0] neg_hi:[0,1]
	v_pk_add_f32 v[204:205], v[50:51], v[52:53] op_sel:[0,1] op_sel_hi:[1,0] neg_lo:[0,1]
	v_pk_mul_f32 v[206:207], v[210:211], v[210:211] op_sel:[1,1] op_sel_hi:[1,0]
	v_pk_fma_f32 v[212:213], v[210:211], v[210:211], v[206:207] op_sel_hi:[0,1,1] neg_lo:[0,0,1]
	v_pk_mul_f32 v[206:207], v[210:211], v[212:213] op_sel:[1,1] op_sel_hi:[1,0]
	v_pk_fma_f32 v[220:221], v[210:211], v[212:213], v[206:207] op_sel_hi:[0,1,1] neg_lo:[0,0,1]
	v_pk_mul_f32 v[50:51], v[210:211], v[202:203] op_sel:[1,1] op_sel_hi:[1,0]
	v_pk_fma_f32 v[50:51], v[210:211], v[202:203], v[50:51] op_sel_hi:[0,1,1] neg_lo:[0,0,1]
	v_pk_mul_f32 v[52:53], v[212:213], v[56:57] op_sel:[1,1] op_sel_hi:[1,0]
	v_pk_fma_f32 v[52:53], v[212:213], v[56:57], v[52:53] op_sel_hi:[0,1,1] neg_lo:[0,0,1]
	v_pk_mul_f32 v[56:57], v[220:221], v[204:205] op_sel:[1,1] op_sel_hi:[1,0]
	v_pk_fma_f32 v[56:57], v[220:221], v[204:205], v[56:57] op_sel_hi:[0,1,1] neg_lo:[0,0,1]
	v_add_f32_e32 v214, 0x3e600000, v201
	v_cos_f32_e32 v210, v214
	v_sin_f32_e64 v211, -v214
	s_waitcnt lgkmcnt(0)
; DI f32x2 cmul(f32x2 a, f32x2 b) { return mkf2(a.x * b.x - a.y * b.y, a.x * b.y + a.y * b.x); }
; DI void fft8192(f32x2* buf, const f32x2* __restrict__ tw) {
;     ...
; #pragma unroll 2
;   for (int ls = 0; ls < 12; ls += 2) {
;     const int s = 1 << ls;
;     f32x2 a[8], b[8], c[8], d[8];
;     __syncthreads();
; #pragma unroll
;     for (int e = 0; e < 8; ++e) {
;       const int i = tid + 256 * e;
;       const int pi = SW(i);
;       a[e] = buf[pi]; b[e] = buf[pi + 2048]; c[e] = buf[pi + 4096]; d[e] = buf[pi + 6144];
;     }
;     __syncthreads();
; #pragma unroll
;     for (int e = 0; e < 8; ++e) {
;       const int i = tid + 256 * e;
;       const int q = i & (s - 1);
;       const int ps = i - q;
;       const float rev = (float)ps * (1.f / 8192.f);
;       const f32x2 w1 = mkf2(__builtin_amdgcn_cosf(rev), -__builtin_amdgcn_sinf(rev));
;       const f32x2 w2 = cmul(w1, w1), w3 = cmul(w1, w2);
;       const f32x2 apc = mkf2(a[e].x + c[e].x, a[e].y + c[e].y), amc = mkf2(a[e].x - c[e].x, a[e].y - c[e].y);
;       const f32x2 bpd = mkf2(b[e].x + d[e].x, b[e].y + d[e].y), bmd = mkf2(b[e].x - d[e].x, b[e].y - d[e].y);
;       const int o = 4 * i - 3 * q;
;       buf[SW(o)] = mkf2(apc.x + bpd.x, apc.y + bpd.y);
;       buf[SW(o + s)] = cmul(w1, mkf2(amc.x + bmd.y, amc.y - bmd.x));
;       buf[SW(o + 2 * s)] = cmul(w2, mkf2(apc.x - bpd.x, apc.y - bpd.y));
;       buf[SW(o + 3 * s)] = cmul(w3, mkf2(amc.x - bmd.y, amc.y + bmd.x));
;     }
	v_pk_add_f32 v[202:203], v[58:59], v[62:63]
	v_pk_add_f32 v[58:59], v[58:59], v[62:63] neg_lo:[0,1] neg_hi:[0,1]
	v_pk_add_f32 v[204:205], v[60:61], v[64:65]
	v_pk_add_f32 v[60:61], v[60:61], v[64:65] neg_lo:[0,1] neg_hi:[0,1]
	v_pk_add_f32 v[62:63], v[202:203], v[204:205]
	v_pk_add_f32 v[64:65], v[202:203], v[204:205] neg_lo:[0,1] neg_hi:[0,1]
	v_pk_add_f32 v[202:203], v[58:59], v[60:61] op_sel:[0,1] op_sel_hi:[1,0] neg_hi:[0,1]
	v_pk_add_f32 v[204:205], v[58:59], v[60:61] op_sel:[0,1] op_sel_hi:[1,0] neg_lo:[0,1]
	v_pk_mul_f32 v[206:207], v[210:211], v[210:211] op_sel:[1,1] op_sel_hi:[1,0]
	v_pk_fma_f32 v[212:213], v[210:211], v[210:211], v[206:207] op_sel_hi:[0,1,1] neg_lo:[0,0,1]
	v_pk_mul_f32 v[206:207], v[210:211], v[212:213] op_sel:[1,1] op_sel_hi:[1,0]
	v_pk_fma_f32 v[220:221], v[210:211], v[212:213], v[206:207] op_sel_hi:[0,1,1] neg_lo:[0,0,1]
	v_pk_mul_f32 v[58:59], v[210:211], v[202:203] op_sel:[1,1] op_sel_hi:[1,0]
	v_pk_fma_f32 v[58:59], v[210:211], v[202:203], v[58:59] op_sel_hi:[0,1,1] neg_lo:[0,0,1]
	v_pk_mul_f32 v[60:61], v[212:213], v[64:65] op_sel:[1,1] op_sel_hi:[1,0]
	v_pk_fma_f32 v[60:61], v[212:213], v[64:65], v[60:61] op_sel_hi:[0,1,1] neg_lo:[0,0,1]
	v_pk_mul_f32 v[64:65], v[220:221], v[204:205] op_sel:[1,1] op_sel_hi:[1,0]
	v_pk_fma_f32 v[64:65], v[220:221], v[204:205], v[64:65] op_sel_hi:[0,1,1] neg_lo:[0,0,1]
	s_barrier
	ds_write_b64 v156, v[6:7] offset:0
	ds_write_b64 v158, v[2:3] offset:0
	ds_write_b64 v160, v[4:5] offset:0
	ds_write_b64 v162, v[8:9] offset:0
	ds_write_b64 v156, v[14:15] offset:8192
	ds_write_b64 v158, v[10:11] offset:8192
	ds_write_b64 v160, v[12:13] offset:8192
	ds_write_b64 v162, v[16:17] offset:8192
	ds_write_b64 v156, v[22:23] offset:16384
	ds_write_b64 v158, v[18:19] offset:16384
	ds_write_b64 v160, v[20:21] offset:16384
	ds_write_b64 v162, v[24:25] offset:16384
	ds_write_b64 v156, v[30:31] offset:24576
	ds_write_b64 v158, v[26:27] offset:24576
	ds_write_b64 v160, v[28:29] offset:24576
	ds_write_b64 v162, v[32:33] offset:24576
	ds_write_b64 v156, v[38:39] offset:32768
	ds_write_b64 v158, v[34:35] offset:32768
	ds_write_b64 v160, v[36:37] offset:32768
	ds_write_b64 v162, v[40:41] offset:32768
	ds_write_b64 v156, v[46:47] offset:40960
	ds_write_b64 v158, v[42:43] offset:40960
	ds_write_b64 v160, v[44:45] offset:40960
	ds_write_b64 v162, v[48:49] offset:40960
	ds_write_b64 v156, v[54:55] offset:49152
	ds_write_b64 v158, v[50:51] offset:49152
	ds_write_b64 v160, v[52:53] offset:49152
	ds_write_b64 v162, v[56:57] offset:49152
	ds_write_b64 v156, v[62:63] offset:57344
	ds_write_b64 v158, v[58:59] offset:57344
	ds_write_b64 v160, v[60:61] offset:57344
	ds_write_b64 v162, v[64:65] offset:57344
	s_waitcnt lgkmcnt(0)
	s_barrier
	ds_read2st64_b64 v[2:5], v154 offset0:0 offset1:32
	ds_read2st64_b64 v[6:9], v154 offset0:64 offset1:96
	ds_read2st64_b64 v[10:13], v154 offset0:4 offset1:36
	ds_read2st64_b64 v[14:17], v154 offset0:68 offset1:100
	ds_read2st64_b64 v[18:21], v154 offset0:8 offset1:40
	ds_read2st64_b64 v[22:25], v154 offset0:72 offset1:104
	ds_read2st64_b64 v[26:29], v154 offset0:12 offset1:44
	ds_read2st64_b64 v[30:33], v154 offset0:76 offset1:108
	ds_read2st64_b64 v[34:37], v154 offset0:16 offset1:48
	ds_read2st64_b64 v[38:41], v154 offset0:80 offset1:112
	ds_read2st64_b64 v[42:45], v154 offset0:20 offset1:52
	ds_read2st64_b64 v[46:49], v154 offset0:84 offset1:116
	ds_read2st64_b64 v[50:53], v154 offset0:24 offset1:56
	ds_read2st64_b64 v[54:57], v154 offset0:88 offset1:120
	ds_read2st64_b64 v[58:61], v154 offset0:28 offset1:60
	ds_read2st64_b64 v[62:65], v154 offset0:92 offset1:124
	v_and_b32_e32 v166, 63, v0
	v_lshlrev_b32_e32 v164, 2, v0
	v_mad_i32_i24 v164, v166, -3, v164
	v_sub_u32_e32 v166, v0, v166
	v_cvt_f32_u32_e32 v201, v166
	v_mul_f32_e32 v201, 0x39000000, v201
	v_bfe_i32 v166, v164, 5, 1
	v_bfe_i32 v168, v164, 6, 1
	v_and_b32_e32 v166, 5, v166
	v_and_b32_e32 v168, 26, v168
	v_xor_b32_e32 v166, v166, v168
	v_xor_b32_e32 v166, v166, v164
	v_lshlrev_b32_e32 v156, 3, v166
	v_xor_b32_e32 v158, 0x2d0, v156
	v_xor_b32_e32 v160, 0x400, v156
	v_xor_b32_e32 v162, 0x6d0, v156
	v_cos_f32_e32 v210, v201
	v_sin_f32_e64 v211, -v201
	s_waitcnt lgkmcnt(14)
	v_pk_add_f32 v[202:203], v[2:3], v[6:7]
	v_pk_add_f32 v[2:3], v[2:3], v[6:7] neg_lo:[0,1] neg_hi:[0,1]
	v_pk_add_f32 v[204:205], v[4:5], v[8:9]
	v_pk_add_f32 v[4:5], v[4:5], v[8:9] neg_lo:[0,1] neg_hi:[0,1]
	v_pk_add_f32 v[6:7], v[202:203], v[204:205]
	v_pk_add_f32 v[8:9], v[202:203], v[204:205] neg_lo:[0,1] neg_hi:[0,1]
	v_pk_add_f32 v[202:203], v[2:3], v[4:5] op_sel:[0,1] op_sel_hi:[1,0] neg_hi:[0,1]
	v_pk_add_f32 v[204:205], v[2:3], v[4:5] op_sel:[0,1] op_sel_hi:[1,0] neg_lo:[0,1]
	v_pk_mul_f32 v[206:207], v[210:211], v[210:211] op_sel:[1,1] op_sel_hi:[1,0]
	v_pk_fma_f32 v[212:213], v[210:211], v[210:211], v[206:207] op_sel_hi:[0,1,1] neg_lo:[0,0,1]
	v_pk_mul_f32 v[206:207], v[210:211], v[212:213] op_sel:[1,1] op_sel_hi:[1,0]
	v_pk_fma_f32 v[220:221], v[210:211], v[212:213], v[206:207] op_sel_hi:[0,1,1] neg_lo:[0,0,1]
	v_pk_mul_f32 v[2:3], v[210:211], v[202:203] op_sel:[1,1] op_sel_hi:[1,0]
	v_pk_fma_f32 v[2:3], v[210:211], v[202:203], v[2:3] op_sel_hi:[0,1,1] neg_lo:[0,0,1]
	v_pk_mul_f32 v[4:5], v[212:213], v[8:9] op_sel:[1,1] op_sel_hi:[1,0]
	v_pk_fma_f32 v[4:5], v[212:213], v[8:9], v[4:5] op_sel_hi:[0,1,1] neg_lo:[0,0,1]
	v_pk_mul_f32 v[8:9], v[220:221], v[204:205] op_sel:[1,1] op_sel_hi:[1,0]
	v_pk_fma_f32 v[8:9], v[220:221], v[204:205], v[8:9] op_sel_hi:[0,1,1] neg_lo:[0,0,1]
	v_add_f32_e32 v214, 0x3d000000, v201
	v_cos_f32_e32 v210, v214
	v_sin_f32_e64 v211, -v214
	s_waitcnt lgkmcnt(12)
; DI f32x2 cmul(f32x2 a, f32x2 b) { return mkf2(a.x * b.x - a.y * b.y, a.x * b.y + a.y * b.x); }
; DI void fft8192(f32x2* buf, const f32x2* __restrict__ tw) {
;     ...
; #pragma unroll
;     for (int e = 0; e < 8; ++e) {
;       const int i = tid + 256 * e;
;       const int q = i & (s - 1);
;       const int ps = i - q;
;       const float rev = (float)ps * (1.f / 8192.f);
;       const f32x2 w1 = mkf2(__builtin_amdgcn_cosf(rev), -__builtin_amdgcn_sinf(rev));
;       const f32x2 w2 = cmul(w1, w1), w3 = cmul(w1, w2);
;       const f32x2 apc = mkf2(a[e].x + c[e].x, a[e].y + c[e].y), amc = mkf2(a[e].x - c[e].x, a[e].y - c[e].y);
;       const f32x2 bpd = mkf2(b[e].x + d[e].x, b[e].y + d[e].y), bmd = mkf2(b[e].x - d[e].x, b[e].y - d[e].y);
;       const int o = 4 * i - 3 * q;
;       buf[SW(o)] = mkf2(apc.x + bpd.x, apc.y + bpd.y);
;       buf[SW(o + s)] = cmul(w1, mkf2(amc.x + bmd.y, amc.y - bmd.x));
;       buf[SW(o + 2 * s)] = cmul(w2, mkf2(apc.x - bpd.x, apc.y - bpd.y));
;       buf[SW(o + 3 * s)] = cmul(w3, mkf2(amc.x - bmd.y, amc.y + bmd.x));
;     }
	v_pk_add_f32 v[202:203], v[10:11], v[14:15]
	v_pk_add_f32 v[10:11], v[10:11], v[14:15] neg_lo:[0,1] neg_hi:[0,1]
	v_pk_add_f32 v[204:205], v[12:13], v[16:17]
	v_pk_add_f32 v[12:13], v[12:13], v[16:17] neg_lo:[0,1] neg_hi:[0,1]
	v_pk_add_f32 v[14:15], v[202:203], v[204:205]
	v_pk_add_f32 v[16:17], v[202:203], v[204:205] neg_lo:[0,1] neg_hi:[0,1]
	v_pk_add_f32 v[202:203], v[10:11], v[12:13] op_sel:[0,1] op_sel_hi:[1,0] neg_hi:[0,1]
	v_pk_add_f32 v[204:205], v[10:11], v[12:13] op_sel:[0,1] op_sel_hi:[1,0] neg_lo:[0,1]
	v_pk_mul_f32 v[206:207], v[210:211], v[210:211] op_sel:[1,1] op_sel_hi:[1,0]
	v_pk_fma_f32 v[212:213], v[210:211], v[210:211], v[206:207] op_sel_hi:[0,1,1] neg_lo:[0,0,1]
	v_pk_mul_f32 v[206:207], v[210:211], v[212:213] op_sel:[1,1] op_sel_hi:[1,0]
	v_pk_fma_f32 v[220:221], v[210:211], v[212:213], v[206:207] op_sel_hi:[0,1,1] neg_lo:[0,0,1]
	v_pk_mul_f32 v[10:11], v[210:211], v[202:203] op_sel:[1,1] op_sel_hi:[1,0]
	v_pk_fma_f32 v[10:11], v[210:211], v[202:203], v[10:11] op_sel_hi:[0,1,1] neg_lo:[0,0,1]
	v_pk_mul_f32 v[12:13], v[212:213], v[16:17] op_sel:[1,1] op_sel_hi:[1,0]
	v_pk_fma_f32 v[12:13], v[212:213], v[16:17], v[12:13] op_sel_hi:[0,1,1] neg_lo:[0,0,1]
	v_pk_mul_f32 v[16:17], v[220:221], v[204:205] op_sel:[1,1] op_sel_hi:[1,0]
	v_pk_fma_f32 v[16:17], v[220:221], v[204:205], v[16:17] op_sel_hi:[0,1,1] neg_lo:[0,0,1]
	v_add_f32_e32 v214, 0x3d800000, v201
	v_cos_f32_e32 v210, v214
	v_sin_f32_e64 v211, -v214
	s_waitcnt lgkmcnt(10)
	v_pk_add_f32 v[202:203], v[18:19], v[22:23]
	v_pk_add_f32 v[18:19], v[18:19], v[22:23] neg_lo:[0,1] neg_hi:[0,1]
	v_pk_add_f32 v[204:205], v[20:21], v[24:25]
	v_pk_add_f32 v[20:21], v[20:21], v[24:25] neg_lo:[0,1] neg_hi:[0,1]
	v_pk_add_f32 v[22:23], v[202:203], v[204:205]
	v_pk_add_f32 v[24:25], v[202:203], v[204:205] neg_lo:[0,1] neg_hi:[0,1]
	v_pk_add_f32 v[202:203], v[18:19], v[20:21] op_sel:[0,1] op_sel_hi:[1,0] neg_hi:[0,1]
	v_pk_add_f32 v[204:205], v[18:19], v[20:21] op_sel:[0,1] op_sel_hi:[1,0] neg_lo:[0,1]
	v_pk_mul_f32 v[206:207], v[210:211], v[210:211] op_sel:[1,1] op_sel_hi:[1,0]
	v_pk_fma_f32 v[212:213], v[210:211], v[210:211], v[206:207] op_sel_hi:[0,1,1] neg_lo:[0,0,1]
	v_pk_mul_f32 v[206:207], v[210:211], v[212:213] op_sel:[1,1] op_sel_hi:[1,0]
	v_pk_fma_f32 v[220:221], v[210:211], v[212:213], v[206:207] op_sel_hi:[0,1,1] neg_lo:[0,0,1]
	v_pk_mul_f32 v[18:19], v[210:211], v[202:203] op_sel:[1,1] op_sel_hi:[1,0]
	v_pk_fma_f32 v[18:19], v[210:211], v[202:203], v[18:19] op_sel_hi:[0,1,1] neg_lo:[0,0,1]
	v_pk_mul_f32 v[20:21], v[212:213], v[24:25] op_sel:[1,1] op_sel_hi:[1,0]
	v_pk_fma_f32 v[20:21], v[212:213], v[24:25], v[20:21] op_sel_hi:[0,1,1] neg_lo:[0,0,1]
	v_pk_mul_f32 v[24:25], v[220:221], v[204:205] op_sel:[1,1] op_sel_hi:[1,0]
	v_pk_fma_f32 v[24:25], v[220:221], v[204:205], v[24:25] op_sel_hi:[0,1,1] neg_lo:[0,0,1]
	v_add_f32_e32 v214, 0x3dc00000, v201
	v_cos_f32_e32 v210, v214
	v_sin_f32_e64 v211, -v214
	s_waitcnt lgkmcnt(8)
	v_pk_add_f32 v[202:203], v[26:27], v[30:31]
	v_pk_add_f32 v[26:27], v[26:27], v[30:31] neg_lo:[0,1] neg_hi:[0,1]
	v_pk_add_f32 v[204:205], v[28:29], v[32:33]
	v_pk_add_f32 v[28:29], v[28:29], v[32:33] neg_lo:[0,1] neg_hi:[0,1]
	v_pk_add_f32 v[30:31], v[202:203], v[204:205]
	v_pk_add_f32 v[32:33], v[202:203], v[204:205] neg_lo:[0,1] neg_hi:[0,1]
	v_pk_add_f32 v[202:203], v[26:27], v[28:29] op_sel:[0,1] op_sel_hi:[1,0] neg_hi:[0,1]
	v_pk_add_f32 v[204:205], v[26:27], v[28:29] op_sel:[0,1] op_sel_hi:[1,0] neg_lo:[0,1]
	v_pk_mul_f32 v[206:207], v[210:211], v[210:211] op_sel:[1,1] op_sel_hi:[1,0]
	v_pk_fma_f32 v[212:213], v[210:211], v[210:211], v[206:207] op_sel_hi:[0,1,1] neg_lo:[0,0,1]
	v_pk_mul_f32 v[206:207], v[210:211], v[212:213] op_sel:[1,1] op_sel_hi:[1,0]
	v_pk_fma_f32 v[220:221], v[210:211], v[212:213], v[206:207] op_sel_hi:[0,1,1] neg_lo:[0,0,1]
	v_pk_mul_f32 v[26:27], v[210:211], v[202:203] op_sel:[1,1] op_sel_hi:[1,0]
	v_pk_fma_f32 v[26:27], v[210:211], v[202:203], v[26:27] op_sel_hi:[0,1,1] neg_lo:[0,0,1]
	v_pk_mul_f32 v[28:29], v[212:213], v[32:33] op_sel:[1,1] op_sel_hi:[1,0]
	v_pk_fma_f32 v[28:29], v[212:213], v[32:33], v[28:29] op_sel_hi:[0,1,1] neg_lo:[0,0,1]
	v_pk_mul_f32 v[32:33], v[220:221], v[204:205] op_sel:[1,1] op_sel_hi:[1,0]
	v_pk_fma_f32 v[32:33], v[220:221], v[204:205], v[32:33] op_sel_hi:[0,1,1] neg_lo:[0,0,1]
	v_add_f32_e32 v214, 0x3e000000, v201
	v_cos_f32_e32 v210, v214
	v_sin_f32_e64 v211, -v214
	s_waitcnt lgkmcnt(6)
	v_pk_add_f32 v[202:203], v[34:35], v[38:39]
	v_pk_add_f32 v[34:35], v[34:35], v[38:39] neg_lo:[0,1] neg_hi:[0,1]
	v_pk_add_f32 v[204:205], v[36:37], v[40:41]
	v_pk_add_f32 v[36:37], v[36:37], v[40:41] neg_lo:[0,1] neg_hi:[0,1]
	v_pk_add_f32 v[38:39], v[202:203], v[204:205]
	v_pk_add_f32 v[40:41], v[202:203], v[204:205] neg_lo:[0,1] neg_hi:[0,1]
	v_pk_add_f32 v[202:203], v[34:35], v[36:37] op_sel:[0,1] op_sel_hi:[1,0] neg_hi:[0,1]
	v_pk_add_f32 v[204:205], v[34:35], v[36:37] op_sel:[0,1] op_sel_hi:[1,0] neg_lo:[0,1]
	v_pk_mul_f32 v[206:207], v[210:211], v[210:211] op_sel:[1,1] op_sel_hi:[1,0]
	v_pk_fma_f32 v[212:213], v[210:211], v[210:211], v[206:207] op_sel_hi:[0,1,1] neg_lo:[0,0,1]
	v_pk_mul_f32 v[206:207], v[210:211], v[212:213] op_sel:[1,1] op_sel_hi:[1,0]
	v_pk_fma_f32 v[220:221], v[210:211], v[212:213], v[206:207] op_sel_hi:[0,1,1] neg_lo:[0,0,1]
	v_pk_mul_f32 v[34:35], v[210:211], v[202:203] op_sel:[1,1] op_sel_hi:[1,0]
	v_pk_fma_f32 v[34:35], v[210:211], v[202:203], v[34:35] op_sel_hi:[0,1,1] neg_lo:[0,0,1]
	v_pk_mul_f32 v[36:37], v[212:213], v[40:41] op_sel:[1,1] op_sel_hi:[1,0]
	v_pk_fma_f32 v[36:37], v[212:213], v[40:41], v[36:37] op_sel_hi:[0,1,1] neg_lo:[0,0,1]
	v_pk_mul_f32 v[40:41], v[220:221], v[204:205] op_sel:[1,1] op_sel_hi:[1,0]
	v_pk_fma_f32 v[40:41], v[220:221], v[204:205], v[40:41] op_sel_hi:[0,1,1] neg_lo:[0,0,1]
	v_add_f32_e32 v214, 0x3e200000, v201
	v_cos_f32_e32 v210, v214
	v_sin_f32_e64 v211, -v214
	s_waitcnt lgkmcnt(4)
; DI f32x2 cmul(f32x2 a, f32x2 b) { return mkf2(a.x * b.x - a.y * b.y, a.x * b.y + a.y * b.x); }
; DI void fft8192(f32x2* buf, const f32x2* __restrict__ tw) {
;     ...
; #pragma unroll
;     for (int e = 0; e < 8; ++e) {
;       const int i = tid + 256 * e;
;       const int q = i & (s - 1);
;       const int ps = i - q;
;       const float rev = (float)ps * (1.f / 8192.f);
;       const f32x2 w1 = mkf2(__builtin_amdgcn_cosf(rev), -__builtin_amdgcn_sinf(rev));
;       const f32x2 w2 = cmul(w1, w1), w3 = cmul(w1, w2);
;       const f32x2 apc = mkf2(a[e].x + c[e].x, a[e].y + c[e].y), amc = mkf2(a[e].x - c[e].x, a[e].y - c[e].y);
;       const f32x2 bpd = mkf2(b[e].x + d[e].x, b[e].y + d[e].y), bmd = mkf2(b[e].x - d[e].x, b[e].y - d[e].y);
;       const int o = 4 * i - 3 * q;
;       buf[SW(o)] = mkf2(apc.x + bpd.x, apc.y + bpd.y);
;       buf[SW(o + s)] = cmul(w1, mkf2(amc.x + bmd.y, amc.y - bmd.x));
;       buf[SW(o + 2 * s)] = cmul(w2, mkf2(apc.x - bpd.x, apc.y - bpd.y));
;       buf[SW(o + 3 * s)] = cmul(w3, mkf2(amc.x - bmd.y, amc.y + bmd.x));
;     }
	v_pk_add_f32 v[202:203], v[42:43], v[46:47]
	v_pk_add_f32 v[42:43], v[42:43], v[46:47] neg_lo:[0,1] neg_hi:[0,1]
	v_pk_add_f32 v[204:205], v[44:45], v[48:49]
	v_pk_add_f32 v[44:45], v[44:45], v[48:49] neg_lo:[0,1] neg_hi:[0,1]
	v_pk_add_f32 v[46:47], v[202:203], v[204:205]
	v_pk_add_f32 v[48:49], v[202:203], v[204:205] neg_lo:[0,1] neg_hi:[0,1]
	v_pk_add_f32 v[202:203], v[42:43], v[44:45] op_sel:[0,1] op_sel_hi:[1,0] neg_hi:[0,1]
	v_pk_add_f32 v[204:205], v[42:43], v[44:45] op_sel:[0,1] op_sel_hi:[1,0] neg_lo:[0,1]
	v_pk_mul_f32 v[206:207], v[210:211], v[210:211] op_sel:[1,1] op_sel_hi:[1,0]
	v_pk_fma_f32 v[212:213], v[210:211], v[210:211], v[206:207] op_sel_hi:[0,1,1] neg_lo:[0,0,1]
	v_pk_mul_f32 v[206:207], v[210:211], v[212:213] op_sel:[1,1] op_sel_hi:[1,0]
	v_pk_fma_f32 v[220:221], v[210:211], v[212:213], v[206:207] op_sel_hi:[0,1,1] neg_lo:[0,0,1]
	v_pk_mul_f32 v[42:43], v[210:211], v[202:203] op_sel:[1,1] op_sel_hi:[1,0]
	v_pk_fma_f32 v[42:43], v[210:211], v[202:203], v[42:43] op_sel_hi:[0,1,1] neg_lo:[0,0,1]
	v_pk_mul_f32 v[44:45], v[212:213], v[48:49] op_sel:[1,1] op_sel_hi:[1,0]
	v_pk_fma_f32 v[44:45], v[212:213], v[48:49], v[44:45] op_sel_hi:[0,1,1] neg_lo:[0,0,1]
	v_pk_mul_f32 v[48:49], v[220:221], v[204:205] op_sel:[1,1] op_sel_hi:[1,0]
	v_pk_fma_f32 v[48:49], v[220:221], v[204:205], v[48:49] op_sel_hi:[0,1,1] neg_lo:[0,0,1]
	v_add_f32_e32 v214, 0x3e400000, v201
	v_cos_f32_e32 v210, v214
	v_sin_f32_e64 v211, -v214
	s_waitcnt lgkmcnt(2)
	v_pk_add_f32 v[202:203], v[50:51], v[54:55]
	v_pk_add_f32 v[50:51], v[50:51], v[54:55] neg_lo:[0,1] neg_hi:[0,1]
	v_pk_add_f32 v[204:205], v[52:53], v[56:57]
	v_pk_add_f32 v[52:53], v[52:53], v[56:57] neg_lo:[0,1] neg_hi:[0,1]
	v_pk_add_f32 v[54:55], v[202:203], v[204:205]
	v_pk_add_f32 v[56:57], v[202:203], v[204:205] neg_lo:[0,1] neg_hi:[0,1]
	v_pk_add_f32 v[202:203], v[50:51], v[52:53] op_sel:[0,1] op_sel_hi:[1,0] neg_hi:[0,1]
	v_pk_add_f32 v[204:205], v[50:51], v[52:53] op_sel:[0,1] op_sel_hi:[1,0] neg_lo:[0,1]
	v_pk_mul_f32 v[206:207], v[210:211], v[210:211] op_sel:[1,1] op_sel_hi:[1,0]
	v_pk_fma_f32 v[212:213], v[210:211], v[210:211], v[206:207] op_sel_hi:[0,1,1] neg_lo:[0,0,1]
	v_pk_mul_f32 v[206:207], v[210:211], v[212:213] op_sel:[1,1] op_sel_hi:[1,0]
	v_pk_fma_f32 v[220:221], v[210:211], v[212:213], v[206:207] op_sel_hi:[0,1,1] neg_lo:[0,0,1]
	v_pk_mul_f32 v[50:51], v[210:211], v[202:203] op_sel:[1,1] op_sel_hi:[1,0]
	v_pk_fma_f32 v[50:51], v[210:211], v[202:203], v[50:51] op_sel_hi:[0,1,1] neg_lo:[0,0,1]
	v_pk_mul_f32 v[52:53], v[212:213], v[56:57] op_sel:[1,1] op_sel_hi:[1,0]
	v_pk_fma_f32 v[52:53], v[212:213], v[56:57], v[52:53] op_sel_hi:[0,1,1] neg_lo:[0,0,1]
	v_pk_mul_f32 v[56:57], v[220:221], v[204:205] op_sel:[1,1] op_sel_hi:[1,0]
	v_pk_fma_f32 v[56:57], v[220:221], v[204:205], v[56:57] op_sel_hi:[0,1,1] neg_lo:[0,0,1]
	v_add_f32_e32 v214, 0x3e600000, v201
	v_cos_f32_e32 v210, v214
	v_sin_f32_e64 v211, -v214
	s_waitcnt lgkmcnt(0)
	v_pk_add_f32 v[202:203], v[58:59], v[62:63]
	v_pk_add_f32 v[58:59], v[58:59], v[62:63] neg_lo:[0,1] neg_hi:[0,1]
	v_pk_add_f32 v[204:205], v[60:61], v[64:65]
	v_pk_add_f32 v[60:61], v[60:61], v[64:65] neg_lo:[0,1] neg_hi:[0,1]
	v_pk_add_f32 v[62:63], v[202:203], v[204:205]
	v_pk_add_f32 v[64:65], v[202:203], v[204:205] neg_lo:[0,1] neg_hi:[0,1]
	v_pk_add_f32 v[202:203], v[58:59], v[60:61] op_sel:[0,1] op_sel_hi:[1,0] neg_hi:[0,1]
	v_pk_add_f32 v[204:205], v[58:59], v[60:61] op_sel:[0,1] op_sel_hi:[1,0] neg_lo:[0,1]
	v_pk_mul_f32 v[206:207], v[210:211], v[210:211] op_sel:[1,1] op_sel_hi:[1,0]
	v_pk_fma_f32 v[212:213], v[210:211], v[210:211], v[206:207] op_sel_hi:[0,1,1] neg_lo:[0,0,1]
	v_pk_mul_f32 v[206:207], v[210:211], v[212:213] op_sel:[1,1] op_sel_hi:[1,0]
	v_pk_fma_f32 v[220:221], v[210:211], v[212:213], v[206:207] op_sel_hi:[0,1,1] neg_lo:[0,0,1]
	v_pk_mul_f32 v[58:59], v[210:211], v[202:203] op_sel:[1,1] op_sel_hi:[1,0]
	v_pk_fma_f32 v[58:59], v[210:211], v[202:203], v[58:59] op_sel_hi:[0,1,1] neg_lo:[0,0,1]
	v_pk_mul_f32 v[60:61], v[212:213], v[64:65] op_sel:[1,1] op_sel_hi:[1,0]
	v_pk_fma_f32 v[60:61], v[212:213], v[64:65], v[60:61] op_sel_hi:[0,1,1] neg_lo:[0,0,1]
	v_pk_mul_f32 v[64:65], v[220:221], v[204:205] op_sel:[1,1] op_sel_hi:[1,0]
	v_pk_fma_f32 v[64:65], v[220:221], v[204:205], v[64:65] op_sel_hi:[0,1,1] neg_lo:[0,0,1]
	s_barrier
	ds_write_b64 v156, v[6:7] offset:0
	ds_write_b64 v158, v[2:3] offset:0
	ds_write_b64 v160, v[4:5] offset:0
	ds_write_b64 v162, v[8:9] offset:0
	ds_write_b64 v156, v[14:15] offset:8192
	ds_write_b64 v158, v[10:11] offset:8192
	ds_write_b64 v160, v[12:13] offset:8192
	ds_write_b64 v162, v[16:17] offset:8192
	ds_write_b64 v156, v[22:23] offset:16384
	ds_write_b64 v158, v[18:19] offset:16384
	ds_write_b64 v160, v[20:21] offset:16384
	ds_write_b64 v162, v[24:25] offset:16384
	ds_write_b64 v156, v[30:31] offset:24576
	ds_write_b64 v158, v[26:27] offset:24576
	ds_write_b64 v160, v[28:29] offset:24576
	ds_write_b64 v162, v[32:33] offset:24576
	ds_write_b64 v156, v[38:39] offset:32768
	ds_write_b64 v158, v[34:35] offset:32768
	ds_write_b64 v160, v[36:37] offset:32768
	ds_write_b64 v162, v[40:41] offset:32768
	ds_write_b64 v156, v[46:47] offset:40960
	ds_write_b64 v158, v[42:43] offset:40960
	ds_write_b64 v160, v[44:45] offset:40960
	ds_write_b64 v162, v[48:49] offset:40960
	ds_write_b64 v156, v[54:55] offset:49152
	ds_write_b64 v158, v[50:51] offset:49152
	ds_write_b64 v160, v[52:53] offset:49152
	ds_write_b64 v162, v[56:57] offset:49152
	ds_write_b64 v156, v[62:63] offset:57344
	ds_write_b64 v158, v[58:59] offset:57344
	ds_write_b64 v160, v[60:61] offset:57344
	ds_write_b64 v162, v[64:65] offset:57344
	s_waitcnt lgkmcnt(0)
	s_barrier
; DI f32x2 cmul(f32x2 a, f32x2 b) { return mkf2(a.x * b.x - a.y * b.y, a.x * b.y + a.y * b.x); }
; DI void fft8192(f32x2* buf, const f32x2* __restrict__ tw) {
;     ...
; #pragma unroll 2
;   for (int ls = 0; ls < 12; ls += 2) {
;     const int s = 1 << ls;
;     f32x2 a[8], b[8], c[8], d[8];
;     __syncthreads();
; #pragma unroll
;     for (int e = 0; e < 8; ++e) {
;       const int i = tid + 256 * e;
;       const int pi = SW(i);
;       a[e] = buf[pi]; b[e] = buf[pi + 2048]; c[e] = buf[pi + 4096]; d[e] = buf[pi + 6144];
;     }
;     __syncthreads();
; #pragma unroll
;     for (int e = 0; e < 8; ++e) {
;       const int i = tid + 256 * e;
;       const int q = i & (s - 1);
;       const int ps = i - q;
;       const float rev = (float)ps * (1.f / 8192.f);
;       const f32x2 w1 = mkf2(__builtin_amdgcn_cosf(rev), -__builtin_amdgcn_sinf(rev));
;       const f32x2 w2 = cmul(w1, w1), w3 = cmul(w1, w2);
;       const f32x2 apc = mkf2(a[e].x + c[e].x, a[e].y + c[e].y), amc = mkf2(a[e].x - c[e].x, a[e].y - c[e].y);
;       const f32x2 bpd = mkf2(b[e].x + d[e].x, b[e].y + d[e].y), bmd = mkf2(b[e].x - d[e].x, b[e].y - d[e].y);
;       const int o = 4 * i - 3 * q;
;       buf[SW(o)] = mkf2(apc.x + bpd.x, apc.y + bpd.y);
;       buf[SW(o + s)] = cmul(w1, mkf2(amc.x + bmd.y, amc.y - bmd.x));
;       buf[SW(o + 2 * s)] = cmul(w2, mkf2(apc.x - bpd.x, apc.y - bpd.y));
;       buf[SW(o + 3 * s)] = cmul(w3, mkf2(amc.x - bmd.y, amc.y + bmd.x));
;     }
	ds_read2st64_b64 v[2:5], v154 offset0:0 offset1:32
	ds_read2st64_b64 v[6:9], v154 offset0:64 offset1:96
	ds_read2st64_b64 v[10:13], v154 offset0:4 offset1:36
	ds_read2st64_b64 v[14:17], v154 offset0:68 offset1:100
	ds_read2st64_b64 v[18:21], v154 offset0:8 offset1:40
	ds_read2st64_b64 v[22:25], v154 offset0:72 offset1:104
	ds_read2st64_b64 v[26:29], v154 offset0:12 offset1:44
	ds_read2st64_b64 v[30:33], v154 offset0:76 offset1:108
	ds_read2st64_b64 v[34:37], v154 offset0:16 offset1:48
	ds_read2st64_b64 v[38:41], v154 offset0:80 offset1:112
	ds_read2st64_b64 v[42:45], v154 offset0:20 offset1:52
	ds_read2st64_b64 v[46:49], v154 offset0:84 offset1:116
	ds_read2st64_b64 v[50:53], v154 offset0:24 offset1:56
	ds_read2st64_b64 v[54:57], v154 offset0:88 offset1:120
	ds_read2st64_b64 v[58:61], v154 offset0:28 offset1:60
	ds_read2st64_b64 v[62:65], v154 offset0:92 offset1:124
	s_waitcnt lgkmcnt(14)
	v_pk_add_f32 v[202:203], v[2:3], v[6:7]
	v_pk_add_f32 v[2:3], v[2:3], v[6:7] neg_lo:[0,1] neg_hi:[0,1]
	v_pk_add_f32 v[204:205], v[4:5], v[8:9]
	v_pk_add_f32 v[4:5], v[4:5], v[8:9] neg_lo:[0,1] neg_hi:[0,1]
	v_pk_add_f32 v[6:7], v[202:203], v[204:205]
	v_pk_add_f32 v[8:9], v[202:203], v[204:205] neg_lo:[0,1] neg_hi:[0,1]
	v_pk_add_f32 v[202:203], v[2:3], v[4:5] op_sel:[0,1] op_sel_hi:[1,0] neg_hi:[0,1]
	v_pk_add_f32 v[4:5], v[2:3], v[4:5] op_sel:[0,1] op_sel_hi:[1,0] neg_lo:[0,1]
	v_pk_mov_b32 v[2:3], v[202:203], v[202:203] op_sel:[0,1]
	v_cos_f32_e32 v210, 0x3d000000
	v_sin_f32_e32 v211, 0xbd000000
	s_waitcnt lgkmcnt(12)
	v_pk_add_f32 v[202:203], v[10:11], v[14:15]
	v_pk_add_f32 v[10:11], v[10:11], v[14:15] neg_lo:[0,1] neg_hi:[0,1]
	v_pk_add_f32 v[204:205], v[12:13], v[16:17]
	v_pk_add_f32 v[12:13], v[12:13], v[16:17] neg_lo:[0,1] neg_hi:[0,1]
	v_pk_add_f32 v[14:15], v[202:203], v[204:205]
	v_pk_add_f32 v[16:17], v[202:203], v[204:205] neg_lo:[0,1] neg_hi:[0,1]
	v_pk_add_f32 v[202:203], v[10:11], v[12:13] op_sel:[0,1] op_sel_hi:[1,0] neg_hi:[0,1]
	v_pk_add_f32 v[204:205], v[10:11], v[12:13] op_sel:[0,1] op_sel_hi:[1,0] neg_lo:[0,1]
	v_pk_mul_f32 v[206:207], v[210:211], v[210:211] op_sel:[1,1] op_sel_hi:[1,0]
	v_pk_fma_f32 v[212:213], v[210:211], v[210:211], v[206:207] op_sel_hi:[0,1,1] neg_lo:[0,0,1]
	v_pk_mul_f32 v[206:207], v[210:211], v[212:213] op_sel:[1,1] op_sel_hi:[1,0]
	v_pk_fma_f32 v[220:221], v[210:211], v[212:213], v[206:207] op_sel_hi:[0,1,1] neg_lo:[0,0,1]
	v_pk_mul_f32 v[10:11], v[210:211], v[202:203] op_sel:[1,1] op_sel_hi:[1,0]
	v_pk_fma_f32 v[10:11], v[210:211], v[202:203], v[10:11] op_sel_hi:[0,1,1] neg_lo:[0,0,1]
	v_pk_mul_f32 v[12:13], v[212:213], v[16:17] op_sel:[1,1] op_sel_hi:[1,0]
	v_pk_fma_f32 v[12:13], v[212:213], v[16:17], v[12:13] op_sel_hi:[0,1,1] neg_lo:[0,0,1]
	v_pk_mul_f32 v[16:17], v[220:221], v[204:205] op_sel:[1,1] op_sel_hi:[1,0]
	v_pk_fma_f32 v[16:17], v[220:221], v[204:205], v[16:17] op_sel_hi:[0,1,1] neg_lo:[0,0,1]
	v_cos_f32_e32 v210, 0x3d800000
	v_sin_f32_e32 v211, 0xbd800000
	s_waitcnt lgkmcnt(10)
	v_pk_add_f32 v[202:203], v[18:19], v[22:23]
	v_pk_add_f32 v[18:19], v[18:19], v[22:23] neg_lo:[0,1] neg_hi:[0,1]
	v_pk_add_f32 v[204:205], v[20:21], v[24:25]
	v_pk_add_f32 v[20:21], v[20:21], v[24:25] neg_lo:[0,1] neg_hi:[0,1]
	v_pk_add_f32 v[22:23], v[202:203], v[204:205]
	v_pk_add_f32 v[24:25], v[202:203], v[204:205] neg_lo:[0,1] neg_hi:[0,1]
	v_pk_add_f32 v[202:203], v[18:19], v[20:21] op_sel:[0,1] op_sel_hi:[1,0] neg_hi:[0,1]
	v_pk_add_f32 v[204:205], v[18:19], v[20:21] op_sel:[0,1] op_sel_hi:[1,0] neg_lo:[0,1]
	v_pk_mul_f32 v[206:207], v[210:211], v[210:211] op_sel:[1,1] op_sel_hi:[1,0]
	v_pk_fma_f32 v[212:213], v[210:211], v[210:211], v[206:207] op_sel_hi:[0,1,1] neg_lo:[0,0,1]
	v_pk_mul_f32 v[206:207], v[210:211], v[212:213] op_sel:[1,1] op_sel_hi:[1,0]
	v_pk_fma_f32 v[220:221], v[210:211], v[212:213], v[206:207] op_sel_hi:[0,1,1] neg_lo:[0,0,1]
	v_pk_mul_f32 v[18:19], v[210:211], v[202:203] op_sel:[1,1] op_sel_hi:[1,0]
	v_pk_fma_f32 v[18:19], v[210:211], v[202:203], v[18:19] op_sel_hi:[0,1,1] neg_lo:[0,0,1]
	v_pk_mul_f32 v[20:21], v[212:213], v[24:25] op_sel:[1,1] op_sel_hi:[1,0]
	v_pk_fma_f32 v[20:21], v[212:213], v[24:25], v[20:21] op_sel_hi:[0,1,1] neg_lo:[0,0,1]
	v_pk_mul_f32 v[24:25], v[220:221], v[204:205] op_sel:[1,1] op_sel_hi:[1,0]
	v_pk_fma_f32 v[24:25], v[220:221], v[204:205], v[24:25] op_sel_hi:[0,1,1] neg_lo:[0,0,1]
	v_cos_f32_e32 v210, 0x3dc00000
	v_sin_f32_e32 v211, 0xbdc00000
	s_waitcnt lgkmcnt(8)
	v_pk_add_f32 v[202:203], v[26:27], v[30:31]
	v_pk_add_f32 v[26:27], v[26:27], v[30:31] neg_lo:[0,1] neg_hi:[0,1]
	v_pk_add_f32 v[204:205], v[28:29], v[32:33]
	v_pk_add_f32 v[28:29], v[28:29], v[32:33] neg_lo:[0,1] neg_hi:[0,1]
	v_pk_add_f32 v[30:31], v[202:203], v[204:205]
	v_pk_add_f32 v[32:33], v[202:203], v[204:205] neg_lo:[0,1] neg_hi:[0,1]
	v_pk_add_f32 v[202:203], v[26:27], v[28:29] op_sel:[0,1] op_sel_hi:[1,0] neg_hi:[0,1]
	v_pk_add_f32 v[204:205], v[26:27], v[28:29] op_sel:[0,1] op_sel_hi:[1,0] neg_lo:[0,1]
	v_pk_mul_f32 v[206:207], v[210:211], v[210:211] op_sel:[1,1] op_sel_hi:[1,0]
	v_pk_fma_f32 v[212:213], v[210:211], v[210:211], v[206:207] op_sel_hi:[0,1,1] neg_lo:[0,0,1]
	v_pk_mul_f32 v[206:207], v[210:211], v[212:213] op_sel:[1,1] op_sel_hi:[1,0]
	v_pk_fma_f32 v[220:221], v[210:211], v[212:213], v[206:207] op_sel_hi:[0,1,1] neg_lo:[0,0,1]
	v_pk_mul_f32 v[26:27], v[210:211], v[202:203] op_sel:[1,1] op_sel_hi:[1,0]
	v_pk_fma_f32 v[26:27], v[210:211], v[202:203], v[26:27] op_sel_hi:[0,1,1] neg_lo:[0,0,1]
	v_pk_mul_f32 v[28:29], v[212:213], v[32:33] op_sel:[1,1] op_sel_hi:[1,0]
	v_pk_fma_f32 v[28:29], v[212:213], v[32:33], v[28:29] op_sel_hi:[0,1,1] neg_lo:[0,0,1]
	v_pk_mul_f32 v[32:33], v[220:221], v[204:205] op_sel:[1,1] op_sel_hi:[1,0]
	v_pk_fma_f32 v[32:33], v[220:221], v[204:205], v[32:33] op_sel_hi:[0,1,1] neg_lo:[0,0,1]
	v_cos_f32_e32 v210, 0x3e000000
	v_sin_f32_e32 v211, 0xbe000000
	s_waitcnt lgkmcnt(6)
; DI f32x2 cmul(f32x2 a, f32x2 b) { return mkf2(a.x * b.x - a.y * b.y, a.x * b.y + a.y * b.x); }
; DI void fft8192(f32x2* buf, const f32x2* __restrict__ tw) {
;     ...
; #pragma unroll
;     for (int e = 0; e < 8; ++e) {
;       const int i = tid + 256 * e;
;       const int q = i & (s - 1);
;       const int ps = i - q;
;       const float rev = (float)ps * (1.f / 8192.f);
;       const f32x2 w1 = mkf2(__builtin_amdgcn_cosf(rev), -__builtin_amdgcn_sinf(rev));
;       const f32x2 w2 = cmul(w1, w1), w3 = cmul(w1, w2);
;       const f32x2 apc = mkf2(a[e].x + c[e].x, a[e].y + c[e].y), amc = mkf2(a[e].x - c[e].x, a[e].y - c[e].y);
;       const f32x2 bpd = mkf2(b[e].x + d[e].x, b[e].y + d[e].y), bmd = mkf2(b[e].x - d[e].x, b[e].y - d[e].y);
;       const int o = 4 * i - 3 * q;
;       buf[SW(o)] = mkf2(apc.x + bpd.x, apc.y + bpd.y);
;       buf[SW(o + s)] = cmul(w1, mkf2(amc.x + bmd.y, amc.y - bmd.x));
;       buf[SW(o + 2 * s)] = cmul(w2, mkf2(apc.x - bpd.x, apc.y - bpd.y));
;       buf[SW(o + 3 * s)] = cmul(w3, mkf2(amc.x - bmd.y, amc.y + bmd.x));
;     }
	v_pk_add_f32 v[202:203], v[34:35], v[38:39]
	v_pk_add_f32 v[34:35], v[34:35], v[38:39] neg_lo:[0,1] neg_hi:[0,1]
	v_pk_add_f32 v[204:205], v[36:37], v[40:41]
	v_pk_add_f32 v[36:37], v[36:37], v[40:41] neg_lo:[0,1] neg_hi:[0,1]
	v_pk_add_f32 v[38:39], v[202:203], v[204:205]
	v_pk_add_f32 v[40:41], v[202:203], v[204:205] neg_lo:[0,1] neg_hi:[0,1]
	v_pk_add_f32 v[202:203], v[34:35], v[36:37] op_sel:[0,1] op_sel_hi:[1,0] neg_hi:[0,1]
	v_pk_add_f32 v[204:205], v[34:35], v[36:37] op_sel:[0,1] op_sel_hi:[1,0] neg_lo:[0,1]
	v_pk_mul_f32 v[206:207], v[210:211], v[210:211] op_sel:[1,1] op_sel_hi:[1,0]
	v_pk_fma_f32 v[212:213], v[210:211], v[210:211], v[206:207] op_sel_hi:[0,1,1] neg_lo:[0,0,1]
	v_pk_mul_f32 v[206:207], v[210:211], v[212:213] op_sel:[1,1] op_sel_hi:[1,0]
	v_pk_fma_f32 v[220:221], v[210:211], v[212:213], v[206:207] op_sel_hi:[0,1,1] neg_lo:[0,0,1]
	v_pk_mul_f32 v[34:35], v[210:211], v[202:203] op_sel:[1,1] op_sel_hi:[1,0]
	v_pk_fma_f32 v[34:35], v[210:211], v[202:203], v[34:35] op_sel_hi:[0,1,1] neg_lo:[0,0,1]
	v_pk_mul_f32 v[36:37], v[212:213], v[40:41] op_sel:[1,1] op_sel_hi:[1,0]
	v_pk_fma_f32 v[36:37], v[212:213], v[40:41], v[36:37] op_sel_hi:[0,1,1] neg_lo:[0,0,1]
	v_pk_mul_f32 v[40:41], v[220:221], v[204:205] op_sel:[1,1] op_sel_hi:[1,0]
	v_pk_fma_f32 v[40:41], v[220:221], v[204:205], v[40:41] op_sel_hi:[0,1,1] neg_lo:[0,0,1]
	v_cos_f32_e32 v210, 0x3e200000
	v_sin_f32_e32 v211, 0xbe200000
	s_waitcnt lgkmcnt(4)
	v_pk_add_f32 v[202:203], v[42:43], v[46:47]
	v_pk_add_f32 v[42:43], v[42:43], v[46:47] neg_lo:[0,1] neg_hi:[0,1]
	v_pk_add_f32 v[204:205], v[44:45], v[48:49]
	v_pk_add_f32 v[44:45], v[44:45], v[48:49] neg_lo:[0,1] neg_hi:[0,1]
	v_pk_add_f32 v[46:47], v[202:203], v[204:205]
	v_pk_add_f32 v[48:49], v[202:203], v[204:205] neg_lo:[0,1] neg_hi:[0,1]
	v_pk_add_f32 v[202:203], v[42:43], v[44:45] op_sel:[0,1] op_sel_hi:[1,0] neg_hi:[0,1]
	v_pk_add_f32 v[204:205], v[42:43], v[44:45] op_sel:[0,1] op_sel_hi:[1,0] neg_lo:[0,1]
	v_pk_mul_f32 v[206:207], v[210:211], v[210:211] op_sel:[1,1] op_sel_hi:[1,0]
	v_pk_fma_f32 v[212:213], v[210:211], v[210:211], v[206:207] op_sel_hi:[0,1,1] neg_lo:[0,0,1]
	v_pk_mul_f32 v[206:207], v[210:211], v[212:213] op_sel:[1,1] op_sel_hi:[1,0]
	v_pk_fma_f32 v[220:221], v[210:211], v[212:213], v[206:207] op_sel_hi:[0,1,1] neg_lo:[0,0,1]
	v_pk_mul_f32 v[42:43], v[210:211], v[202:203] op_sel:[1,1] op_sel_hi:[1,0]
	v_pk_fma_f32 v[42:43], v[210:211], v[202:203], v[42:43] op_sel_hi:[0,1,1] neg_lo:[0,0,1]
	v_pk_mul_f32 v[44:45], v[212:213], v[48:49] op_sel:[1,1] op_sel_hi:[1,0]
	v_pk_fma_f32 v[44:45], v[212:213], v[48:49], v[44:45] op_sel_hi:[0,1,1] neg_lo:[0,0,1]
	v_pk_mul_f32 v[48:49], v[220:221], v[204:205] op_sel:[1,1] op_sel_hi:[1,0]
	v_pk_fma_f32 v[48:49], v[220:221], v[204:205], v[48:49] op_sel_hi:[0,1,1] neg_lo:[0,0,1]
	v_cos_f32_e32 v210, 0x3e400000
	v_sin_f32_e32 v211, 0xbe400000
	s_waitcnt lgkmcnt(2)
	v_pk_add_f32 v[202:203], v[50:51], v[54:55]
	v_pk_add_f32 v[50:51], v[50:51], v[54:55] neg_lo:[0,1] neg_hi:[0,1]
	v_pk_add_f32 v[204:205], v[52:53], v[56:57]
	v_pk_add_f32 v[52:53], v[52:53], v[56:57] neg_lo:[0,1] neg_hi:[0,1]
	v_pk_add_f32 v[54:55], v[202:203], v[204:205]
	v_pk_add_f32 v[56:57], v[202:203], v[204:205] neg_lo:[0,1] neg_hi:[0,1]
	v_pk_add_f32 v[202:203], v[50:51], v[52:53] op_sel:[0,1] op_sel_hi:[1,0] neg_hi:[0,1]
	v_pk_add_f32 v[204:205], v[50:51], v[52:53] op_sel:[0,1] op_sel_hi:[1,0] neg_lo:[0,1]
	v_pk_mul_f32 v[206:207], v[210:211], v[210:211] op_sel:[1,1] op_sel_hi:[1,0]
	v_pk_fma_f32 v[212:213], v[210:211], v[210:211], v[206:207] op_sel_hi:[0,1,1] neg_lo:[0,0,1]
	v_pk_mul_f32 v[206:207], v[210:211], v[212:213] op_sel:[1,1] op_sel_hi:[1,0]
	v_pk_fma_f32 v[220:221], v[210:211], v[212:213], v[206:207] op_sel_hi:[0,1,1] neg_lo:[0,0,1]
	v_pk_mul_f32 v[50:51], v[210:211], v[202:203] op_sel:[1,1] op_sel_hi:[1,0]
	v_pk_fma_f32 v[50:51], v[210:211], v[202:203], v[50:51] op_sel_hi:[0,1,1] neg_lo:[0,0,1]
	v_pk_mul_f32 v[52:53], v[212:213], v[56:57] op_sel:[1,1] op_sel_hi:[1,0]
	v_pk_fma_f32 v[52:53], v[212:213], v[56:57], v[52:53] op_sel_hi:[0,1,1] neg_lo:[0,0,1]
	v_pk_mul_f32 v[56:57], v[220:221], v[204:205] op_sel:[1,1] op_sel_hi:[1,0]
	v_pk_fma_f32 v[56:57], v[220:221], v[204:205], v[56:57] op_sel_hi:[0,1,1] neg_lo:[0,0,1]
	v_cos_f32_e32 v210, 0x3e600000
	v_sin_f32_e32 v211, 0xbe600000
	s_waitcnt lgkmcnt(0)
	v_pk_add_f32 v[202:203], v[58:59], v[62:63]
	v_pk_add_f32 v[58:59], v[58:59], v[62:63] neg_lo:[0,1] neg_hi:[0,1]
	v_pk_add_f32 v[204:205], v[60:61], v[64:65]
	v_pk_add_f32 v[60:61], v[60:61], v[64:65] neg_lo:[0,1] neg_hi:[0,1]
	v_pk_add_f32 v[62:63], v[202:203], v[204:205]
	v_pk_add_f32 v[64:65], v[202:203], v[204:205] neg_lo:[0,1] neg_hi:[0,1]
	v_pk_add_f32 v[202:203], v[58:59], v[60:61] op_sel:[0,1] op_sel_hi:[1,0] neg_hi:[0,1]
	v_pk_add_f32 v[204:205], v[58:59], v[60:61] op_sel:[0,1] op_sel_hi:[1,0] neg_lo:[0,1]
	v_pk_mul_f32 v[206:207], v[210:211], v[210:211] op_sel:[1,1] op_sel_hi:[1,0]
	v_pk_fma_f32 v[212:213], v[210:211], v[210:211], v[206:207] op_sel_hi:[0,1,1] neg_lo:[0,0,1]
	v_pk_mul_f32 v[206:207], v[210:211], v[212:213] op_sel:[1,1] op_sel_hi:[1,0]
	v_pk_fma_f32 v[220:221], v[210:211], v[212:213], v[206:207] op_sel_hi:[0,1,1] neg_lo:[0,0,1]
	v_pk_mul_f32 v[58:59], v[210:211], v[202:203] op_sel:[1,1] op_sel_hi:[1,0]
	v_pk_fma_f32 v[58:59], v[210:211], v[202:203], v[58:59] op_sel_hi:[0,1,1] neg_lo:[0,0,1]
	v_pk_mul_f32 v[60:61], v[212:213], v[64:65] op_sel:[1,1] op_sel_hi:[1,0]
	v_pk_fma_f32 v[60:61], v[212:213], v[64:65], v[60:61] op_sel_hi:[0,1,1] neg_lo:[0,0,1]
	v_pk_mul_f32 v[64:65], v[220:221], v[204:205] op_sel:[1,1] op_sel_hi:[1,0]
	v_pk_fma_f32 v[64:65], v[220:221], v[204:205], v[64:65] op_sel_hi:[0,1,1] neg_lo:[0,0,1]
	s_barrier
; DI f32x2 cmul(f32x2 a, f32x2 b) { return mkf2(a.x * b.x - a.y * b.y, a.x * b.y + a.y * b.x); }
; DI void fft8192(f32x2* buf, const f32x2* __restrict__ tw) {
;     ...
; #pragma unroll 2
;   for (int ls = 0; ls < 12; ls += 2) {
;     const int s = 1 << ls;
;     f32x2 a[8], b[8], c[8], d[8];
;     __syncthreads();
; #pragma unroll
;     for (int e = 0; e < 8; ++e) {
;       const int i = tid + 256 * e;
;       const int pi = SW(i);
;       a[e] = buf[pi]; b[e] = buf[pi + 2048]; c[e] = buf[pi + 4096]; d[e] = buf[pi + 6144];
;     }
;     __syncthreads();
; #pragma unroll
;     for (int e = 0; e < 8; ++e) {
;       const int i = tid + 256 * e;
;       const int q = i & (s - 1);
;       const int ps = i - q;
;       const float rev = (float)ps * (1.f / 8192.f);
;       const f32x2 w1 = mkf2(__builtin_amdgcn_cosf(rev), -__builtin_amdgcn_sinf(rev));
;       const f32x2 w2 = cmul(w1, w1), w3 = cmul(w1, w2);
;       const f32x2 apc = mkf2(a[e].x + c[e].x, a[e].y + c[e].y), amc = mkf2(a[e].x - c[e].x, a[e].y - c[e].y);
;       const f32x2 bpd = mkf2(b[e].x + d[e].x, b[e].y + d[e].y), bmd = mkf2(b[e].x - d[e].x, b[e].y - d[e].y);
;       const int o = 4 * i - 3 * q;
;       buf[SW(o)] = mkf2(apc.x + bpd.x, apc.y + bpd.y);
;       buf[SW(o + s)] = cmul(w1, mkf2(amc.x + bmd.y, amc.y - bmd.x));
;       buf[SW(o + 2 * s)] = cmul(w2, mkf2(apc.x - bpd.x, apc.y - bpd.y));
;       buf[SW(o + 3 * s)] = cmul(w3, mkf2(amc.x - bmd.y, amc.y + bmd.x));
;     }
	ds_write_b64 v154, v[6:7] offset:0
	ds_write_b64 v154, v[2:3] offset:2048
	ds_write_b64 v154, v[8:9] offset:4096
	ds_write_b64 v154, v[4:5] offset:6144
	ds_write_b64 v154, v[14:15] offset:8192
	ds_write_b64 v154, v[10:11] offset:10240
	ds_write_b64 v154, v[12:13] offset:12288
	ds_write_b64 v154, v[16:17] offset:14336
	ds_write_b64 v154, v[22:23] offset:16384
	ds_write_b64 v154, v[18:19] offset:18432
	ds_write_b64 v154, v[20:21] offset:20480
	ds_write_b64 v154, v[24:25] offset:22528
	ds_write_b64 v154, v[30:31] offset:24576
	ds_write_b64 v154, v[26:27] offset:26624
	ds_write_b64 v154, v[28:29] offset:28672
	ds_write_b64 v154, v[32:33] offset:30720
	ds_write_b64 v154, v[38:39] offset:32768
	ds_write_b64 v154, v[34:35] offset:34816
	ds_write_b64 v154, v[36:37] offset:36864
	ds_write_b64 v154, v[40:41] offset:38912
	ds_write_b64 v154, v[46:47] offset:40960
	ds_write_b64 v154, v[42:43] offset:43008
	ds_write_b64 v154, v[44:45] offset:45056
	ds_write_b64 v154, v[48:49] offset:47104
	ds_write_b64 v154, v[54:55] offset:49152
	ds_write_b64 v154, v[50:51] offset:51200
	ds_write_b64 v154, v[52:53] offset:53248
	ds_write_b64 v154, v[56:57] offset:55296
	ds_write_b64 v154, v[62:63] offset:57344
	ds_write_b64 v154, v[58:59] offset:59392
	ds_write_b64 v154, v[60:61] offset:61440
	ds_write_b64 v154, v[64:65] offset:63488
	s_waitcnt lgkmcnt(0)
	s_barrier
	ds_read2st64_b64 v[2:5], v154 offset0:0 offset1:32
	ds_read2st64_b64 v[6:9], v154 offset0:64 offset1:96
	ds_read2st64_b64 v[10:13], v154 offset0:4 offset1:36
	ds_read2st64_b64 v[14:17], v154 offset0:68 offset1:100
	ds_read2st64_b64 v[18:21], v154 offset0:8 offset1:40
	ds_read2st64_b64 v[22:25], v154 offset0:72 offset1:104
	ds_read2st64_b64 v[26:29], v154 offset0:12 offset1:44
	ds_read2st64_b64 v[30:33], v154 offset0:76 offset1:108
	ds_read2st64_b64 v[34:37], v154 offset0:16 offset1:48
	ds_read2st64_b64 v[38:41], v154 offset0:80 offset1:112
	ds_read2st64_b64 v[42:45], v154 offset0:20 offset1:52
	ds_read2st64_b64 v[46:49], v154 offset0:84 offset1:116
	ds_read2st64_b64 v[50:53], v154 offset0:24 offset1:56
	ds_read2st64_b64 v[54:57], v154 offset0:88 offset1:120
	ds_read2st64_b64 v[58:61], v154 offset0:28 offset1:60
	ds_read2st64_b64 v[62:65], v154 offset0:92 offset1:124
	s_waitcnt lgkmcnt(14)
	v_pk_add_f32 v[202:203], v[2:3], v[6:7]
	v_pk_add_f32 v[2:3], v[2:3], v[6:7] neg_lo:[0,1] neg_hi:[0,1]
	v_pk_add_f32 v[204:205], v[4:5], v[8:9]
	v_pk_add_f32 v[4:5], v[4:5], v[8:9] neg_lo:[0,1] neg_hi:[0,1]
	v_pk_add_f32 v[6:7], v[202:203], v[204:205]
	v_pk_add_f32 v[8:9], v[202:203], v[204:205] neg_lo:[0,1] neg_hi:[0,1]
	v_pk_add_f32 v[202:203], v[2:3], v[4:5] op_sel:[0,1] op_sel_hi:[1,0] neg_hi:[0,1]
	v_pk_add_f32 v[4:5], v[2:3], v[4:5] op_sel:[0,1] op_sel_hi:[1,0] neg_lo:[0,1]
	v_pk_mov_b32 v[2:3], v[202:203], v[202:203] op_sel:[0,1]
	s_waitcnt lgkmcnt(12)
	v_pk_add_f32 v[202:203], v[10:11], v[14:15]
	v_pk_add_f32 v[10:11], v[10:11], v[14:15] neg_lo:[0,1] neg_hi:[0,1]
	v_pk_add_f32 v[204:205], v[12:13], v[16:17]
	v_pk_add_f32 v[12:13], v[12:13], v[16:17] neg_lo:[0,1] neg_hi:[0,1]
	v_pk_add_f32 v[14:15], v[202:203], v[204:205]
	v_pk_add_f32 v[16:17], v[202:203], v[204:205] neg_lo:[0,1] neg_hi:[0,1]
	v_pk_add_f32 v[202:203], v[10:11], v[12:13] op_sel:[0,1] op_sel_hi:[1,0] neg_hi:[0,1]
	v_pk_add_f32 v[12:13], v[10:11], v[12:13] op_sel:[0,1] op_sel_hi:[1,0] neg_lo:[0,1]
	v_pk_mov_b32 v[10:11], v[202:203], v[202:203] op_sel:[0,1]
	s_waitcnt lgkmcnt(10)
	v_pk_add_f32 v[202:203], v[18:19], v[22:23]
	v_pk_add_f32 v[18:19], v[18:19], v[22:23] neg_lo:[0,1] neg_hi:[0,1]
	v_pk_add_f32 v[204:205], v[20:21], v[24:25]
	v_pk_add_f32 v[20:21], v[20:21], v[24:25] neg_lo:[0,1] neg_hi:[0,1]
	v_pk_add_f32 v[22:23], v[202:203], v[204:205]
	v_pk_add_f32 v[24:25], v[202:203], v[204:205] neg_lo:[0,1] neg_hi:[0,1]
	v_pk_add_f32 v[202:203], v[18:19], v[20:21] op_sel:[0,1] op_sel_hi:[1,0] neg_hi:[0,1]
	v_pk_add_f32 v[20:21], v[18:19], v[20:21] op_sel:[0,1] op_sel_hi:[1,0] neg_lo:[0,1]
	v_pk_mov_b32 v[18:19], v[202:203], v[202:203] op_sel:[0,1]
	s_waitcnt lgkmcnt(8)
	v_pk_add_f32 v[202:203], v[26:27], v[30:31]
	v_pk_add_f32 v[26:27], v[26:27], v[30:31] neg_lo:[0,1] neg_hi:[0,1]
	v_pk_add_f32 v[204:205], v[28:29], v[32:33]
	v_pk_add_f32 v[28:29], v[28:29], v[32:33] neg_lo:[0,1] neg_hi:[0,1]
	v_pk_add_f32 v[30:31], v[202:203], v[204:205]
	v_pk_add_f32 v[32:33], v[202:203], v[204:205] neg_lo:[0,1] neg_hi:[0,1]
	v_pk_add_f32 v[202:203], v[26:27], v[28:29] op_sel:[0,1] op_sel_hi:[1,0] neg_hi:[0,1]
	v_pk_add_f32 v[28:29], v[26:27], v[28:29] op_sel:[0,1] op_sel_hi:[1,0] neg_lo:[0,1]
	v_pk_mov_b32 v[26:27], v[202:203], v[202:203] op_sel:[0,1]
	v_cos_f32_e32 v210, 0x3e000000
	v_sin_f32_e32 v211, 0xbe000000
	s_waitcnt lgkmcnt(6)
	v_pk_add_f32 v[202:203], v[34:35], v[38:39]
	v_pk_add_f32 v[34:35], v[34:35], v[38:39] neg_lo:[0,1] neg_hi:[0,1]
	v_pk_add_f32 v[204:205], v[36:37], v[40:41]
	v_pk_add_f32 v[36:37], v[36:37], v[40:41] neg_lo:[0,1] neg_hi:[0,1]
	v_pk_add_f32 v[38:39], v[202:203], v[204:205]
	v_pk_add_f32 v[40:41], v[202:203], v[204:205] neg_lo:[0,1] neg_hi:[0,1]
	v_pk_add_f32 v[202:203], v[34:35], v[36:37] op_sel:[0,1] op_sel_hi:[1,0] neg_hi:[0,1]
	v_pk_add_f32 v[204:205], v[34:35], v[36:37] op_sel:[0,1] op_sel_hi:[1,0] neg_lo:[0,1]
	v_pk_mul_f32 v[206:207], v[210:211], v[210:211] op_sel:[1,1] op_sel_hi:[1,0]
	v_pk_fma_f32 v[212:213], v[210:211], v[210:211], v[206:207] op_sel_hi:[0,1,1] neg_lo:[0,0,1]
	v_pk_mul_f32 v[206:207], v[210:211], v[212:213] op_sel:[1,1] op_sel_hi:[1,0]
	v_pk_fma_f32 v[220:221], v[210:211], v[212:213], v[206:207] op_sel_hi:[0,1,1] neg_lo:[0,0,1]
	v_pk_mul_f32 v[34:35], v[210:211], v[202:203] op_sel:[1,1] op_sel_hi:[1,0]
	v_pk_fma_f32 v[34:35], v[210:211], v[202:203], v[34:35] op_sel_hi:[0,1,1] neg_lo:[0,0,1]
	v_pk_mul_f32 v[36:37], v[212:213], v[40:41] op_sel:[1,1] op_sel_hi:[1,0]
	v_pk_fma_f32 v[36:37], v[212:213], v[40:41], v[36:37] op_sel_hi:[0,1,1] neg_lo:[0,0,1]
	v_pk_mul_f32 v[40:41], v[220:221], v[204:205] op_sel:[1,1] op_sel_hi:[1,0]
	v_pk_fma_f32 v[40:41], v[220:221], v[204:205], v[40:41] op_sel_hi:[0,1,1] neg_lo:[0,0,1]
	v_cos_f32_e32 v210, 0x3e000000
	v_sin_f32_e32 v211, 0xbe000000
	s_waitcnt lgkmcnt(4)
; DI f32x2 cmul(f32x2 a, f32x2 b) { return mkf2(a.x * b.x - a.y * b.y, a.x * b.y + a.y * b.x); }
; DI void fft8192(f32x2* buf, const f32x2* __restrict__ tw) {
;     ...
; #pragma unroll
;     for (int e = 0; e < 8; ++e) {
;       const int i = tid + 256 * e;
;       const int q = i & (s - 1);
;       const int ps = i - q;
;       const float rev = (float)ps * (1.f / 8192.f);
;       const f32x2 w1 = mkf2(__builtin_amdgcn_cosf(rev), -__builtin_amdgcn_sinf(rev));
;       const f32x2 w2 = cmul(w1, w1), w3 = cmul(w1, w2);
;       const f32x2 apc = mkf2(a[e].x + c[e].x, a[e].y + c[e].y), amc = mkf2(a[e].x - c[e].x, a[e].y - c[e].y);
;       const f32x2 bpd = mkf2(b[e].x + d[e].x, b[e].y + d[e].y), bmd = mkf2(b[e].x - d[e].x, b[e].y - d[e].y);
;       const int o = 4 * i - 3 * q;
;       buf[SW(o)] = mkf2(apc.x + bpd.x, apc.y + bpd.y);
;       buf[SW(o + s)] = cmul(w1, mkf2(amc.x + bmd.y, amc.y - bmd.x));
;       buf[SW(o + 2 * s)] = cmul(w2, mkf2(apc.x - bpd.x, apc.y - bpd.y));
;       buf[SW(o + 3 * s)] = cmul(w3, mkf2(amc.x - bmd.y, amc.y + bmd.x));
;     }
	v_pk_add_f32 v[202:203], v[42:43], v[46:47]
	v_pk_add_f32 v[42:43], v[42:43], v[46:47] neg_lo:[0,1] neg_hi:[0,1]
	v_pk_add_f32 v[204:205], v[44:45], v[48:49]
	v_pk_add_f32 v[44:45], v[44:45], v[48:49] neg_lo:[0,1] neg_hi:[0,1]
	v_pk_add_f32 v[46:47], v[202:203], v[204:205]
	v_pk_add_f32 v[48:49], v[202:203], v[204:205] neg_lo:[0,1] neg_hi:[0,1]
	v_pk_add_f32 v[202:203], v[42:43], v[44:45] op_sel:[0,1] op_sel_hi:[1,0] neg_hi:[0,1]
	v_pk_add_f32 v[204:205], v[42:43], v[44:45] op_sel:[0,1] op_sel_hi:[1,0] neg_lo:[0,1]
	v_pk_mul_f32 v[206:207], v[210:211], v[210:211] op_sel:[1,1] op_sel_hi:[1,0]
	v_pk_fma_f32 v[212:213], v[210:211], v[210:211], v[206:207] op_sel_hi:[0,1,1] neg_lo:[0,0,1]
	v_pk_mul_f32 v[206:207], v[210:211], v[212:213] op_sel:[1,1] op_sel_hi:[1,0]
	v_pk_fma_f32 v[220:221], v[210:211], v[212:213], v[206:207] op_sel_hi:[0,1,1] neg_lo:[0,0,1]
	v_pk_mul_f32 v[42:43], v[210:211], v[202:203] op_sel:[1,1] op_sel_hi:[1,0]
	v_pk_fma_f32 v[42:43], v[210:211], v[202:203], v[42:43] op_sel_hi:[0,1,1] neg_lo:[0,0,1]
	v_pk_mul_f32 v[44:45], v[212:213], v[48:49] op_sel:[1,1] op_sel_hi:[1,0]
	v_pk_fma_f32 v[44:45], v[212:213], v[48:49], v[44:45] op_sel_hi:[0,1,1] neg_lo:[0,0,1]
	v_pk_mul_f32 v[48:49], v[220:221], v[204:205] op_sel:[1,1] op_sel_hi:[1,0]
	v_pk_fma_f32 v[48:49], v[220:221], v[204:205], v[48:49] op_sel_hi:[0,1,1] neg_lo:[0,0,1]
	v_cos_f32_e32 v210, 0x3e000000
	v_sin_f32_e32 v211, 0xbe000000
	s_waitcnt lgkmcnt(2)
	v_pk_add_f32 v[202:203], v[50:51], v[54:55]
	v_pk_add_f32 v[50:51], v[50:51], v[54:55] neg_lo:[0,1] neg_hi:[0,1]
	v_pk_add_f32 v[204:205], v[52:53], v[56:57]
	v_pk_add_f32 v[52:53], v[52:53], v[56:57] neg_lo:[0,1] neg_hi:[0,1]
	v_pk_add_f32 v[54:55], v[202:203], v[204:205]
	v_pk_add_f32 v[56:57], v[202:203], v[204:205] neg_lo:[0,1] neg_hi:[0,1]
	v_pk_add_f32 v[202:203], v[50:51], v[52:53] op_sel:[0,1] op_sel_hi:[1,0] neg_hi:[0,1]
	v_pk_add_f32 v[204:205], v[50:51], v[52:53] op_sel:[0,1] op_sel_hi:[1,0] neg_lo:[0,1]
	v_pk_mul_f32 v[206:207], v[210:211], v[210:211] op_sel:[1,1] op_sel_hi:[1,0]
	v_pk_fma_f32 v[212:213], v[210:211], v[210:211], v[206:207] op_sel_hi:[0,1,1] neg_lo:[0,0,1]
	v_pk_mul_f32 v[206:207], v[210:211], v[212:213] op_sel:[1,1] op_sel_hi:[1,0]
	v_pk_fma_f32 v[220:221], v[210:211], v[212:213], v[206:207] op_sel_hi:[0,1,1] neg_lo:[0,0,1]
	v_pk_mul_f32 v[50:51], v[210:211], v[202:203] op_sel:[1,1] op_sel_hi:[1,0]
	v_pk_fma_f32 v[50:51], v[210:211], v[202:203], v[50:51] op_sel_hi:[0,1,1] neg_lo:[0,0,1]
	v_pk_mul_f32 v[52:53], v[212:213], v[56:57] op_sel:[1,1] op_sel_hi:[1,0]
	v_pk_fma_f32 v[52:53], v[212:213], v[56:57], v[52:53] op_sel_hi:[0,1,1] neg_lo:[0,0,1]
	v_pk_mul_f32 v[56:57], v[220:221], v[204:205] op_sel:[1,1] op_sel_hi:[1,0]
	v_pk_fma_f32 v[56:57], v[220:221], v[204:205], v[56:57] op_sel_hi:[0,1,1] neg_lo:[0,0,1]
	v_cos_f32_e32 v210, 0x3e000000
	v_sin_f32_e32 v211, 0xbe000000
	s_waitcnt lgkmcnt(0)
	v_pk_add_f32 v[202:203], v[58:59], v[62:63]
	v_pk_add_f32 v[58:59], v[58:59], v[62:63] neg_lo:[0,1] neg_hi:[0,1]
	v_pk_add_f32 v[204:205], v[60:61], v[64:65]
	v_pk_add_f32 v[60:61], v[60:61], v[64:65] neg_lo:[0,1] neg_hi:[0,1]
	v_pk_add_f32 v[62:63], v[202:203], v[204:205]
	v_pk_add_f32 v[64:65], v[202:203], v[204:205] neg_lo:[0,1] neg_hi:[0,1]
	v_pk_add_f32 v[202:203], v[58:59], v[60:61] op_sel:[0,1] op_sel_hi:[1,0] neg_hi:[0,1]
	v_pk_add_f32 v[204:205], v[58:59], v[60:61] op_sel:[0,1] op_sel_hi:[1,0] neg_lo:[0,1]
	v_pk_mul_f32 v[206:207], v[210:211], v[210:211] op_sel:[1,1] op_sel_hi:[1,0]
	v_pk_fma_f32 v[212:213], v[210:211], v[210:211], v[206:207] op_sel_hi:[0,1,1] neg_lo:[0,0,1]
	v_pk_mul_f32 v[206:207], v[210:211], v[212:213] op_sel:[1,1] op_sel_hi:[1,0]
	v_pk_fma_f32 v[220:221], v[210:211], v[212:213], v[206:207] op_sel_hi:[0,1,1] neg_lo:[0,0,1]
	v_pk_mul_f32 v[58:59], v[210:211], v[202:203] op_sel:[1,1] op_sel_hi:[1,0]
	v_pk_fma_f32 v[58:59], v[210:211], v[202:203], v[58:59] op_sel_hi:[0,1,1] neg_lo:[0,0,1]
	v_pk_mul_f32 v[60:61], v[212:213], v[64:65] op_sel:[1,1] op_sel_hi:[1,0]
	v_pk_fma_f32 v[60:61], v[212:213], v[64:65], v[60:61] op_sel_hi:[0,1,1] neg_lo:[0,0,1]
	v_pk_mul_f32 v[64:65], v[220:221], v[204:205] op_sel:[1,1] op_sel_hi:[1,0]
	v_pk_fma_f32 v[64:65], v[220:221], v[204:205], v[64:65] op_sel_hi:[0,1,1] neg_lo:[0,0,1]
	s_barrier
	ds_write_b64 v154, v[6:7] offset:0
	ds_write_b64 v154, v[2:3] offset:8192
	ds_write_b64 v154, v[8:9] offset:16384
	ds_write_b64 v154, v[4:5] offset:24576
	ds_write_b64 v154, v[14:15] offset:2048
	ds_write_b64 v154, v[10:11] offset:10240
	ds_write_b64 v154, v[16:17] offset:18432
	ds_write_b64 v154, v[12:13] offset:26624
	ds_write_b64 v154, v[22:23] offset:4096
	ds_write_b64 v154, v[18:19] offset:12288
	ds_write_b64 v154, v[24:25] offset:20480
	ds_write_b64 v154, v[20:21] offset:28672
	ds_write_b64 v154, v[30:31] offset:6144
	ds_write_b64 v154, v[26:27] offset:14336
	ds_write_b64 v154, v[32:33] offset:22528
	ds_write_b64 v154, v[28:29] offset:30720
	ds_write_b64 v154, v[38:39] offset:32768
	ds_write_b64 v154, v[34:35] offset:40960
	ds_write_b64 v154, v[36:37] offset:49152
	ds_write_b64 v154, v[40:41] offset:57344
	ds_write_b64 v154, v[46:47] offset:34816
	ds_write_b64 v154, v[42:43] offset:43008
	ds_write_b64 v154, v[44:45] offset:51200
	ds_write_b64 v154, v[48:49] offset:59392
	ds_write_b64 v154, v[54:55] offset:36864
	ds_write_b64 v154, v[50:51] offset:45056
	ds_write_b64 v154, v[52:53] offset:53248
	ds_write_b64 v154, v[56:57] offset:61440
	ds_write_b64 v154, v[62:63] offset:38912
	ds_write_b64 v154, v[58:59] offset:47104
	ds_write_b64 v154, v[60:61] offset:55296
	ds_write_b64 v154, v[64:65] offset:63488
	s_waitcnt lgkmcnt(0)
	s_barrier
; DI void fft8192(f32x2* buf, const f32x2* __restrict__ tw) {
;     ...
;   {
;     f32x2 a[16], b[16];
;     __syncthreads();
; #pragma unroll
;     for (int e = 0; e < 16; ++e) { const int pi = SW(tid + 256 * e); a[e] = buf[pi]; b[e] = buf[pi + 4096]; }
;     __syncthreads();
; #pragma unroll
;     for (int e = 0; e < 16; ++e) {
;       const int pi = SW(tid + 256 * e);
;       buf[pi] = mkf2(a[e].x + b[e].x, a[e].y + b[e].y);
;       buf[pi + 4096] = mkf2(a[e].x - b[e].x, a[e].y - b[e].y);
;     }
;     __syncthreads();
;   }
; DI void hyena_unit(KP p, int l, int c, char* smem) {
;     ...
;       const u16* g0 = Zhy + (size_t)(b0 * 1536 + gcol) * 4096;
;       const u16* g1 = Zhy + (size_t)(b1 * 1536 + gcol) * 4096;
	ds_read2st64_b64 v[2:5], v154 offset0:0 offset1:64
	ds_read2st64_b64 v[6:9], v154 offset0:4 offset1:68
	ds_read2st64_b64 v[10:13], v154 offset0:8 offset1:72
	ds_read2st64_b64 v[14:17], v154 offset0:12 offset1:76
	ds_read2st64_b64 v[18:21], v154 offset0:16 offset1:80
	ds_read2st64_b64 v[22:25], v154 offset0:20 offset1:84
	ds_read2st64_b64 v[26:29], v154 offset0:24 offset1:88
	ds_read2st64_b64 v[30:33], v154 offset0:28 offset1:92
	ds_read2st64_b64 v[34:37], v154 offset0:32 offset1:96
	ds_read2st64_b64 v[38:41], v154 offset0:36 offset1:100
	ds_read2st64_b64 v[42:45], v154 offset0:40 offset1:104
	ds_read2st64_b64 v[46:49], v154 offset0:44 offset1:108
	ds_read2st64_b64 v[50:53], v154 offset0:48 offset1:112
	ds_read2st64_b64 v[54:57], v154 offset0:52 offset1:116
	ds_read2st64_b64 v[58:61], v154 offset0:56 offset1:120
	ds_read2st64_b64 v[62:65], v154 offset0:60 offset1:124
	s_waitcnt lgkmcnt(15)
	v_pk_add_f32 v[202:203], v[2:3], v[4:5]
	v_pk_add_f32 v[4:5], v[2:3], v[4:5] neg_lo:[0,1] neg_hi:[0,1]
	s_waitcnt lgkmcnt(14)
	v_pk_add_f32 v[204:205], v[6:7], v[8:9]
	v_pk_add_f32 v[8:9], v[6:7], v[8:9] neg_lo:[0,1] neg_hi:[0,1]
	s_waitcnt lgkmcnt(13)
	v_pk_add_f32 v[206:207], v[10:11], v[12:13]
	v_pk_add_f32 v[12:13], v[10:11], v[12:13] neg_lo:[0,1] neg_hi:[0,1]
	s_waitcnt lgkmcnt(12)
	v_pk_add_f32 v[208:209], v[14:15], v[16:17]
	v_pk_add_f32 v[16:17], v[14:15], v[16:17] neg_lo:[0,1] neg_hi:[0,1]
	s_waitcnt lgkmcnt(11)
	v_pk_add_f32 v[210:211], v[18:19], v[20:21]
	v_pk_add_f32 v[20:21], v[18:19], v[20:21] neg_lo:[0,1] neg_hi:[0,1]
	s_waitcnt lgkmcnt(10)
	v_pk_add_f32 v[212:213], v[22:23], v[24:25]
	v_pk_add_f32 v[24:25], v[22:23], v[24:25] neg_lo:[0,1] neg_hi:[0,1]
	s_waitcnt lgkmcnt(9)
	v_pk_add_f32 v[220:221], v[26:27], v[28:29]
	v_pk_add_f32 v[28:29], v[26:27], v[28:29] neg_lo:[0,1] neg_hi:[0,1]
	s_waitcnt lgkmcnt(8)
	v_pk_add_f32 v[224:225], v[30:31], v[32:33]
	v_pk_add_f32 v[32:33], v[30:31], v[32:33] neg_lo:[0,1] neg_hi:[0,1]
	s_waitcnt lgkmcnt(7)
	v_pk_add_f32 v[226:227], v[34:35], v[36:37]
	v_pk_add_f32 v[36:37], v[34:35], v[36:37] neg_lo:[0,1] neg_hi:[0,1]
	s_waitcnt lgkmcnt(6)
	v_pk_add_f32 v[230:231], v[38:39], v[40:41]
	v_pk_add_f32 v[40:41], v[38:39], v[40:41] neg_lo:[0,1] neg_hi:[0,1]
	s_waitcnt lgkmcnt(5)
	v_pk_add_f32 v[232:233], v[42:43], v[44:45]
	v_pk_add_f32 v[44:45], v[42:43], v[44:45] neg_lo:[0,1] neg_hi:[0,1]
	s_waitcnt lgkmcnt(4)
	v_pk_add_f32 v[236:237], v[46:47], v[48:49]
	v_pk_add_f32 v[48:49], v[46:47], v[48:49] neg_lo:[0,1] neg_hi:[0,1]
	s_waitcnt lgkmcnt(3)
	v_pk_add_f32 v[238:239], v[50:51], v[52:53]
	v_pk_add_f32 v[52:53], v[50:51], v[52:53] neg_lo:[0,1] neg_hi:[0,1]
	s_waitcnt lgkmcnt(2)
	v_pk_add_f32 v[240:241], v[54:55], v[56:57]
	v_pk_add_f32 v[56:57], v[54:55], v[56:57] neg_lo:[0,1] neg_hi:[0,1]
	s_waitcnt lgkmcnt(1)
	v_pk_add_f32 v[244:245], v[58:59], v[60:61]
	v_pk_add_f32 v[60:61], v[58:59], v[60:61] neg_lo:[0,1] neg_hi:[0,1]
	s_waitcnt lgkmcnt(0)
	v_pk_add_f32 v[246:247], v[62:63], v[64:65]
	v_pk_add_f32 v[64:65], v[62:63], v[64:65] neg_lo:[0,1] neg_hi:[0,1]
	s_barrier
	ds_write2st64_b64 v154, v[202:203], v[4:5] offset0:0 offset1:64
	ds_write2st64_b64 v154, v[204:205], v[8:9] offset0:4 offset1:68
	ds_write2st64_b64 v154, v[206:207], v[12:13] offset0:8 offset1:72
	ds_write2st64_b64 v154, v[208:209], v[16:17] offset0:12 offset1:76
	ds_write2st64_b64 v154, v[210:211], v[20:21] offset0:16 offset1:80
	ds_write2st64_b64 v154, v[212:213], v[24:25] offset0:20 offset1:84
	ds_write2st64_b64 v154, v[220:221], v[28:29] offset0:24 offset1:88
	ds_write2st64_b64 v154, v[224:225], v[32:33] offset0:28 offset1:92
	ds_write2st64_b64 v154, v[226:227], v[36:37] offset0:32 offset1:96
	ds_write2st64_b64 v154, v[230:231], v[40:41] offset0:36 offset1:100
	ds_write2st64_b64 v154, v[232:233], v[44:45] offset0:40 offset1:104
	ds_write2st64_b64 v154, v[236:237], v[48:49] offset0:44 offset1:108
	ds_write2st64_b64 v154, v[238:239], v[52:53] offset0:48 offset1:112
	ds_write2st64_b64 v154, v[240:241], v[56:57] offset0:52 offset1:116
	ds_write2st64_b64 v154, v[244:245], v[60:61] offset0:56 offset1:120
	ds_write2st64_b64 v154, v[246:247], v[64:65] offset0:60 offset1:124
	s_lshl_b32 s2, s83, 11
	s_lshl_b32 s4, s78, 10
	s_sub_i32 s2, s28, s2
	s_sub_i32 s4, s6, s4
	s_ashr_i32 s3, s2, 31
	s_ashr_i32 s5, s4, 31
	s_lshl_b64 s[2:3], s[2:3], 13
	s_lshl_b64 s[4:5], s[4:5], 13
	s_add_u32 s8, s55, s2
	s_addc_u32 s9, s81, s3
	s_add_u32 s10, s55, s4
	s_addc_u32 s11, s81, s5
	s_add_i32 s2, s82, s21
	s_ashr_i32 s3, s2, 31
	s_lshl_b64 s[2:3], s[2:3], 13
	s_add_u32 s6, s80, s2
	s_addc_u32 s7, s76, s3
	s_add_i32 s4, s29, s21
	s_ashr_i32 s5, s4, 31
	s_lshl_b64 s[4:5], s[4:5], 13
	s_add_u32 s12, s80, s4
	s_addc_u32 s13, s76, s5
	s_and_b64 s[4:5], s[96:97], exec
	s_cselect_b32 s5, s25, s9
	s_cselect_b32 s4, s24, s8
	s_cselect_b32 s9, s27, s11
	s_cselect_b32 s8, s26, s10
	v_lshl_add_u64 v[4:5], s[4:5], 0, v[68:69]
	s_add_i32 s4, s77, s82
	s_ashr_i32 s5, s4, 31
	s_lshl_b64 s[4:5], s[4:5], 13
	v_lshl_add_u64 v[2:3], s[8:9], 0, v[68:69]
	v_lshl_add_u64 v[6:7], v[70:71], 0, s[4:5]
	v_lshl_add_u64 v[8:9], v[70:71], 0, s[2:3]
	s_mov_b64 s[22:23], 0
	v_mov_b32_e32 v198, v66
	s_waitcnt lgkmcnt(0)
	s_barrier
; DI float bf2f(u16 v) { return __uint_as_float(((unsigned)v) << 16); }
; DI float sconv3(const u16* row, int t, int n, float w0, float w1, float w2, float bias) {
;   float xm = (t > 0) ? bf2f(row[t - 1]) : 0.f, x0 = bf2f(row[t]), xp = (t + 1 < n) ? bf2f(row[t + 1]) : 0.f;
;   return w0 * xm + w1 * x0 + w2 * xp + bias;
; DI void hyena_unit(KP p, int l, int c, char* smem) {
;     ...
;       const u16* g0 = Zhy + (size_t)(b0 * 1536 + gcol) * 4096;
;       const u16* g1 = Zhy + (size_t)(b1 * 1536 + gcol) * 4096;
; #pragma unroll 4
;       for (int jj = 0; jj < 16; ++jj) {
;         const int t = tid + 256 * jj;
;         const f32x2 r = buf[SW(t)];
;         const float y0 = r.x * (1.f / 8192.f), y1 = -r.y * (1.f / 8192.f);
;         const float x0 = sconv3(g0, t, 4096, gw0, gw1, gw2, gb), x1 = sconv3(g1, t, 4096, gw0, gw1, gw2, gb);
;         if (o == 0) { r0[t] = f2bf(x0 * y0); r1[t] = f2bf(x1 * y1); }
;         else { y0p[t] = f2bf(x0 * y0); y1p[t] = f2bf(x1 * y1); }
;       }
	v_lshlrev_b32_e32 v201, 1, v66
	v_xor_b32_e32 v203, v66, v155
	v_add_u32_e32 v202, 0x1000, v201
	v_lshlrev_b32_e32 v203, 3, v203
	s_mov_b64 s[8:9], 0x1000
	v_lshl_add_u64 v[204:205], v[4:5], 0, s[8:9]
	v_lshl_add_u64 v[206:207], v[2:3], 0, s[8:9]
	v_cmp_eq_u32_e64 s[8:9], 0, v66
	v_cmp_eq_u32_e32 vcc, 0xff, v66
	s_mov_b64 s[10:11], vcc
	ds_read_b64 v[224:225], v203
	ds_read_b64 v[226:227], v203 offset:2048
	ds_read_b64 v[230:231], v203 offset:4096
	ds_read_b64 v[232:233], v203 offset:6144
	ds_read_b64 v[236:237], v203 offset:8192
	ds_read_b64 v[238:239], v203 offset:10240
	ds_read_b64 v[240:241], v203 offset:12288
	ds_read_b64 v[244:245], v203 offset:14336
	global_load_ushort v10, v201, s[6:7] offset:-2
	global_load_ushort v11, v201, s[6:7] offset:0
	global_load_ushort v12, v201, s[6:7] offset:2
	global_load_ushort v13, v201, s[12:13] offset:-2
	global_load_ushort v14, v201, s[12:13] offset:0
	global_load_ushort v15, v201, s[12:13] offset:2
	global_load_ushort v16, v201, s[6:7] offset:510
	global_load_ushort v17, v201, s[6:7] offset:512
	global_load_ushort v18, v201, s[6:7] offset:514
	global_load_ushort v19, v201, s[12:13] offset:510
	global_load_ushort v20, v201, s[12:13] offset:512
	global_load_ushort v21, v201, s[12:13] offset:514
	global_load_ushort v22, v201, s[6:7] offset:1022
	global_load_ushort v23, v201, s[6:7] offset:1024
	global_load_ushort v24, v201, s[6:7] offset:1026
	global_load_ushort v25, v201, s[12:13] offset:1022
	global_load_ushort v26, v201, s[12:13] offset:1024
	global_load_ushort v27, v201, s[12:13] offset:1026
	global_load_ushort v28, v201, s[6:7] offset:1534
	global_load_ushort v29, v201, s[6:7] offset:1536
	global_load_ushort v30, v201, s[6:7] offset:1538
	global_load_ushort v31, v201, s[12:13] offset:1534
	global_load_ushort v32, v201, s[12:13] offset:1536
	global_load_ushort v34, v201, s[12:13] offset:1538
	global_load_ushort v35, v201, s[6:7] offset:2046
	global_load_ushort v36, v201, s[6:7] offset:2048
	global_load_ushort v37, v201, s[6:7] offset:2050
	global_load_ushort v38, v201, s[12:13] offset:2046
	global_load_ushort v39, v201, s[12:13] offset:2048
	global_load_ushort v40, v201, s[12:13] offset:2050
	global_load_ushort v41, v201, s[6:7] offset:2558
	global_load_ushort v42, v201, s[6:7] offset:2560
	global_load_ushort v43, v201, s[6:7] offset:2562
	global_load_ushort v44, v201, s[12:13] offset:2558
	global_load_ushort v45, v201, s[12:13] offset:2560
	global_load_ushort v46, v201, s[12:13] offset:2562
	global_load_ushort v47, v201, s[6:7] offset:3070
	global_load_ushort v48, v201, s[6:7] offset:3072
	global_load_ushort v49, v201, s[6:7] offset:3074
	global_load_ushort v50, v201, s[12:13] offset:3070
	global_load_ushort v51, v201, s[12:13] offset:3072
	global_load_ushort v52, v201, s[12:13] offset:3074
	global_load_ushort v53, v201, s[6:7] offset:3582
	global_load_ushort v54, v201, s[6:7] offset:3584
	global_load_ushort v55, v201, s[6:7] offset:3586
	global_load_ushort v56, v201, s[12:13] offset:3582
	global_load_ushort v57, v201, s[12:13] offset:3584
	global_load_ushort v58, v201, s[12:13] offset:3586
	s_waitcnt vmcnt(42)
	s_waitcnt lgkmcnt(0)
	v_cndmask_b32_e64 v10, v10, 0, s[8:9]
	v_cndmask_b32_e64 v13, v13, 0, s[8:9]
	v_lshlrev_b32_e32 v10, 16, v10
	v_lshlrev_b32_e32 v11, 16, v11
	v_lshlrev_b32_e32 v12, 16, v12
	v_lshlrev_b32_e32 v13, 16, v13
	v_lshlrev_b32_e32 v14, 16, v14
	v_lshlrev_b32_e32 v15, 16, v15
	v_mul_f32_e32 v11, v196, v11
	v_mul_f32_e32 v14, v196, v14
	v_fmac_f32_e32 v11, v74, v10
	v_fmac_f32_e32 v14, v74, v13
	v_fmac_f32_e32 v11, v75, v12
	v_fmac_f32_e32 v14, v75, v15
	v_mul_f32_e32 v10, 0x39000000, v224
	v_mul_f32_e32 v13, 0xb9000000, v225
	v_add_f32_e32 v11, v195, v11
	v_add_f32_e32 v14, v195, v14
	v_mul_f32_e32 v10, v10, v11
	v_mul_f32_e32 v13, v13, v14
	v_cvt_pk_bf16_f32 v10, v10, v10
	v_cvt_pk_bf16_f32 v13, v13, v13
	global_store_short v[4:5], v10, off
	global_store_short v[2:3], v13, off
	s_waitcnt vmcnt(38)
	v_lshlrev_b32_e32 v16, 16, v16
	v_lshlrev_b32_e32 v17, 16, v17
	v_lshlrev_b32_e32 v18, 16, v18
	v_lshlrev_b32_e32 v19, 16, v19
	v_lshlrev_b32_e32 v20, 16, v20
	v_lshlrev_b32_e32 v21, 16, v21
	v_mul_f32_e32 v17, v196, v17
	v_mul_f32_e32 v20, v196, v20
	v_fmac_f32_e32 v17, v74, v16
	v_fmac_f32_e32 v20, v74, v19
	v_fmac_f32_e32 v17, v75, v18
	v_fmac_f32_e32 v20, v75, v21
	v_mul_f32_e32 v16, 0x39000000, v226
	v_mul_f32_e32 v19, 0xb9000000, v227
	v_add_f32_e32 v17, v195, v17
	v_add_f32_e32 v20, v195, v20
	v_mul_f32_e32 v16, v16, v17
	v_mul_f32_e32 v19, v19, v20
	v_cvt_pk_bf16_f32 v16, v16, v16
	v_cvt_pk_bf16_f32 v19, v19, v19
	global_store_short v[4:5], v16, off offset:512
	global_store_short v[2:3], v19, off offset:512
	s_waitcnt vmcnt(34)
	v_lshlrev_b32_e32 v22, 16, v22
	v_lshlrev_b32_e32 v23, 16, v23
	v_lshlrev_b32_e32 v24, 16, v24
	v_lshlrev_b32_e32 v25, 16, v25
	v_lshlrev_b32_e32 v26, 16, v26
	v_lshlrev_b32_e32 v27, 16, v27
	v_mul_f32_e32 v23, v196, v23
	v_mul_f32_e32 v26, v196, v26
	v_fmac_f32_e32 v23, v74, v22
	v_fmac_f32_e32 v26, v74, v25
	v_fmac_f32_e32 v23, v75, v24
	v_fmac_f32_e32 v26, v75, v27
	v_mul_f32_e32 v22, 0x39000000, v230
	v_mul_f32_e32 v25, 0xb9000000, v231
	v_add_f32_e32 v23, v195, v23
	v_add_f32_e32 v26, v195, v26
	v_mul_f32_e32 v22, v22, v23
	v_mul_f32_e32 v25, v25, v26
	v_cvt_pk_bf16_f32 v22, v22, v22
	v_cvt_pk_bf16_f32 v25, v25, v25
	global_store_short v[4:5], v22, off offset:1024
	global_store_short v[2:3], v25, off offset:1024
	s_waitcnt vmcnt(30)
; DI float bf2f(u16 v) { return __uint_as_float(((unsigned)v) << 16); }
; DI float sconv3(const u16* row, int t, int n, float w0, float w1, float w2, float bias) {
;   float xm = (t > 0) ? bf2f(row[t - 1]) : 0.f, x0 = bf2f(row[t]), xp = (t + 1 < n) ? bf2f(row[t + 1]) : 0.f;
;   return w0 * xm + w1 * x0 + w2 * xp + bias;
; DI void hyena_unit(KP p, int l, int c, char* smem) {
;     ...
;       const u16* g0 = Zhy + (size_t)(b0 * 1536 + gcol) * 4096;
;       const u16* g1 = Zhy + (size_t)(b1 * 1536 + gcol) * 4096;
; #pragma unroll 4
;       for (int jj = 0; jj < 16; ++jj) {
;         const int t = tid + 256 * jj;
;         const f32x2 r = buf[SW(t)];
;         const float y0 = r.x * (1.f / 8192.f), y1 = -r.y * (1.f / 8192.f);
;         const float x0 = sconv3(g0, t, 4096, gw0, gw1, gw2, gb), x1 = sconv3(g1, t, 4096, gw0, gw1, gw2, gb);
;         if (o == 0) { r0[t] = f2bf(x0 * y0); r1[t] = f2bf(x1 * y1); }
;         else { y0p[t] = f2bf(x0 * y0); y1p[t] = f2bf(x1 * y1); }
;       }
	v_lshlrev_b32_e32 v28, 16, v28
	v_lshlrev_b32_e32 v29, 16, v29
	v_lshlrev_b32_e32 v30, 16, v30
	v_lshlrev_b32_e32 v31, 16, v31
	v_lshlrev_b32_e32 v32, 16, v32
	v_lshlrev_b32_e32 v34, 16, v34
	v_mul_f32_e32 v29, v196, v29
	v_mul_f32_e32 v32, v196, v32
	v_fmac_f32_e32 v29, v74, v28
	v_fmac_f32_e32 v32, v74, v31
	v_fmac_f32_e32 v29, v75, v30
	v_fmac_f32_e32 v32, v75, v34
	v_mul_f32_e32 v28, 0x39000000, v232
	v_mul_f32_e32 v31, 0xb9000000, v233
	v_add_f32_e32 v29, v195, v29
	v_add_f32_e32 v32, v195, v32
	v_mul_f32_e32 v28, v28, v29
	v_mul_f32_e32 v31, v31, v32
	v_cvt_pk_bf16_f32 v28, v28, v28
	v_cvt_pk_bf16_f32 v31, v31, v31
	global_store_short v[4:5], v28, off offset:1536
	global_store_short v[2:3], v31, off offset:1536
	s_waitcnt vmcnt(26)
	v_lshlrev_b32_e32 v35, 16, v35
	v_lshlrev_b32_e32 v36, 16, v36
	v_lshlrev_b32_e32 v37, 16, v37
	v_lshlrev_b32_e32 v38, 16, v38
	v_lshlrev_b32_e32 v39, 16, v39
	v_lshlrev_b32_e32 v40, 16, v40
	v_mul_f32_e32 v36, v196, v36
	v_mul_f32_e32 v39, v196, v39
	v_fmac_f32_e32 v36, v74, v35
	v_fmac_f32_e32 v39, v74, v38
	v_fmac_f32_e32 v36, v75, v37
	v_fmac_f32_e32 v39, v75, v40
	v_mul_f32_e32 v35, 0x39000000, v236
	v_mul_f32_e32 v38, 0xb9000000, v237
	v_add_f32_e32 v36, v195, v36
	v_add_f32_e32 v39, v195, v39
	v_mul_f32_e32 v35, v35, v36
	v_mul_f32_e32 v38, v38, v39
	v_cvt_pk_bf16_f32 v35, v35, v35
	v_cvt_pk_bf16_f32 v38, v38, v38
	global_store_short v[4:5], v35, off offset:2048
	global_store_short v[2:3], v38, off offset:2048
	s_waitcnt vmcnt(22)
	v_lshlrev_b32_e32 v41, 16, v41
	v_lshlrev_b32_e32 v42, 16, v42
	v_lshlrev_b32_e32 v43, 16, v43
	v_lshlrev_b32_e32 v44, 16, v44
	v_lshlrev_b32_e32 v45, 16, v45
	v_lshlrev_b32_e32 v46, 16, v46
	v_mul_f32_e32 v42, v196, v42
	v_mul_f32_e32 v45, v196, v45
	v_fmac_f32_e32 v42, v74, v41
	v_fmac_f32_e32 v45, v74, v44
	v_fmac_f32_e32 v42, v75, v43
	v_fmac_f32_e32 v45, v75, v46
	v_mul_f32_e32 v41, 0x39000000, v238
	v_mul_f32_e32 v44, 0xb9000000, v239
	v_add_f32_e32 v42, v195, v42
	v_add_f32_e32 v45, v195, v45
	v_mul_f32_e32 v41, v41, v42
	v_mul_f32_e32 v44, v44, v45
	v_cvt_pk_bf16_f32 v41, v41, v41
	v_cvt_pk_bf16_f32 v44, v44, v44
	global_store_short v[4:5], v41, off offset:2560
	global_store_short v[2:3], v44, off offset:2560
	s_waitcnt vmcnt(18)
	v_lshlrev_b32_e32 v47, 16, v47
	v_lshlrev_b32_e32 v48, 16, v48
	v_lshlrev_b32_e32 v49, 16, v49
	v_lshlrev_b32_e32 v50, 16, v50
	v_lshlrev_b32_e32 v51, 16, v51
	v_lshlrev_b32_e32 v52, 16, v52
	v_mul_f32_e32 v48, v196, v48
	v_mul_f32_e32 v51, v196, v51
	v_fmac_f32_e32 v48, v74, v47
	v_fmac_f32_e32 v51, v74, v50
	v_fmac_f32_e32 v48, v75, v49
	v_fmac_f32_e32 v51, v75, v52
	v_mul_f32_e32 v47, 0x39000000, v240
	v_mul_f32_e32 v50, 0xb9000000, v241
	v_add_f32_e32 v48, v195, v48
	v_add_f32_e32 v51, v195, v51
	v_mul_f32_e32 v47, v47, v48
	v_mul_f32_e32 v50, v50, v51
	v_cvt_pk_bf16_f32 v47, v47, v47
	v_cvt_pk_bf16_f32 v50, v50, v50
	global_store_short v[4:5], v47, off offset:3072
	global_store_short v[2:3], v50, off offset:3072
	s_waitcnt vmcnt(14)
	v_lshlrev_b32_e32 v53, 16, v53
	v_lshlrev_b32_e32 v54, 16, v54
	v_lshlrev_b32_e32 v55, 16, v55
	v_lshlrev_b32_e32 v56, 16, v56
	v_lshlrev_b32_e32 v57, 16, v57
	v_lshlrev_b32_e32 v58, 16, v58
	v_mul_f32_e32 v54, v196, v54
	v_mul_f32_e32 v57, v196, v57
	v_fmac_f32_e32 v54, v74, v53
	v_fmac_f32_e32 v57, v74, v56
	v_fmac_f32_e32 v54, v75, v55
	v_fmac_f32_e32 v57, v75, v58
	v_mul_f32_e32 v53, 0x39000000, v244
	v_mul_f32_e32 v56, 0xb9000000, v245
	v_add_f32_e32 v54, v195, v54
	v_add_f32_e32 v57, v195, v57
	v_mul_f32_e32 v53, v53, v54
	v_mul_f32_e32 v56, v56, v57
	v_cvt_pk_bf16_f32 v53, v53, v53
	v_cvt_pk_bf16_f32 v56, v56, v56
	global_store_short v[4:5], v53, off offset:3584
	global_store_short v[2:3], v56, off offset:3584
	ds_read_b64 v[224:225], v203 offset:16384
	ds_read_b64 v[226:227], v203 offset:18432
	ds_read_b64 v[230:231], v203 offset:20480
	ds_read_b64 v[232:233], v203 offset:22528
	ds_read_b64 v[236:237], v203 offset:24576
	ds_read_b64 v[238:239], v203 offset:26624
	ds_read_b64 v[240:241], v203 offset:28672
	ds_read_b64 v[244:245], v203 offset:30720
	global_load_ushort v10, v202, s[6:7] offset:-2
	global_load_ushort v11, v202, s[6:7] offset:0
	global_load_ushort v12, v202, s[6:7] offset:2
	global_load_ushort v13, v202, s[12:13] offset:-2
	global_load_ushort v14, v202, s[12:13] offset:0
	global_load_ushort v15, v202, s[12:13] offset:2
	global_load_ushort v16, v202, s[6:7] offset:510
	global_load_ushort v17, v202, s[6:7] offset:512
	global_load_ushort v18, v202, s[6:7] offset:514
	global_load_ushort v19, v202, s[12:13] offset:510
	global_load_ushort v20, v202, s[12:13] offset:512
	global_load_ushort v21, v202, s[12:13] offset:514
	global_load_ushort v22, v202, s[6:7] offset:1022
	global_load_ushort v23, v202, s[6:7] offset:1024
	global_load_ushort v24, v202, s[6:7] offset:1026
	global_load_ushort v25, v202, s[12:13] offset:1022
	global_load_ushort v26, v202, s[12:13] offset:1024
	global_load_ushort v27, v202, s[12:13] offset:1026
	global_load_ushort v28, v202, s[6:7] offset:1534
	global_load_ushort v29, v202, s[6:7] offset:1536
	global_load_ushort v30, v202, s[6:7] offset:1538
	global_load_ushort v31, v202, s[12:13] offset:1534
	global_load_ushort v32, v202, s[12:13] offset:1536
	global_load_ushort v34, v202, s[12:13] offset:1538
	global_load_ushort v35, v202, s[6:7] offset:2046
	global_load_ushort v36, v202, s[6:7] offset:2048
	global_load_ushort v37, v202, s[6:7] offset:2050
	global_load_ushort v38, v202, s[12:13] offset:2046
	global_load_ushort v39, v202, s[12:13] offset:2048
	global_load_ushort v40, v202, s[12:13] offset:2050
	global_load_ushort v41, v202, s[6:7] offset:2558
	global_load_ushort v42, v202, s[6:7] offset:2560
	global_load_ushort v43, v202, s[6:7] offset:2562
	global_load_ushort v44, v202, s[12:13] offset:2558
	global_load_ushort v45, v202, s[12:13] offset:2560
	global_load_ushort v46, v202, s[12:13] offset:2562
	global_load_ushort v47, v202, s[6:7] offset:3070
	global_load_ushort v48, v202, s[6:7] offset:3072
	global_load_ushort v49, v202, s[6:7] offset:3074
	global_load_ushort v50, v202, s[12:13] offset:3070
	global_load_ushort v51, v202, s[12:13] offset:3072
	global_load_ushort v52, v202, s[12:13] offset:3074
	global_load_ushort v53, v202, s[6:7] offset:3582
	global_load_ushort v54, v202, s[6:7] offset:3584
	global_load_ushort v55, v202, s[6:7] offset:3586
	global_load_ushort v56, v202, s[12:13] offset:3582
	global_load_ushort v57, v202, s[12:13] offset:3584
	global_load_ushort v58, v202, s[12:13] offset:3586
	s_waitcnt vmcnt(42)
; DI float bf2f(u16 v) { return __uint_as_float(((unsigned)v) << 16); }
; DI float sconv3(const u16* row, int t, int n, float w0, float w1, float w2, float bias) {
;   float xm = (t > 0) ? bf2f(row[t - 1]) : 0.f, x0 = bf2f(row[t]), xp = (t + 1 < n) ? bf2f(row[t + 1]) : 0.f;
;   return w0 * xm + w1 * x0 + w2 * xp + bias;
; DI void hyena_unit(KP p, int l, int c, char* smem) {
;     ...
;       const u16* g0 = Zhy + (size_t)(b0 * 1536 + gcol) * 4096;
;       const u16* g1 = Zhy + (size_t)(b1 * 1536 + gcol) * 4096;
; #pragma unroll 4
;       for (int jj = 0; jj < 16; ++jj) {
;         const int t = tid + 256 * jj;
;         const f32x2 r = buf[SW(t)];
;         const float y0 = r.x * (1.f / 8192.f), y1 = -r.y * (1.f / 8192.f);
;         const float x0 = sconv3(g0, t, 4096, gw0, gw1, gw2, gb), x1 = sconv3(g1, t, 4096, gw0, gw1, gw2, gb);
;         if (o == 0) { r0[t] = f2bf(x0 * y0); r1[t] = f2bf(x1 * y1); }
;         else { y0p[t] = f2bf(x0 * y0); y1p[t] = f2bf(x1 * y1); }
;       }
	s_waitcnt lgkmcnt(0)
	v_lshlrev_b32_e32 v10, 16, v10
	v_lshlrev_b32_e32 v11, 16, v11
	v_lshlrev_b32_e32 v12, 16, v12
	v_lshlrev_b32_e32 v13, 16, v13
	v_lshlrev_b32_e32 v14, 16, v14
	v_lshlrev_b32_e32 v15, 16, v15
	v_mul_f32_e32 v11, v196, v11
	v_mul_f32_e32 v14, v196, v14
	v_fmac_f32_e32 v11, v74, v10
	v_fmac_f32_e32 v14, v74, v13
	v_fmac_f32_e32 v11, v75, v12
	v_fmac_f32_e32 v14, v75, v15
	v_mul_f32_e32 v10, 0x39000000, v224
	v_mul_f32_e32 v13, 0xb9000000, v225
	v_add_f32_e32 v11, v195, v11
	v_add_f32_e32 v14, v195, v14
	v_mul_f32_e32 v10, v10, v11
	v_mul_f32_e32 v13, v13, v14
	v_cvt_pk_bf16_f32 v10, v10, v10
	v_cvt_pk_bf16_f32 v13, v13, v13
	global_store_short v[204:205], v10, off
	global_store_short v[206:207], v13, off
	s_waitcnt vmcnt(38)
	v_lshlrev_b32_e32 v16, 16, v16
	v_lshlrev_b32_e32 v17, 16, v17
	v_lshlrev_b32_e32 v18, 16, v18
	v_lshlrev_b32_e32 v19, 16, v19
	v_lshlrev_b32_e32 v20, 16, v20
	v_lshlrev_b32_e32 v21, 16, v21
	v_mul_f32_e32 v17, v196, v17
	v_mul_f32_e32 v20, v196, v20
	v_fmac_f32_e32 v17, v74, v16
	v_fmac_f32_e32 v20, v74, v19
	v_fmac_f32_e32 v17, v75, v18
	v_fmac_f32_e32 v20, v75, v21
	v_mul_f32_e32 v16, 0x39000000, v226
	v_mul_f32_e32 v19, 0xb9000000, v227
	v_add_f32_e32 v17, v195, v17
	v_add_f32_e32 v20, v195, v20
	v_mul_f32_e32 v16, v16, v17
	v_mul_f32_e32 v19, v19, v20
	v_cvt_pk_bf16_f32 v16, v16, v16
	v_cvt_pk_bf16_f32 v19, v19, v19
	global_store_short v[204:205], v16, off offset:512
	global_store_short v[206:207], v19, off offset:512
	s_waitcnt vmcnt(34)
	v_lshlrev_b32_e32 v22, 16, v22
	v_lshlrev_b32_e32 v23, 16, v23
	v_lshlrev_b32_e32 v24, 16, v24
	v_lshlrev_b32_e32 v25, 16, v25
	v_lshlrev_b32_e32 v26, 16, v26
	v_lshlrev_b32_e32 v27, 16, v27
	v_mul_f32_e32 v23, v196, v23
	v_mul_f32_e32 v26, v196, v26
	v_fmac_f32_e32 v23, v74, v22
	v_fmac_f32_e32 v26, v74, v25
	v_fmac_f32_e32 v23, v75, v24
	v_fmac_f32_e32 v26, v75, v27
	v_mul_f32_e32 v22, 0x39000000, v230
	v_mul_f32_e32 v25, 0xb9000000, v231
	v_add_f32_e32 v23, v195, v23
	v_add_f32_e32 v26, v195, v26
	v_mul_f32_e32 v22, v22, v23
	v_mul_f32_e32 v25, v25, v26
	v_cvt_pk_bf16_f32 v22, v22, v22
	v_cvt_pk_bf16_f32 v25, v25, v25
	global_store_short v[204:205], v22, off offset:1024
	global_store_short v[206:207], v25, off offset:1024
	s_waitcnt vmcnt(30)
	v_lshlrev_b32_e32 v28, 16, v28
	v_lshlrev_b32_e32 v29, 16, v29
	v_lshlrev_b32_e32 v30, 16, v30
	v_lshlrev_b32_e32 v31, 16, v31
	v_lshlrev_b32_e32 v32, 16, v32
	v_lshlrev_b32_e32 v34, 16, v34
	v_mul_f32_e32 v29, v196, v29
	v_mul_f32_e32 v32, v196, v32
	v_fmac_f32_e32 v29, v74, v28
	v_fmac_f32_e32 v32, v74, v31
	v_fmac_f32_e32 v29, v75, v30
	v_fmac_f32_e32 v32, v75, v34
	v_mul_f32_e32 v28, 0x39000000, v232
	v_mul_f32_e32 v31, 0xb9000000, v233
	v_add_f32_e32 v29, v195, v29
	v_add_f32_e32 v32, v195, v32
	v_mul_f32_e32 v28, v28, v29
	v_mul_f32_e32 v31, v31, v32
	v_cvt_pk_bf16_f32 v28, v28, v28
	v_cvt_pk_bf16_f32 v31, v31, v31
	global_store_short v[204:205], v28, off offset:1536
	global_store_short v[206:207], v31, off offset:1536
	s_waitcnt vmcnt(26)
	v_lshlrev_b32_e32 v35, 16, v35
	v_lshlrev_b32_e32 v36, 16, v36
	v_lshlrev_b32_e32 v37, 16, v37
	v_lshlrev_b32_e32 v38, 16, v38
	v_lshlrev_b32_e32 v39, 16, v39
	v_lshlrev_b32_e32 v40, 16, v40
	v_mul_f32_e32 v36, v196, v36
	v_mul_f32_e32 v39, v196, v39
	v_fmac_f32_e32 v36, v74, v35
	v_fmac_f32_e32 v39, v74, v38
	v_fmac_f32_e32 v36, v75, v37
	v_fmac_f32_e32 v39, v75, v40
	v_mul_f32_e32 v35, 0x39000000, v236
	v_mul_f32_e32 v38, 0xb9000000, v237
	v_add_f32_e32 v36, v195, v36
	v_add_f32_e32 v39, v195, v39
	v_mul_f32_e32 v35, v35, v36
	v_mul_f32_e32 v38, v38, v39
	v_cvt_pk_bf16_f32 v35, v35, v35
	v_cvt_pk_bf16_f32 v38, v38, v38
	global_store_short v[204:205], v35, off offset:2048
	global_store_short v[206:207], v38, off offset:2048
	s_waitcnt vmcnt(22)
	v_lshlrev_b32_e32 v41, 16, v41
	v_lshlrev_b32_e32 v42, 16, v42
	v_lshlrev_b32_e32 v43, 16, v43
	v_lshlrev_b32_e32 v44, 16, v44
	v_lshlrev_b32_e32 v45, 16, v45
	v_lshlrev_b32_e32 v46, 16, v46
	v_mul_f32_e32 v42, v196, v42
	v_mul_f32_e32 v45, v196, v45
	v_fmac_f32_e32 v42, v74, v41
	v_fmac_f32_e32 v45, v74, v44
	v_fmac_f32_e32 v42, v75, v43
	v_fmac_f32_e32 v45, v75, v46
	v_mul_f32_e32 v41, 0x39000000, v238
	v_mul_f32_e32 v44, 0xb9000000, v239
	v_add_f32_e32 v42, v195, v42
	v_add_f32_e32 v45, v195, v45
	v_mul_f32_e32 v41, v41, v42
	v_mul_f32_e32 v44, v44, v45
	v_cvt_pk_bf16_f32 v41, v41, v41
	v_cvt_pk_bf16_f32 v44, v44, v44
	global_store_short v[204:205], v41, off offset:2560
	global_store_short v[206:207], v44, off offset:2560
	s_waitcnt vmcnt(18)
	v_lshlrev_b32_e32 v47, 16, v47
	v_lshlrev_b32_e32 v48, 16, v48
	v_lshlrev_b32_e32 v49, 16, v49
	v_lshlrev_b32_e32 v50, 16, v50
	v_lshlrev_b32_e32 v51, 16, v51
	v_lshlrev_b32_e32 v52, 16, v52
	v_mul_f32_e32 v48, v196, v48
	v_mul_f32_e32 v51, v196, v51
	v_fmac_f32_e32 v48, v74, v47
	v_fmac_f32_e32 v51, v74, v50
	v_fmac_f32_e32 v48, v75, v49
	v_fmac_f32_e32 v51, v75, v52
	v_mul_f32_e32 v47, 0x39000000, v240
	v_mul_f32_e32 v50, 0xb9000000, v241
	v_add_f32_e32 v48, v195, v48
	v_add_f32_e32 v51, v195, v51
	v_mul_f32_e32 v47, v47, v48
	v_mul_f32_e32 v50, v50, v51
	v_cvt_pk_bf16_f32 v47, v47, v47
	v_cvt_pk_bf16_f32 v50, v50, v50
	global_store_short v[204:205], v47, off offset:3072
	global_store_short v[206:207], v50, off offset:3072
	s_waitcnt vmcnt(14)
	v_cndmask_b32_e64 v55, v55, 0, s[10:11]
	v_cndmask_b32_e64 v58, v58, 0, s[10:11]
	v_lshlrev_b32_e32 v53, 16, v53
	v_lshlrev_b32_e32 v54, 16, v54
	v_lshlrev_b32_e32 v55, 16, v55
	v_lshlrev_b32_e32 v56, 16, v56
	v_lshlrev_b32_e32 v57, 16, v57
	v_lshlrev_b32_e32 v58, 16, v58
	v_mul_f32_e32 v54, v196, v54
	v_mul_f32_e32 v57, v196, v57
	v_fmac_f32_e32 v54, v74, v53
	v_fmac_f32_e32 v57, v74, v56
	v_fmac_f32_e32 v54, v75, v55
	v_fmac_f32_e32 v57, v75, v58
	v_mul_f32_e32 v53, 0x39000000, v244
	v_mul_f32_e32 v56, 0xb9000000, v245
	v_add_f32_e32 v54, v195, v54
	v_add_f32_e32 v57, v195, v57
	v_mul_f32_e32 v53, v53, v54
	v_mul_f32_e32 v56, v56, v57
	v_cvt_pk_bf16_f32 v53, v53, v53
	v_cvt_pk_bf16_f32 v56, v56, v56
	global_store_short v[204:205], v53, off offset:3584
	global_store_short v[206:207], v56, off offset:3584
	s_branch .LBB0_936

;     ...
;     if (tid < 64) {
;       const int c = tid;
;       float h = 0.f, A = 1.f;
;       if (pass == 3) { const f32x2 c0 = ((const f32x2*)carry)[(0 * 2 + dir) * 64 + c], c1 = ((const f32x2*)carry)[(1 * 2 + dir) * 64 + c]; h = c1.x * c0.y + c1.y; }
;       if (dir == 0) {
; #pragma unroll 8
;         for (int t = 0; t < 64; ++t) { float a = sa[c * 65 + t]; h = a * h + sb[c * 65 + t]; A *= a; sb[c * 65 + t] = h; }
.LBB0_1582:
	v_mov_b32_e32 v35, v34
	v_add_u32_e32 v36, 0x4100, v35
	ds_read2_b32 v[132:133], v35 offset0:0 offset1:1
	ds_read2_b32 v[134:135], v35 offset0:2 offset1:3
	ds_read2_b32 v[136:137], v35 offset0:4 offset1:5
	ds_read2_b32 v[138:139], v35 offset0:6 offset1:7
	ds_read2_b32 v[140:141], v36 offset0:0 offset1:1
	ds_read2_b32 v[142:143], v36 offset0:2 offset1:3
	ds_read2_b32 v[144:145], v36 offset0:4 offset1:5
	ds_read2_b32 v[146:147], v36 offset0:6 offset1:7
	ds_read2_b32 v[148:149], v35 offset0:8 offset1:9
	ds_read2_b32 v[150:151], v35 offset0:10 offset1:11
	ds_read2_b32 v[152:153], v35 offset0:12 offset1:13
	ds_read2_b32 v[154:155], v35 offset0:14 offset1:15
	ds_read2_b32 v[156:157], v36 offset0:8 offset1:9
	ds_read2_b32 v[158:159], v36 offset0:10 offset1:11
	ds_read2_b32 v[160:161], v36 offset0:12 offset1:13
	ds_read2_b32 v[162:163], v36 offset0:14 offset1:15
	s_waitcnt lgkmcnt(8)
	v_fma_f32 v140, v37, v132, v140
	v_fma_f32 v141, v140, v133, v141
	v_fma_f32 v142, v141, v134, v142
	v_fma_f32 v143, v142, v135, v143
	v_fma_f32 v144, v143, v136, v144
	v_fma_f32 v145, v144, v137, v145
	v_fma_f32 v146, v145, v138, v146
	v_fma_f32 v147, v146, v139, v147
	v_mov_b32_e32 v37, v147
	ds_write2_b32 v36, v140, v141 offset0:0 offset1:1
	ds_write2_b32 v36, v142, v143 offset0:2 offset1:3
	ds_write2_b32 v36, v144, v145 offset0:4 offset1:5
	ds_write2_b32 v36, v146, v147 offset0:6 offset1:7
	ds_read2_b32 v[132:133], v35 offset0:16 offset1:17
	ds_read2_b32 v[134:135], v35 offset0:18 offset1:19
	ds_read2_b32 v[136:137], v35 offset0:20 offset1:21
	ds_read2_b32 v[138:139], v35 offset0:22 offset1:23
	ds_read2_b32 v[140:141], v36 offset0:16 offset1:17
	ds_read2_b32 v[142:143], v36 offset0:18 offset1:19
	ds_read2_b32 v[144:145], v36 offset0:20 offset1:21
	ds_read2_b32 v[146:147], v36 offset0:22 offset1:23
	s_waitcnt lgkmcnt(12)
	v_fma_f32 v156, v37, v148, v156
	v_fma_f32 v157, v156, v149, v157
	v_fma_f32 v158, v157, v150, v158
	v_fma_f32 v159, v158, v151, v159
	v_fma_f32 v160, v159, v152, v160
	v_fma_f32 v161, v160, v153, v161
	v_fma_f32 v162, v161, v154, v162
	v_fma_f32 v163, v162, v155, v163
	v_mov_b32_e32 v37, v163
	ds_write2_b32 v36, v156, v157 offset0:8 offset1:9
	ds_write2_b32 v36, v158, v159 offset0:10 offset1:11
	ds_write2_b32 v36, v160, v161 offset0:12 offset1:13
	ds_write2_b32 v36, v162, v163 offset0:14 offset1:15
	ds_read2_b32 v[148:149], v35 offset0:24 offset1:25
	ds_read2_b32 v[150:151], v35 offset0:26 offset1:27
	ds_read2_b32 v[152:153], v35 offset0:28 offset1:29
	ds_read2_b32 v[154:155], v35 offset0:30 offset1:31
	ds_read2_b32 v[156:157], v36 offset0:24 offset1:25
	ds_read2_b32 v[158:159], v36 offset0:26 offset1:27
	ds_read2_b32 v[160:161], v36 offset0:28 offset1:29
	ds_read2_b32 v[162:163], v36 offset0:30 offset1:31
	s_waitcnt lgkmcnt(12)
	v_fma_f32 v140, v37, v132, v140
	v_fma_f32 v141, v140, v133, v141
	v_fma_f32 v142, v141, v134, v142
	v_fma_f32 v143, v142, v135, v143
	v_fma_f32 v144, v143, v136, v144
	v_fma_f32 v145, v144, v137, v145
	v_fma_f32 v146, v145, v138, v146
	v_fma_f32 v147, v146, v139, v147
	v_mov_b32_e32 v37, v147
	ds_write2_b32 v36, v140, v141 offset0:16 offset1:17
	ds_write2_b32 v36, v142, v143 offset0:18 offset1:19
	ds_write2_b32 v36, v144, v145 offset0:20 offset1:21
	ds_write2_b32 v36, v146, v147 offset0:22 offset1:23
	ds_read2_b32 v[132:133], v35 offset0:32 offset1:33
	ds_read2_b32 v[134:135], v35 offset0:34 offset1:35
	ds_read2_b32 v[136:137], v35 offset0:36 offset1:37
	ds_read2_b32 v[138:139], v35 offset0:38 offset1:39
	ds_read2_b32 v[140:141], v36 offset0:32 offset1:33
	ds_read2_b32 v[142:143], v36 offset0:34 offset1:35
	ds_read2_b32 v[144:145], v36 offset0:36 offset1:37
	ds_read2_b32 v[146:147], v36 offset0:38 offset1:39
	s_waitcnt lgkmcnt(12)
;     ...
;       if (dir == 0) {
; #pragma unroll 8
;         for (int t = 0; t < 64; ++t) { float a = sa[c * 65 + t]; h = a * h + sb[c * 65 + t]; A *= a; sb[c * 65 + t] = h; }
	v_fma_f32 v156, v37, v148, v156
	v_fma_f32 v157, v156, v149, v157
	v_fma_f32 v158, v157, v150, v158
	v_fma_f32 v159, v158, v151, v159
	v_fma_f32 v160, v159, v152, v160
	v_fma_f32 v161, v160, v153, v161
	v_fma_f32 v162, v161, v154, v162
	v_fma_f32 v163, v162, v155, v163
	v_mov_b32_e32 v37, v163
	ds_write2_b32 v36, v156, v157 offset0:24 offset1:25
	ds_write2_b32 v36, v158, v159 offset0:26 offset1:27
	ds_write2_b32 v36, v160, v161 offset0:28 offset1:29
	ds_write2_b32 v36, v162, v163 offset0:30 offset1:31
	ds_read2_b32 v[148:149], v35 offset0:40 offset1:41
	ds_read2_b32 v[150:151], v35 offset0:42 offset1:43
	ds_read2_b32 v[152:153], v35 offset0:44 offset1:45
	ds_read2_b32 v[154:155], v35 offset0:46 offset1:47
	ds_read2_b32 v[156:157], v36 offset0:40 offset1:41
	ds_read2_b32 v[158:159], v36 offset0:42 offset1:43
	ds_read2_b32 v[160:161], v36 offset0:44 offset1:45
	ds_read2_b32 v[162:163], v36 offset0:46 offset1:47
	s_waitcnt lgkmcnt(12)
	v_fma_f32 v140, v37, v132, v140
	v_fma_f32 v141, v140, v133, v141
	v_fma_f32 v142, v141, v134, v142
	v_fma_f32 v143, v142, v135, v143
	v_fma_f32 v144, v143, v136, v144
	v_fma_f32 v145, v144, v137, v145
	v_fma_f32 v146, v145, v138, v146
	v_fma_f32 v147, v146, v139, v147
	v_mov_b32_e32 v37, v147
	ds_write2_b32 v36, v140, v141 offset0:32 offset1:33
	ds_write2_b32 v36, v142, v143 offset0:34 offset1:35
	ds_write2_b32 v36, v144, v145 offset0:36 offset1:37
	ds_write2_b32 v36, v146, v147 offset0:38 offset1:39
	ds_read2_b32 v[132:133], v35 offset0:48 offset1:49
	ds_read2_b32 v[134:135], v35 offset0:50 offset1:51
	ds_read2_b32 v[136:137], v35 offset0:52 offset1:53
	ds_read2_b32 v[138:139], v35 offset0:54 offset1:55
	ds_read2_b32 v[140:141], v36 offset0:48 offset1:49
	ds_read2_b32 v[142:143], v36 offset0:50 offset1:51
	ds_read2_b32 v[144:145], v36 offset0:52 offset1:53
	ds_read2_b32 v[146:147], v36 offset0:54 offset1:55
	s_waitcnt lgkmcnt(12)
	v_fma_f32 v156, v37, v148, v156
	v_fma_f32 v157, v156, v149, v157
	v_fma_f32 v158, v157, v150, v158
	v_fma_f32 v159, v158, v151, v159
	v_fma_f32 v160, v159, v152, v160
	v_fma_f32 v161, v160, v153, v161
	v_fma_f32 v162, v161, v154, v162
	v_fma_f32 v163, v162, v155, v163
	v_mov_b32_e32 v37, v163
	ds_write2_b32 v36, v156, v157 offset0:40 offset1:41
	ds_write2_b32 v36, v158, v159 offset0:42 offset1:43
	ds_write2_b32 v36, v160, v161 offset0:44 offset1:45
	ds_write2_b32 v36, v162, v163 offset0:46 offset1:47
	ds_read2_b32 v[148:149], v35 offset0:56 offset1:57
	ds_read2_b32 v[150:151], v35 offset0:58 offset1:59
	ds_read2_b32 v[152:153], v35 offset0:60 offset1:61
	ds_read2_b32 v[154:155], v35 offset0:62 offset1:63
	ds_read2_b32 v[156:157], v36 offset0:56 offset1:57
	ds_read2_b32 v[158:159], v36 offset0:58 offset1:59
	ds_read2_b32 v[160:161], v36 offset0:60 offset1:61
	ds_read2_b32 v[162:163], v36 offset0:62 offset1:63
	s_waitcnt lgkmcnt(12)
	v_fma_f32 v140, v37, v132, v140
	v_fma_f32 v141, v140, v133, v141
	v_fma_f32 v142, v141, v134, v142
	v_fma_f32 v143, v142, v135, v143
	v_fma_f32 v144, v143, v136, v144
	v_fma_f32 v145, v144, v137, v145
	v_fma_f32 v146, v145, v138, v146
	v_fma_f32 v147, v146, v139, v147
	v_mov_b32_e32 v37, v147
	ds_write2_b32 v36, v140, v141 offset0:48 offset1:49
	ds_write2_b32 v36, v142, v143 offset0:50 offset1:51
	ds_write2_b32 v36, v144, v145 offset0:52 offset1:53
	ds_write2_b32 v36, v146, v147 offset0:54 offset1:55
	s_waitcnt lgkmcnt(4)
	v_fma_f32 v156, v37, v148, v156
	v_fma_f32 v157, v156, v149, v157
	v_fma_f32 v158, v157, v150, v158
	v_fma_f32 v159, v158, v151, v159
	v_fma_f32 v160, v159, v152, v160
	v_fma_f32 v161, v160, v153, v161
	v_fma_f32 v162, v161, v154, v162
	v_fma_f32 v163, v162, v155, v163
	v_mov_b32_e32 v37, v163
	ds_write2_b32 v36, v156, v157 offset0:56 offset1:57
	ds_write2_b32 v36, v158, v159 offset0:58 offset1:59
	ds_write2_b32 v36, v160, v161 offset0:60 offset1:61
	ds_write2_b32 v36, v162, v163 offset0:62 offset1:63

;     ...
;       } else {
; #pragma unroll 8
;         for (int t = 63; t >= 0; --t) { float a = sa[c * 65 + t]; h = a * h + sb[c * 65 + t]; A *= a; sb[c * 65 + t] = h; }
;       }
.LBB0_1653:
	v_add_u32_e32 v5, 0xffffff20, v4
	v_add_u32_e32 v3, 0x4100, v5
	ds_read2_b32 v[132:133], v5 offset0:56 offset1:57
	ds_read2_b32 v[134:135], v5 offset0:58 offset1:59
	ds_read2_b32 v[136:137], v5 offset0:60 offset1:61
	ds_read2_b32 v[138:139], v5 offset0:62 offset1:63
	ds_read2_b32 v[140:141], v3 offset0:56 offset1:57
	ds_read2_b32 v[142:143], v3 offset0:58 offset1:59
	ds_read2_b32 v[144:145], v3 offset0:60 offset1:61
	ds_read2_b32 v[146:147], v3 offset0:62 offset1:63
	ds_read2_b32 v[148:149], v5 offset0:48 offset1:49
	ds_read2_b32 v[150:151], v5 offset0:50 offset1:51
	ds_read2_b32 v[152:153], v5 offset0:52 offset1:53
	ds_read2_b32 v[154:155], v5 offset0:54 offset1:55
	ds_read2_b32 v[156:157], v3 offset0:48 offset1:49
	ds_read2_b32 v[158:159], v3 offset0:50 offset1:51
	ds_read2_b32 v[160:161], v3 offset0:52 offset1:53
	ds_read2_b32 v[162:163], v3 offset0:54 offset1:55
	s_waitcnt lgkmcnt(8)
	v_fma_f32 v147, v2, v139, v147
	v_fma_f32 v146, v147, v138, v146
	v_fma_f32 v145, v146, v137, v145
	v_fma_f32 v144, v145, v136, v144
	v_fma_f32 v143, v144, v135, v143
	v_fma_f32 v142, v143, v134, v142
	v_fma_f32 v141, v142, v133, v141
	v_fma_f32 v140, v141, v132, v140
	v_mov_b32_e32 v2, v140
	ds_write2_b32 v3, v140, v141 offset0:56 offset1:57
	ds_write2_b32 v3, v142, v143 offset0:58 offset1:59
	ds_write2_b32 v3, v144, v145 offset0:60 offset1:61
	ds_write2_b32 v3, v146, v147 offset0:62 offset1:63
	ds_read2_b32 v[132:133], v5 offset0:40 offset1:41
	ds_read2_b32 v[134:135], v5 offset0:42 offset1:43
	ds_read2_b32 v[136:137], v5 offset0:44 offset1:45
	ds_read2_b32 v[138:139], v5 offset0:46 offset1:47
	ds_read2_b32 v[140:141], v3 offset0:40 offset1:41
	ds_read2_b32 v[142:143], v3 offset0:42 offset1:43
	ds_read2_b32 v[144:145], v3 offset0:44 offset1:45
	ds_read2_b32 v[146:147], v3 offset0:46 offset1:47
	s_waitcnt lgkmcnt(12)
	v_fma_f32 v163, v2, v155, v163
	v_fma_f32 v162, v163, v154, v162
	v_fma_f32 v161, v162, v153, v161
	v_fma_f32 v160, v161, v152, v160
	v_fma_f32 v159, v160, v151, v159
	v_fma_f32 v158, v159, v150, v158
	v_fma_f32 v157, v158, v149, v157
	v_fma_f32 v156, v157, v148, v156
	v_mov_b32_e32 v2, v156
	ds_write2_b32 v3, v156, v157 offset0:48 offset1:49
	ds_write2_b32 v3, v158, v159 offset0:50 offset1:51
	ds_write2_b32 v3, v160, v161 offset0:52 offset1:53
	ds_write2_b32 v3, v162, v163 offset0:54 offset1:55
	ds_read2_b32 v[148:149], v5 offset0:32 offset1:33
	ds_read2_b32 v[150:151], v5 offset0:34 offset1:35
	ds_read2_b32 v[152:153], v5 offset0:36 offset1:37
	ds_read2_b32 v[154:155], v5 offset0:38 offset1:39
	ds_read2_b32 v[156:157], v3 offset0:32 offset1:33
	ds_read2_b32 v[158:159], v3 offset0:34 offset1:35
	ds_read2_b32 v[160:161], v3 offset0:36 offset1:37
	ds_read2_b32 v[162:163], v3 offset0:38 offset1:39
	s_waitcnt lgkmcnt(12)
	v_fma_f32 v147, v2, v139, v147
	v_fma_f32 v146, v147, v138, v146
	v_fma_f32 v145, v146, v137, v145
	v_fma_f32 v144, v145, v136, v144
	v_fma_f32 v143, v144, v135, v143
	v_fma_f32 v142, v143, v134, v142
	v_fma_f32 v141, v142, v133, v141
	v_fma_f32 v140, v141, v132, v140
	v_mov_b32_e32 v2, v140
	ds_write2_b32 v3, v140, v141 offset0:40 offset1:41
	ds_write2_b32 v3, v142, v143 offset0:42 offset1:43
	ds_write2_b32 v3, v144, v145 offset0:44 offset1:45
	ds_write2_b32 v3, v146, v147 offset0:46 offset1:47
	ds_read2_b32 v[132:133], v5 offset0:24 offset1:25
	ds_read2_b32 v[134:135], v5 offset0:26 offset1:27
	ds_read2_b32 v[136:137], v5 offset0:28 offset1:29
	ds_read2_b32 v[138:139], v5 offset0:30 offset1:31
	ds_read2_b32 v[140:141], v3 offset0:24 offset1:25
	ds_read2_b32 v[142:143], v3 offset0:26 offset1:27
	ds_read2_b32 v[144:145], v3 offset0:28 offset1:29
	ds_read2_b32 v[146:147], v3 offset0:30 offset1:31
	s_waitcnt lgkmcnt(12)
;     ...
;       } else {
; #pragma unroll 8
;         for (int t = 63; t >= 0; --t) { float a = sa[c * 65 + t]; h = a * h + sb[c * 65 + t]; A *= a; sb[c * 65 + t] = h; }
;       }
	v_fma_f32 v163, v2, v155, v163
	v_fma_f32 v162, v163, v154, v162
	v_fma_f32 v161, v162, v153, v161
	v_fma_f32 v160, v161, v152, v160
	v_fma_f32 v159, v160, v151, v159
	v_fma_f32 v158, v159, v150, v158
	v_fma_f32 v157, v158, v149, v157
	v_fma_f32 v156, v157, v148, v156
	v_mov_b32_e32 v2, v156
	ds_write2_b32 v3, v156, v157 offset0:32 offset1:33
	ds_write2_b32 v3, v158, v159 offset0:34 offset1:35
	ds_write2_b32 v3, v160, v161 offset0:36 offset1:37
	ds_write2_b32 v3, v162, v163 offset0:38 offset1:39
	ds_read2_b32 v[148:149], v5 offset0:16 offset1:17
	ds_read2_b32 v[150:151], v5 offset0:18 offset1:19
	ds_read2_b32 v[152:153], v5 offset0:20 offset1:21
	ds_read2_b32 v[154:155], v5 offset0:22 offset1:23
	ds_read2_b32 v[156:157], v3 offset0:16 offset1:17
	ds_read2_b32 v[158:159], v3 offset0:18 offset1:19
	ds_read2_b32 v[160:161], v3 offset0:20 offset1:21
	ds_read2_b32 v[162:163], v3 offset0:22 offset1:23
	s_waitcnt lgkmcnt(12)
	v_fma_f32 v147, v2, v139, v147
	v_fma_f32 v146, v147, v138, v146
	v_fma_f32 v145, v146, v137, v145
	v_fma_f32 v144, v145, v136, v144
	v_fma_f32 v143, v144, v135, v143
	v_fma_f32 v142, v143, v134, v142
	v_fma_f32 v141, v142, v133, v141
	v_fma_f32 v140, v141, v132, v140
	v_mov_b32_e32 v2, v140
	ds_write2_b32 v3, v140, v141 offset0:24 offset1:25
	ds_write2_b32 v3, v142, v143 offset0:26 offset1:27
	ds_write2_b32 v3, v144, v145 offset0:28 offset1:29
	ds_write2_b32 v3, v146, v147 offset0:30 offset1:31
	ds_read2_b32 v[132:133], v5 offset0:8 offset1:9
	ds_read2_b32 v[134:135], v5 offset0:10 offset1:11
	ds_read2_b32 v[136:137], v5 offset0:12 offset1:13
	ds_read2_b32 v[138:139], v5 offset0:14 offset1:15
	ds_read2_b32 v[140:141], v3 offset0:8 offset1:9
	ds_read2_b32 v[142:143], v3 offset0:10 offset1:11
	ds_read2_b32 v[144:145], v3 offset0:12 offset1:13
	ds_read2_b32 v[146:147], v3 offset0:14 offset1:15
	s_waitcnt lgkmcnt(12)
	v_fma_f32 v163, v2, v155, v163
	v_fma_f32 v162, v163, v154, v162
	v_fma_f32 v161, v162, v153, v161
	v_fma_f32 v160, v161, v152, v160
	v_fma_f32 v159, v160, v151, v159
	v_fma_f32 v158, v159, v150, v158
	v_fma_f32 v157, v158, v149, v157
	v_fma_f32 v156, v157, v148, v156
	v_mov_b32_e32 v2, v156
	ds_write2_b32 v3, v156, v157 offset0:16 offset1:17
	ds_write2_b32 v3, v158, v159 offset0:18 offset1:19
	ds_write2_b32 v3, v160, v161 offset0:20 offset1:21
	ds_write2_b32 v3, v162, v163 offset0:22 offset1:23
	ds_read2_b32 v[148:149], v5 offset0:0 offset1:1
	ds_read2_b32 v[150:151], v5 offset0:2 offset1:3
	ds_read2_b32 v[152:153], v5 offset0:4 offset1:5
	ds_read2_b32 v[154:155], v5 offset0:6 offset1:7
	ds_read2_b32 v[156:157], v3 offset0:0 offset1:1
	ds_read2_b32 v[158:159], v3 offset0:2 offset1:3
	ds_read2_b32 v[160:161], v3 offset0:4 offset1:5
	ds_read2_b32 v[162:163], v3 offset0:6 offset1:7
	s_waitcnt lgkmcnt(12)
	v_fma_f32 v147, v2, v139, v147
	v_fma_f32 v146, v147, v138, v146
	v_fma_f32 v145, v146, v137, v145
	v_fma_f32 v144, v145, v136, v144
	v_fma_f32 v143, v144, v135, v143
	v_fma_f32 v142, v143, v134, v142
	v_fma_f32 v141, v142, v133, v141
	v_fma_f32 v140, v141, v132, v140
	v_mov_b32_e32 v2, v140
	ds_write2_b32 v3, v140, v141 offset0:8 offset1:9
	ds_write2_b32 v3, v142, v143 offset0:10 offset1:11
	ds_write2_b32 v3, v144, v145 offset0:12 offset1:13
	ds_write2_b32 v3, v146, v147 offset0:14 offset1:15
	s_waitcnt lgkmcnt(4)
	v_fma_f32 v163, v2, v155, v163
	v_fma_f32 v162, v163, v154, v162
	v_fma_f32 v161, v162, v153, v161
	v_fma_f32 v160, v161, v152, v160
	v_fma_f32 v159, v160, v151, v159
	v_fma_f32 v158, v159, v150, v158
	v_fma_f32 v157, v158, v149, v157
	v_fma_f32 v156, v157, v148, v156
	v_mov_b32_e32 v2, v156
	ds_write2_b32 v3, v156, v157 offset0:0 offset1:1
	ds_write2_b32 v3, v158, v159 offset0:2 offset1:3
	ds_write2_b32 v3, v160, v161 offset0:4 offset1:5
	ds_write2_b32 v3, v162, v163 offset0:6 offset1:7
	s_branch .LBB0_1154

; #define MFMA32(a, b, c) __builtin_amdgcn_mfma_f32_32x32x16_bf16((a), (b), (c), 0, 0, 0)
; DI int tidx() { int t = __builtin_amdgcn_workitem_id_x(); asm volatile("" : "+v"(t)); return t; }
; #define GEMM_LOADG(kk) { const int ka_ = amode ? (((kk) >> 6) * 96) : (kk); \
;     _Pragma("unroll") for (int i = 0; i < 4; ++i) ra[i] = *(const u32x4*)(A + (size_t)(lr + 32 * i) * lda + ka_ + lk); \
;     _Pragma("unroll") for (int i = 0; i < 2 * NT; ++i) rb[i] = *(const u32x4*)(Bt + (size_t)(lr + 32 * i) * ldb + (kk) + lk); }
; #define GEMM_STORES(buf) { u16* As_ = S + (buf) * TILE; u16* Bs_ = As_ + 128 * LS; \
;     _Pragma("unroll") for (int i = 0; i < 4; ++i) *(u32x4*)(As_ + (lr + 32 * i) * LS + lk) = ra[i]; \
;     _Pragma("unroll") for (int i = 0; i < 2 * NT; ++i) *(u32x4*)(Bs_ + (lr + 32 * i) * LS + lk) = rb[i]; }
; template <int NT>
; DI void gemm_main_np(f32x16 (&acc)[2][NT], const u16* __restrict__ A, int lda, int amode, const u16* __restrict__ Bt,
;                   int ldb, int K, char* smem) {
;     ...
;   GEMM_LOADG(0)
;   __syncthreads();
;   GEMM_STORES(0)
;   if (K > 64) GEMM_LOADG(64)
;   __syncthreads();
;   for (int k0 = 0; k0 < K; k0 += 64) {
;     const int cur = (k0 >> 6) & 1;
;     if (k0 + 64 < K) {
;       GEMM_STORES(cur ^ 1)
;       if (k0 + 128 < K) GEMM_LOADG(k0 + 128)
;     }
;     const u16* As = S + cur * TILE;
;     const u16* Bs = As + 128 * LS;
; #pragma unroll
;     for (int s = 0; s < 4; ++s) {
;       bf16x8 a[2], b[NT];
; #pragma unroll
;       for (int i = 0; i < 2; ++i) a[i] = *(const bf16x8*)(As + (wm * 64 + i * 32 + l31) * LS + s * 16 + hh * 8);
; #pragma unroll
;       for (int j = 0; j < NT; ++j) b[j] = *(const bf16x8*)(Bs + (wn * 32 * NT + j * 32 + l31) * LS + s * 16 + hh * 8);
; #pragma unroll
;       for (int i = 0; i < 2; ++i)
; #pragma unroll
;         for (int j = 0; j < NT; ++j) acc[i][j] = MFMA32(a[i], b[j], acc[i][j]);
;     }
; DI void resid_ctx_half(KP p, int l, int u, int which, const u16* A, int K, const u16* Wt, const float* xin, float* xout, char* smem) {
;   const int mt = 128 + (u >> 4), nt = u & 15;
;   const int lane = tidx() & 63, w = tidx() >> 6, wm = w >> 1, wn = w & 1, l31 = lane & 31, hh = lane >> 5;
;   f32x16 acc[2][1];
;   zero_acc(acc[0][0]); zero_acc(acc[1][0]);
;   gemm_main_np<1>(acc, A + (size_t)mt * 128 * K, K, 0, Wt + (size_t)nt * 64 * K, K, K, smem);
.LBB0_1791:
	s_mov_b64 s[2:3], s[0:1]
	s_add_i32 s18, s28, 0xfffffe00
	s_load_dwordx2 s[16:17], s[2:3], 0x130
	s_lshl_b32 s2, s18, 3
	s_and_b32 s2, s2, 0x380
	v_mov_b32_e32 v50, v0
	v_mov_b32_e32 v51, v0
	s_lshl_b32 s3, s2, 11
	v_mov_b32_e32 v54, v0
	s_add_u32 s4, s38, s3
	s_addc_u32 s5, s39, 0
	v_lshlrev_b32_e32 v2, 4, v54
	v_ashrrev_i32_e32 v26, 3, v54
	v_and_b32_e32 v198, 0x70, v2
	s_lshl_b32 s3, s18, 6
	v_lshl_add_u64 v[28:29], s[4:5], 0, v[198:199]
	s_mov_b64 s[4:5], 0xc6d0000
	v_ashrrev_i32_e32 v27, 31, v26
	s_and_b32 s3, s3, 0x3c0
	v_lshl_add_u64 v[14:15], v[28:29], 0, s[4:5]
	v_lshlrev_b64 v[30:31], 11, v[26:27]
	s_mov_b64 s[4:5], 0x10000
	s_lshl_b32 s18, s3, 11
	v_lshl_add_u64 v[38:39], v[14:15], 0, v[30:31]
	v_lshl_add_u64 v[32:33], v[30:31], 0, s[4:5]
	s_mov_b64 s[4:5], 0x20000
	s_add_u32 s18, s43, s18
	global_load_dwordx4 v[2:5], v[38:39], off
	v_lshl_add_u64 v[40:41], v[14:15], 0, v[32:33]
	v_lshl_add_u64 v[36:37], v[30:31], 0, s[4:5]
	s_mov_b64 s[4:5], 0x30000
	s_addc_u32 s19, s42, 0
	global_load_dwordx4 v[6:9], v[40:41], off
	v_lshl_add_u64 v[42:43], v[14:15], 0, v[36:37]
	v_lshl_add_u64 v[52:53], v[30:31], 0, s[4:5]
	global_load_dwordx4 v[10:13], v[42:43], off
	v_lshl_add_u64 v[44:45], v[14:15], 0, v[52:53]
	v_lshl_add_u64 v[22:23], s[18:19], 0, v[198:199]
	global_load_dwordx4 v[14:17], v[44:45], off
	v_lshl_add_u64 v[46:47], v[22:23], 0, v[30:31]
	global_load_dwordx4 v[18:21], v[46:47], off
	v_lshl_add_u64 v[48:49], v[22:23], 0, v[32:33]
	global_load_dwordx4 v[22:25], v[48:49], off
	v_mad_u64_u32 v[34:35], s[4:5], v26, s60, v[198:199]
	s_mov_b64 s[4:5], 0xc6d0080
	s_waitcnt lgkmcnt(0)
	s_barrier
	v_and_b32_e32 v27, 31, v54
	s_add_u32 s16, s16, 0xe420000
	s_addc_u32 s17, s17, 0
	s_waitcnt vmcnt(5)
	ds_write_b128 v34, v[2:5]
	s_waitcnt vmcnt(4)
	ds_write_b128 v34, v[6:9] offset:4608
	s_waitcnt vmcnt(3)
	ds_write_b128 v34, v[10:13] offset:9216
	s_waitcnt vmcnt(2)
	ds_write_b128 v34, v[14:17] offset:13824
	s_waitcnt vmcnt(1)
	ds_write_b128 v34, v[18:21] offset:18432
	s_waitcnt vmcnt(0)
	ds_write_b128 v34, v[22:25] offset:23040
	v_lshl_add_u64 v[14:15], v[28:29], 0, s[4:5]
	v_lshl_add_u64 v[2:3], v[14:15], 0, v[30:31]
	global_load_dwordx4 v[2:5], v[2:3], off
	v_lshl_add_u64 v[6:7], v[14:15], 0, v[32:33]
	global_load_dwordx4 v[6:9], v[6:7], off
	v_lshl_add_u64 v[10:11], v[14:15], 0, v[36:37]
	global_load_dwordx4 v[10:13], v[10:11], off
	v_lshl_add_u64 v[14:15], v[14:15], 0, v[52:53]
	v_lshl_add_u64 v[18:19], s[18:19], 0, v[30:31]
	global_load_dwordx4 v[14:17], v[14:15], off
	v_lshl_add_u64 v[18:19], v[18:19], 0, v[198:199]
	v_lshl_add_u64 v[22:23], s[18:19], 0, v[32:33]
	global_load_dwordx4 v[18:21], v[18:19], off offset:128
	v_lshl_add_u64 v[22:23], v[22:23], 0, v[198:199]
	global_load_dwordx4 v[22:25], v[22:23], off offset:128
	s_waitcnt lgkmcnt(0)
	s_barrier
	v_lshrrev_b32_e32 v28, 1, v54
	v_and_or_b32 v29, v28, s31, v27
	v_and_b32_e32 v26, 16, v28
	v_and_or_b32 v27, v28, 32, v27
	v_mad_u64_u32 v[36:37], s[4:5], v29, s60, v[26:27]
	v_mad_u32_u24 v35, v27, s60, v26
	s_waitcnt vmcnt(5)
	ds_write_b128 v34, v[2:5] offset:27648
	s_waitcnt vmcnt(4)
	ds_write_b128 v34, v[6:9] offset:32256
	s_waitcnt vmcnt(3)
	ds_write_b128 v34, v[10:13] offset:36864
	s_waitcnt vmcnt(2)
	ds_write_b128 v34, v[14:17] offset:41472
	s_waitcnt vmcnt(1)
	ds_write_b128 v34, v[18:21] offset:46080
	s_waitcnt vmcnt(0)
	ds_write_b128 v34, v[22:25] offset:50688
	ds_read_b128 v[96:99], v36 offset:4608
	ds_read_b128 v[104:107], v36
	ds_read_b128 v[108:111], v36 offset:32
	ds_read_b128 v[112:115], v35 offset:18432
	ds_read_b128 v[116:119], v35 offset:18464
	ds_read_b128 v[120:123], v36 offset:4640
	ds_read_b128 v[132:135], v36 offset:64
	ds_read_b128 v[136:139], v36 offset:4672
	ds_read_b128 v[140:143], v35 offset:18496
	ds_read_b128 v[144:147], v36 offset:96
	ds_read_b128 v[148:151], v36 offset:4704
	ds_read_b128 v[152:155], v35 offset:18528
	global_load_dwordx4 v[52:55], v[38:39], off offset:256
	global_load_dwordx4 v[56:59], v[40:41], off offset:256
	global_load_dwordx4 v[60:63], v[42:43], off offset:256
	global_load_dwordx4 v[64:67], v[44:45], off offset:256
	global_load_dwordx4 v[68:71], v[46:47], off offset:256
	global_load_dwordx4 v[72:75], v[48:49], off offset:256
	s_waitcnt lgkmcnt(10)
	s_waitcnt lgkmcnt(8)
	v_mfma_f32_32x32x16_bf16 v[18:33], v[104:107], v[112:115], 0
	v_mfma_f32_32x32x16_bf16 v[2:17], v[96:99], v[112:115], 0
	s_waitcnt lgkmcnt(7)
	v_mfma_f32_32x32x16_bf16 v[18:33], v[108:111], v[116:119], v[18:33]
	s_waitcnt lgkmcnt(6)
	v_mfma_f32_32x32x16_bf16 v[2:17], v[120:123], v[116:119], v[2:17]
	s_waitcnt lgkmcnt(5)
	s_waitcnt lgkmcnt(3)
	v_mfma_f32_32x32x16_bf16 v[18:33], v[132:135], v[140:143], v[18:33]
	v_mfma_f32_32x32x16_bf16 v[2:17], v[136:139], v[140:143], v[2:17]
	s_waitcnt lgkmcnt(0)
	s_barrier
; #define MFMA32(a, b, c) __builtin_amdgcn_mfma_f32_32x32x16_bf16((a), (b), (c), 0, 0, 0)
; #define GEMM_LOADG(kk) { const int ka_ = amode ? (((kk) >> 6) * 96) : (kk); \
;     _Pragma("unroll") for (int i = 0; i < 4; ++i) ra[i] = *(const u32x4*)(A + (size_t)(lr + 32 * i) * lda + ka_ + lk); \
;     _Pragma("unroll") for (int i = 0; i < 2 * NT; ++i) rb[i] = *(const u32x4*)(Bt + (size_t)(lr + 32 * i) * ldb + (kk) + lk); }
; #define GEMM_STORES(buf) { u16* As_ = S + (buf) * TILE; u16* Bs_ = As_ + 128 * LS; \
;     _Pragma("unroll") for (int i = 0; i < 4; ++i) *(u32x4*)(As_ + (lr + 32 * i) * LS + lk) = ra[i]; \
;     _Pragma("unroll") for (int i = 0; i < 2 * NT; ++i) *(u32x4*)(Bs_ + (lr + 32 * i) * LS + lk) = rb[i]; }
; template <int NT>
; DI void gemm_main_np(f32x16 (&acc)[2][NT], const u16* __restrict__ A, int lda, int amode, const u16* __restrict__ Bt,
;                   int ldb, int K, char* smem) {
;     ...
;   for (int k0 = 0; k0 < K; k0 += 64) {
;     const int cur = (k0 >> 6) & 1;
;     if (k0 + 64 < K) {
;       GEMM_STORES(cur ^ 1)
;       if (k0 + 128 < K) GEMM_LOADG(k0 + 128)
;     }
;     const u16* As = S + cur * TILE;
;     const u16* Bs = As + 128 * LS;
; #pragma unroll
;     for (int s = 0; s < 4; ++s) {
;       bf16x8 a[2], b[NT];
; #pragma unroll
;       for (int i = 0; i < 2; ++i) a[i] = *(const bf16x8*)(As + (wm * 64 + i * 32 + l31) * LS + s * 16 + hh * 8);
; #pragma unroll
;       for (int j = 0; j < NT; ++j) b[j] = *(const bf16x8*)(Bs + (wn * 32 * NT + j * 32 + l31) * LS + s * 16 + hh * 8);
; #pragma unroll
;       for (int i = 0; i < 2; ++i)
; #pragma unroll
;         for (int j = 0; j < NT; ++j) acc[i][j] = MFMA32(a[i], b[j], acc[i][j]);
;     }
	s_waitcnt vmcnt(5)
	ds_write_b128 v34, v[52:55]
	s_waitcnt vmcnt(4)
	ds_write_b128 v34, v[56:59] offset:4608
	s_waitcnt vmcnt(3)
	ds_write_b128 v34, v[60:63] offset:9216
	s_waitcnt vmcnt(2)
	ds_write_b128 v34, v[64:67] offset:13824
	s_waitcnt vmcnt(1)
	ds_write_b128 v34, v[68:71] offset:18432
	s_waitcnt vmcnt(0)
	ds_write_b128 v34, v[72:75] offset:23040
	ds_read_b128 v[156:159], v36 offset:32256
	ds_read_b128 v[160:163], v36 offset:27648
	ds_read_b128 v[164:167], v36 offset:27680
	ds_read_b128 v[168:171], v35 offset:46080
	ds_read_b128 v[172:175], v35 offset:46112
	ds_read_b128 v[176:179], v36 offset:32288
	ds_read_b128 v[180:183], v36 offset:27712
	ds_read_b128 v[184:187], v36 offset:32320
	ds_read_b128 v[188:191], v35 offset:46144
	ds_read_b128 v[192:195], v36 offset:27744
	ds_read_b128 v[104:107], v36 offset:32352
	ds_read_b128 v[96:99], v35 offset:46176
	global_load_dwordx4 v[52:55], v[38:39], off offset:384
	global_load_dwordx4 v[56:59], v[40:41], off offset:384
	global_load_dwordx4 v[60:63], v[42:43], off offset:384
	global_load_dwordx4 v[64:67], v[44:45], off offset:384
	global_load_dwordx4 v[68:71], v[46:47], off offset:384
	global_load_dwordx4 v[72:75], v[48:49], off offset:384
	v_mfma_f32_32x32x16_bf16 v[2:17], v[148:151], v[152:155], v[2:17]
	v_mfma_f32_32x32x16_bf16 v[18:33], v[144:147], v[152:155], v[18:33]
	s_waitcnt lgkmcnt(11)
	s_waitcnt lgkmcnt(8)
	v_mfma_f32_32x32x16_bf16 v[2:17], v[156:159], v[168:171], v[2:17]
	v_mfma_f32_32x32x16_bf16 v[18:33], v[160:163], v[168:171], v[18:33]
	s_waitcnt lgkmcnt(7)
	v_mfma_f32_32x32x16_bf16 v[18:33], v[164:167], v[172:175], v[18:33]
	s_waitcnt lgkmcnt(6)
	v_mfma_f32_32x32x16_bf16 v[2:17], v[176:179], v[172:175], v[2:17]
	s_waitcnt lgkmcnt(5)
	s_waitcnt lgkmcnt(3)
	v_mfma_f32_32x32x16_bf16 v[18:33], v[180:183], v[188:191], v[18:33]
	v_mfma_f32_32x32x16_bf16 v[2:17], v[184:187], v[188:191], v[2:17]
	s_waitcnt lgkmcnt(0)
	s_barrier
	s_waitcnt vmcnt(5)
	ds_write_b128 v34, v[52:55] offset:27648
	s_waitcnt vmcnt(4)
	ds_write_b128 v34, v[56:59] offset:32256
	s_waitcnt vmcnt(3)
	ds_write_b128 v34, v[60:63] offset:36864
	s_waitcnt vmcnt(2)
	ds_write_b128 v34, v[64:67] offset:41472
	s_waitcnt vmcnt(1)
	ds_write_b128 v34, v[68:71] offset:46080
	s_waitcnt vmcnt(0)
	ds_write_b128 v34, v[72:75] offset:50688
	ds_read_b128 v[112:115], v36 offset:4608
	ds_read_b128 v[108:111], v36
	ds_read_b128 v[120:123], v36 offset:32
	ds_read_b128 v[116:119], v35 offset:18432
	ds_read_b128 v[132:135], v35 offset:18464
	ds_read_b128 v[136:139], v36 offset:4640
	ds_read_b128 v[140:143], v36 offset:64
	ds_read_b128 v[148:151], v36 offset:4672
	ds_read_b128 v[144:147], v35 offset:18496
	ds_read_b128 v[152:155], v36 offset:96
	ds_read_b128 v[156:159], v36 offset:4704
	ds_read_b128 v[160:163], v35 offset:18528
	global_load_dwordx4 v[52:55], v[38:39], off offset:512
	global_load_dwordx4 v[56:59], v[40:41], off offset:512
	global_load_dwordx4 v[60:63], v[42:43], off offset:512
	global_load_dwordx4 v[64:67], v[44:45], off offset:512
	global_load_dwordx4 v[68:71], v[46:47], off offset:512
	global_load_dwordx4 v[72:75], v[48:49], off offset:512
	v_mfma_f32_32x32x16_bf16 v[2:17], v[104:107], v[96:99], v[2:17]
	v_mfma_f32_32x32x16_bf16 v[18:33], v[192:195], v[96:99], v[18:33]
	s_waitcnt lgkmcnt(11)
	s_waitcnt lgkmcnt(8)
	v_mfma_f32_32x32x16_bf16 v[2:17], v[112:115], v[116:119], v[2:17]
	v_mfma_f32_32x32x16_bf16 v[18:33], v[108:111], v[116:119], v[18:33]
	s_waitcnt lgkmcnt(7)
	v_mfma_f32_32x32x16_bf16 v[18:33], v[120:123], v[132:135], v[18:33]
	s_waitcnt lgkmcnt(6)
	v_mfma_f32_32x32x16_bf16 v[2:17], v[136:139], v[132:135], v[2:17]
	s_waitcnt lgkmcnt(5)
	s_waitcnt lgkmcnt(3)
	v_mfma_f32_32x32x16_bf16 v[18:33], v[140:143], v[144:147], v[18:33]
	v_mfma_f32_32x32x16_bf16 v[2:17], v[148:151], v[144:147], v[2:17]
	s_waitcnt lgkmcnt(0)
	s_barrier
	s_waitcnt vmcnt(5)
	ds_write_b128 v34, v[52:55]
	s_waitcnt vmcnt(4)
	ds_write_b128 v34, v[56:59] offset:4608
	s_waitcnt vmcnt(3)
	ds_write_b128 v34, v[60:63] offset:9216
	s_waitcnt vmcnt(2)
	ds_write_b128 v34, v[64:67] offset:13824
	s_waitcnt vmcnt(1)
	ds_write_b128 v34, v[68:71] offset:18432
	s_waitcnt vmcnt(0)
	ds_write_b128 v34, v[72:75] offset:23040
	ds_read_b128 v[168:171], v36 offset:32256
	ds_read_b128 v[164:167], v36 offset:27648
	ds_read_b128 v[176:179], v36 offset:27680
	ds_read_b128 v[172:175], v35 offset:46080
	ds_read_b128 v[180:183], v35 offset:46112
	ds_read_b128 v[184:187], v36 offset:32288
	ds_read_b128 v[188:191], v36 offset:27712
	ds_read_b128 v[104:107], v36 offset:32320
	ds_read_b128 v[192:195], v35 offset:46144
	ds_read_b128 v[96:99], v36 offset:27744
	ds_read_b128 v[112:115], v36 offset:32352
	ds_read_b128 v[108:111], v35 offset:46176
	global_load_dwordx4 v[52:55], v[38:39], off offset:640
	global_load_dwordx4 v[56:59], v[40:41], off offset:640
	global_load_dwordx4 v[60:63], v[42:43], off offset:640
	global_load_dwordx4 v[64:67], v[44:45], off offset:640
	global_load_dwordx4 v[68:71], v[46:47], off offset:640
	global_load_dwordx4 v[72:75], v[48:49], off offset:640
	v_mfma_f32_32x32x16_bf16 v[2:17], v[156:159], v[160:163], v[2:17]
	v_mfma_f32_32x32x16_bf16 v[18:33], v[152:155], v[160:163], v[18:33]
	s_waitcnt lgkmcnt(11)
	s_waitcnt lgkmcnt(8)
	v_mfma_f32_32x32x16_bf16 v[2:17], v[168:171], v[172:175], v[2:17]
	v_mfma_f32_32x32x16_bf16 v[18:33], v[164:167], v[172:175], v[18:33]
	s_waitcnt lgkmcnt(7)
	v_mfma_f32_32x32x16_bf16 v[18:33], v[176:179], v[180:183], v[18:33]
	s_waitcnt lgkmcnt(6)
	v_mfma_f32_32x32x16_bf16 v[2:17], v[184:187], v[180:183], v[2:17]
	s_waitcnt lgkmcnt(5)
	s_waitcnt lgkmcnt(3)
	v_mfma_f32_32x32x16_bf16 v[18:33], v[188:191], v[192:195], v[18:33]
	v_mfma_f32_32x32x16_bf16 v[2:17], v[104:107], v[192:195], v[2:17]
	s_waitcnt lgkmcnt(0)
	s_barrier
; #define MFMA32(a, b, c) __builtin_amdgcn_mfma_f32_32x32x16_bf16((a), (b), (c), 0, 0, 0)
; #define GEMM_LOADG(kk) { const int ka_ = amode ? (((kk) >> 6) * 96) : (kk); \
;     _Pragma("unroll") for (int i = 0; i < 4; ++i) ra[i] = *(const u32x4*)(A + (size_t)(lr + 32 * i) * lda + ka_ + lk); \
;     _Pragma("unroll") for (int i = 0; i < 2 * NT; ++i) rb[i] = *(const u32x4*)(Bt + (size_t)(lr + 32 * i) * ldb + (kk) + lk); }
; #define GEMM_STORES(buf) { u16* As_ = S + (buf) * TILE; u16* Bs_ = As_ + 128 * LS; \
;     _Pragma("unroll") for (int i = 0; i < 4; ++i) *(u32x4*)(As_ + (lr + 32 * i) * LS + lk) = ra[i]; \
;     _Pragma("unroll") for (int i = 0; i < 2 * NT; ++i) *(u32x4*)(Bs_ + (lr + 32 * i) * LS + lk) = rb[i]; }
; template <int NT>
; DI void gemm_main_np(f32x16 (&acc)[2][NT], const u16* __restrict__ A, int lda, int amode, const u16* __restrict__ Bt,
;                   int ldb, int K, char* smem) {
;     ...
;   for (int k0 = 0; k0 < K; k0 += 64) {
;     const int cur = (k0 >> 6) & 1;
;     if (k0 + 64 < K) {
;       GEMM_STORES(cur ^ 1)
;       if (k0 + 128 < K) GEMM_LOADG(k0 + 128)
;     }
;     const u16* As = S + cur * TILE;
;     const u16* Bs = As + 128 * LS;
; #pragma unroll
;     for (int s = 0; s < 4; ++s) {
;       bf16x8 a[2], b[NT];
; #pragma unroll
;       for (int i = 0; i < 2; ++i) a[i] = *(const bf16x8*)(As + (wm * 64 + i * 32 + l31) * LS + s * 16 + hh * 8);
; #pragma unroll
;       for (int j = 0; j < NT; ++j) b[j] = *(const bf16x8*)(Bs + (wn * 32 * NT + j * 32 + l31) * LS + s * 16 + hh * 8);
; #pragma unroll
;       for (int i = 0; i < 2; ++i)
; #pragma unroll
;         for (int j = 0; j < NT; ++j) acc[i][j] = MFMA32(a[i], b[j], acc[i][j]);
;     }
	s_waitcnt vmcnt(5)
	ds_write_b128 v34, v[52:55] offset:27648
	s_waitcnt vmcnt(4)
	ds_write_b128 v34, v[56:59] offset:32256
	s_waitcnt vmcnt(3)
	ds_write_b128 v34, v[60:63] offset:36864
	s_waitcnt vmcnt(2)
	ds_write_b128 v34, v[64:67] offset:41472
	s_waitcnt vmcnt(1)
	ds_write_b128 v34, v[68:71] offset:46080
	s_waitcnt vmcnt(0)
	ds_write_b128 v34, v[72:75] offset:50688
	ds_read_b128 v[116:119], v36 offset:4608
	ds_read_b128 v[120:123], v36
	ds_read_b128 v[136:139], v36 offset:32
	ds_read_b128 v[132:135], v35 offset:18432
	ds_read_b128 v[140:143], v35 offset:18464
	ds_read_b128 v[148:151], v36 offset:4640
	ds_read_b128 v[144:147], v36 offset:64
	ds_read_b128 v[156:159], v36 offset:4672
	ds_read_b128 v[152:155], v35 offset:18496
	ds_read_b128 v[160:163], v36 offset:96
	ds_read_b128 v[168:171], v36 offset:4704
	ds_read_b128 v[164:167], v35 offset:18528
	global_load_dwordx4 v[52:55], v[38:39], off offset:768
	global_load_dwordx4 v[56:59], v[40:41], off offset:768
	global_load_dwordx4 v[60:63], v[42:43], off offset:768
	global_load_dwordx4 v[64:67], v[44:45], off offset:768
	global_load_dwordx4 v[68:71], v[46:47], off offset:768
	global_load_dwordx4 v[72:75], v[48:49], off offset:768
	v_mfma_f32_32x32x16_bf16 v[2:17], v[112:115], v[108:111], v[2:17]
	v_mfma_f32_32x32x16_bf16 v[18:33], v[96:99], v[108:111], v[18:33]
	s_waitcnt lgkmcnt(11)
	s_waitcnt lgkmcnt(8)
	v_mfma_f32_32x32x16_bf16 v[2:17], v[116:119], v[132:135], v[2:17]
	v_mfma_f32_32x32x16_bf16 v[18:33], v[120:123], v[132:135], v[18:33]
	s_waitcnt lgkmcnt(7)
	v_mfma_f32_32x32x16_bf16 v[18:33], v[136:139], v[140:143], v[18:33]
	s_waitcnt lgkmcnt(6)
	v_mfma_f32_32x32x16_bf16 v[2:17], v[148:151], v[140:143], v[2:17]
	s_waitcnt lgkmcnt(5)
	s_waitcnt lgkmcnt(3)
	v_mfma_f32_32x32x16_bf16 v[18:33], v[144:147], v[152:155], v[18:33]
	v_mfma_f32_32x32x16_bf16 v[2:17], v[156:159], v[152:155], v[2:17]
	s_waitcnt lgkmcnt(0)
	s_barrier
	s_waitcnt vmcnt(5)
	ds_write_b128 v34, v[52:55]
	s_waitcnt vmcnt(4)
	ds_write_b128 v34, v[56:59] offset:4608
	s_waitcnt vmcnt(3)
	ds_write_b128 v34, v[60:63] offset:9216
	s_waitcnt vmcnt(2)
	ds_write_b128 v34, v[64:67] offset:13824
	s_waitcnt vmcnt(1)
	ds_write_b128 v34, v[68:71] offset:18432
	s_waitcnt vmcnt(0)
	ds_write_b128 v34, v[72:75] offset:23040
	ds_read_b128 v[172:175], v36 offset:32256
	ds_read_b128 v[176:179], v36 offset:27648
	ds_read_b128 v[184:187], v36 offset:27680
	ds_read_b128 v[180:183], v35 offset:46080
	ds_read_b128 v[188:191], v35 offset:46112
	ds_read_b128 v[104:107], v36 offset:32288
	ds_read_b128 v[192:195], v36 offset:27712
	ds_read_b128 v[112:115], v36 offset:32320
	ds_read_b128 v[96:99], v35 offset:46144
	ds_read_b128 v[108:111], v36 offset:27744
	ds_read_b128 v[116:119], v36 offset:32352
	ds_read_b128 v[120:123], v35 offset:46176
	global_load_dwordx4 v[52:55], v[38:39], off offset:896
	global_load_dwordx4 v[56:59], v[40:41], off offset:896
	global_load_dwordx4 v[60:63], v[42:43], off offset:896
	global_load_dwordx4 v[64:67], v[44:45], off offset:896
	global_load_dwordx4 v[68:71], v[46:47], off offset:896
	global_load_dwordx4 v[72:75], v[48:49], off offset:896
	v_mfma_f32_32x32x16_bf16 v[2:17], v[168:171], v[164:167], v[2:17]
	v_mfma_f32_32x32x16_bf16 v[18:33], v[160:163], v[164:167], v[18:33]
	s_waitcnt lgkmcnt(11)
	s_waitcnt lgkmcnt(8)
	v_mfma_f32_32x32x16_bf16 v[2:17], v[172:175], v[180:183], v[2:17]
	v_mfma_f32_32x32x16_bf16 v[18:33], v[176:179], v[180:183], v[18:33]
	s_waitcnt lgkmcnt(7)
	v_mfma_f32_32x32x16_bf16 v[18:33], v[184:187], v[188:191], v[18:33]
	s_waitcnt lgkmcnt(6)
	v_mfma_f32_32x32x16_bf16 v[2:17], v[104:107], v[188:191], v[2:17]
	s_waitcnt lgkmcnt(5)
	s_waitcnt lgkmcnt(3)
	v_mfma_f32_32x32x16_bf16 v[18:33], v[192:195], v[96:99], v[18:33]
	v_mfma_f32_32x32x16_bf16 v[2:17], v[112:115], v[96:99], v[2:17]
	s_waitcnt lgkmcnt(0)
	s_barrier
	s_waitcnt vmcnt(5)
	ds_write_b128 v34, v[52:55] offset:27648
	s_waitcnt vmcnt(4)
	ds_write_b128 v34, v[56:59] offset:32256
	s_waitcnt vmcnt(3)
	ds_write_b128 v34, v[60:63] offset:36864
	s_waitcnt vmcnt(2)
	ds_write_b128 v34, v[64:67] offset:41472
	s_waitcnt vmcnt(1)
	ds_write_b128 v34, v[68:71] offset:46080
	s_waitcnt vmcnt(0)
	ds_write_b128 v34, v[72:75] offset:50688
	ds_read_b128 v[132:135], v36 offset:4608
	ds_read_b128 v[136:139], v36
	ds_read_b128 v[148:151], v36 offset:32
	ds_read_b128 v[140:143], v35 offset:18432
	ds_read_b128 v[144:147], v35 offset:18464
	ds_read_b128 v[156:159], v36 offset:4640
	ds_read_b128 v[152:155], v36 offset:64
	ds_read_b128 v[168:171], v36 offset:4672
	ds_read_b128 v[160:163], v35 offset:18496
	ds_read_b128 v[164:167], v36 offset:96
	ds_read_b128 v[172:175], v36 offset:4704
	ds_read_b128 v[176:179], v35 offset:18528
	global_load_dwordx4 v[52:55], v[38:39], off offset:1024
	global_load_dwordx4 v[56:59], v[40:41], off offset:1024
	global_load_dwordx4 v[60:63], v[42:43], off offset:1024
	global_load_dwordx4 v[64:67], v[44:45], off offset:1024
	global_load_dwordx4 v[68:71], v[46:47], off offset:1024
	global_load_dwordx4 v[72:75], v[48:49], off offset:1024
	v_mfma_f32_32x32x16_bf16 v[2:17], v[116:119], v[120:123], v[2:17]
	v_mfma_f32_32x32x16_bf16 v[18:33], v[108:111], v[120:123], v[18:33]
	s_waitcnt lgkmcnt(11)
	s_waitcnt lgkmcnt(8)
	v_mfma_f32_32x32x16_bf16 v[2:17], v[132:135], v[140:143], v[2:17]
	v_mfma_f32_32x32x16_bf16 v[18:33], v[136:139], v[140:143], v[18:33]
	s_waitcnt lgkmcnt(7)
	v_mfma_f32_32x32x16_bf16 v[18:33], v[148:151], v[144:147], v[18:33]
	s_waitcnt lgkmcnt(6)
	v_mfma_f32_32x32x16_bf16 v[2:17], v[156:159], v[144:147], v[2:17]
	s_waitcnt lgkmcnt(5)
	s_waitcnt lgkmcnt(3)
	v_mfma_f32_32x32x16_bf16 v[18:33], v[152:155], v[160:163], v[18:33]
	v_mfma_f32_32x32x16_bf16 v[2:17], v[168:171], v[160:163], v[2:17]
	s_waitcnt lgkmcnt(0)
	s_barrier
; #define MFMA32(a, b, c) __builtin_amdgcn_mfma_f32_32x32x16_bf16((a), (b), (c), 0, 0, 0)
; #define GEMM_LOADG(kk) { const int ka_ = amode ? (((kk) >> 6) * 96) : (kk); \
;     _Pragma("unroll") for (int i = 0; i < 4; ++i) ra[i] = *(const u32x4*)(A + (size_t)(lr + 32 * i) * lda + ka_ + lk); \
;     _Pragma("unroll") for (int i = 0; i < 2 * NT; ++i) rb[i] = *(const u32x4*)(Bt + (size_t)(lr + 32 * i) * ldb + (kk) + lk); }
; #define GEMM_STORES(buf) { u16* As_ = S + (buf) * TILE; u16* Bs_ = As_ + 128 * LS; \
;     _Pragma("unroll") for (int i = 0; i < 4; ++i) *(u32x4*)(As_ + (lr + 32 * i) * LS + lk) = ra[i]; \
;     _Pragma("unroll") for (int i = 0; i < 2 * NT; ++i) *(u32x4*)(Bs_ + (lr + 32 * i) * LS + lk) = rb[i]; }
; template <int NT>
; DI void gemm_main_np(f32x16 (&acc)[2][NT], const u16* __restrict__ A, int lda, int amode, const u16* __restrict__ Bt,
;                   int ldb, int K, char* smem) {
;     ...
;   for (int k0 = 0; k0 < K; k0 += 64) {
;     const int cur = (k0 >> 6) & 1;
;     if (k0 + 64 < K) {
;       GEMM_STORES(cur ^ 1)
;       if (k0 + 128 < K) GEMM_LOADG(k0 + 128)
;     }
;     const u16* As = S + cur * TILE;
;     const u16* Bs = As + 128 * LS;
; #pragma unroll
;     for (int s = 0; s < 4; ++s) {
;       bf16x8 a[2], b[NT];
; #pragma unroll
;       for (int i = 0; i < 2; ++i) a[i] = *(const bf16x8*)(As + (wm * 64 + i * 32 + l31) * LS + s * 16 + hh * 8);
; #pragma unroll
;       for (int j = 0; j < NT; ++j) b[j] = *(const bf16x8*)(Bs + (wn * 32 * NT + j * 32 + l31) * LS + s * 16 + hh * 8);
; #pragma unroll
;       for (int i = 0; i < 2; ++i)
; #pragma unroll
;         for (int j = 0; j < NT; ++j) acc[i][j] = MFMA32(a[i], b[j], acc[i][j]);
;     }
	s_waitcnt vmcnt(5)
	ds_write_b128 v34, v[52:55]
	s_waitcnt vmcnt(4)
	ds_write_b128 v34, v[56:59] offset:4608
	s_waitcnt vmcnt(3)
	ds_write_b128 v34, v[60:63] offset:9216
	s_waitcnt vmcnt(2)
	ds_write_b128 v34, v[64:67] offset:13824
	s_waitcnt vmcnt(1)
	ds_write_b128 v34, v[68:71] offset:18432
	s_waitcnt vmcnt(0)
	ds_write_b128 v34, v[72:75] offset:23040
	ds_read_b128 v[180:183], v36 offset:32256
	ds_read_b128 v[184:187], v36 offset:27648
	ds_read_b128 v[104:107], v36 offset:27680
	ds_read_b128 v[188:191], v35 offset:46080
	ds_read_b128 v[192:195], v35 offset:46112
	ds_read_b128 v[112:115], v36 offset:32288
	ds_read_b128 v[96:99], v36 offset:27712
	ds_read_b128 v[116:119], v36 offset:32320
	ds_read_b128 v[108:111], v35 offset:46144
	ds_read_b128 v[120:123], v36 offset:27744
	ds_read_b128 v[132:135], v36 offset:32352
	ds_read_b128 v[136:139], v35 offset:46176
	global_load_dwordx4 v[52:55], v[38:39], off offset:1152
	global_load_dwordx4 v[56:59], v[40:41], off offset:1152
	global_load_dwordx4 v[60:63], v[42:43], off offset:1152
	global_load_dwordx4 v[64:67], v[44:45], off offset:1152
	global_load_dwordx4 v[68:71], v[46:47], off offset:1152
	global_load_dwordx4 v[72:75], v[48:49], off offset:1152
	v_mfma_f32_32x32x16_bf16 v[2:17], v[172:175], v[176:179], v[2:17]
	v_mfma_f32_32x32x16_bf16 v[18:33], v[164:167], v[176:179], v[18:33]
	s_waitcnt lgkmcnt(11)
	s_waitcnt lgkmcnt(8)
	v_mfma_f32_32x32x16_bf16 v[2:17], v[180:183], v[188:191], v[2:17]
	v_mfma_f32_32x32x16_bf16 v[18:33], v[184:187], v[188:191], v[18:33]
	s_waitcnt lgkmcnt(7)
	v_mfma_f32_32x32x16_bf16 v[18:33], v[104:107], v[192:195], v[18:33]
	s_waitcnt lgkmcnt(6)
	v_mfma_f32_32x32x16_bf16 v[2:17], v[112:115], v[192:195], v[2:17]
	s_waitcnt lgkmcnt(5)
	s_waitcnt lgkmcnt(3)
	v_mfma_f32_32x32x16_bf16 v[18:33], v[96:99], v[108:111], v[18:33]
	v_mfma_f32_32x32x16_bf16 v[2:17], v[116:119], v[108:111], v[2:17]
	s_waitcnt lgkmcnt(0)
	s_barrier
	s_waitcnt vmcnt(5)
	ds_write_b128 v34, v[52:55] offset:27648
	s_waitcnt vmcnt(4)
	ds_write_b128 v34, v[56:59] offset:32256
	s_waitcnt vmcnt(3)
	ds_write_b128 v34, v[60:63] offset:36864
	s_waitcnt vmcnt(2)
	ds_write_b128 v34, v[64:67] offset:41472
	s_waitcnt vmcnt(1)
	ds_write_b128 v34, v[68:71] offset:46080
	s_waitcnt vmcnt(0)
	ds_write_b128 v34, v[72:75] offset:50688
	ds_read_b128 v[140:143], v36 offset:4608
	ds_read_b128 v[148:151], v36
	ds_read_b128 v[156:159], v36 offset:32
	ds_read_b128 v[144:147], v35 offset:18432
	ds_read_b128 v[152:155], v35 offset:18464
	ds_read_b128 v[168:171], v36 offset:4640
	ds_read_b128 v[160:163], v36 offset:64
	ds_read_b128 v[172:175], v36 offset:4672
	ds_read_b128 v[164:167], v35 offset:18496
	ds_read_b128 v[176:179], v36 offset:96
	ds_read_b128 v[180:183], v36 offset:4704
	ds_read_b128 v[184:187], v35 offset:18528
	global_load_dwordx4 v[52:55], v[38:39], off offset:1280
	global_load_dwordx4 v[56:59], v[40:41], off offset:1280
	global_load_dwordx4 v[60:63], v[42:43], off offset:1280
	global_load_dwordx4 v[64:67], v[44:45], off offset:1280
	global_load_dwordx4 v[68:71], v[46:47], off offset:1280
	global_load_dwordx4 v[72:75], v[48:49], off offset:1280
	v_mfma_f32_32x32x16_bf16 v[2:17], v[132:135], v[136:139], v[2:17]
	v_mfma_f32_32x32x16_bf16 v[18:33], v[120:123], v[136:139], v[18:33]
	s_waitcnt lgkmcnt(11)
	s_waitcnt lgkmcnt(8)
	v_mfma_f32_32x32x16_bf16 v[2:17], v[140:143], v[144:147], v[2:17]
	v_mfma_f32_32x32x16_bf16 v[18:33], v[148:151], v[144:147], v[18:33]
	s_waitcnt lgkmcnt(7)
	v_mfma_f32_32x32x16_bf16 v[18:33], v[156:159], v[152:155], v[18:33]
	s_waitcnt lgkmcnt(6)
	v_mfma_f32_32x32x16_bf16 v[2:17], v[168:171], v[152:155], v[2:17]
	s_waitcnt lgkmcnt(5)
	s_waitcnt lgkmcnt(3)
	v_mfma_f32_32x32x16_bf16 v[18:33], v[160:163], v[164:167], v[18:33]
	v_mfma_f32_32x32x16_bf16 v[2:17], v[172:175], v[164:167], v[2:17]
	s_waitcnt lgkmcnt(0)
	s_barrier
	s_waitcnt vmcnt(5)
	ds_write_b128 v34, v[52:55]
	s_waitcnt vmcnt(4)
	ds_write_b128 v34, v[56:59] offset:4608
	s_waitcnt vmcnt(3)
	ds_write_b128 v34, v[60:63] offset:9216
	s_waitcnt vmcnt(2)
	ds_write_b128 v34, v[64:67] offset:13824
	s_waitcnt vmcnt(1)
	ds_write_b128 v34, v[68:71] offset:18432
	s_waitcnt vmcnt(0)
	ds_write_b128 v34, v[72:75] offset:23040
	ds_read_b128 v[188:191], v36 offset:32256
	ds_read_b128 v[104:107], v36 offset:27648
	ds_read_b128 v[112:115], v36 offset:27680
	ds_read_b128 v[192:195], v35 offset:46080
	ds_read_b128 v[96:99], v35 offset:46112
	ds_read_b128 v[116:119], v36 offset:32288
	ds_read_b128 v[108:111], v36 offset:27712
	ds_read_b128 v[132:135], v36 offset:32320
	ds_read_b128 v[120:123], v35 offset:46144
	ds_read_b128 v[136:139], v36 offset:27744
	ds_read_b128 v[140:143], v36 offset:32352
	ds_read_b128 v[148:151], v35 offset:46176
	global_load_dwordx4 v[52:55], v[38:39], off offset:1408
	global_load_dwordx4 v[56:59], v[40:41], off offset:1408
	global_load_dwordx4 v[60:63], v[42:43], off offset:1408
	global_load_dwordx4 v[64:67], v[44:45], off offset:1408
	global_load_dwordx4 v[68:71], v[46:47], off offset:1408
	global_load_dwordx4 v[72:75], v[48:49], off offset:1408
	v_mfma_f32_32x32x16_bf16 v[2:17], v[180:183], v[184:187], v[2:17]
	v_mfma_f32_32x32x16_bf16 v[18:33], v[176:179], v[184:187], v[18:33]
	s_waitcnt lgkmcnt(11)
	s_waitcnt lgkmcnt(8)
	v_mfma_f32_32x32x16_bf16 v[2:17], v[188:191], v[192:195], v[2:17]
	v_mfma_f32_32x32x16_bf16 v[18:33], v[104:107], v[192:195], v[18:33]
	s_waitcnt lgkmcnt(7)
	v_mfma_f32_32x32x16_bf16 v[18:33], v[112:115], v[96:99], v[18:33]
	s_waitcnt lgkmcnt(6)
	v_mfma_f32_32x32x16_bf16 v[2:17], v[116:119], v[96:99], v[2:17]
	s_waitcnt lgkmcnt(5)
	s_waitcnt lgkmcnt(3)
	v_mfma_f32_32x32x16_bf16 v[18:33], v[108:111], v[120:123], v[18:33]
	v_mfma_f32_32x32x16_bf16 v[2:17], v[132:135], v[120:123], v[2:17]
	s_waitcnt lgkmcnt(0)
	s_barrier
; #define MFMA32(a, b, c) __builtin_amdgcn_mfma_f32_32x32x16_bf16((a), (b), (c), 0, 0, 0)
; #define GEMM_LOADG(kk) { const int ka_ = amode ? (((kk) >> 6) * 96) : (kk); \
;     _Pragma("unroll") for (int i = 0; i < 4; ++i) ra[i] = *(const u32x4*)(A + (size_t)(lr + 32 * i) * lda + ka_ + lk); \
;     _Pragma("unroll") for (int i = 0; i < 2 * NT; ++i) rb[i] = *(const u32x4*)(Bt + (size_t)(lr + 32 * i) * ldb + (kk) + lk); }
; #define GEMM_STORES(buf) { u16* As_ = S + (buf) * TILE; u16* Bs_ = As_ + 128 * LS; \
;     _Pragma("unroll") for (int i = 0; i < 4; ++i) *(u32x4*)(As_ + (lr + 32 * i) * LS + lk) = ra[i]; \
;     _Pragma("unroll") for (int i = 0; i < 2 * NT; ++i) *(u32x4*)(Bs_ + (lr + 32 * i) * LS + lk) = rb[i]; }
; template <int NT>
; DI void gemm_main_np(f32x16 (&acc)[2][NT], const u16* __restrict__ A, int lda, int amode, const u16* __restrict__ Bt,
;                   int ldb, int K, char* smem) {
;     ...
;   for (int k0 = 0; k0 < K; k0 += 64) {
;     const int cur = (k0 >> 6) & 1;
;     if (k0 + 64 < K) {
;       GEMM_STORES(cur ^ 1)
;       if (k0 + 128 < K) GEMM_LOADG(k0 + 128)
;     }
;     const u16* As = S + cur * TILE;
;     const u16* Bs = As + 128 * LS;
; #pragma unroll
;     for (int s = 0; s < 4; ++s) {
;       bf16x8 a[2], b[NT];
; #pragma unroll
;       for (int i = 0; i < 2; ++i) a[i] = *(const bf16x8*)(As + (wm * 64 + i * 32 + l31) * LS + s * 16 + hh * 8);
; #pragma unroll
;       for (int j = 0; j < NT; ++j) b[j] = *(const bf16x8*)(Bs + (wn * 32 * NT + j * 32 + l31) * LS + s * 16 + hh * 8);
; #pragma unroll
;       for (int i = 0; i < 2; ++i)
; #pragma unroll
;         for (int j = 0; j < NT; ++j) acc[i][j] = MFMA32(a[i], b[j], acc[i][j]);
;     }
	s_waitcnt vmcnt(5)
	ds_write_b128 v34, v[52:55] offset:27648
	s_waitcnt vmcnt(4)
	ds_write_b128 v34, v[56:59] offset:32256
	s_waitcnt vmcnt(3)
	ds_write_b128 v34, v[60:63] offset:36864
	s_waitcnt vmcnt(2)
	ds_write_b128 v34, v[64:67] offset:41472
	s_waitcnt vmcnt(1)
	ds_write_b128 v34, v[68:71] offset:46080
	s_waitcnt vmcnt(0)
	ds_write_b128 v34, v[72:75] offset:50688
	ds_read_b128 v[144:147], v36 offset:4608
	ds_read_b128 v[156:159], v36
	ds_read_b128 v[168:171], v36 offset:32
	ds_read_b128 v[152:155], v35 offset:18432
	ds_read_b128 v[160:163], v35 offset:18464
	ds_read_b128 v[172:175], v36 offset:4640
	ds_read_b128 v[164:167], v36 offset:64
	ds_read_b128 v[180:183], v36 offset:4672
	ds_read_b128 v[176:179], v35 offset:18496
	ds_read_b128 v[184:187], v36 offset:96
	ds_read_b128 v[188:191], v36 offset:4704
	ds_read_b128 v[104:107], v35 offset:18528
	global_load_dwordx4 v[52:55], v[38:39], off offset:1536
	global_load_dwordx4 v[56:59], v[40:41], off offset:1536
	global_load_dwordx4 v[60:63], v[42:43], off offset:1536
	global_load_dwordx4 v[64:67], v[44:45], off offset:1536
	global_load_dwordx4 v[68:71], v[46:47], off offset:1536
	global_load_dwordx4 v[72:75], v[48:49], off offset:1536
	v_mfma_f32_32x32x16_bf16 v[2:17], v[140:143], v[148:151], v[2:17]
	v_mfma_f32_32x32x16_bf16 v[18:33], v[136:139], v[148:151], v[18:33]
	s_waitcnt lgkmcnt(11)
	s_waitcnt lgkmcnt(8)
	v_mfma_f32_32x32x16_bf16 v[2:17], v[144:147], v[152:155], v[2:17]
	v_mfma_f32_32x32x16_bf16 v[18:33], v[156:159], v[152:155], v[18:33]
	s_waitcnt lgkmcnt(7)
	v_mfma_f32_32x32x16_bf16 v[18:33], v[168:171], v[160:163], v[18:33]
	s_waitcnt lgkmcnt(6)
	v_mfma_f32_32x32x16_bf16 v[2:17], v[172:175], v[160:163], v[2:17]
	s_waitcnt lgkmcnt(5)
	s_waitcnt lgkmcnt(3)
	v_mfma_f32_32x32x16_bf16 v[18:33], v[164:167], v[176:179], v[18:33]
	v_mfma_f32_32x32x16_bf16 v[2:17], v[180:183], v[176:179], v[2:17]
	s_waitcnt lgkmcnt(0)
	s_barrier
	s_waitcnt vmcnt(5)
	ds_write_b128 v34, v[52:55]
	s_waitcnt vmcnt(4)
	ds_write_b128 v34, v[56:59] offset:4608
	s_waitcnt vmcnt(3)
	ds_write_b128 v34, v[60:63] offset:9216
	s_waitcnt vmcnt(2)
	ds_write_b128 v34, v[64:67] offset:13824
	s_waitcnt vmcnt(1)
	ds_write_b128 v34, v[68:71] offset:18432
	s_waitcnt vmcnt(0)
	ds_write_b128 v34, v[72:75] offset:23040
	ds_read_b128 v[192:195], v36 offset:32256
	ds_read_b128 v[112:115], v36 offset:27648
	ds_read_b128 v[116:119], v36 offset:27680
	ds_read_b128 v[96:99], v35 offset:46080
	ds_read_b128 v[108:111], v35 offset:46112
	ds_read_b128 v[132:135], v36 offset:32288
	ds_read_b128 v[120:123], v36 offset:27712
	ds_read_b128 v[140:143], v36 offset:32320
	ds_read_b128 v[136:139], v35 offset:46144
	ds_read_b128 v[148:151], v36 offset:27744
	ds_read_b128 v[144:147], v36 offset:32352
	ds_read_b128 v[156:159], v35 offset:46176
	global_load_dwordx4 v[52:55], v[38:39], off offset:1664
	global_load_dwordx4 v[56:59], v[40:41], off offset:1664
	global_load_dwordx4 v[60:63], v[42:43], off offset:1664
	global_load_dwordx4 v[64:67], v[44:45], off offset:1664
	global_load_dwordx4 v[68:71], v[46:47], off offset:1664
	global_load_dwordx4 v[72:75], v[48:49], off offset:1664
	v_mfma_f32_32x32x16_bf16 v[2:17], v[188:191], v[104:107], v[2:17]
	v_mfma_f32_32x32x16_bf16 v[18:33], v[184:187], v[104:107], v[18:33]
	s_waitcnt lgkmcnt(11)
	s_waitcnt lgkmcnt(8)
	v_mfma_f32_32x32x16_bf16 v[2:17], v[192:195], v[96:99], v[2:17]
	v_mfma_f32_32x32x16_bf16 v[18:33], v[112:115], v[96:99], v[18:33]
	s_waitcnt lgkmcnt(7)
	v_mfma_f32_32x32x16_bf16 v[18:33], v[116:119], v[108:111], v[18:33]
	s_waitcnt lgkmcnt(6)
	v_mfma_f32_32x32x16_bf16 v[2:17], v[132:135], v[108:111], v[2:17]
	s_waitcnt lgkmcnt(5)
	s_waitcnt lgkmcnt(3)
	v_mfma_f32_32x32x16_bf16 v[18:33], v[120:123], v[136:139], v[18:33]
	v_mfma_f32_32x32x16_bf16 v[2:17], v[140:143], v[136:139], v[2:17]
	s_waitcnt lgkmcnt(0)
	s_barrier
	s_waitcnt vmcnt(5)
	ds_write_b128 v34, v[52:55] offset:27648
	s_waitcnt vmcnt(4)
	ds_write_b128 v34, v[56:59] offset:32256
	s_waitcnt vmcnt(3)
	ds_write_b128 v34, v[60:63] offset:36864
	s_waitcnt vmcnt(2)
	ds_write_b128 v34, v[64:67] offset:41472
	s_waitcnt vmcnt(1)
	ds_write_b128 v34, v[68:71] offset:46080
	s_waitcnt vmcnt(0)
	ds_write_b128 v34, v[72:75] offset:50688
	ds_read_b128 v[152:155], v36 offset:4608
	ds_read_b128 v[168:171], v36
	ds_read_b128 v[172:175], v36 offset:32
	ds_read_b128 v[160:163], v35 offset:18432
	ds_read_b128 v[164:167], v35 offset:18464
	ds_read_b128 v[180:183], v36 offset:4640
	ds_read_b128 v[176:179], v36 offset:64
	ds_read_b128 v[188:191], v36 offset:4672
	ds_read_b128 v[184:187], v35 offset:18496
	ds_read_b128 v[104:107], v36 offset:96
	ds_read_b128 v[192:195], v36 offset:4704
	ds_read_b128 v[112:115], v35 offset:18528
	global_load_dwordx4 v[52:55], v[38:39], off offset:1792
	global_load_dwordx4 v[56:59], v[40:41], off offset:1792
	global_load_dwordx4 v[60:63], v[42:43], off offset:1792
	global_load_dwordx4 v[64:67], v[44:45], off offset:1792
	global_load_dwordx4 v[68:71], v[46:47], off offset:1792
	global_load_dwordx4 v[72:75], v[48:49], off offset:1792
	v_mfma_f32_32x32x16_bf16 v[2:17], v[144:147], v[156:159], v[2:17]
	v_mfma_f32_32x32x16_bf16 v[18:33], v[148:151], v[156:159], v[18:33]
	s_waitcnt lgkmcnt(11)
	s_waitcnt lgkmcnt(8)
	v_mfma_f32_32x32x16_bf16 v[2:17], v[152:155], v[160:163], v[2:17]
	v_mfma_f32_32x32x16_bf16 v[18:33], v[168:171], v[160:163], v[18:33]
	s_waitcnt lgkmcnt(7)
	v_mfma_f32_32x32x16_bf16 v[18:33], v[172:175], v[164:167], v[18:33]
	s_waitcnt lgkmcnt(6)
	v_mfma_f32_32x32x16_bf16 v[2:17], v[180:183], v[164:167], v[2:17]
	s_waitcnt lgkmcnt(5)
	s_waitcnt lgkmcnt(3)
	v_mfma_f32_32x32x16_bf16 v[18:33], v[176:179], v[184:187], v[18:33]
	v_mfma_f32_32x32x16_bf16 v[2:17], v[188:191], v[184:187], v[2:17]
	s_waitcnt lgkmcnt(0)
	s_barrier
; #define MFMA32(a, b, c) __builtin_amdgcn_mfma_f32_32x32x16_bf16((a), (b), (c), 0, 0, 0)
; #define GEMM_LOADG(kk) { const int ka_ = amode ? (((kk) >> 6) * 96) : (kk); \
;     _Pragma("unroll") for (int i = 0; i < 4; ++i) ra[i] = *(const u32x4*)(A + (size_t)(lr + 32 * i) * lda + ka_ + lk); \
;     _Pragma("unroll") for (int i = 0; i < 2 * NT; ++i) rb[i] = *(const u32x4*)(Bt + (size_t)(lr + 32 * i) * ldb + (kk) + lk); }
; #define GEMM_STORES(buf) { u16* As_ = S + (buf) * TILE; u16* Bs_ = As_ + 128 * LS; \
;     _Pragma("unroll") for (int i = 0; i < 4; ++i) *(u32x4*)(As_ + (lr + 32 * i) * LS + lk) = ra[i]; \
;     _Pragma("unroll") for (int i = 0; i < 2 * NT; ++i) *(u32x4*)(Bs_ + (lr + 32 * i) * LS + lk) = rb[i]; }
; template <int NT>
; DI void gemm_main_np(f32x16 (&acc)[2][NT], const u16* __restrict__ A, int lda, int amode, const u16* __restrict__ Bt,
;                   int ldb, int K, char* smem) {
;     ...
;   for (int k0 = 0; k0 < K; k0 += 64) {
;     const int cur = (k0 >> 6) & 1;
;     if (k0 + 64 < K) {
;       GEMM_STORES(cur ^ 1)
;       if (k0 + 128 < K) GEMM_LOADG(k0 + 128)
;     }
;     const u16* As = S + cur * TILE;
;     const u16* Bs = As + 128 * LS;
; #pragma unroll
;     for (int s = 0; s < 4; ++s) {
;       bf16x8 a[2], b[NT];
; #pragma unroll
;       for (int i = 0; i < 2; ++i) a[i] = *(const bf16x8*)(As + (wm * 64 + i * 32 + l31) * LS + s * 16 + hh * 8);
; #pragma unroll
;       for (int j = 0; j < NT; ++j) b[j] = *(const bf16x8*)(Bs + (wn * 32 * NT + j * 32 + l31) * LS + s * 16 + hh * 8);
; #pragma unroll
;       for (int i = 0; i < 2; ++i)
; #pragma unroll
;         for (int j = 0; j < NT; ++j) acc[i][j] = MFMA32(a[i], b[j], acc[i][j]);
;     }
	s_waitcnt vmcnt(5)
	ds_write_b128 v34, v[52:55]
	s_waitcnt vmcnt(4)
	ds_write_b128 v34, v[56:59] offset:4608
	s_waitcnt vmcnt(3)
	ds_write_b128 v34, v[60:63] offset:9216
	s_waitcnt vmcnt(2)
	ds_write_b128 v34, v[64:67] offset:13824
	s_waitcnt vmcnt(1)
	ds_write_b128 v34, v[68:71] offset:18432
	s_waitcnt vmcnt(0)
	ds_write_b128 v34, v[72:75] offset:23040
	ds_read_b128 v[96:99], v36 offset:32256
	ds_read_b128 v[116:119], v36 offset:27648
	ds_read_b128 v[132:135], v36 offset:27680
	ds_read_b128 v[108:111], v35 offset:46080
	ds_read_b128 v[120:123], v35 offset:46112
	ds_read_b128 v[140:143], v36 offset:32288
	ds_read_b128 v[136:139], v36 offset:27712
	ds_read_b128 v[144:147], v36 offset:32320
	ds_read_b128 v[148:151], v35 offset:46144
	ds_read_b128 v[156:159], v36 offset:27744
	ds_read_b128 v[152:155], v36 offset:32352
	ds_read_b128 v[168:171], v35 offset:46176
	global_load_dwordx4 v[52:55], v[38:39], off offset:1920
	s_nop 0
	global_load_dwordx4 v[38:41], v[40:41], off offset:1920
	s_nop 0
	global_load_dwordx4 v[56:59], v[42:43], off offset:1920
	s_nop 0
	global_load_dwordx4 v[42:45], v[44:45], off offset:1920
	s_nop 0
	global_load_dwordx4 v[60:63], v[46:47], off offset:1920
	s_nop 0
	global_load_dwordx4 v[46:49], v[48:49], off offset:1920
	v_mfma_f32_32x32x16_bf16 v[2:17], v[192:195], v[112:115], v[2:17]
	v_mfma_f32_32x32x16_bf16 v[18:33], v[104:107], v[112:115], v[18:33]
	s_waitcnt lgkmcnt(11)
	s_waitcnt lgkmcnt(8)
	v_mfma_f32_32x32x16_bf16 v[2:17], v[96:99], v[108:111], v[2:17]
	v_mfma_f32_32x32x16_bf16 v[18:33], v[116:119], v[108:111], v[18:33]
	s_waitcnt lgkmcnt(6)
	v_mfma_f32_32x32x16_bf16 v[2:17], v[140:143], v[120:123], v[2:17]
	v_mfma_f32_32x32x16_bf16 v[18:33], v[132:135], v[120:123], v[18:33]
	s_waitcnt lgkmcnt(4)
	s_waitcnt lgkmcnt(3)
	v_mfma_f32_32x32x16_bf16 v[2:17], v[144:147], v[148:151], v[2:17]
	v_mfma_f32_32x32x16_bf16 v[18:33], v[136:139], v[148:151], v[18:33]
	s_waitcnt lgkmcnt(0)
	s_barrier
	s_waitcnt vmcnt(5)
	ds_write_b128 v34, v[52:55] offset:27648
	s_waitcnt vmcnt(4)
	ds_write_b128 v34, v[38:41] offset:32256
	s_waitcnt vmcnt(3)
	ds_write_b128 v34, v[56:59] offset:36864
	s_waitcnt vmcnt(2)
	ds_write_b128 v34, v[42:45] offset:41472
	s_waitcnt vmcnt(1)
	ds_write_b128 v34, v[60:63] offset:46080
	s_waitcnt vmcnt(0)
	ds_write_b128 v34, v[46:49] offset:50688
	ds_read_b128 v[160:163], v36 offset:4608
	ds_read_b128 v[172:175], v36
	ds_read_b128 v[180:183], v36 offset:32
	ds_read_b128 v[164:167], v35 offset:18432
	ds_read_b128 v[176:179], v35 offset:18464
	ds_read_b128 v[188:191], v36 offset:4640
	ds_read_b128 v[184:187], v36 offset:64
	ds_read_b128 v[192:195], v36 offset:4672
	ds_read_b128 v[104:107], v35 offset:18496
	ds_read_b128 v[112:115], v36 offset:96
	ds_read_b128 v[96:99], v36 offset:4704
	ds_read_b128 v[116:119], v35 offset:18528
	v_mfma_f32_32x32x16_bf16 v[2:17], v[152:155], v[168:171], v[2:17]
	v_mfma_f32_32x32x16_bf16 v[18:33], v[156:159], v[168:171], v[18:33]
	s_waitcnt lgkmcnt(11)
	s_waitcnt lgkmcnt(8)
	v_mfma_f32_32x32x16_bf16 v[2:17], v[160:163], v[164:167], v[2:17]
	v_mfma_f32_32x32x16_bf16 v[18:33], v[172:175], v[164:167], v[18:33]
	s_waitcnt lgkmcnt(7)
	v_mfma_f32_32x32x16_bf16 v[18:33], v[180:183], v[176:179], v[18:33]
	s_waitcnt lgkmcnt(6)
	v_mfma_f32_32x32x16_bf16 v[2:17], v[188:191], v[176:179], v[2:17]
	s_waitcnt lgkmcnt(5)
	s_waitcnt lgkmcnt(3)
	v_mfma_f32_32x32x16_bf16 v[18:33], v[184:187], v[104:107], v[18:33]
	v_mfma_f32_32x32x16_bf16 v[2:17], v[192:195], v[104:107], v[2:17]
	s_waitcnt lgkmcnt(0)
	s_barrier
	ds_read_b128 v[108:111], v35 offset:46176
	ds_read_b128 v[140:143], v36 offset:32352
	ds_read_b128 v[132:135], v36 offset:27744
	ds_read_b128 v[120:123], v35 offset:46144
	ds_read_b128 v[144:147], v36 offset:32320
	ds_read_b128 v[136:139], v36 offset:27712
	ds_read_b128 v[148:151], v35 offset:46080
	ds_read_b128 v[152:155], v35 offset:46112
	ds_read_b128 v[156:159], v36 offset:32288
	ds_read_b128 v[168:171], v36 offset:27648
	ds_read_b128 v[160:163], v36 offset:27680
	ds_read_b128 v[172:175], v36 offset:32256
	v_mfma_f32_32x32x16_bf16 v[18:33], v[112:115], v[116:119], v[18:33]
	v_mfma_f32_32x32x16_bf16 v[2:17], v[96:99], v[116:119], v[2:17]
	s_waitcnt lgkmcnt(0)
	s_barrier
; DI int crow(int r, int hh) { return (r & 3) + 8 * (r >> 2) + 4 * hh; }
; DI void resid_ctx_half(KP p, int l, int u, int which, const u16* A, int K, const u16* Wt, const float* xin, float* xout, char* smem) {
;     ...
;   const float* gate = (const float*)(p->ws + OFF_MODS) + (size_t)(l * 5 + 4) * 6144 + which * 3072 + 2048;
; #pragma unroll
;   for (int i = 0; i < 2; ++i) {
;     const int mrow0 = (mt - 128) * 128 + wm * 64 + i * 32, n = nt * 64 + wn * 32 + l31;
;     const float gv = gate[n];
; #pragma unroll
;     for (int r = 0; r < 16; ++r) {
;       const size_t o = (size_t)(mrow0 + crow(r, hh)) * 1024 + n;
;       xout[o] = xin[o] + gv * acc[i][0][r];
;     }
;   }
	s_load_dwordx2 s[4:5], s[14:15], 0x130
	s_waitcnt lgkmcnt(0)
	s_add_u32 s4, s4, s10
	v_mfma_f32_32x32x16_bf16 v[18:33], v[168:171], v[148:151], v[18:33]
	s_addc_u32 s5, s5, s11
	v_mfma_f32_32x32x16_bf16 v[2:17], v[172:175], v[148:151], v[2:17]
	v_lshrrev_b32_e32 v36, 1, v51
	v_and_b32_e32 v34, 31, v50
	v_and_b32_e32 v36, 32, v36
	v_or3_b32 v34, v34, v36, s3
	v_ashrrev_i32_e32 v35, 1, v51
	v_lshlrev_b32_e32 v198, 2, v34
	v_lshrrev_b32_e32 v34, 3, v50
	v_mfma_f32_32x32x16_bf16 v[18:33], v[160:163], v[152:155], v[18:33]
	v_and_b32_e32 v35, 0xffffffc0, v35
	v_and_or_b32 v34, v34, 4, s2
	v_add_u32_e32 v34, v34, v35
	v_ashrrev_i32_e32 v35, 31, v34
	v_lshl_add_u64 v[36:37], s[4:5], 0, v[198:199]
	s_mov_b32 s2, 0xe83a000
	v_add_co_u32_e32 v36, vcc, s2, v36
	v_mfma_f32_32x32x16_bf16 v[2:17], v[156:159], v[152:155], v[2:17]
	s_nop 0
	v_addc_co_u32_e32 v37, vcc, 0, v37, vcc
	v_mfma_f32_32x32x16_bf16 v[18:33], v[136:139], v[120:123], v[18:33]
	v_mfma_f32_32x32x16_bf16 v[2:17], v[144:147], v[120:123], v[2:17]
	v_mfma_f32_32x32x16_bf16 v[18:33], v[132:135], v[108:111], v[18:33]
	v_mfma_f32_32x32x16_bf16 v[2:17], v[140:143], v[108:111], v[2:17]
	global_load_dword v38, v[36:37], off
	v_lshl_or_b32 v196, v34, 12, v198
	v_mov_b32_e32 v132, v196
	v_add_u32_e32 v133, 0x1000, v196
	v_add_u32_e32 v134, 0x2000, v196
	v_add_u32_e32 v135, 0x3000, v196
	v_add_u32_e32 v136, 0x8000, v196
	v_add_u32_e32 v137, 0x9000, v196
	v_add_u32_e32 v138, 0xa000, v196
	v_add_u32_e32 v139, 0xb000, v196
	v_add_u32_e32 v140, 0x10000, v196
	v_add_u32_e32 v141, 0x11000, v196
	v_add_u32_e32 v142, 0x12000, v196
	v_add_u32_e32 v143, 0x13000, v196
	v_add_u32_e32 v144, 0x18000, v196
	v_add_u32_e32 v145, 0x19000, v196
	v_add_u32_e32 v146, 0x1a000, v196
	v_add_u32_e32 v147, 0x1b000, v196
	v_add_u32_e32 v148, 0x20000, v196
	v_add_u32_e32 v149, 0x21000, v196
	v_add_u32_e32 v150, 0x22000, v196
	v_add_u32_e32 v151, 0x23000, v196
	v_add_u32_e32 v152, 0x28000, v196
	v_add_u32_e32 v153, 0x29000, v196
	v_add_u32_e32 v154, 0x2a000, v196
	v_add_u32_e32 v155, 0x2b000, v196
	v_add_u32_e32 v156, 0x30000, v196
	v_add_u32_e32 v157, 0x31000, v196
	v_add_u32_e32 v158, 0x32000, v196
	v_add_u32_e32 v159, 0x33000, v196
	v_add_u32_e32 v160, 0x38000, v196
	v_add_u32_e32 v161, 0x39000, v196
	v_add_u32_e32 v162, 0x3a000, v196
	v_add_u32_e32 v163, 0x3b000, v196
	global_load_dword v164, v132, s[12:13]
	global_load_dword v165, v133, s[12:13]
	global_load_dword v166, v134, s[12:13]
	global_load_dword v167, v135, s[12:13]
	global_load_dword v168, v136, s[12:13]
	global_load_dword v169, v137, s[12:13]
	global_load_dword v170, v138, s[12:13]
	global_load_dword v171, v139, s[12:13]
	global_load_dword v172, v140, s[12:13]
	global_load_dword v173, v141, s[12:13]
	global_load_dword v174, v142, s[12:13]
	global_load_dword v175, v143, s[12:13]
	global_load_dword v176, v144, s[12:13]
	global_load_dword v177, v145, s[12:13]
	global_load_dword v178, v146, s[12:13]
	global_load_dword v179, v147, s[12:13]
	global_load_dword v180, v148, s[12:13]
	global_load_dword v181, v149, s[12:13]
	global_load_dword v182, v150, s[12:13]
	global_load_dword v183, v151, s[12:13]
	global_load_dword v184, v152, s[12:13]
	global_load_dword v185, v153, s[12:13]
	global_load_dword v186, v154, s[12:13]
	global_load_dword v187, v155, s[12:13]
	global_load_dword v188, v156, s[12:13]
	global_load_dword v189, v157, s[12:13]
	global_load_dword v190, v158, s[12:13]
	global_load_dword v191, v159, s[12:13]
	global_load_dword v192, v160, s[12:13]
	global_load_dword v193, v161, s[12:13]
	global_load_dword v194, v162, s[12:13]
	global_load_dword v195, v163, s[12:13]
	s_waitcnt vmcnt(31)
	v_fma_f32 v18, v18, v38, v164
	global_store_dword v132, v18, s[16:17]
	s_waitcnt vmcnt(31)
	v_fma_f32 v19, v19, v38, v165
	global_store_dword v133, v19, s[16:17]
	s_waitcnt vmcnt(31)
	v_fma_f32 v20, v20, v38, v166
	global_store_dword v134, v20, s[16:17]
	s_waitcnt vmcnt(31)
	v_fma_f32 v21, v21, v38, v167
	global_store_dword v135, v21, s[16:17]
	s_waitcnt vmcnt(31)
	v_fma_f32 v22, v22, v38, v168
	global_store_dword v136, v22, s[16:17]
	s_waitcnt vmcnt(31)
	v_fma_f32 v23, v23, v38, v169
	global_store_dword v137, v23, s[16:17]
	s_waitcnt vmcnt(31)
	v_fma_f32 v24, v24, v38, v170
	global_store_dword v138, v24, s[16:17]
	s_waitcnt vmcnt(31)
	v_fma_f32 v25, v25, v38, v171
	global_store_dword v139, v25, s[16:17]
	s_waitcnt vmcnt(31)
	v_fma_f32 v26, v26, v38, v172
	global_store_dword v140, v26, s[16:17]
	s_waitcnt vmcnt(31)
	v_fma_f32 v27, v27, v38, v173
	global_store_dword v141, v27, s[16:17]
	s_waitcnt vmcnt(31)
	v_fma_f32 v28, v28, v38, v174
	global_store_dword v142, v28, s[16:17]
	s_waitcnt vmcnt(31)
	v_fma_f32 v29, v29, v38, v175
	global_store_dword v143, v29, s[16:17]
	s_waitcnt vmcnt(31)
	v_fma_f32 v30, v30, v38, v176
	global_store_dword v144, v30, s[16:17]
	s_waitcnt vmcnt(31)
	v_fma_f32 v31, v31, v38, v177
	global_store_dword v145, v31, s[16:17]
	s_waitcnt vmcnt(31)
	v_fma_f32 v32, v32, v38, v178
	global_store_dword v146, v32, s[16:17]
	s_waitcnt vmcnt(31)
	v_fma_f32 v33, v33, v38, v179
	global_store_dword v147, v33, s[16:17]
	s_waitcnt vmcnt(31)
	v_fma_f32 v2, v2, v38, v180
	global_store_dword v148, v2, s[16:17]
	s_waitcnt vmcnt(31)
	v_fma_f32 v3, v3, v38, v181
	global_store_dword v149, v3, s[16:17]
	s_waitcnt vmcnt(31)
	v_fma_f32 v4, v4, v38, v182
	global_store_dword v150, v4, s[16:17]
	s_waitcnt vmcnt(31)
	v_fma_f32 v5, v5, v38, v183
	global_store_dword v151, v5, s[16:17]
	s_waitcnt vmcnt(31)
	v_fma_f32 v6, v6, v38, v184
	global_store_dword v152, v6, s[16:17]
	s_waitcnt vmcnt(31)
	v_fma_f32 v7, v7, v38, v185
	global_store_dword v153, v7, s[16:17]
	s_waitcnt vmcnt(31)
	v_fma_f32 v8, v8, v38, v186
	global_store_dword v154, v8, s[16:17]
	s_waitcnt vmcnt(31)
	v_fma_f32 v9, v9, v38, v187
	global_store_dword v155, v9, s[16:17]
	s_waitcnt vmcnt(31)
	v_fma_f32 v10, v10, v38, v188
	global_store_dword v156, v10, s[16:17]
	s_waitcnt vmcnt(31)
	v_fma_f32 v11, v11, v38, v189
	global_store_dword v157, v11, s[16:17]
	s_waitcnt vmcnt(31)
	v_fma_f32 v12, v12, v38, v190
	global_store_dword v158, v12, s[16:17]
	s_waitcnt vmcnt(31)
	v_fma_f32 v13, v13, v38, v191
	global_store_dword v159, v13, s[16:17]
	s_waitcnt vmcnt(31)
	v_fma_f32 v14, v14, v38, v192
	global_store_dword v160, v14, s[16:17]
	s_waitcnt vmcnt(31)
	v_fma_f32 v15, v15, v38, v193
	global_store_dword v161, v15, s[16:17]
	s_waitcnt vmcnt(31)
	v_fma_f32 v16, v16, v38, v194
	global_store_dword v162, v16, s[16:17]
	s_waitcnt vmcnt(31)
	v_fma_f32 v17, v17, v38, v195
	global_store_dword v163, v17, s[16:17]
	s_branch .LBB0_1785
